# v67 + s_setprio 1 issued before the LOAD segment's closing s_waitcnt (hidden in the wait's shadow)
# speedup vs baseline: 1.0094x; 1.0094x over previous
.LBB0_297:
	s_add_u32 s47, s38, s46
	s_addc_u32 s66, s39, 0
	s_add_u32 s64, s47, 0x100
	s_addc_u32 s65, s66, 0
	s_and_b64 s[48:49], s[44:45], exec
	s_cselect_b32 s49, s70, s65
	s_cselect_b32 s48, s71, s64
	s_add_u32 s46, s36, s46
	s_addc_u32 s64, s37, 0
	s_add_u32 s46, s46, 0x100
	s_addc_u32 s64, s64, 0
	s_and_b64 s[44:45], s[44:45], exec
	s_cselect_b32 s65, s72, s64
	s_cselect_b32 s64, s73, s46
	s_add_u32 s68, s47, 0x10080
	ds_read_b128 v[150:153], v146
	ds_read_b128 v[154:157], v146 offset:1024
	ds_read_b128 v[158:161], v146 offset:2048
	ds_read_b128 v[162:165], v146 offset:3072
	ds_read_b128 v[166:169], v147
	ds_read_b128 v[170:173], v147 offset:1024
	ds_read_b128 v[174:177], v147 offset:2048
	ds_read_b128 v[178:181], v147 offset:3072
	s_addc_u32 s69, s66, 0
	s_add_i32 s83, s30, s2
	s_add_i32 m0, s16, 0xc000
	s_add_i32 s84, s16, 0xe000
	s_add_i32 s80, s83, 0x2000
	s_add_u32 s66, s64, 0x40000
	s_addc_u32 s67, s65, 0
	s_add_i32 s82, s31, s2
	s_add_i32 s81, s82, 0x2000
	s_add_i32 s79, 0, 0x18000
	s_add_i32 s78, 0, 0x1c000
	s_add_u32 s46, s48, 0x10000
	s_addc_u32 s47, s49, 0
	s_add_i32 s77, s79, s2
	s_add_i32 s75, s77, 0x2000
	s_add_u32 s44, s64, 0x40080
	s_addc_u32 s45, s65, 0
	s_add_i32 s76, s78, s2
	s_add_i32 s74, s76, 0x2000
	v_lshl_add_u64 v[202:203], s[68:69], 0, v[130:131]
	ds_read_b128 v[182:185], v148
	ds_read_b128 v[186:189], v148 offset:1024
	ds_read_b128 v[190:193], v148 offset:2048
	ds_read_b128 v[194:197], v148 offset:3072
	ds_read_b128 v[198:201], v148 offset:4096
	ds_read_b128 v[206:209], v148 offset:5120
	ds_read_b128 v[210:213], v148 offset:6144
	ds_read_b128 v[214:217], v148 offset:7168
	global_load_lds_dwordx4 v[202:203], off
	s_mov_b32 m0, s84
	v_lshl_add_u64 v[202:203], s[68:69], 0, v[132:133]
	global_load_lds_dwordx4 v[202:203], off
	s_setprio 1
	s_waitcnt vmcnt(8) lgkmcnt(0)
	s_barrier
	v_mfma_f32_16x16x32_bf16 v[126:129], v[150:153], v[182:185], v[126:129]
	v_mfma_f32_16x16x32_bf16 v[122:125], v[158:161], v[182:185], v[122:125]
	v_mfma_f32_16x16x32_bf16 v[118:121], v[150:153], v[190:193], v[118:121]
	v_mfma_f32_16x16x32_bf16 v[114:117], v[158:161], v[190:193], v[114:117]
	v_mfma_f32_16x16x32_bf16 v[102:105], v[150:153], v[198:201], v[102:105]
	v_mfma_f32_16x16x32_bf16 v[98:101], v[158:161], v[198:201], v[98:101]
	v_mfma_f32_16x16x32_bf16 v[86:89], v[150:153], v[210:213], v[86:89]
	v_mfma_f32_16x16x32_bf16 v[82:85], v[158:161], v[210:213], v[82:85]
	v_mfma_f32_16x16x32_bf16 v[126:129], v[154:157], v[186:189], v[126:129]
	v_mfma_f32_16x16x32_bf16 v[122:125], v[162:165], v[186:189], v[122:125]
	v_mfma_f32_16x16x32_bf16 v[118:121], v[154:157], v[194:197], v[118:121]
	v_mfma_f32_16x16x32_bf16 v[114:117], v[162:165], v[194:197], v[114:117]
	v_mfma_f32_16x16x32_bf16 v[102:105], v[154:157], v[206:209], v[102:105]
	v_mfma_f32_16x16x32_bf16 v[98:101], v[162:165], v[206:209], v[98:101]
	v_mfma_f32_16x16x32_bf16 v[86:89], v[154:157], v[214:217], v[86:89]
	v_mfma_f32_16x16x32_bf16 v[82:85], v[162:165], v[214:217], v[82:85]
	v_mfma_f32_16x16x32_bf16 v[110:113], v[166:169], v[182:185], v[110:113]
	v_mfma_f32_16x16x32_bf16 v[106:109], v[174:177], v[182:185], v[106:109]
	v_mfma_f32_16x16x32_bf16 v[94:97], v[166:169], v[190:193], v[94:97]
	v_mfma_f32_16x16x32_bf16 v[90:93], v[174:177], v[190:193], v[90:93]
	v_mfma_f32_16x16x32_bf16 v[78:81], v[166:169], v[198:201], v[78:81]
	v_mfma_f32_16x16x32_bf16 v[74:77], v[174:177], v[198:201], v[74:77]
	v_mfma_f32_16x16x32_bf16 v[70:73], v[166:169], v[210:213], v[70:73]
	v_mfma_f32_16x16x32_bf16 v[66:69], v[174:177], v[210:213], v[66:69]
	v_mfma_f32_16x16x32_bf16 v[110:113], v[170:173], v[186:189], v[110:113]
	v_mfma_f32_16x16x32_bf16 v[106:109], v[178:181], v[186:189], v[106:109]
	v_mfma_f32_16x16x32_bf16 v[94:97], v[170:173], v[194:197], v[94:97]
	v_mfma_f32_16x16x32_bf16 v[90:93], v[178:181], v[194:197], v[90:93]
	v_mfma_f32_16x16x32_bf16 v[78:81], v[170:173], v[206:209], v[78:81]
	v_mfma_f32_16x16x32_bf16 v[74:77], v[178:181], v[206:209], v[74:77]
	v_mfma_f32_16x16x32_bf16 v[70:73], v[170:173], v[214:217], v[70:73]
	v_mfma_f32_16x16x32_bf16 v[66:69], v[178:181], v[214:217], v[66:69]
	s_setprio 0
	s_barrier
	s_mov_b32 m0, s83
	v_lshl_add_u64 v[202:203], s[64:65], 0, v[136:137]
	ds_read_b128 v[182:185], v148 offset:16384
	ds_read_b128 v[186:189], v148 offset:17408
	ds_read_b128 v[190:193], v148 offset:18432
	ds_read_b128 v[194:197], v148 offset:19456
	ds_read_b128 v[198:201], v148 offset:20480
	ds_read_b128 v[206:209], v148 offset:21504
	ds_read_b128 v[210:213], v148 offset:22528
	ds_read_b128 v[214:217], v148 offset:23552
	global_load_lds_dwordx4 v[202:203], off
	v_lshl_add_u64 v[218:219], s[64:65], 0, v[134:135]
	s_mov_b32 m0, s80
	v_lshl_add_u64 v[220:221], s[66:67], 0, v[136:137]
	global_load_lds_dwordx4 v[218:219], off
	s_mov_b32 m0, s82
	v_lshl_add_u64 v[222:223], s[48:49], 0, v[132:133]
	global_load_lds_dwordx4 v[220:221], off
	s_mov_b32 m0, s81
	v_lshl_add_u64 v[220:221], s[66:67], 0, v[134:135]
	global_load_lds_dwordx4 v[220:221], off
	s_mov_b32 m0, s16
	v_lshl_add_u64 v[220:221], s[48:49], 0, v[130:131]
	global_load_lds_dwordx4 v[220:221], off
	s_mov_b32 m0, s17
	s_nop 0
	global_load_lds_dwordx4 v[222:223], off
	s_setprio 1
	s_waitcnt vmcnt(8) lgkmcnt(0)
	s_barrier
	v_mfma_f32_16x16x32_bf16 v[62:65], v[150:153], v[182:185], v[62:65]
	v_mfma_f32_16x16x32_bf16 v[58:61], v[158:161], v[182:185], v[58:61]
	v_mfma_f32_16x16x32_bf16 v[54:57], v[150:153], v[190:193], v[54:57]
	v_mfma_f32_16x16x32_bf16 v[50:53], v[158:161], v[190:193], v[50:53]
	v_mfma_f32_16x16x32_bf16 v[38:41], v[150:153], v[198:201], v[38:41]
	v_mfma_f32_16x16x32_bf16 v[34:37], v[158:161], v[198:201], v[34:37]
	v_mfma_f32_16x16x32_bf16 v[22:25], v[150:153], v[210:213], v[22:25]
	v_mfma_f32_16x16x32_bf16 v[18:21], v[158:161], v[210:213], v[18:21]
	v_mfma_f32_16x16x32_bf16 v[62:65], v[154:157], v[186:189], v[62:65]
	v_mfma_f32_16x16x32_bf16 v[58:61], v[162:165], v[186:189], v[58:61]
	v_mfma_f32_16x16x32_bf16 v[54:57], v[154:157], v[194:197], v[54:57]
	v_mfma_f32_16x16x32_bf16 v[50:53], v[162:165], v[194:197], v[50:53]
	v_mfma_f32_16x16x32_bf16 v[38:41], v[154:157], v[206:209], v[38:41]
	v_mfma_f32_16x16x32_bf16 v[34:37], v[162:165], v[206:209], v[34:37]
	v_mfma_f32_16x16x32_bf16 v[22:25], v[154:157], v[214:217], v[22:25]
	v_mfma_f32_16x16x32_bf16 v[18:21], v[162:165], v[214:217], v[18:21]
	v_mfma_f32_16x16x32_bf16 v[46:49], v[166:169], v[182:185], v[46:49]
	v_mfma_f32_16x16x32_bf16 v[42:45], v[174:177], v[182:185], v[42:45]
	v_mfma_f32_16x16x32_bf16 v[30:33], v[166:169], v[190:193], v[30:33]
	v_mfma_f32_16x16x32_bf16 v[26:29], v[174:177], v[190:193], v[26:29]
	v_mfma_f32_16x16x32_bf16 v[14:17], v[166:169], v[198:201], v[14:17]
	v_mfma_f32_16x16x32_bf16 v[10:13], v[174:177], v[198:201], v[10:13]
	v_mfma_f32_16x16x32_bf16 v[6:9], v[166:169], v[210:213], v[6:9]
	v_mfma_f32_16x16x32_bf16 v[2:5], v[174:177], v[210:213], v[2:5]
	v_mfma_f32_16x16x32_bf16 v[46:49], v[170:173], v[186:189], v[46:49]
	v_mfma_f32_16x16x32_bf16 v[42:45], v[178:181], v[186:189], v[42:45]
	v_mfma_f32_16x16x32_bf16 v[30:33], v[170:173], v[194:197], v[30:33]
	v_mfma_f32_16x16x32_bf16 v[26:29], v[178:181], v[194:197], v[26:29]
	v_mfma_f32_16x16x32_bf16 v[14:17], v[170:173], v[206:209], v[14:17]
	v_mfma_f32_16x16x32_bf16 v[10:13], v[178:181], v[206:209], v[10:13]
	v_mfma_f32_16x16x32_bf16 v[6:9], v[170:173], v[214:217], v[6:9]
	v_mfma_f32_16x16x32_bf16 v[2:5], v[178:181], v[214:217], v[2:5]
	s_setprio 0
	s_barrier
	v_add_u32_e32 v149, s79, v145
	ds_read_b128 v[150:153], v149
	ds_read_b128 v[154:157], v149 offset:1024
	ds_read_b128 v[158:161], v149 offset:2048
	ds_read_b128 v[162:165], v149 offset:3072
	v_add_u32_e32 v149, s78, v145
	ds_read_b128 v[166:169], v149
	ds_read_b128 v[170:173], v149 offset:1024
	ds_read_b128 v[174:177], v149 offset:2048
	ds_read_b128 v[178:181], v149 offset:3072
	s_mov_b32 m0, s18
	v_lshl_add_u64 v[224:225], s[46:47], 0, v[130:131]
	ds_read_b128 v[182:185], v148 offset:32768
	ds_read_b128 v[186:189], v148 offset:33792
	ds_read_b128 v[190:193], v148 offset:34816
	ds_read_b128 v[194:197], v148 offset:35840
	ds_read_b128 v[198:201], v148 offset:36864
	ds_read_b128 v[206:209], v148 offset:37888
	ds_read_b128 v[210:213], v148 offset:38912
	ds_read_b128 v[214:217], v148 offset:39936
	global_load_lds_dwordx4 v[224:225], off
	s_mov_b32 m0, s19
	v_lshl_add_u64 v[224:225], s[46:47], 0, v[132:133]
	global_load_lds_dwordx4 v[224:225], off
	s_setprio 1
	s_waitcnt vmcnt(8) lgkmcnt(0)
	s_barrier
	v_mfma_f32_16x16x32_bf16 v[126:129], v[150:153], v[182:185], v[126:129]
	v_mfma_f32_16x16x32_bf16 v[122:125], v[158:161], v[182:185], v[122:125]
	v_mfma_f32_16x16x32_bf16 v[118:121], v[150:153], v[190:193], v[118:121]
	v_mfma_f32_16x16x32_bf16 v[114:117], v[158:161], v[190:193], v[114:117]
	v_mfma_f32_16x16x32_bf16 v[102:105], v[150:153], v[198:201], v[102:105]
	v_mfma_f32_16x16x32_bf16 v[98:101], v[158:161], v[198:201], v[98:101]
	v_mfma_f32_16x16x32_bf16 v[86:89], v[150:153], v[210:213], v[86:89]
	v_mfma_f32_16x16x32_bf16 v[82:85], v[158:161], v[210:213], v[82:85]
	v_mfma_f32_16x16x32_bf16 v[126:129], v[154:157], v[186:189], v[126:129]
	v_mfma_f32_16x16x32_bf16 v[122:125], v[162:165], v[186:189], v[122:125]
	v_mfma_f32_16x16x32_bf16 v[118:121], v[154:157], v[194:197], v[118:121]
	v_mfma_f32_16x16x32_bf16 v[114:117], v[162:165], v[194:197], v[114:117]
	v_mfma_f32_16x16x32_bf16 v[102:105], v[154:157], v[206:209], v[102:105]
	v_mfma_f32_16x16x32_bf16 v[98:101], v[162:165], v[206:209], v[98:101]
	v_mfma_f32_16x16x32_bf16 v[86:89], v[154:157], v[214:217], v[86:89]
	v_mfma_f32_16x16x32_bf16 v[82:85], v[162:165], v[214:217], v[82:85]
	v_mfma_f32_16x16x32_bf16 v[110:113], v[166:169], v[182:185], v[110:113]
	v_mfma_f32_16x16x32_bf16 v[106:109], v[174:177], v[182:185], v[106:109]
	v_mfma_f32_16x16x32_bf16 v[94:97], v[166:169], v[190:193], v[94:97]
	v_mfma_f32_16x16x32_bf16 v[90:93], v[174:177], v[190:193], v[90:93]
	v_mfma_f32_16x16x32_bf16 v[78:81], v[166:169], v[198:201], v[78:81]
	v_mfma_f32_16x16x32_bf16 v[74:77], v[174:177], v[198:201], v[74:77]
	v_mfma_f32_16x16x32_bf16 v[70:73], v[166:169], v[210:213], v[70:73]
	v_mfma_f32_16x16x32_bf16 v[66:69], v[174:177], v[210:213], v[66:69]
	v_mfma_f32_16x16x32_bf16 v[110:113], v[170:173], v[186:189], v[110:113]
	v_mfma_f32_16x16x32_bf16 v[106:109], v[178:181], v[186:189], v[106:109]
	v_mfma_f32_16x16x32_bf16 v[94:97], v[170:173], v[194:197], v[94:97]
	v_mfma_f32_16x16x32_bf16 v[90:93], v[178:181], v[194:197], v[90:93]
	v_mfma_f32_16x16x32_bf16 v[78:81], v[170:173], v[206:209], v[78:81]
	v_mfma_f32_16x16x32_bf16 v[74:77], v[178:181], v[206:209], v[74:77]
	v_mfma_f32_16x16x32_bf16 v[70:73], v[170:173], v[214:217], v[70:73]
	v_mfma_f32_16x16x32_bf16 v[66:69], v[178:181], v[214:217], v[66:69]
	s_setprio 0
	s_barrier
	s_mov_b32 m0, s77
	v_lshl_add_u64 v[202:203], v[202:203], 0, s[8:9]
	ds_read_b128 v[182:185], v148 offset:49152
	ds_read_b128 v[186:189], v148 offset:50176
	ds_read_b128 v[190:193], v148 offset:51200
	ds_read_b128 v[194:197], v148 offset:52224
	ds_read_b128 v[198:201], v148 offset:53248
	ds_read_b128 v[206:209], v148 offset:54272
	ds_read_b128 v[210:213], v148 offset:55296
	ds_read_b128 v[214:217], v148 offset:56320
	global_load_lds_dwordx4 v[202:203], off
	s_mov_b32 m0, s75
	v_lshl_add_u64 v[202:203], v[218:219], 0, s[8:9]
	global_load_lds_dwordx4 v[202:203], off
	s_mov_b32 m0, s76
	v_lshl_add_u64 v[202:203], s[44:45], 0, v[136:137]
	global_load_lds_dwordx4 v[202:203], off
	s_mov_b32 m0, s74
	v_lshl_add_u64 v[202:203], s[44:45], 0, v[134:135]
	global_load_lds_dwordx4 v[202:203], off
	s_mov_b32 m0, s28
	v_lshl_add_u64 v[202:203], v[220:221], 0, s[8:9]
	global_load_lds_dwordx4 v[202:203], off
	s_mov_b32 m0, s29
	v_lshl_add_u64 v[202:203], v[222:223], 0, s[8:9]
	global_load_lds_dwordx4 v[202:203], off
	s_setprio 1
	s_waitcnt vmcnt(8) lgkmcnt(0)
	s_barrier
	v_mfma_f32_16x16x32_bf16 v[62:65], v[150:153], v[182:185], v[62:65]
	v_mfma_f32_16x16x32_bf16 v[58:61], v[158:161], v[182:185], v[58:61]
	v_mfma_f32_16x16x32_bf16 v[54:57], v[150:153], v[190:193], v[54:57]
	v_mfma_f32_16x16x32_bf16 v[50:53], v[158:161], v[190:193], v[50:53]
	v_mfma_f32_16x16x32_bf16 v[38:41], v[150:153], v[198:201], v[38:41]
	v_mfma_f32_16x16x32_bf16 v[34:37], v[158:161], v[198:201], v[34:37]
	v_mfma_f32_16x16x32_bf16 v[22:25], v[150:153], v[210:213], v[22:25]
	v_mfma_f32_16x16x32_bf16 v[18:21], v[158:161], v[210:213], v[18:21]
	v_mfma_f32_16x16x32_bf16 v[62:65], v[154:157], v[186:189], v[62:65]
	v_mfma_f32_16x16x32_bf16 v[58:61], v[162:165], v[186:189], v[58:61]
	v_mfma_f32_16x16x32_bf16 v[54:57], v[154:157], v[194:197], v[54:57]
	v_mfma_f32_16x16x32_bf16 v[50:53], v[162:165], v[194:197], v[50:53]
	v_mfma_f32_16x16x32_bf16 v[38:41], v[154:157], v[206:209], v[38:41]
	v_mfma_f32_16x16x32_bf16 v[34:37], v[162:165], v[206:209], v[34:37]
	v_mfma_f32_16x16x32_bf16 v[22:25], v[154:157], v[214:217], v[22:25]
	v_mfma_f32_16x16x32_bf16 v[18:21], v[162:165], v[214:217], v[18:21]
	v_mfma_f32_16x16x32_bf16 v[46:49], v[166:169], v[182:185], v[46:49]
	v_mfma_f32_16x16x32_bf16 v[42:45], v[174:177], v[182:185], v[42:45]
	v_mfma_f32_16x16x32_bf16 v[30:33], v[166:169], v[190:193], v[30:33]
	v_mfma_f32_16x16x32_bf16 v[26:29], v[174:177], v[190:193], v[26:29]
	v_mfma_f32_16x16x32_bf16 v[14:17], v[166:169], v[198:201], v[14:17]
	v_mfma_f32_16x16x32_bf16 v[10:13], v[174:177], v[198:201], v[10:13]
	v_mfma_f32_16x16x32_bf16 v[6:9], v[166:169], v[210:213], v[6:9]
	v_mfma_f32_16x16x32_bf16 v[2:5], v[174:177], v[210:213], v[2:5]
	v_mfma_f32_16x16x32_bf16 v[46:49], v[170:173], v[186:189], v[46:49]
	v_mfma_f32_16x16x32_bf16 v[42:45], v[178:181], v[186:189], v[42:45]
	v_mfma_f32_16x16x32_bf16 v[30:33], v[170:173], v[194:197], v[30:33]
	v_mfma_f32_16x16x32_bf16 v[26:29], v[178:181], v[194:197], v[26:29]
	v_mfma_f32_16x16x32_bf16 v[14:17], v[170:173], v[206:209], v[14:17]
	v_mfma_f32_16x16x32_bf16 v[10:13], v[178:181], v[206:209], v[10:13]
	v_mfma_f32_16x16x32_bf16 v[6:9], v[170:173], v[214:217], v[6:9]
	v_mfma_f32_16x16x32_bf16 v[2:5], v[178:181], v[214:217], v[2:5]
	s_setprio 0
	s_barrier
	s_movk_i32 s46, 0x100
	s_andn2_b64 vcc, exec, s[42:43]
	s_mov_b64 s[44:45], -1
	s_mov_b64 s[42:43], 0
	s_cbranch_vccz .LBB0_297
	s_and_b64 vcc, exec, s[10:11]
	s_cbranch_vccz .LBB0_300
	s_barrier

.LBB0_313:
	s_add_u32 s49, s38, s48
	s_addc_u32 s68, s39, 0
	s_add_u32 s66, s49, 0x100
	s_addc_u32 s67, s68, 0
	s_and_b64 s[64:65], s[46:47], exec
	s_cselect_b32 s65, s43, s67
	s_cselect_b32 s64, s75, s66
	s_add_u32 s48, s36, s48
	s_addc_u32 s66, s37, 0
	s_add_u32 s48, s48, 0x100
	s_addc_u32 s66, s66, 0
	s_and_b64 s[46:47], s[46:47], exec
	s_cselect_b32 s67, s76, s66
	s_cselect_b32 s66, s77, s48
	s_add_u32 s70, s49, 0x10080
	ds_read_b128 v[144:147], v140
	ds_read_b128 v[148:151], v140 offset:1024
	ds_read_b128 v[152:155], v140 offset:2048
	ds_read_b128 v[156:159], v140 offset:3072
	ds_read_b128 v[160:163], v141
	ds_read_b128 v[164:167], v141 offset:1024
	ds_read_b128 v[168:171], v141 offset:2048
	ds_read_b128 v[172:175], v141 offset:3072
	s_addc_u32 s71, s68, 0
	s_add_i32 s87, s33, s2
	s_add_i32 m0, s16, 0xc000
	s_add_i32 s88, s16, 0xe000
	s_add_i32 s84, s87, 0x2000
	s_add_u32 s68, s66, 0x1000
	s_addc_u32 s69, s67, 0
	s_add_i32 s86, s34, s2
	s_add_i32 s85, s86, 0x2000
	s_add_i32 s83, 0, 0x18000
	s_add_i32 s82, 0, 0x1c000
	s_add_u32 s48, s64, 0x10000
	s_addc_u32 s49, s65, 0
	s_add_i32 s81, s83, s2
	s_add_i32 s79, s81, 0x2000
	s_add_u32 s46, s66, 0x1080
	s_addc_u32 s47, s67, 0
	s_add_i32 s80, s82, s2
	s_add_i32 s78, s80, 0x2000
	v_lshl_add_u64 v[210:211], s[70:71], 0, v[130:131]
	ds_read_b128 v[176:179], v142
	ds_read_b128 v[180:183], v142 offset:1024
	ds_read_b128 v[184:187], v142 offset:2048
	ds_read_b128 v[188:191], v142 offset:3072
	ds_read_b128 v[192:195], v142 offset:4096
	ds_read_b128 v[196:199], v142 offset:5120
	ds_read_b128 v[200:203], v142 offset:6144
	ds_read_b128 v[206:209], v142 offset:7168
	global_load_lds_dwordx4 v[210:211], off
	s_mov_b32 m0, s88
	v_lshl_add_u64 v[210:211], s[70:71], 0, v[132:133]
	global_load_lds_dwordx4 v[210:211], off
	s_setprio 1
	s_waitcnt vmcnt(8) lgkmcnt(0)
	s_barrier
	v_mfma_f32_16x16x32_bf16 v[126:129], v[144:147], v[176:179], v[126:129]
	v_mfma_f32_16x16x32_bf16 v[122:125], v[152:155], v[176:179], v[122:125]
	v_mfma_f32_16x16x32_bf16 v[118:121], v[144:147], v[184:187], v[118:121]
	v_mfma_f32_16x16x32_bf16 v[114:117], v[152:155], v[184:187], v[114:117]
	v_mfma_f32_16x16x32_bf16 v[102:105], v[144:147], v[192:195], v[102:105]
	v_mfma_f32_16x16x32_bf16 v[98:101], v[152:155], v[192:195], v[98:101]
	v_mfma_f32_16x16x32_bf16 v[86:89], v[144:147], v[200:203], v[86:89]
	v_mfma_f32_16x16x32_bf16 v[82:85], v[152:155], v[200:203], v[82:85]
	v_mfma_f32_16x16x32_bf16 v[126:129], v[148:151], v[180:183], v[126:129]
	v_mfma_f32_16x16x32_bf16 v[122:125], v[156:159], v[180:183], v[122:125]
	v_mfma_f32_16x16x32_bf16 v[118:121], v[148:151], v[188:191], v[118:121]
	v_mfma_f32_16x16x32_bf16 v[114:117], v[156:159], v[188:191], v[114:117]
	v_mfma_f32_16x16x32_bf16 v[102:105], v[148:151], v[196:199], v[102:105]
	v_mfma_f32_16x16x32_bf16 v[98:101], v[156:159], v[196:199], v[98:101]
	v_mfma_f32_16x16x32_bf16 v[86:89], v[148:151], v[206:209], v[86:89]
	v_mfma_f32_16x16x32_bf16 v[82:85], v[156:159], v[206:209], v[82:85]
	v_mfma_f32_16x16x32_bf16 v[110:113], v[160:163], v[176:179], v[110:113]
	v_mfma_f32_16x16x32_bf16 v[106:109], v[168:171], v[176:179], v[106:109]
	v_mfma_f32_16x16x32_bf16 v[94:97], v[160:163], v[184:187], v[94:97]
	v_mfma_f32_16x16x32_bf16 v[90:93], v[168:171], v[184:187], v[90:93]
	v_mfma_f32_16x16x32_bf16 v[78:81], v[160:163], v[192:195], v[78:81]
	v_mfma_f32_16x16x32_bf16 v[74:77], v[168:171], v[192:195], v[74:77]
	v_mfma_f32_16x16x32_bf16 v[70:73], v[160:163], v[200:203], v[70:73]
	v_mfma_f32_16x16x32_bf16 v[66:69], v[168:171], v[200:203], v[66:69]
	v_mfma_f32_16x16x32_bf16 v[110:113], v[164:167], v[180:183], v[110:113]
	v_mfma_f32_16x16x32_bf16 v[106:109], v[172:175], v[180:183], v[106:109]
	v_mfma_f32_16x16x32_bf16 v[94:97], v[164:167], v[188:191], v[94:97]
	v_mfma_f32_16x16x32_bf16 v[90:93], v[172:175], v[188:191], v[90:93]
	v_mfma_f32_16x16x32_bf16 v[78:81], v[164:167], v[196:199], v[78:81]
	v_mfma_f32_16x16x32_bf16 v[74:77], v[172:175], v[196:199], v[74:77]
	v_mfma_f32_16x16x32_bf16 v[70:73], v[164:167], v[206:209], v[70:73]
	v_mfma_f32_16x16x32_bf16 v[66:69], v[172:175], v[206:209], v[66:69]
	s_setprio 0
	s_barrier
	s_mov_b32 m0, s87
	v_lshl_add_u64 v[210:211], s[66:67], 0, v[136:137]
	ds_read_b128 v[176:179], v142 offset:16384
	ds_read_b128 v[180:183], v142 offset:17408
	ds_read_b128 v[184:187], v142 offset:18432
	ds_read_b128 v[188:191], v142 offset:19456
	ds_read_b128 v[192:195], v142 offset:20480
	ds_read_b128 v[196:199], v142 offset:21504
	ds_read_b128 v[200:203], v142 offset:22528
	ds_read_b128 v[206:209], v142 offset:23552
	global_load_lds_dwordx4 v[210:211], off
	v_lshl_add_u64 v[212:213], s[66:67], 0, v[134:135]
	s_mov_b32 m0, s84
	v_lshl_add_u64 v[214:215], s[68:69], 0, v[136:137]
	global_load_lds_dwordx4 v[212:213], off
	s_mov_b32 m0, s86
	v_lshl_add_u64 v[216:217], s[64:65], 0, v[132:133]
	global_load_lds_dwordx4 v[214:215], off
	s_mov_b32 m0, s85
	v_lshl_add_u64 v[214:215], s[68:69], 0, v[134:135]
	global_load_lds_dwordx4 v[214:215], off
	s_mov_b32 m0, s16
	v_lshl_add_u64 v[214:215], s[64:65], 0, v[130:131]
	global_load_lds_dwordx4 v[214:215], off
	s_mov_b32 m0, s17
	s_nop 0
	global_load_lds_dwordx4 v[216:217], off
	s_setprio 1
	s_waitcnt vmcnt(8) lgkmcnt(0)
	s_barrier
	v_mfma_f32_16x16x32_bf16 v[62:65], v[144:147], v[176:179], v[62:65]
	v_mfma_f32_16x16x32_bf16 v[58:61], v[152:155], v[176:179], v[58:61]
	v_mfma_f32_16x16x32_bf16 v[54:57], v[144:147], v[184:187], v[54:57]
	v_mfma_f32_16x16x32_bf16 v[50:53], v[152:155], v[184:187], v[50:53]
	v_mfma_f32_16x16x32_bf16 v[38:41], v[144:147], v[192:195], v[38:41]
	v_mfma_f32_16x16x32_bf16 v[34:37], v[152:155], v[192:195], v[34:37]
	v_mfma_f32_16x16x32_bf16 v[22:25], v[144:147], v[200:203], v[22:25]
	v_mfma_f32_16x16x32_bf16 v[18:21], v[152:155], v[200:203], v[18:21]
	v_mfma_f32_16x16x32_bf16 v[62:65], v[148:151], v[180:183], v[62:65]
	v_mfma_f32_16x16x32_bf16 v[58:61], v[156:159], v[180:183], v[58:61]
	v_mfma_f32_16x16x32_bf16 v[54:57], v[148:151], v[188:191], v[54:57]
	v_mfma_f32_16x16x32_bf16 v[50:53], v[156:159], v[188:191], v[50:53]
	v_mfma_f32_16x16x32_bf16 v[38:41], v[148:151], v[196:199], v[38:41]
	v_mfma_f32_16x16x32_bf16 v[34:37], v[156:159], v[196:199], v[34:37]
	v_mfma_f32_16x16x32_bf16 v[22:25], v[148:151], v[206:209], v[22:25]
	v_mfma_f32_16x16x32_bf16 v[18:21], v[156:159], v[206:209], v[18:21]
	v_mfma_f32_16x16x32_bf16 v[46:49], v[160:163], v[176:179], v[46:49]
	v_mfma_f32_16x16x32_bf16 v[42:45], v[168:171], v[176:179], v[42:45]
	v_mfma_f32_16x16x32_bf16 v[30:33], v[160:163], v[184:187], v[30:33]
	v_mfma_f32_16x16x32_bf16 v[26:29], v[168:171], v[184:187], v[26:29]
	v_mfma_f32_16x16x32_bf16 v[14:17], v[160:163], v[192:195], v[14:17]
	v_mfma_f32_16x16x32_bf16 v[10:13], v[168:171], v[192:195], v[10:13]
	v_mfma_f32_16x16x32_bf16 v[6:9], v[160:163], v[200:203], v[6:9]
	v_mfma_f32_16x16x32_bf16 v[2:5], v[168:171], v[200:203], v[2:5]
	v_mfma_f32_16x16x32_bf16 v[46:49], v[164:167], v[180:183], v[46:49]
	v_mfma_f32_16x16x32_bf16 v[42:45], v[172:175], v[180:183], v[42:45]
	v_mfma_f32_16x16x32_bf16 v[30:33], v[164:167], v[188:191], v[30:33]
	v_mfma_f32_16x16x32_bf16 v[26:29], v[172:175], v[188:191], v[26:29]
	v_mfma_f32_16x16x32_bf16 v[14:17], v[164:167], v[196:199], v[14:17]
	v_mfma_f32_16x16x32_bf16 v[10:13], v[172:175], v[196:199], v[10:13]
	v_mfma_f32_16x16x32_bf16 v[6:9], v[164:167], v[206:209], v[6:9]
	v_mfma_f32_16x16x32_bf16 v[2:5], v[172:175], v[206:209], v[2:5]
	s_setprio 0
	s_barrier
	v_add_u32_e32 v143, s83, v139
	ds_read_b128 v[144:147], v143
	ds_read_b128 v[148:151], v143 offset:1024
	ds_read_b128 v[152:155], v143 offset:2048
	ds_read_b128 v[156:159], v143 offset:3072
	v_add_u32_e32 v143, s82, v139
	ds_read_b128 v[160:163], v143
	ds_read_b128 v[164:167], v143 offset:1024
	ds_read_b128 v[168:171], v143 offset:2048
	ds_read_b128 v[172:175], v143 offset:3072
	s_mov_b32 m0, s18
	v_lshl_add_u64 v[218:219], s[48:49], 0, v[130:131]
	ds_read_b128 v[176:179], v142 offset:32768
	ds_read_b128 v[180:183], v142 offset:33792
	ds_read_b128 v[184:187], v142 offset:34816
	ds_read_b128 v[188:191], v142 offset:35840
	ds_read_b128 v[192:195], v142 offset:36864
	ds_read_b128 v[196:199], v142 offset:37888
	ds_read_b128 v[200:203], v142 offset:38912
	ds_read_b128 v[206:209], v142 offset:39936
	global_load_lds_dwordx4 v[218:219], off
	s_mov_b32 m0, s19
	v_lshl_add_u64 v[218:219], s[48:49], 0, v[132:133]
	global_load_lds_dwordx4 v[218:219], off
	s_setprio 1
	s_waitcnt vmcnt(8) lgkmcnt(0)
	s_barrier
	v_mfma_f32_16x16x32_bf16 v[126:129], v[144:147], v[176:179], v[126:129]
	v_mfma_f32_16x16x32_bf16 v[122:125], v[152:155], v[176:179], v[122:125]
	v_mfma_f32_16x16x32_bf16 v[118:121], v[144:147], v[184:187], v[118:121]
	v_mfma_f32_16x16x32_bf16 v[114:117], v[152:155], v[184:187], v[114:117]
	v_mfma_f32_16x16x32_bf16 v[102:105], v[144:147], v[192:195], v[102:105]
	v_mfma_f32_16x16x32_bf16 v[98:101], v[152:155], v[192:195], v[98:101]
	v_mfma_f32_16x16x32_bf16 v[86:89], v[144:147], v[200:203], v[86:89]
	v_mfma_f32_16x16x32_bf16 v[82:85], v[152:155], v[200:203], v[82:85]
	v_mfma_f32_16x16x32_bf16 v[126:129], v[148:151], v[180:183], v[126:129]
	v_mfma_f32_16x16x32_bf16 v[122:125], v[156:159], v[180:183], v[122:125]
	v_mfma_f32_16x16x32_bf16 v[118:121], v[148:151], v[188:191], v[118:121]
	v_mfma_f32_16x16x32_bf16 v[114:117], v[156:159], v[188:191], v[114:117]
	v_mfma_f32_16x16x32_bf16 v[102:105], v[148:151], v[196:199], v[102:105]
	v_mfma_f32_16x16x32_bf16 v[98:101], v[156:159], v[196:199], v[98:101]
	v_mfma_f32_16x16x32_bf16 v[86:89], v[148:151], v[206:209], v[86:89]
	v_mfma_f32_16x16x32_bf16 v[82:85], v[156:159], v[206:209], v[82:85]
	v_mfma_f32_16x16x32_bf16 v[110:113], v[160:163], v[176:179], v[110:113]
	v_mfma_f32_16x16x32_bf16 v[106:109], v[168:171], v[176:179], v[106:109]
	v_mfma_f32_16x16x32_bf16 v[94:97], v[160:163], v[184:187], v[94:97]
	v_mfma_f32_16x16x32_bf16 v[90:93], v[168:171], v[184:187], v[90:93]
	v_mfma_f32_16x16x32_bf16 v[78:81], v[160:163], v[192:195], v[78:81]
	v_mfma_f32_16x16x32_bf16 v[74:77], v[168:171], v[192:195], v[74:77]
	v_mfma_f32_16x16x32_bf16 v[70:73], v[160:163], v[200:203], v[70:73]
	v_mfma_f32_16x16x32_bf16 v[66:69], v[168:171], v[200:203], v[66:69]
	v_mfma_f32_16x16x32_bf16 v[110:113], v[164:167], v[180:183], v[110:113]
	v_mfma_f32_16x16x32_bf16 v[106:109], v[172:175], v[180:183], v[106:109]
	v_mfma_f32_16x16x32_bf16 v[94:97], v[164:167], v[188:191], v[94:97]
	v_mfma_f32_16x16x32_bf16 v[90:93], v[172:175], v[188:191], v[90:93]
	v_mfma_f32_16x16x32_bf16 v[78:81], v[164:167], v[196:199], v[78:81]
	v_mfma_f32_16x16x32_bf16 v[74:77], v[172:175], v[196:199], v[74:77]
	v_mfma_f32_16x16x32_bf16 v[70:73], v[164:167], v[206:209], v[70:73]
	v_mfma_f32_16x16x32_bf16 v[66:69], v[172:175], v[206:209], v[66:69]
	s_setprio 0
	s_barrier
	s_mov_b32 m0, s81
	v_lshl_add_u64 v[210:211], v[210:211], 0, s[8:9]
	ds_read_b128 v[176:179], v142 offset:49152
	ds_read_b128 v[180:183], v142 offset:50176
	ds_read_b128 v[184:187], v142 offset:51200
	ds_read_b128 v[188:191], v142 offset:52224
	ds_read_b128 v[192:195], v142 offset:53248
	ds_read_b128 v[196:199], v142 offset:54272
	ds_read_b128 v[200:203], v142 offset:55296
	ds_read_b128 v[206:209], v142 offset:56320
	global_load_lds_dwordx4 v[210:211], off
	s_mov_b32 m0, s79
	v_lshl_add_u64 v[210:211], v[212:213], 0, s[8:9]
	global_load_lds_dwordx4 v[210:211], off
	s_mov_b32 m0, s80
	v_lshl_add_u64 v[210:211], s[46:47], 0, v[136:137]
	global_load_lds_dwordx4 v[210:211], off
	s_mov_b32 m0, s78
	v_lshl_add_u64 v[210:211], s[46:47], 0, v[134:135]
	global_load_lds_dwordx4 v[210:211], off
	s_mov_b32 m0, s30
	v_lshl_add_u64 v[210:211], v[214:215], 0, s[8:9]
	global_load_lds_dwordx4 v[210:211], off
	s_mov_b32 m0, s31
	v_lshl_add_u64 v[210:211], v[216:217], 0, s[8:9]
	global_load_lds_dwordx4 v[210:211], off
	s_setprio 1
	s_waitcnt vmcnt(8) lgkmcnt(0)
	s_barrier
	v_mfma_f32_16x16x32_bf16 v[62:65], v[144:147], v[176:179], v[62:65]
	v_mfma_f32_16x16x32_bf16 v[58:61], v[152:155], v[176:179], v[58:61]
	v_mfma_f32_16x16x32_bf16 v[54:57], v[144:147], v[184:187], v[54:57]
	v_mfma_f32_16x16x32_bf16 v[50:53], v[152:155], v[184:187], v[50:53]
	v_mfma_f32_16x16x32_bf16 v[38:41], v[144:147], v[192:195], v[38:41]
	v_mfma_f32_16x16x32_bf16 v[34:37], v[152:155], v[192:195], v[34:37]
	v_mfma_f32_16x16x32_bf16 v[22:25], v[144:147], v[200:203], v[22:25]
	v_mfma_f32_16x16x32_bf16 v[18:21], v[152:155], v[200:203], v[18:21]
	v_mfma_f32_16x16x32_bf16 v[62:65], v[148:151], v[180:183], v[62:65]
	v_mfma_f32_16x16x32_bf16 v[58:61], v[156:159], v[180:183], v[58:61]
	v_mfma_f32_16x16x32_bf16 v[54:57], v[148:151], v[188:191], v[54:57]
	v_mfma_f32_16x16x32_bf16 v[50:53], v[156:159], v[188:191], v[50:53]
	v_mfma_f32_16x16x32_bf16 v[38:41], v[148:151], v[196:199], v[38:41]
	v_mfma_f32_16x16x32_bf16 v[34:37], v[156:159], v[196:199], v[34:37]
	v_mfma_f32_16x16x32_bf16 v[22:25], v[148:151], v[206:209], v[22:25]
	v_mfma_f32_16x16x32_bf16 v[18:21], v[156:159], v[206:209], v[18:21]
	v_mfma_f32_16x16x32_bf16 v[46:49], v[160:163], v[176:179], v[46:49]
	v_mfma_f32_16x16x32_bf16 v[42:45], v[168:171], v[176:179], v[42:45]
	v_mfma_f32_16x16x32_bf16 v[30:33], v[160:163], v[184:187], v[30:33]
	v_mfma_f32_16x16x32_bf16 v[26:29], v[168:171], v[184:187], v[26:29]
	v_mfma_f32_16x16x32_bf16 v[14:17], v[160:163], v[192:195], v[14:17]
	v_mfma_f32_16x16x32_bf16 v[10:13], v[168:171], v[192:195], v[10:13]
	v_mfma_f32_16x16x32_bf16 v[6:9], v[160:163], v[200:203], v[6:9]
	v_mfma_f32_16x16x32_bf16 v[2:5], v[168:171], v[200:203], v[2:5]
	v_mfma_f32_16x16x32_bf16 v[46:49], v[164:167], v[180:183], v[46:49]
	v_mfma_f32_16x16x32_bf16 v[42:45], v[172:175], v[180:183], v[42:45]
	v_mfma_f32_16x16x32_bf16 v[30:33], v[164:167], v[188:191], v[30:33]
	v_mfma_f32_16x16x32_bf16 v[26:29], v[172:175], v[188:191], v[26:29]
	v_mfma_f32_16x16x32_bf16 v[14:17], v[164:167], v[196:199], v[14:17]
	v_mfma_f32_16x16x32_bf16 v[10:13], v[172:175], v[196:199], v[10:13]
	v_mfma_f32_16x16x32_bf16 v[6:9], v[164:167], v[206:209], v[6:9]
	v_mfma_f32_16x16x32_bf16 v[2:5], v[172:175], v[206:209], v[2:5]
	s_setprio 0
	s_barrier
	s_movk_i32 s48, 0x100
	s_andn2_b64 vcc, exec, s[44:45]
	s_mov_b64 s[46:47], -1
	s_mov_b64 s[44:45], 0
	s_cbranch_vccz .LBB0_313
	s_and_b64 vcc, exec, s[10:11]
	s_cbranch_vccz .LBB0_316
	s_barrier

.LBB0_383:
	s_add_u32 s26, s0, s22
	s_addc_u32 s27, s1, s23
	s_and_b64 s[44:45], s[36:37], exec
	s_cselect_b32 s15, s27, s43
	s_cselect_b32 s39, s26, s42
	s_add_u32 s66, s42, 0x100
	s_addc_u32 s67, s43, 0
	s_mov_b32 s68, -2
	s_mov_b64 s[42:43], 0
	ds_read_b128 v[152:155], v146
	ds_read_b128 v[156:159], v146 offset:1024
	ds_read_b128 v[160:163], v146 offset:2048
	ds_read_b128 v[164:167], v146 offset:3072
	ds_read_b128 v[168:171], v147
	ds_read_b128 v[172:175], v147 offset:1024
	ds_read_b128 v[176:179], v147 offset:2048
	ds_read_b128 v[180:183], v147 offset:3072
	s_add_u32 s44, s42, 0x100
	s_addc_u32 s45, s43, 0
	s_add_u32 s46, s66, s42
	s_addc_u32 s47, s67, s43
	s_cmp_eq_u32 s68, 4
	s_cselect_b32 s48, 0, s44
	s_cselect_b32 s49, 0, s45
	s_cselect_b32 s46, s39, s46
	s_cselect_b32 s47, s15, s47
	s_add_u32 s48, s6, s48
	s_addc_u32 s49, s7, s49
	s_mov_b32 m0, s29
	v_lshl_add_u64 v[218:219], v[138:139], 0, s[42:43]
	ds_read_b128 v[184:187], v148
	ds_read_b128 v[188:191], v148 offset:1024
	ds_read_b128 v[192:195], v148 offset:2048
	ds_read_b128 v[196:199], v148 offset:3072
	ds_read_b128 v[200:203], v148 offset:4096
	ds_read_b128 v[206:209], v148 offset:5120
	ds_read_b128 v[210:213], v148 offset:6144
	ds_read_b128 v[214:217], v148 offset:7168
	global_load_lds_dwordx4 v[218:219], off
	s_mov_b32 m0, s30
	v_lshl_add_u64 v[218:219], v[140:141], 0, s[42:43]
	global_load_lds_dwordx4 v[218:219], off
	s_setprio 1
	s_waitcnt vmcnt(8) lgkmcnt(0)
	s_barrier
	v_mfma_f32_16x16x32_bf16 v[126:129], v[152:155], v[184:187], 0
	v_mfma_f32_16x16x32_bf16 v[122:125], v[160:163], v[184:187], 0
	v_mfma_f32_16x16x32_bf16 v[118:121], v[152:155], v[192:195], 0
	v_mfma_f32_16x16x32_bf16 v[114:117], v[160:163], v[192:195], 0
	v_mfma_f32_16x16x32_bf16 v[102:105], v[152:155], v[200:203], 0
	v_mfma_f32_16x16x32_bf16 v[98:101], v[160:163], v[200:203], 0
	v_mfma_f32_16x16x32_bf16 v[86:89], v[152:155], v[210:213], 0
	v_mfma_f32_16x16x32_bf16 v[82:85], v[160:163], v[210:213], 0
	v_mfma_f32_16x16x32_bf16 v[126:129], v[156:159], v[188:191], v[126:129]
	v_mfma_f32_16x16x32_bf16 v[122:125], v[164:167], v[188:191], v[122:125]
	v_mfma_f32_16x16x32_bf16 v[118:121], v[156:159], v[196:199], v[118:121]
	v_mfma_f32_16x16x32_bf16 v[114:117], v[164:167], v[196:199], v[114:117]
	v_mfma_f32_16x16x32_bf16 v[102:105], v[156:159], v[206:209], v[102:105]
	v_mfma_f32_16x16x32_bf16 v[98:101], v[164:167], v[206:209], v[98:101]
	v_mfma_f32_16x16x32_bf16 v[86:89], v[156:159], v[214:217], v[86:89]
	v_mfma_f32_16x16x32_bf16 v[82:85], v[164:167], v[214:217], v[82:85]
	v_mfma_f32_16x16x32_bf16 v[110:113], v[168:171], v[184:187], 0
	v_mfma_f32_16x16x32_bf16 v[106:109], v[176:179], v[184:187], 0
	v_mfma_f32_16x16x32_bf16 v[94:97], v[168:171], v[192:195], 0
	v_mfma_f32_16x16x32_bf16 v[90:93], v[176:179], v[192:195], 0
	v_mfma_f32_16x16x32_bf16 v[78:81], v[168:171], v[200:203], 0
	v_mfma_f32_16x16x32_bf16 v[74:77], v[176:179], v[200:203], 0
	v_mfma_f32_16x16x32_bf16 v[70:73], v[168:171], v[210:213], 0
	v_mfma_f32_16x16x32_bf16 v[66:69], v[176:179], v[210:213], 0
	v_mfma_f32_16x16x32_bf16 v[110:113], v[172:175], v[188:191], v[110:113]
	v_mfma_f32_16x16x32_bf16 v[106:109], v[180:183], v[188:191], v[106:109]
	v_mfma_f32_16x16x32_bf16 v[94:97], v[172:175], v[196:199], v[94:97]
	v_mfma_f32_16x16x32_bf16 v[90:93], v[180:183], v[196:199], v[90:93]
	v_mfma_f32_16x16x32_bf16 v[78:81], v[172:175], v[206:209], v[78:81]
	v_mfma_f32_16x16x32_bf16 v[74:77], v[180:183], v[206:209], v[74:77]
	v_mfma_f32_16x16x32_bf16 v[70:73], v[172:175], v[214:217], v[70:73]
	v_mfma_f32_16x16x32_bf16 v[66:69], v[180:183], v[214:217], v[66:69]
	s_setprio 0
	s_barrier
	s_mov_b32 m0, s31
	v_lshl_add_u64 v[218:219], s[46:47], 0, v[134:135]
	s_add_u32 s42, s46, 0x20000
	ds_read_b128 v[184:187], v148 offset:16384
	ds_read_b128 v[188:191], v148 offset:17408
	ds_read_b128 v[192:195], v148 offset:18432
	ds_read_b128 v[196:199], v148 offset:19456
	ds_read_b128 v[200:203], v148 offset:20480
	ds_read_b128 v[206:209], v148 offset:21504
	ds_read_b128 v[210:213], v148 offset:22528
	ds_read_b128 v[214:217], v148 offset:23552
	global_load_lds_dwordx4 v[218:219], off
	v_lshl_add_u64 v[220:221], s[46:47], 0, v[130:131]
	s_mov_b32 m0, s33
	s_addc_u32 s43, s47, 0
	global_load_lds_dwordx4 v[220:221], off
	v_lshl_add_u64 v[222:223], s[42:43], 0, v[134:135]
	s_mov_b32 m0, s34
	v_lshl_add_u64 v[224:225], s[48:49], 0, v[132:133]
	global_load_lds_dwordx4 v[222:223], off
	s_mov_b32 m0, s35
	v_lshl_add_u64 v[222:223], s[42:43], 0, v[130:131]
	global_load_lds_dwordx4 v[222:223], off
	s_mov_b32 m0, s2
	v_lshl_add_u64 v[222:223], s[48:49], 0, v[136:137]
	global_load_lds_dwordx4 v[222:223], off
	s_mov_b32 m0, s3
	s_nop 0
	global_load_lds_dwordx4 v[224:225], off
	s_setprio 1
	s_waitcnt vmcnt(8) lgkmcnt(0)
	s_barrier
	v_mfma_f32_16x16x32_bf16 v[62:65], v[152:155], v[184:187], 0
	v_mfma_f32_16x16x32_bf16 v[58:61], v[160:163], v[184:187], 0
	v_mfma_f32_16x16x32_bf16 v[54:57], v[152:155], v[192:195], 0
	v_mfma_f32_16x16x32_bf16 v[50:53], v[160:163], v[192:195], 0
	v_mfma_f32_16x16x32_bf16 v[38:41], v[152:155], v[200:203], 0
	v_mfma_f32_16x16x32_bf16 v[34:37], v[160:163], v[200:203], 0
	v_mfma_f32_16x16x32_bf16 v[22:25], v[152:155], v[210:213], 0
	v_mfma_f32_16x16x32_bf16 v[18:21], v[160:163], v[210:213], 0
	v_mfma_f32_16x16x32_bf16 v[62:65], v[156:159], v[188:191], v[62:65]
	v_mfma_f32_16x16x32_bf16 v[58:61], v[164:167], v[188:191], v[58:61]
	v_mfma_f32_16x16x32_bf16 v[54:57], v[156:159], v[196:199], v[54:57]
	v_mfma_f32_16x16x32_bf16 v[50:53], v[164:167], v[196:199], v[50:53]
	v_mfma_f32_16x16x32_bf16 v[38:41], v[156:159], v[206:209], v[38:41]
	v_mfma_f32_16x16x32_bf16 v[34:37], v[164:167], v[206:209], v[34:37]
	v_mfma_f32_16x16x32_bf16 v[22:25], v[156:159], v[214:217], v[22:25]
	v_mfma_f32_16x16x32_bf16 v[18:21], v[164:167], v[214:217], v[18:21]
	v_mfma_f32_16x16x32_bf16 v[46:49], v[168:171], v[184:187], 0
	v_mfma_f32_16x16x32_bf16 v[42:45], v[176:179], v[184:187], 0
	v_mfma_f32_16x16x32_bf16 v[30:33], v[168:171], v[192:195], 0
	v_mfma_f32_16x16x32_bf16 v[26:29], v[176:179], v[192:195], 0
	v_mfma_f32_16x16x32_bf16 v[14:17], v[168:171], v[200:203], 0
	v_mfma_f32_16x16x32_bf16 v[10:13], v[176:179], v[200:203], 0
	v_mfma_f32_16x16x32_bf16 v[6:9], v[168:171], v[210:213], 0
	v_mfma_f32_16x16x32_bf16 v[2:5], v[176:179], v[210:213], 0
	v_mfma_f32_16x16x32_bf16 v[46:49], v[172:175], v[188:191], v[46:49]
	v_mfma_f32_16x16x32_bf16 v[42:45], v[180:183], v[188:191], v[42:45]
	v_mfma_f32_16x16x32_bf16 v[30:33], v[172:175], v[196:199], v[30:33]
	v_mfma_f32_16x16x32_bf16 v[26:29], v[180:183], v[196:199], v[26:29]
	v_mfma_f32_16x16x32_bf16 v[14:17], v[172:175], v[206:209], v[14:17]
	v_mfma_f32_16x16x32_bf16 v[10:13], v[180:183], v[206:209], v[10:13]
	v_mfma_f32_16x16x32_bf16 v[6:9], v[172:175], v[214:217], v[6:9]
	v_mfma_f32_16x16x32_bf16 v[2:5], v[180:183], v[214:217], v[2:5]
	s_setprio 0
	s_barrier
	ds_read_b128 v[152:155], v149
	ds_read_b128 v[156:159], v149 offset:1024
	ds_read_b128 v[160:163], v149 offset:2048
	ds_read_b128 v[164:167], v149 offset:3072
	ds_read_b128 v[168:171], v150
	ds_read_b128 v[172:175], v150 offset:1024
	ds_read_b128 v[176:179], v150 offset:2048
	ds_read_b128 v[180:183], v150 offset:3072
	s_add_u32 s42, s48, 0x20000
	s_addc_u32 s43, s49, 0
	s_mov_b32 m0, s16
	v_lshl_add_u64 v[226:227], s[42:43], 0, v[136:137]
	ds_read_b128 v[184:187], v148 offset:32768
	ds_read_b128 v[188:191], v148 offset:33792
	ds_read_b128 v[192:195], v148 offset:34816
	ds_read_b128 v[196:199], v148 offset:35840
	ds_read_b128 v[200:203], v148 offset:36864
	ds_read_b128 v[206:209], v148 offset:37888
	ds_read_b128 v[210:213], v148 offset:38912
	ds_read_b128 v[214:217], v148 offset:39936
	global_load_lds_dwordx4 v[226:227], off
	s_mov_b32 m0, s17
	v_lshl_add_u64 v[226:227], s[42:43], 0, v[132:133]
	global_load_lds_dwordx4 v[226:227], off
	s_setprio 1
	s_waitcnt vmcnt(8) lgkmcnt(0)
	s_barrier
	v_mfma_f32_16x16x32_bf16 v[126:129], v[152:155], v[184:187], v[126:129]
	v_mfma_f32_16x16x32_bf16 v[122:125], v[160:163], v[184:187], v[122:125]
	v_mfma_f32_16x16x32_bf16 v[118:121], v[152:155], v[192:195], v[118:121]
	v_mfma_f32_16x16x32_bf16 v[114:117], v[160:163], v[192:195], v[114:117]
	v_mfma_f32_16x16x32_bf16 v[102:105], v[152:155], v[200:203], v[102:105]
	v_mfma_f32_16x16x32_bf16 v[98:101], v[160:163], v[200:203], v[98:101]
	v_mfma_f32_16x16x32_bf16 v[86:89], v[152:155], v[210:213], v[86:89]
	v_mfma_f32_16x16x32_bf16 v[82:85], v[160:163], v[210:213], v[82:85]
	v_mfma_f32_16x16x32_bf16 v[126:129], v[156:159], v[188:191], v[126:129]
	v_mfma_f32_16x16x32_bf16 v[122:125], v[164:167], v[188:191], v[122:125]
	v_mfma_f32_16x16x32_bf16 v[118:121], v[156:159], v[196:199], v[118:121]
	v_mfma_f32_16x16x32_bf16 v[114:117], v[164:167], v[196:199], v[114:117]
	v_mfma_f32_16x16x32_bf16 v[102:105], v[156:159], v[206:209], v[102:105]
	v_mfma_f32_16x16x32_bf16 v[98:101], v[164:167], v[206:209], v[98:101]
	v_mfma_f32_16x16x32_bf16 v[86:89], v[156:159], v[214:217], v[86:89]
	v_mfma_f32_16x16x32_bf16 v[82:85], v[164:167], v[214:217], v[82:85]
	v_mfma_f32_16x16x32_bf16 v[110:113], v[168:171], v[184:187], v[110:113]
	v_mfma_f32_16x16x32_bf16 v[106:109], v[176:179], v[184:187], v[106:109]
	v_mfma_f32_16x16x32_bf16 v[94:97], v[168:171], v[192:195], v[94:97]
	v_mfma_f32_16x16x32_bf16 v[90:93], v[176:179], v[192:195], v[90:93]
	v_mfma_f32_16x16x32_bf16 v[78:81], v[168:171], v[200:203], v[78:81]
	v_mfma_f32_16x16x32_bf16 v[74:77], v[176:179], v[200:203], v[74:77]
	v_mfma_f32_16x16x32_bf16 v[70:73], v[168:171], v[210:213], v[70:73]
	v_mfma_f32_16x16x32_bf16 v[66:69], v[176:179], v[210:213], v[66:69]
	v_mfma_f32_16x16x32_bf16 v[110:113], v[172:175], v[188:191], v[110:113]
	v_mfma_f32_16x16x32_bf16 v[106:109], v[180:183], v[188:191], v[106:109]
	v_mfma_f32_16x16x32_bf16 v[94:97], v[172:175], v[196:199], v[94:97]
	v_mfma_f32_16x16x32_bf16 v[90:93], v[180:183], v[196:199], v[90:93]
	v_mfma_f32_16x16x32_bf16 v[78:81], v[172:175], v[206:209], v[78:81]
	v_mfma_f32_16x16x32_bf16 v[74:77], v[180:183], v[206:209], v[74:77]
	v_mfma_f32_16x16x32_bf16 v[70:73], v[172:175], v[214:217], v[70:73]
	v_mfma_f32_16x16x32_bf16 v[66:69], v[180:183], v[214:217], v[66:69]
	s_setprio 0
	s_barrier
	s_mov_b32 m0, s62
	v_lshl_add_u64 v[218:219], v[218:219], 0, s[10:11]
	s_add_u32 s42, s46, 0x20080
	ds_read_b128 v[184:187], v148 offset:49152
	ds_read_b128 v[188:191], v148 offset:50176
	ds_read_b128 v[192:195], v148 offset:51200
	ds_read_b128 v[196:199], v148 offset:52224
	ds_read_b128 v[200:203], v148 offset:53248
	ds_read_b128 v[206:209], v148 offset:54272
	ds_read_b128 v[210:213], v148 offset:55296
	ds_read_b128 v[214:217], v148 offset:56320
	global_load_lds_dwordx4 v[218:219], off
	v_lshl_add_u64 v[218:219], v[220:221], 0, s[10:11]
	s_mov_b32 m0, s63
	s_addc_u32 s43, s47, 0
	global_load_lds_dwordx4 v[218:219], off
	s_mov_b32 m0, s64
	v_lshl_add_u64 v[218:219], s[42:43], 0, v[134:135]
	global_load_lds_dwordx4 v[218:219], off
	s_mov_b32 m0, s65
	v_lshl_add_u64 v[218:219], s[42:43], 0, v[130:131]
	global_load_lds_dwordx4 v[218:219], off
	s_mov_b32 m0, s25
	v_lshl_add_u64 v[218:219], v[222:223], 0, s[10:11]
	global_load_lds_dwordx4 v[218:219], off
	s_mov_b32 m0, s28
	v_lshl_add_u64 v[218:219], v[224:225], 0, s[10:11]
	global_load_lds_dwordx4 v[218:219], off
	s_setprio 1
	s_waitcnt vmcnt(8) lgkmcnt(0)
	s_barrier
	v_mfma_f32_16x16x32_bf16 v[62:65], v[152:155], v[184:187], v[62:65]
	v_mfma_f32_16x16x32_bf16 v[58:61], v[160:163], v[184:187], v[58:61]
	v_mfma_f32_16x16x32_bf16 v[54:57], v[152:155], v[192:195], v[54:57]
	v_mfma_f32_16x16x32_bf16 v[50:53], v[160:163], v[192:195], v[50:53]
	v_mfma_f32_16x16x32_bf16 v[38:41], v[152:155], v[200:203], v[38:41]
	v_mfma_f32_16x16x32_bf16 v[34:37], v[160:163], v[200:203], v[34:37]
	v_mfma_f32_16x16x32_bf16 v[22:25], v[152:155], v[210:213], v[22:25]
	v_mfma_f32_16x16x32_bf16 v[18:21], v[160:163], v[210:213], v[18:21]
	v_mfma_f32_16x16x32_bf16 v[62:65], v[156:159], v[188:191], v[62:65]
	v_mfma_f32_16x16x32_bf16 v[58:61], v[164:167], v[188:191], v[58:61]
	v_mfma_f32_16x16x32_bf16 v[54:57], v[156:159], v[196:199], v[54:57]
	v_mfma_f32_16x16x32_bf16 v[50:53], v[164:167], v[196:199], v[50:53]
	v_mfma_f32_16x16x32_bf16 v[38:41], v[156:159], v[206:209], v[38:41]
	v_mfma_f32_16x16x32_bf16 v[34:37], v[164:167], v[206:209], v[34:37]
	v_mfma_f32_16x16x32_bf16 v[22:25], v[156:159], v[214:217], v[22:25]
	v_mfma_f32_16x16x32_bf16 v[18:21], v[164:167], v[214:217], v[18:21]
	v_mfma_f32_16x16x32_bf16 v[46:49], v[168:171], v[184:187], v[46:49]
	v_mfma_f32_16x16x32_bf16 v[42:45], v[176:179], v[184:187], v[42:45]
	v_mfma_f32_16x16x32_bf16 v[30:33], v[168:171], v[192:195], v[30:33]
	v_mfma_f32_16x16x32_bf16 v[26:29], v[176:179], v[192:195], v[26:29]
	v_mfma_f32_16x16x32_bf16 v[14:17], v[168:171], v[200:203], v[14:17]
	v_mfma_f32_16x16x32_bf16 v[10:13], v[176:179], v[200:203], v[10:13]
	v_mfma_f32_16x16x32_bf16 v[6:9], v[168:171], v[210:213], v[6:9]
	v_mfma_f32_16x16x32_bf16 v[2:5], v[176:179], v[210:213], v[2:5]
	v_mfma_f32_16x16x32_bf16 v[46:49], v[172:175], v[188:191], v[46:49]
	v_mfma_f32_16x16x32_bf16 v[42:45], v[180:183], v[188:191], v[42:45]
	v_mfma_f32_16x16x32_bf16 v[30:33], v[172:175], v[196:199], v[30:33]
	v_mfma_f32_16x16x32_bf16 v[26:29], v[180:183], v[196:199], v[26:29]
	v_mfma_f32_16x16x32_bf16 v[14:17], v[172:175], v[206:209], v[14:17]
	v_mfma_f32_16x16x32_bf16 v[10:13], v[180:183], v[206:209], v[10:13]
	v_mfma_f32_16x16x32_bf16 v[6:9], v[172:175], v[214:217], v[6:9]
	v_mfma_f32_16x16x32_bf16 v[2:5], v[180:183], v[214:217], v[2:5]
	s_setprio 0
	s_barrier
	s_add_i32 s68, s68, 2
	s_cmp_gt_u32 s68, 5
	s_mov_b64 s[42:43], s[44:45]
.LBB0_384:
	ds_read_b128 v[152:155], v146
	ds_read_b128 v[156:159], v146 offset:1024
	ds_read_b128 v[160:163], v146 offset:2048
	ds_read_b128 v[164:167], v146 offset:3072
	ds_read_b128 v[168:171], v147
	ds_read_b128 v[172:175], v147 offset:1024
	ds_read_b128 v[176:179], v147 offset:2048
	ds_read_b128 v[180:183], v147 offset:3072
	s_add_u32 s44, s42, 0x100
	s_addc_u32 s45, s43, 0
	s_add_u32 s46, s66, s42
	s_addc_u32 s47, s67, s43
	s_cmp_eq_u32 s68, 4
	s_cselect_b32 s48, 0, s44
	s_cselect_b32 s49, 0, s45
	s_cselect_b32 s46, s39, s46
	s_cselect_b32 s47, s15, s47
	s_add_u32 s48, s6, s48
	s_addc_u32 s49, s7, s49
	s_mov_b32 m0, s29
	v_lshl_add_u64 v[218:219], v[138:139], 0, s[42:43]
	ds_read_b128 v[184:187], v148
	ds_read_b128 v[188:191], v148 offset:1024
	ds_read_b128 v[192:195], v148 offset:2048
	ds_read_b128 v[196:199], v148 offset:3072
	ds_read_b128 v[200:203], v148 offset:4096
	ds_read_b128 v[206:209], v148 offset:5120
	ds_read_b128 v[210:213], v148 offset:6144
	ds_read_b128 v[214:217], v148 offset:7168
	global_load_lds_dwordx4 v[218:219], off
	s_mov_b32 m0, s30
	v_lshl_add_u64 v[218:219], v[140:141], 0, s[42:43]
	global_load_lds_dwordx4 v[218:219], off
	s_setprio 1
	s_waitcnt vmcnt(8) lgkmcnt(0)
	s_barrier
	v_mfma_f32_16x16x32_bf16 v[126:129], v[152:155], v[184:187], v[126:129]
	v_mfma_f32_16x16x32_bf16 v[122:125], v[160:163], v[184:187], v[122:125]
	v_mfma_f32_16x16x32_bf16 v[118:121], v[152:155], v[192:195], v[118:121]
	v_mfma_f32_16x16x32_bf16 v[114:117], v[160:163], v[192:195], v[114:117]
	v_mfma_f32_16x16x32_bf16 v[102:105], v[152:155], v[200:203], v[102:105]
	v_mfma_f32_16x16x32_bf16 v[98:101], v[160:163], v[200:203], v[98:101]
	v_mfma_f32_16x16x32_bf16 v[86:89], v[152:155], v[210:213], v[86:89]
	v_mfma_f32_16x16x32_bf16 v[82:85], v[160:163], v[210:213], v[82:85]
	v_mfma_f32_16x16x32_bf16 v[126:129], v[156:159], v[188:191], v[126:129]
	v_mfma_f32_16x16x32_bf16 v[122:125], v[164:167], v[188:191], v[122:125]
	v_mfma_f32_16x16x32_bf16 v[118:121], v[156:159], v[196:199], v[118:121]
	v_mfma_f32_16x16x32_bf16 v[114:117], v[164:167], v[196:199], v[114:117]
	v_mfma_f32_16x16x32_bf16 v[102:105], v[156:159], v[206:209], v[102:105]
	v_mfma_f32_16x16x32_bf16 v[98:101], v[164:167], v[206:209], v[98:101]
	v_mfma_f32_16x16x32_bf16 v[86:89], v[156:159], v[214:217], v[86:89]
	v_mfma_f32_16x16x32_bf16 v[82:85], v[164:167], v[214:217], v[82:85]
	v_mfma_f32_16x16x32_bf16 v[110:113], v[168:171], v[184:187], v[110:113]
	v_mfma_f32_16x16x32_bf16 v[106:109], v[176:179], v[184:187], v[106:109]
	v_mfma_f32_16x16x32_bf16 v[94:97], v[168:171], v[192:195], v[94:97]
	v_mfma_f32_16x16x32_bf16 v[90:93], v[176:179], v[192:195], v[90:93]
	v_mfma_f32_16x16x32_bf16 v[78:81], v[168:171], v[200:203], v[78:81]
	v_mfma_f32_16x16x32_bf16 v[74:77], v[176:179], v[200:203], v[74:77]
	v_mfma_f32_16x16x32_bf16 v[70:73], v[168:171], v[210:213], v[70:73]
	v_mfma_f32_16x16x32_bf16 v[66:69], v[176:179], v[210:213], v[66:69]
	v_mfma_f32_16x16x32_bf16 v[110:113], v[172:175], v[188:191], v[110:113]
	v_mfma_f32_16x16x32_bf16 v[106:109], v[180:183], v[188:191], v[106:109]
	v_mfma_f32_16x16x32_bf16 v[94:97], v[172:175], v[196:199], v[94:97]
	v_mfma_f32_16x16x32_bf16 v[90:93], v[180:183], v[196:199], v[90:93]
	v_mfma_f32_16x16x32_bf16 v[78:81], v[172:175], v[206:209], v[78:81]
	v_mfma_f32_16x16x32_bf16 v[74:77], v[180:183], v[206:209], v[74:77]
	v_mfma_f32_16x16x32_bf16 v[70:73], v[172:175], v[214:217], v[70:73]
	v_mfma_f32_16x16x32_bf16 v[66:69], v[180:183], v[214:217], v[66:69]
	s_setprio 0
	s_barrier
	s_mov_b32 m0, s31
	v_lshl_add_u64 v[218:219], s[46:47], 0, v[134:135]
	s_add_u32 s42, s46, 0x20000
	ds_read_b128 v[184:187], v148 offset:16384
	ds_read_b128 v[188:191], v148 offset:17408
	ds_read_b128 v[192:195], v148 offset:18432
	ds_read_b128 v[196:199], v148 offset:19456
	ds_read_b128 v[200:203], v148 offset:20480
	ds_read_b128 v[206:209], v148 offset:21504
	ds_read_b128 v[210:213], v148 offset:22528
	ds_read_b128 v[214:217], v148 offset:23552
	global_load_lds_dwordx4 v[218:219], off
	v_lshl_add_u64 v[220:221], s[46:47], 0, v[130:131]
	s_mov_b32 m0, s33
	s_addc_u32 s43, s47, 0
	global_load_lds_dwordx4 v[220:221], off
	v_lshl_add_u64 v[222:223], s[42:43], 0, v[134:135]
	s_mov_b32 m0, s34
	v_lshl_add_u64 v[224:225], s[48:49], 0, v[132:133]
	global_load_lds_dwordx4 v[222:223], off
	s_mov_b32 m0, s35
	v_lshl_add_u64 v[222:223], s[42:43], 0, v[130:131]
	global_load_lds_dwordx4 v[222:223], off
	s_mov_b32 m0, s2
	v_lshl_add_u64 v[222:223], s[48:49], 0, v[136:137]
	global_load_lds_dwordx4 v[222:223], off
	s_mov_b32 m0, s3
	s_nop 0
	global_load_lds_dwordx4 v[224:225], off
	s_setprio 1
	s_waitcnt vmcnt(8) lgkmcnt(0)
	s_barrier
	v_mfma_f32_16x16x32_bf16 v[62:65], v[152:155], v[184:187], v[62:65]
	v_mfma_f32_16x16x32_bf16 v[58:61], v[160:163], v[184:187], v[58:61]
	v_mfma_f32_16x16x32_bf16 v[54:57], v[152:155], v[192:195], v[54:57]
	v_mfma_f32_16x16x32_bf16 v[50:53], v[160:163], v[192:195], v[50:53]
	v_mfma_f32_16x16x32_bf16 v[38:41], v[152:155], v[200:203], v[38:41]
	v_mfma_f32_16x16x32_bf16 v[34:37], v[160:163], v[200:203], v[34:37]
	v_mfma_f32_16x16x32_bf16 v[22:25], v[152:155], v[210:213], v[22:25]
	v_mfma_f32_16x16x32_bf16 v[18:21], v[160:163], v[210:213], v[18:21]
	v_mfma_f32_16x16x32_bf16 v[62:65], v[156:159], v[188:191], v[62:65]
	v_mfma_f32_16x16x32_bf16 v[58:61], v[164:167], v[188:191], v[58:61]
	v_mfma_f32_16x16x32_bf16 v[54:57], v[156:159], v[196:199], v[54:57]
	v_mfma_f32_16x16x32_bf16 v[50:53], v[164:167], v[196:199], v[50:53]
	v_mfma_f32_16x16x32_bf16 v[38:41], v[156:159], v[206:209], v[38:41]
	v_mfma_f32_16x16x32_bf16 v[34:37], v[164:167], v[206:209], v[34:37]
	v_mfma_f32_16x16x32_bf16 v[22:25], v[156:159], v[214:217], v[22:25]
	v_mfma_f32_16x16x32_bf16 v[18:21], v[164:167], v[214:217], v[18:21]
	v_mfma_f32_16x16x32_bf16 v[46:49], v[168:171], v[184:187], v[46:49]
	v_mfma_f32_16x16x32_bf16 v[42:45], v[176:179], v[184:187], v[42:45]
	v_mfma_f32_16x16x32_bf16 v[30:33], v[168:171], v[192:195], v[30:33]
	v_mfma_f32_16x16x32_bf16 v[26:29], v[176:179], v[192:195], v[26:29]
	v_mfma_f32_16x16x32_bf16 v[14:17], v[168:171], v[200:203], v[14:17]
	v_mfma_f32_16x16x32_bf16 v[10:13], v[176:179], v[200:203], v[10:13]
	v_mfma_f32_16x16x32_bf16 v[6:9], v[168:171], v[210:213], v[6:9]
	v_mfma_f32_16x16x32_bf16 v[2:5], v[176:179], v[210:213], v[2:5]
	v_mfma_f32_16x16x32_bf16 v[46:49], v[172:175], v[188:191], v[46:49]
	v_mfma_f32_16x16x32_bf16 v[42:45], v[180:183], v[188:191], v[42:45]
	v_mfma_f32_16x16x32_bf16 v[30:33], v[172:175], v[196:199], v[30:33]
	v_mfma_f32_16x16x32_bf16 v[26:29], v[180:183], v[196:199], v[26:29]
	v_mfma_f32_16x16x32_bf16 v[14:17], v[172:175], v[206:209], v[14:17]
	v_mfma_f32_16x16x32_bf16 v[10:13], v[180:183], v[206:209], v[10:13]
	v_mfma_f32_16x16x32_bf16 v[6:9], v[172:175], v[214:217], v[6:9]
	v_mfma_f32_16x16x32_bf16 v[2:5], v[180:183], v[214:217], v[2:5]
	s_setprio 0
	s_barrier
	ds_read_b128 v[152:155], v149
	ds_read_b128 v[156:159], v149 offset:1024
	ds_read_b128 v[160:163], v149 offset:2048
	ds_read_b128 v[164:167], v149 offset:3072
	ds_read_b128 v[168:171], v150
	ds_read_b128 v[172:175], v150 offset:1024
	ds_read_b128 v[176:179], v150 offset:2048
	ds_read_b128 v[180:183], v150 offset:3072
	s_add_u32 s42, s48, 0x20000
	s_addc_u32 s43, s49, 0
	s_mov_b32 m0, s16
	v_lshl_add_u64 v[226:227], s[42:43], 0, v[136:137]
	ds_read_b128 v[184:187], v148 offset:32768
	ds_read_b128 v[188:191], v148 offset:33792
	ds_read_b128 v[192:195], v148 offset:34816
	ds_read_b128 v[196:199], v148 offset:35840
	ds_read_b128 v[200:203], v148 offset:36864
	ds_read_b128 v[206:209], v148 offset:37888
	ds_read_b128 v[210:213], v148 offset:38912
	ds_read_b128 v[214:217], v148 offset:39936
	global_load_lds_dwordx4 v[226:227], off
	s_mov_b32 m0, s17
	v_lshl_add_u64 v[226:227], s[42:43], 0, v[132:133]
	global_load_lds_dwordx4 v[226:227], off
	s_setprio 1
	s_waitcnt vmcnt(8) lgkmcnt(0)
	s_barrier
	v_mfma_f32_16x16x32_bf16 v[126:129], v[152:155], v[184:187], v[126:129]
	v_mfma_f32_16x16x32_bf16 v[122:125], v[160:163], v[184:187], v[122:125]
	v_mfma_f32_16x16x32_bf16 v[118:121], v[152:155], v[192:195], v[118:121]
	v_mfma_f32_16x16x32_bf16 v[114:117], v[160:163], v[192:195], v[114:117]
	v_mfma_f32_16x16x32_bf16 v[102:105], v[152:155], v[200:203], v[102:105]
	v_mfma_f32_16x16x32_bf16 v[98:101], v[160:163], v[200:203], v[98:101]
	v_mfma_f32_16x16x32_bf16 v[86:89], v[152:155], v[210:213], v[86:89]
	v_mfma_f32_16x16x32_bf16 v[82:85], v[160:163], v[210:213], v[82:85]
	v_mfma_f32_16x16x32_bf16 v[126:129], v[156:159], v[188:191], v[126:129]
	v_mfma_f32_16x16x32_bf16 v[122:125], v[164:167], v[188:191], v[122:125]
	v_mfma_f32_16x16x32_bf16 v[118:121], v[156:159], v[196:199], v[118:121]
	v_mfma_f32_16x16x32_bf16 v[114:117], v[164:167], v[196:199], v[114:117]
	v_mfma_f32_16x16x32_bf16 v[102:105], v[156:159], v[206:209], v[102:105]
	v_mfma_f32_16x16x32_bf16 v[98:101], v[164:167], v[206:209], v[98:101]
	v_mfma_f32_16x16x32_bf16 v[86:89], v[156:159], v[214:217], v[86:89]
	v_mfma_f32_16x16x32_bf16 v[82:85], v[164:167], v[214:217], v[82:85]
	v_mfma_f32_16x16x32_bf16 v[110:113], v[168:171], v[184:187], v[110:113]
	v_mfma_f32_16x16x32_bf16 v[106:109], v[176:179], v[184:187], v[106:109]
	v_mfma_f32_16x16x32_bf16 v[94:97], v[168:171], v[192:195], v[94:97]
	v_mfma_f32_16x16x32_bf16 v[90:93], v[176:179], v[192:195], v[90:93]
	v_mfma_f32_16x16x32_bf16 v[78:81], v[168:171], v[200:203], v[78:81]
	v_mfma_f32_16x16x32_bf16 v[74:77], v[176:179], v[200:203], v[74:77]
	v_mfma_f32_16x16x32_bf16 v[70:73], v[168:171], v[210:213], v[70:73]
	v_mfma_f32_16x16x32_bf16 v[66:69], v[176:179], v[210:213], v[66:69]
	v_mfma_f32_16x16x32_bf16 v[110:113], v[172:175], v[188:191], v[110:113]
	v_mfma_f32_16x16x32_bf16 v[106:109], v[180:183], v[188:191], v[106:109]
	v_mfma_f32_16x16x32_bf16 v[94:97], v[172:175], v[196:199], v[94:97]
	v_mfma_f32_16x16x32_bf16 v[90:93], v[180:183], v[196:199], v[90:93]
	v_mfma_f32_16x16x32_bf16 v[78:81], v[172:175], v[206:209], v[78:81]
	v_mfma_f32_16x16x32_bf16 v[74:77], v[180:183], v[206:209], v[74:77]
	v_mfma_f32_16x16x32_bf16 v[70:73], v[172:175], v[214:217], v[70:73]
	v_mfma_f32_16x16x32_bf16 v[66:69], v[180:183], v[214:217], v[66:69]
	s_setprio 0
	s_barrier
	s_mov_b32 m0, s62
	v_lshl_add_u64 v[218:219], v[218:219], 0, s[10:11]
	s_add_u32 s42, s46, 0x20080
	ds_read_b128 v[184:187], v148 offset:49152
	ds_read_b128 v[188:191], v148 offset:50176
	ds_read_b128 v[192:195], v148 offset:51200
	ds_read_b128 v[196:199], v148 offset:52224
	ds_read_b128 v[200:203], v148 offset:53248
	ds_read_b128 v[206:209], v148 offset:54272
	ds_read_b128 v[210:213], v148 offset:55296
	ds_read_b128 v[214:217], v148 offset:56320
	global_load_lds_dwordx4 v[218:219], off
	v_lshl_add_u64 v[218:219], v[220:221], 0, s[10:11]
	s_mov_b32 m0, s63
	s_addc_u32 s43, s47, 0
	global_load_lds_dwordx4 v[218:219], off
	s_mov_b32 m0, s64
	v_lshl_add_u64 v[218:219], s[42:43], 0, v[134:135]
	global_load_lds_dwordx4 v[218:219], off
	s_mov_b32 m0, s65
	v_lshl_add_u64 v[218:219], s[42:43], 0, v[130:131]
	global_load_lds_dwordx4 v[218:219], off
	s_mov_b32 m0, s25
	v_lshl_add_u64 v[218:219], v[222:223], 0, s[10:11]
	global_load_lds_dwordx4 v[218:219], off
	s_mov_b32 m0, s28
	v_lshl_add_u64 v[218:219], v[224:225], 0, s[10:11]
	global_load_lds_dwordx4 v[218:219], off
	s_setprio 1
	s_waitcnt vmcnt(8) lgkmcnt(0)
	s_barrier
	v_mfma_f32_16x16x32_bf16 v[62:65], v[152:155], v[184:187], v[62:65]
	v_mfma_f32_16x16x32_bf16 v[58:61], v[160:163], v[184:187], v[58:61]
	v_mfma_f32_16x16x32_bf16 v[54:57], v[152:155], v[192:195], v[54:57]
	v_mfma_f32_16x16x32_bf16 v[50:53], v[160:163], v[192:195], v[50:53]
	v_mfma_f32_16x16x32_bf16 v[38:41], v[152:155], v[200:203], v[38:41]
	v_mfma_f32_16x16x32_bf16 v[34:37], v[160:163], v[200:203], v[34:37]
	v_mfma_f32_16x16x32_bf16 v[22:25], v[152:155], v[210:213], v[22:25]
	v_mfma_f32_16x16x32_bf16 v[18:21], v[160:163], v[210:213], v[18:21]
	v_mfma_f32_16x16x32_bf16 v[62:65], v[156:159], v[188:191], v[62:65]
	v_mfma_f32_16x16x32_bf16 v[58:61], v[164:167], v[188:191], v[58:61]
	v_mfma_f32_16x16x32_bf16 v[54:57], v[156:159], v[196:199], v[54:57]
	v_mfma_f32_16x16x32_bf16 v[50:53], v[164:167], v[196:199], v[50:53]
	v_mfma_f32_16x16x32_bf16 v[38:41], v[156:159], v[206:209], v[38:41]
	v_mfma_f32_16x16x32_bf16 v[34:37], v[164:167], v[206:209], v[34:37]
	v_mfma_f32_16x16x32_bf16 v[22:25], v[156:159], v[214:217], v[22:25]
	v_mfma_f32_16x16x32_bf16 v[18:21], v[164:167], v[214:217], v[18:21]
	v_mfma_f32_16x16x32_bf16 v[46:49], v[168:171], v[184:187], v[46:49]
	v_mfma_f32_16x16x32_bf16 v[42:45], v[176:179], v[184:187], v[42:45]
	v_mfma_f32_16x16x32_bf16 v[30:33], v[168:171], v[192:195], v[30:33]
	v_mfma_f32_16x16x32_bf16 v[26:29], v[176:179], v[192:195], v[26:29]
	v_mfma_f32_16x16x32_bf16 v[14:17], v[168:171], v[200:203], v[14:17]
	v_mfma_f32_16x16x32_bf16 v[10:13], v[176:179], v[200:203], v[10:13]
	v_mfma_f32_16x16x32_bf16 v[6:9], v[168:171], v[210:213], v[6:9]
	v_mfma_f32_16x16x32_bf16 v[2:5], v[176:179], v[210:213], v[2:5]
	v_mfma_f32_16x16x32_bf16 v[46:49], v[172:175], v[188:191], v[46:49]
	v_mfma_f32_16x16x32_bf16 v[42:45], v[180:183], v[188:191], v[42:45]
	v_mfma_f32_16x16x32_bf16 v[30:33], v[172:175], v[196:199], v[30:33]
	v_mfma_f32_16x16x32_bf16 v[26:29], v[180:183], v[196:199], v[26:29]
	v_mfma_f32_16x16x32_bf16 v[14:17], v[172:175], v[206:209], v[14:17]
	v_mfma_f32_16x16x32_bf16 v[10:13], v[180:183], v[206:209], v[10:13]
	v_mfma_f32_16x16x32_bf16 v[6:9], v[172:175], v[214:217], v[6:9]
	v_mfma_f32_16x16x32_bf16 v[2:5], v[180:183], v[214:217], v[2:5]
	s_setprio 0
	s_barrier
	s_add_i32 s68, s68, 2
	s_cmp_gt_u32 s68, 5
	s_mov_b64 s[42:43], s[44:45]
	s_cbranch_scc0 .LBB0_384
	s_and_b64 vcc, exec, s[12:13]
	s_cbranch_vccz .LBB0_387
	s_barrier

.LBB0_406:
	s_lshl_b32 s74, s12, 7
	s_add_i32 s12, s12, 2
	v_cndmask_b32_e64 v138, 0, 1, s[66:67]
	s_lshl_b64 s[66:67], s[12:13], 7
	s_and_b64 s[68:69], s[64:65], exec
	s_cselect_b32 s66, 0, s66
	s_cselect_b32 s67, 0, s67
	s_add_u32 s70, s8, s66
	s_addc_u32 s71, s9, s67
	s_lshl_b64 s[66:67], s[12:13], 12
	s_add_u32 s12, s48, s66
	s_addc_u32 s66, s49, s67
	s_and_b64 s[64:65], s[64:65], exec
	s_cselect_b32 s73, s14, s66
	s_cselect_b32 s72, s15, s12
	s_add_u32 s76, s10, s74
	s_addc_u32 s77, s11, 0
	s_add_i32 s91, s62, s16
	s_add_i32 m0, s17, 0xc000
	s_add_i32 s92, s17, 0xe000
	s_add_i32 s88, s91, 0x2000
	s_add_u32 s74, s72, 0x10000
	ds_read_b128 v[146:149], v141
	ds_read_b128 v[150:153], v141 offset:1024
	ds_read_b128 v[154:157], v141 offset:2048
	ds_read_b128 v[158:161], v141 offset:3072
	ds_read_b128 v[162:165], v143
	ds_read_b128 v[166:169], v143 offset:1024
	ds_read_b128 v[170:173], v143 offset:2048
	ds_read_b128 v[174:177], v143 offset:3072
	s_addc_u32 s75, s73, 0
	s_add_i32 s90, s63, s16
	s_add_i32 s89, s90, 0x2000
	s_add_i32 s87, 0, 0x18000
	s_add_i32 s86, 0, 0x1c000
	s_add_u32 s68, s70, 0x10000
	s_addc_u32 s69, s71, 0
	s_add_u32 s64, s72, 0x1000
	s_addc_u32 s65, s73, 0
	s_add_i32 s85, s87, s16
	s_add_i32 s83, s85, 0x2000
	s_add_u32 s66, s72, 0x11000
	s_addc_u32 s67, s73, 0
	s_add_i32 s84, s86, s16
	s_add_i32 s12, s84, 0x2000
	v_cmp_ne_u32_e32 vcc, 1, v138
	v_lshl_add_u64 v[202:203], s[76:77], 0, v[136:137]
	v_lshl_add_u64 v[202:203], v[202:203], 0, s[36:37]
	ds_read_b128 v[178:181], v144
	ds_read_b128 v[182:185], v144 offset:1024
	ds_read_b128 v[186:189], v144 offset:2048
	ds_read_b128 v[190:193], v144 offset:3072
	ds_read_b128 v[194:197], v144 offset:4096
	ds_read_b128 v[198:201], v144 offset:5120
	ds_read_b128 v[206:209], v144 offset:6144
	ds_read_b128 v[210:213], v144 offset:7168
	global_load_lds_dwordx4 v[202:203], off
	v_lshl_add_u64 v[202:203], s[76:77], 0, v[132:133]
	s_mov_b32 m0, s92
	v_lshl_add_u64 v[202:203], v[202:203], 0, s[36:37]
	global_load_lds_dwordx4 v[202:203], off
	s_setprio 1
	s_waitcnt vmcnt(8) lgkmcnt(0)
	s_barrier
	v_mfma_f32_16x16x32_bf16 v[126:129], v[146:149], v[178:181], v[126:129]
	v_mfma_f32_16x16x32_bf16 v[122:125], v[154:157], v[178:181], v[122:125]
	v_mfma_f32_16x16x32_bf16 v[118:121], v[146:149], v[186:189], v[118:121]
	v_mfma_f32_16x16x32_bf16 v[110:113], v[154:157], v[186:189], v[110:113]
	v_mfma_f32_16x16x32_bf16 v[102:105], v[146:149], v[194:197], v[102:105]
	v_mfma_f32_16x16x32_bf16 v[98:101], v[154:157], v[194:197], v[98:101]
	v_mfma_f32_16x16x32_bf16 v[86:89], v[146:149], v[206:209], v[86:89]
	v_mfma_f32_16x16x32_bf16 v[82:85], v[154:157], v[206:209], v[82:85]
	v_mfma_f32_16x16x32_bf16 v[126:129], v[150:153], v[182:185], v[126:129]
	v_mfma_f32_16x16x32_bf16 v[122:125], v[158:161], v[182:185], v[122:125]
	v_mfma_f32_16x16x32_bf16 v[118:121], v[150:153], v[190:193], v[118:121]
	v_mfma_f32_16x16x32_bf16 v[110:113], v[158:161], v[190:193], v[110:113]
	v_mfma_f32_16x16x32_bf16 v[102:105], v[150:153], v[198:201], v[102:105]
	v_mfma_f32_16x16x32_bf16 v[98:101], v[158:161], v[198:201], v[98:101]
	v_mfma_f32_16x16x32_bf16 v[86:89], v[150:153], v[210:213], v[86:89]
	v_mfma_f32_16x16x32_bf16 v[82:85], v[158:161], v[210:213], v[82:85]
	v_mfma_f32_16x16x32_bf16 v[114:117], v[162:165], v[178:181], v[114:117]
	v_mfma_f32_16x16x32_bf16 v[106:109], v[170:173], v[178:181], v[106:109]
	v_mfma_f32_16x16x32_bf16 v[94:97], v[162:165], v[186:189], v[94:97]
	v_mfma_f32_16x16x32_bf16 v[90:93], v[170:173], v[186:189], v[90:93]
	v_mfma_f32_16x16x32_bf16 v[78:81], v[162:165], v[194:197], v[78:81]
	v_mfma_f32_16x16x32_bf16 v[74:77], v[170:173], v[194:197], v[74:77]
	v_mfma_f32_16x16x32_bf16 v[70:73], v[162:165], v[206:209], v[70:73]
	v_mfma_f32_16x16x32_bf16 v[66:69], v[170:173], v[206:209], v[66:69]
	v_mfma_f32_16x16x32_bf16 v[114:117], v[166:169], v[182:185], v[114:117]
	v_mfma_f32_16x16x32_bf16 v[106:109], v[174:177], v[182:185], v[106:109]
	v_mfma_f32_16x16x32_bf16 v[94:97], v[166:169], v[190:193], v[94:97]
	v_mfma_f32_16x16x32_bf16 v[90:93], v[174:177], v[190:193], v[90:93]
	v_mfma_f32_16x16x32_bf16 v[78:81], v[166:169], v[198:201], v[78:81]
	v_mfma_f32_16x16x32_bf16 v[74:77], v[174:177], v[198:201], v[74:77]
	v_mfma_f32_16x16x32_bf16 v[70:73], v[166:169], v[210:213], v[70:73]
	v_mfma_f32_16x16x32_bf16 v[66:69], v[174:177], v[210:213], v[66:69]
	s_setprio 0
	s_barrier
	s_mov_b32 m0, s91
	v_lshl_add_u64 v[202:203], s[72:73], 0, v[134:135]
	ds_read_b128 v[178:181], v144 offset:16384
	ds_read_b128 v[182:185], v144 offset:17408
	ds_read_b128 v[186:189], v144 offset:18432
	ds_read_b128 v[190:193], v144 offset:19456
	ds_read_b128 v[194:197], v144 offset:20480
	ds_read_b128 v[198:201], v144 offset:21504
	ds_read_b128 v[206:209], v144 offset:22528
	ds_read_b128 v[210:213], v144 offset:23552
	global_load_lds_dwordx4 v[202:203], off
	v_lshl_add_u64 v[202:203], s[72:73], 0, v[130:131]
	s_mov_b32 m0, s88
	v_lshl_add_u64 v[214:215], s[70:71], 0, v[132:133]
	global_load_lds_dwordx4 v[202:203], off
	s_mov_b32 m0, s90
	v_lshl_add_u64 v[202:203], s[74:75], 0, v[134:135]
	global_load_lds_dwordx4 v[202:203], off
	s_mov_b32 m0, s89
	v_lshl_add_u64 v[202:203], s[74:75], 0, v[130:131]
	global_load_lds_dwordx4 v[202:203], off
	s_mov_b32 m0, s17
	v_lshl_add_u64 v[202:203], s[70:71], 0, v[136:137]
	global_load_lds_dwordx4 v[202:203], off
	s_mov_b32 m0, s18
	s_nop 0
	global_load_lds_dwordx4 v[214:215], off
	s_setprio 1
	s_waitcnt vmcnt(8) lgkmcnt(0)
	s_barrier
	v_mfma_f32_16x16x32_bf16 v[62:65], v[146:149], v[178:181], v[62:65]
	v_mfma_f32_16x16x32_bf16 v[58:61], v[154:157], v[178:181], v[58:61]
	v_mfma_f32_16x16x32_bf16 v[54:57], v[146:149], v[186:189], v[54:57]
	v_mfma_f32_16x16x32_bf16 v[50:53], v[154:157], v[186:189], v[50:53]
	v_mfma_f32_16x16x32_bf16 v[38:41], v[146:149], v[194:197], v[38:41]
	v_mfma_f32_16x16x32_bf16 v[34:37], v[154:157], v[194:197], v[34:37]
	v_mfma_f32_16x16x32_bf16 v[22:25], v[146:149], v[206:209], v[22:25]
	v_mfma_f32_16x16x32_bf16 v[18:21], v[154:157], v[206:209], v[18:21]
	v_mfma_f32_16x16x32_bf16 v[62:65], v[150:153], v[182:185], v[62:65]
	v_mfma_f32_16x16x32_bf16 v[58:61], v[158:161], v[182:185], v[58:61]
	v_mfma_f32_16x16x32_bf16 v[54:57], v[150:153], v[190:193], v[54:57]
	v_mfma_f32_16x16x32_bf16 v[50:53], v[158:161], v[190:193], v[50:53]
	v_mfma_f32_16x16x32_bf16 v[38:41], v[150:153], v[198:201], v[38:41]
	v_mfma_f32_16x16x32_bf16 v[34:37], v[158:161], v[198:201], v[34:37]
	v_mfma_f32_16x16x32_bf16 v[22:25], v[150:153], v[210:213], v[22:25]
	v_mfma_f32_16x16x32_bf16 v[18:21], v[158:161], v[210:213], v[18:21]
	v_mfma_f32_16x16x32_bf16 v[46:49], v[162:165], v[178:181], v[46:49]
	v_mfma_f32_16x16x32_bf16 v[42:45], v[170:173], v[178:181], v[42:45]
	v_mfma_f32_16x16x32_bf16 v[30:33], v[162:165], v[186:189], v[30:33]
	v_mfma_f32_16x16x32_bf16 v[26:29], v[170:173], v[186:189], v[26:29]
	v_mfma_f32_16x16x32_bf16 v[14:17], v[162:165], v[194:197], v[14:17]
	v_mfma_f32_16x16x32_bf16 v[10:13], v[170:173], v[194:197], v[10:13]
	v_mfma_f32_16x16x32_bf16 v[6:9], v[162:165], v[206:209], v[6:9]
	v_mfma_f32_16x16x32_bf16 v[2:5], v[170:173], v[206:209], v[2:5]
	v_mfma_f32_16x16x32_bf16 v[46:49], v[166:169], v[182:185], v[46:49]
	v_mfma_f32_16x16x32_bf16 v[42:45], v[174:177], v[182:185], v[42:45]
	v_mfma_f32_16x16x32_bf16 v[30:33], v[166:169], v[190:193], v[30:33]
	v_mfma_f32_16x16x32_bf16 v[26:29], v[174:177], v[190:193], v[26:29]
	v_mfma_f32_16x16x32_bf16 v[14:17], v[166:169], v[198:201], v[14:17]
	v_mfma_f32_16x16x32_bf16 v[10:13], v[174:177], v[198:201], v[10:13]
	v_mfma_f32_16x16x32_bf16 v[6:9], v[166:169], v[210:213], v[6:9]
	v_mfma_f32_16x16x32_bf16 v[2:5], v[174:177], v[210:213], v[2:5]
	s_setprio 0
	s_barrier
	v_add_u32_e32 v138, s87, v140
	ds_read_b128 v[146:149], v138
	ds_read_b128 v[150:153], v138 offset:1024
	ds_read_b128 v[154:157], v138 offset:2048
	ds_read_b128 v[158:161], v138 offset:3072
	v_add_u32_e32 v138, s86, v140
	ds_read_b128 v[162:165], v138
	ds_read_b128 v[166:169], v138 offset:1024
	ds_read_b128 v[170:173], v138 offset:2048
	ds_read_b128 v[174:177], v138 offset:3072
	s_mov_b32 m0, s19
	v_lshl_add_u64 v[216:217], s[68:69], 0, v[136:137]
	ds_read_b128 v[178:181], v144 offset:32768
	ds_read_b128 v[182:185], v144 offset:33792
	ds_read_b128 v[186:189], v144 offset:34816
	ds_read_b128 v[190:193], v144 offset:35840
	ds_read_b128 v[194:197], v144 offset:36864
	ds_read_b128 v[198:201], v144 offset:37888
	ds_read_b128 v[206:209], v144 offset:38912
	ds_read_b128 v[210:213], v144 offset:39936
	global_load_lds_dwordx4 v[216:217], off
	s_mov_b32 m0, s24
	v_lshl_add_u64 v[216:217], s[68:69], 0, v[132:133]
	global_load_lds_dwordx4 v[216:217], off
	s_setprio 1
	s_waitcnt vmcnt(8) lgkmcnt(0)
	s_barrier
	v_mfma_f32_16x16x32_bf16 v[126:129], v[146:149], v[178:181], v[126:129]
	v_mfma_f32_16x16x32_bf16 v[122:125], v[154:157], v[178:181], v[122:125]
	v_mfma_f32_16x16x32_bf16 v[118:121], v[146:149], v[186:189], v[118:121]
	v_mfma_f32_16x16x32_bf16 v[110:113], v[154:157], v[186:189], v[110:113]
	v_mfma_f32_16x16x32_bf16 v[102:105], v[146:149], v[194:197], v[102:105]
	v_mfma_f32_16x16x32_bf16 v[98:101], v[154:157], v[194:197], v[98:101]
	v_mfma_f32_16x16x32_bf16 v[86:89], v[146:149], v[206:209], v[86:89]
	v_mfma_f32_16x16x32_bf16 v[82:85], v[154:157], v[206:209], v[82:85]
	v_mfma_f32_16x16x32_bf16 v[126:129], v[150:153], v[182:185], v[126:129]
	v_mfma_f32_16x16x32_bf16 v[122:125], v[158:161], v[182:185], v[122:125]
	v_mfma_f32_16x16x32_bf16 v[118:121], v[150:153], v[190:193], v[118:121]
	v_mfma_f32_16x16x32_bf16 v[110:113], v[158:161], v[190:193], v[110:113]
	v_mfma_f32_16x16x32_bf16 v[102:105], v[150:153], v[198:201], v[102:105]
	v_mfma_f32_16x16x32_bf16 v[98:101], v[158:161], v[198:201], v[98:101]
	v_mfma_f32_16x16x32_bf16 v[86:89], v[150:153], v[210:213], v[86:89]
	v_mfma_f32_16x16x32_bf16 v[82:85], v[158:161], v[210:213], v[82:85]
	v_mfma_f32_16x16x32_bf16 v[114:117], v[162:165], v[178:181], v[114:117]
	v_mfma_f32_16x16x32_bf16 v[106:109], v[170:173], v[178:181], v[106:109]
	v_mfma_f32_16x16x32_bf16 v[94:97], v[162:165], v[186:189], v[94:97]
	v_mfma_f32_16x16x32_bf16 v[90:93], v[170:173], v[186:189], v[90:93]
	v_mfma_f32_16x16x32_bf16 v[78:81], v[162:165], v[194:197], v[78:81]
	v_mfma_f32_16x16x32_bf16 v[74:77], v[170:173], v[194:197], v[74:77]
	v_mfma_f32_16x16x32_bf16 v[70:73], v[162:165], v[206:209], v[70:73]
	v_mfma_f32_16x16x32_bf16 v[66:69], v[170:173], v[206:209], v[66:69]
	v_mfma_f32_16x16x32_bf16 v[114:117], v[166:169], v[182:185], v[114:117]
	v_mfma_f32_16x16x32_bf16 v[106:109], v[174:177], v[182:185], v[106:109]
	v_mfma_f32_16x16x32_bf16 v[94:97], v[166:169], v[190:193], v[94:97]
	v_mfma_f32_16x16x32_bf16 v[90:93], v[174:177], v[190:193], v[90:93]
	v_mfma_f32_16x16x32_bf16 v[78:81], v[166:169], v[198:201], v[78:81]
	v_mfma_f32_16x16x32_bf16 v[74:77], v[174:177], v[198:201], v[74:77]
	v_mfma_f32_16x16x32_bf16 v[70:73], v[166:169], v[210:213], v[70:73]
	v_mfma_f32_16x16x32_bf16 v[66:69], v[174:177], v[210:213], v[66:69]
	s_setprio 0
	s_barrier
	s_mov_b32 m0, s85
	v_lshl_add_u64 v[216:217], s[64:65], 0, v[134:135]
	ds_read_b128 v[178:181], v144 offset:49152
	ds_read_b128 v[182:185], v144 offset:50176
	ds_read_b128 v[186:189], v144 offset:51200
	ds_read_b128 v[190:193], v144 offset:52224
	ds_read_b128 v[194:197], v144 offset:53248
	ds_read_b128 v[198:201], v144 offset:54272
	ds_read_b128 v[206:209], v144 offset:55296
	ds_read_b128 v[210:213], v144 offset:56320
	global_load_lds_dwordx4 v[216:217], off
	v_lshl_add_u64 v[216:217], s[64:65], 0, v[130:131]
	s_mov_b32 m0, s83
	v_lshl_add_u64 v[202:203], v[202:203], 0, s[36:37]
	global_load_lds_dwordx4 v[216:217], off
	s_mov_b32 m0, s84
	v_lshl_add_u64 v[216:217], s[66:67], 0, v[134:135]
	global_load_lds_dwordx4 v[216:217], off
	s_mov_b32 m0, s12
	v_lshl_add_u64 v[216:217], s[66:67], 0, v[130:131]
	global_load_lds_dwordx4 v[216:217], off
	s_mov_b32 m0, s31
	s_nop 0
	global_load_lds_dwordx4 v[202:203], off
	s_mov_b32 m0, s33
	v_lshl_add_u64 v[202:203], v[214:215], 0, s[36:37]
	global_load_lds_dwordx4 v[202:203], off
	s_setprio 1
	s_waitcnt vmcnt(8) lgkmcnt(0)
	s_barrier
	v_mfma_f32_16x16x32_bf16 v[62:65], v[146:149], v[178:181], v[62:65]
	v_mfma_f32_16x16x32_bf16 v[58:61], v[154:157], v[178:181], v[58:61]
	v_mfma_f32_16x16x32_bf16 v[54:57], v[146:149], v[186:189], v[54:57]
	v_mfma_f32_16x16x32_bf16 v[50:53], v[154:157], v[186:189], v[50:53]
	v_mfma_f32_16x16x32_bf16 v[38:41], v[146:149], v[194:197], v[38:41]
	v_mfma_f32_16x16x32_bf16 v[34:37], v[154:157], v[194:197], v[34:37]
	v_mfma_f32_16x16x32_bf16 v[22:25], v[146:149], v[206:209], v[22:25]
	v_mfma_f32_16x16x32_bf16 v[18:21], v[154:157], v[206:209], v[18:21]
	v_mfma_f32_16x16x32_bf16 v[62:65], v[150:153], v[182:185], v[62:65]
	v_mfma_f32_16x16x32_bf16 v[58:61], v[158:161], v[182:185], v[58:61]
	v_mfma_f32_16x16x32_bf16 v[54:57], v[150:153], v[190:193], v[54:57]
	v_mfma_f32_16x16x32_bf16 v[50:53], v[158:161], v[190:193], v[50:53]
	v_mfma_f32_16x16x32_bf16 v[38:41], v[150:153], v[198:201], v[38:41]
	v_mfma_f32_16x16x32_bf16 v[34:37], v[158:161], v[198:201], v[34:37]
	v_mfma_f32_16x16x32_bf16 v[22:25], v[150:153], v[210:213], v[22:25]
	v_mfma_f32_16x16x32_bf16 v[18:21], v[158:161], v[210:213], v[18:21]
	v_mfma_f32_16x16x32_bf16 v[46:49], v[162:165], v[178:181], v[46:49]
	v_mfma_f32_16x16x32_bf16 v[42:45], v[170:173], v[178:181], v[42:45]
	v_mfma_f32_16x16x32_bf16 v[30:33], v[162:165], v[186:189], v[30:33]
	v_mfma_f32_16x16x32_bf16 v[26:29], v[170:173], v[186:189], v[26:29]
	v_mfma_f32_16x16x32_bf16 v[14:17], v[162:165], v[194:197], v[14:17]
	v_mfma_f32_16x16x32_bf16 v[10:13], v[170:173], v[194:197], v[10:13]
	v_mfma_f32_16x16x32_bf16 v[6:9], v[162:165], v[206:209], v[6:9]
	v_mfma_f32_16x16x32_bf16 v[2:5], v[170:173], v[206:209], v[2:5]
	v_mfma_f32_16x16x32_bf16 v[46:49], v[166:169], v[182:185], v[46:49]
	v_mfma_f32_16x16x32_bf16 v[42:45], v[174:177], v[182:185], v[42:45]
	v_mfma_f32_16x16x32_bf16 v[30:33], v[166:169], v[190:193], v[30:33]
	v_mfma_f32_16x16x32_bf16 v[26:29], v[174:177], v[190:193], v[26:29]
	v_mfma_f32_16x16x32_bf16 v[14:17], v[166:169], v[198:201], v[14:17]
	v_mfma_f32_16x16x32_bf16 v[10:13], v[174:177], v[198:201], v[10:13]
	v_mfma_f32_16x16x32_bf16 v[6:9], v[166:169], v[210:213], v[6:9]
	v_mfma_f32_16x16x32_bf16 v[2:5], v[174:177], v[210:213], v[2:5]
	s_setprio 0
	s_barrier
	s_mov_b64 s[66:67], 0
	s_mov_b64 s[64:65], -1
	s_mov_b32 s12, 2
	s_cbranch_vccz .LBB0_406
	s_and_b64 vcc, exec, s[22:23]
	s_cbranch_vccz .LBB0_409
	s_barrier

.LBB0_476:
	s_add_u32 s22, s2, s49
	s_addc_u32 s23, s3, s29
	s_and_b64 s[26:27], s[20:21], exec
	s_cselect_b32 s63, s23, s37
	s_cselect_b32 s64, s22, s36
	s_add_u32 s26, s16, s12
	s_addc_u32 s27, s17, s13
	s_and_b64 s[42:43], s[20:21], exec
	s_cselect_b32 s65, s27, s39
	s_cselect_b32 s66, s26, s38
	s_add_u32 s36, s36, 0x20080
	s_addc_u32 s37, s37, 0
	s_add_u32 s67, s38, 0x100
	s_addc_u32 s68, s39, 0
	s_mov_b32 s69, -2
	ds_read_b128 v[148:151], v144
	ds_read_b128 v[152:155], v144 offset:1024
	ds_read_b128 v[156:159], v144 offset:2048
	ds_read_b128 v[160:163], v144 offset:3072
	ds_read_b128 v[164:167], v145
	ds_read_b128 v[168:171], v145 offset:1024
	ds_read_b128 v[172:175], v145 offset:2048
	ds_read_b128 v[176:179], v145 offset:3072
	s_add_u32 s38, s36, 0xfffe0080
	s_addc_u32 s39, s37, -1
	s_cmp_eq_u32 s69, 4
	s_cselect_b32 s43, s63, s39
	s_cselect_b32 s42, s64, s38
	s_cselect_b32 s39, s65, s68
	s_cselect_b32 s38, s66, s67
	v_lshl_add_u64 v[214:215], s[36:37], 0, v[138:139]
	s_add_i32 m0, s19, 0xc000
	ds_read_b128 v[180:183], v146
	ds_read_b128 v[184:187], v146 offset:1024
	ds_read_b128 v[188:191], v146 offset:2048
	ds_read_b128 v[192:195], v146 offset:3072
	ds_read_b128 v[196:199], v146 offset:4096
	ds_read_b128 v[200:203], v146 offset:5120
	ds_read_b128 v[206:209], v146 offset:6144
	ds_read_b128 v[210:213], v146 offset:7168
	global_load_lds_dwordx4 v[214:215], off
	s_add_i32 m0, s19, 0xe000
	v_lshl_add_u64 v[214:215], s[36:37], 0, v[140:141]
	global_load_lds_dwordx4 v[214:215], off
	s_setprio 1
	s_waitcnt vmcnt(8) lgkmcnt(0)
	s_barrier
	v_mfma_f32_16x16x32_bf16 v[126:129], v[148:151], v[180:183], 0
	v_mfma_f32_16x16x32_bf16 v[122:125], v[156:159], v[180:183], 0
	v_mfma_f32_16x16x32_bf16 v[118:121], v[148:151], v[188:191], 0
	v_mfma_f32_16x16x32_bf16 v[114:117], v[156:159], v[188:191], 0
	v_mfma_f32_16x16x32_bf16 v[102:105], v[148:151], v[196:199], 0
	v_mfma_f32_16x16x32_bf16 v[98:101], v[156:159], v[196:199], 0
	v_mfma_f32_16x16x32_bf16 v[86:89], v[148:151], v[206:209], 0
	v_mfma_f32_16x16x32_bf16 v[82:85], v[156:159], v[206:209], 0
	v_mfma_f32_16x16x32_bf16 v[126:129], v[152:155], v[184:187], v[126:129]
	v_mfma_f32_16x16x32_bf16 v[122:125], v[160:163], v[184:187], v[122:125]
	v_mfma_f32_16x16x32_bf16 v[118:121], v[152:155], v[192:195], v[118:121]
	v_mfma_f32_16x16x32_bf16 v[114:117], v[160:163], v[192:195], v[114:117]
	v_mfma_f32_16x16x32_bf16 v[102:105], v[152:155], v[200:203], v[102:105]
	v_mfma_f32_16x16x32_bf16 v[98:101], v[160:163], v[200:203], v[98:101]
	v_mfma_f32_16x16x32_bf16 v[86:89], v[152:155], v[210:213], v[86:89]
	v_mfma_f32_16x16x32_bf16 v[82:85], v[160:163], v[210:213], v[82:85]
	v_mfma_f32_16x16x32_bf16 v[110:113], v[164:167], v[180:183], 0
	v_mfma_f32_16x16x32_bf16 v[106:109], v[172:175], v[180:183], 0
	v_mfma_f32_16x16x32_bf16 v[94:97], v[164:167], v[188:191], 0
	v_mfma_f32_16x16x32_bf16 v[90:93], v[172:175], v[188:191], 0
	v_mfma_f32_16x16x32_bf16 v[78:81], v[164:167], v[196:199], 0
	v_mfma_f32_16x16x32_bf16 v[74:77], v[172:175], v[196:199], 0
	v_mfma_f32_16x16x32_bf16 v[70:73], v[164:167], v[206:209], 0
	v_mfma_f32_16x16x32_bf16 v[66:69], v[172:175], v[206:209], 0
	v_mfma_f32_16x16x32_bf16 v[110:113], v[168:171], v[184:187], v[110:113]
	v_mfma_f32_16x16x32_bf16 v[106:109], v[176:179], v[184:187], v[106:109]
	v_mfma_f32_16x16x32_bf16 v[94:97], v[168:171], v[192:195], v[94:97]
	v_mfma_f32_16x16x32_bf16 v[90:93], v[176:179], v[192:195], v[90:93]
	v_mfma_f32_16x16x32_bf16 v[78:81], v[168:171], v[200:203], v[78:81]
	v_mfma_f32_16x16x32_bf16 v[74:77], v[176:179], v[200:203], v[74:77]
	v_mfma_f32_16x16x32_bf16 v[70:73], v[168:171], v[210:213], v[70:73]
	v_mfma_f32_16x16x32_bf16 v[66:69], v[176:179], v[210:213], v[66:69]
	s_setprio 0
	s_barrier
	s_add_i32 s70, s35, s18
	v_lshl_add_u64 v[214:215], s[38:39], 0, v[134:135]
	s_mov_b32 m0, s70
	ds_read_b128 v[180:183], v146 offset:16384
	ds_read_b128 v[184:187], v146 offset:17408
	ds_read_b128 v[188:191], v146 offset:18432
	ds_read_b128 v[192:195], v146 offset:19456
	ds_read_b128 v[196:199], v146 offset:20480
	ds_read_b128 v[200:203], v146 offset:21504
	ds_read_b128 v[206:209], v146 offset:22528
	ds_read_b128 v[210:213], v146 offset:23552
	global_load_lds_dwordx4 v[214:215], off
	s_add_i32 m0, s70, 0x2000
	s_add_u32 s70, s38, 0x200000
	v_lshl_add_u64 v[216:217], s[38:39], 0, v[130:131]
	s_addc_u32 s71, s39, 0
	s_add_i32 s72, s44, s18
	global_load_lds_dwordx4 v[216:217], off
	v_lshl_add_u64 v[218:219], s[70:71], 0, v[134:135]
	s_mov_b32 m0, s72
	v_lshl_add_u64 v[220:221], s[42:43], 0, v[132:133]
	global_load_lds_dwordx4 v[218:219], off
	s_add_i32 m0, s72, 0x2000
	v_lshl_add_u64 v[218:219], s[70:71], 0, v[130:131]
	global_load_lds_dwordx4 v[218:219], off
	s_mov_b32 m0, s19
	v_lshl_add_u64 v[218:219], s[42:43], 0, v[136:137]
	global_load_lds_dwordx4 v[218:219], off
	s_mov_b32 m0, s24
	s_nop 0
	global_load_lds_dwordx4 v[220:221], off
	s_setprio 1
	s_waitcnt vmcnt(8) lgkmcnt(0)
	s_barrier
	v_mfma_f32_16x16x32_bf16 v[62:65], v[148:151], v[180:183], 0
	v_mfma_f32_16x16x32_bf16 v[58:61], v[156:159], v[180:183], 0
	v_mfma_f32_16x16x32_bf16 v[54:57], v[148:151], v[188:191], 0
	v_mfma_f32_16x16x32_bf16 v[50:53], v[156:159], v[188:191], 0
	v_mfma_f32_16x16x32_bf16 v[38:41], v[148:151], v[196:199], 0
	v_mfma_f32_16x16x32_bf16 v[34:37], v[156:159], v[196:199], 0
	v_mfma_f32_16x16x32_bf16 v[22:25], v[148:151], v[206:209], 0
	v_mfma_f32_16x16x32_bf16 v[18:21], v[156:159], v[206:209], 0
	v_mfma_f32_16x16x32_bf16 v[62:65], v[152:155], v[184:187], v[62:65]
	v_mfma_f32_16x16x32_bf16 v[58:61], v[160:163], v[184:187], v[58:61]
	v_mfma_f32_16x16x32_bf16 v[54:57], v[152:155], v[192:195], v[54:57]
	v_mfma_f32_16x16x32_bf16 v[50:53], v[160:163], v[192:195], v[50:53]
	v_mfma_f32_16x16x32_bf16 v[38:41], v[152:155], v[200:203], v[38:41]
	v_mfma_f32_16x16x32_bf16 v[34:37], v[160:163], v[200:203], v[34:37]
	v_mfma_f32_16x16x32_bf16 v[22:25], v[152:155], v[210:213], v[22:25]
	v_mfma_f32_16x16x32_bf16 v[18:21], v[160:163], v[210:213], v[18:21]
	v_mfma_f32_16x16x32_bf16 v[46:49], v[164:167], v[180:183], 0
	v_mfma_f32_16x16x32_bf16 v[42:45], v[172:175], v[180:183], 0
	v_mfma_f32_16x16x32_bf16 v[30:33], v[164:167], v[188:191], 0
	v_mfma_f32_16x16x32_bf16 v[26:29], v[172:175], v[188:191], 0
	v_mfma_f32_16x16x32_bf16 v[14:17], v[164:167], v[196:199], 0
	v_mfma_f32_16x16x32_bf16 v[10:13], v[172:175], v[196:199], 0
	v_mfma_f32_16x16x32_bf16 v[6:9], v[164:167], v[206:209], 0
	v_mfma_f32_16x16x32_bf16 v[2:5], v[172:175], v[206:209], 0
	v_mfma_f32_16x16x32_bf16 v[46:49], v[168:171], v[184:187], v[46:49]
	v_mfma_f32_16x16x32_bf16 v[42:45], v[176:179], v[184:187], v[42:45]
	v_mfma_f32_16x16x32_bf16 v[30:33], v[168:171], v[192:195], v[30:33]
	v_mfma_f32_16x16x32_bf16 v[26:29], v[176:179], v[192:195], v[26:29]
	v_mfma_f32_16x16x32_bf16 v[14:17], v[168:171], v[200:203], v[14:17]
	v_mfma_f32_16x16x32_bf16 v[10:13], v[176:179], v[200:203], v[10:13]
	v_mfma_f32_16x16x32_bf16 v[6:9], v[168:171], v[210:213], v[6:9]
	v_mfma_f32_16x16x32_bf16 v[2:5], v[176:179], v[210:213], v[2:5]
	s_setprio 0
	s_barrier
	s_add_i32 s70, 0, 0x18000
	v_add_u32_e32 v147, s70, v143
	s_add_i32 s71, 0, 0x1c000
	ds_read_b128 v[148:151], v147
	ds_read_b128 v[152:155], v147 offset:1024
	ds_read_b128 v[156:159], v147 offset:2048
	ds_read_b128 v[160:163], v147 offset:3072
	v_add_u32_e32 v147, s71, v143
	ds_read_b128 v[164:167], v147
	ds_read_b128 v[168:171], v147 offset:1024
	ds_read_b128 v[172:175], v147 offset:2048
	ds_read_b128 v[176:179], v147 offset:3072
	s_add_u32 s42, s42, 0x20000
	s_addc_u32 s43, s43, 0
	s_mov_b32 m0, s25
	v_lshl_add_u64 v[222:223], s[42:43], 0, v[136:137]
	ds_read_b128 v[180:183], v146 offset:32768
	ds_read_b128 v[184:187], v146 offset:33792
	ds_read_b128 v[188:191], v146 offset:34816
	ds_read_b128 v[192:195], v146 offset:35840
	ds_read_b128 v[196:199], v146 offset:36864
	ds_read_b128 v[200:203], v146 offset:37888
	ds_read_b128 v[206:209], v146 offset:38912
	ds_read_b128 v[210:213], v146 offset:39936
	global_load_lds_dwordx4 v[222:223], off
	s_mov_b32 m0, s28
	v_lshl_add_u64 v[222:223], s[42:43], 0, v[132:133]
	global_load_lds_dwordx4 v[222:223], off
	s_setprio 1
	s_waitcnt vmcnt(8) lgkmcnt(0)
	s_barrier
	v_mfma_f32_16x16x32_bf16 v[126:129], v[148:151], v[180:183], v[126:129]
	v_mfma_f32_16x16x32_bf16 v[122:125], v[156:159], v[180:183], v[122:125]
	v_mfma_f32_16x16x32_bf16 v[118:121], v[148:151], v[188:191], v[118:121]
	v_mfma_f32_16x16x32_bf16 v[114:117], v[156:159], v[188:191], v[114:117]
	v_mfma_f32_16x16x32_bf16 v[102:105], v[148:151], v[196:199], v[102:105]
	v_mfma_f32_16x16x32_bf16 v[98:101], v[156:159], v[196:199], v[98:101]
	v_mfma_f32_16x16x32_bf16 v[86:89], v[148:151], v[206:209], v[86:89]
	v_mfma_f32_16x16x32_bf16 v[82:85], v[156:159], v[206:209], v[82:85]
	v_mfma_f32_16x16x32_bf16 v[126:129], v[152:155], v[184:187], v[126:129]
	v_mfma_f32_16x16x32_bf16 v[122:125], v[160:163], v[184:187], v[122:125]
	v_mfma_f32_16x16x32_bf16 v[118:121], v[152:155], v[192:195], v[118:121]
	v_mfma_f32_16x16x32_bf16 v[114:117], v[160:163], v[192:195], v[114:117]
	v_mfma_f32_16x16x32_bf16 v[102:105], v[152:155], v[200:203], v[102:105]
	v_mfma_f32_16x16x32_bf16 v[98:101], v[160:163], v[200:203], v[98:101]
	v_mfma_f32_16x16x32_bf16 v[86:89], v[152:155], v[210:213], v[86:89]
	v_mfma_f32_16x16x32_bf16 v[82:85], v[160:163], v[210:213], v[82:85]
	v_mfma_f32_16x16x32_bf16 v[110:113], v[164:167], v[180:183], v[110:113]
	v_mfma_f32_16x16x32_bf16 v[106:109], v[172:175], v[180:183], v[106:109]
	v_mfma_f32_16x16x32_bf16 v[94:97], v[164:167], v[188:191], v[94:97]
	v_mfma_f32_16x16x32_bf16 v[90:93], v[172:175], v[188:191], v[90:93]
	v_mfma_f32_16x16x32_bf16 v[78:81], v[164:167], v[196:199], v[78:81]
	v_mfma_f32_16x16x32_bf16 v[74:77], v[172:175], v[196:199], v[74:77]
	v_mfma_f32_16x16x32_bf16 v[70:73], v[164:167], v[206:209], v[70:73]
	v_mfma_f32_16x16x32_bf16 v[66:69], v[172:175], v[206:209], v[66:69]
	v_mfma_f32_16x16x32_bf16 v[110:113], v[168:171], v[184:187], v[110:113]
	v_mfma_f32_16x16x32_bf16 v[106:109], v[176:179], v[184:187], v[106:109]
	v_mfma_f32_16x16x32_bf16 v[94:97], v[168:171], v[192:195], v[94:97]
	v_mfma_f32_16x16x32_bf16 v[90:93], v[176:179], v[192:195], v[90:93]
	v_mfma_f32_16x16x32_bf16 v[78:81], v[168:171], v[200:203], v[78:81]
	v_mfma_f32_16x16x32_bf16 v[74:77], v[176:179], v[200:203], v[74:77]
	v_mfma_f32_16x16x32_bf16 v[70:73], v[168:171], v[210:213], v[70:73]
	v_mfma_f32_16x16x32_bf16 v[66:69], v[176:179], v[210:213], v[66:69]
	s_setprio 0
	s_barrier
	s_add_i32 s42, s70, s18
	v_lshl_add_u64 v[214:215], v[214:215], 0, s[8:9]
	s_mov_b32 m0, s42
	ds_read_b128 v[180:183], v146 offset:49152
	ds_read_b128 v[184:187], v146 offset:50176
	ds_read_b128 v[188:191], v146 offset:51200
	ds_read_b128 v[192:195], v146 offset:52224
	ds_read_b128 v[196:199], v146 offset:53248
	ds_read_b128 v[200:203], v146 offset:54272
	ds_read_b128 v[206:209], v146 offset:55296
	ds_read_b128 v[210:213], v146 offset:56320
	global_load_lds_dwordx4 v[214:215], off
	s_add_i32 m0, s42, 0x2000
	s_add_u32 s38, s38, 0x200080
	v_lshl_add_u64 v[214:215], v[216:217], 0, s[8:9]
	s_addc_u32 s39, s39, 0
	s_add_i32 s42, s71, s18
	global_load_lds_dwordx4 v[214:215], off
	s_mov_b32 m0, s42
	v_lshl_add_u64 v[214:215], s[38:39], 0, v[134:135]
	global_load_lds_dwordx4 v[214:215], off
	s_add_i32 m0, s42, 0x2000
	v_lshl_add_u64 v[214:215], s[38:39], 0, v[130:131]
	global_load_lds_dwordx4 v[214:215], off
	s_mov_b32 m0, s33
	v_lshl_add_u64 v[214:215], v[218:219], 0, s[8:9]
	global_load_lds_dwordx4 v[214:215], off
	s_mov_b32 m0, s34
	v_lshl_add_u64 v[214:215], v[220:221], 0, s[8:9]
	global_load_lds_dwordx4 v[214:215], off
	s_setprio 1
	s_waitcnt vmcnt(8) lgkmcnt(0)
	s_barrier
	v_mfma_f32_16x16x32_bf16 v[62:65], v[148:151], v[180:183], v[62:65]
	v_mfma_f32_16x16x32_bf16 v[58:61], v[156:159], v[180:183], v[58:61]
	v_mfma_f32_16x16x32_bf16 v[54:57], v[148:151], v[188:191], v[54:57]
	v_mfma_f32_16x16x32_bf16 v[50:53], v[156:159], v[188:191], v[50:53]
	v_mfma_f32_16x16x32_bf16 v[38:41], v[148:151], v[196:199], v[38:41]
	v_mfma_f32_16x16x32_bf16 v[34:37], v[156:159], v[196:199], v[34:37]
	v_mfma_f32_16x16x32_bf16 v[22:25], v[148:151], v[206:209], v[22:25]
	v_mfma_f32_16x16x32_bf16 v[18:21], v[156:159], v[206:209], v[18:21]
	v_mfma_f32_16x16x32_bf16 v[62:65], v[152:155], v[184:187], v[62:65]
	v_mfma_f32_16x16x32_bf16 v[58:61], v[160:163], v[184:187], v[58:61]
	v_mfma_f32_16x16x32_bf16 v[54:57], v[152:155], v[192:195], v[54:57]
	v_mfma_f32_16x16x32_bf16 v[50:53], v[160:163], v[192:195], v[50:53]
	v_mfma_f32_16x16x32_bf16 v[38:41], v[152:155], v[200:203], v[38:41]
	v_mfma_f32_16x16x32_bf16 v[34:37], v[160:163], v[200:203], v[34:37]
	v_mfma_f32_16x16x32_bf16 v[22:25], v[152:155], v[210:213], v[22:25]
	v_mfma_f32_16x16x32_bf16 v[18:21], v[160:163], v[210:213], v[18:21]
	v_mfma_f32_16x16x32_bf16 v[46:49], v[164:167], v[180:183], v[46:49]
	v_mfma_f32_16x16x32_bf16 v[42:45], v[172:175], v[180:183], v[42:45]
	v_mfma_f32_16x16x32_bf16 v[30:33], v[164:167], v[188:191], v[30:33]
	v_mfma_f32_16x16x32_bf16 v[26:29], v[172:175], v[188:191], v[26:29]
	v_mfma_f32_16x16x32_bf16 v[14:17], v[164:167], v[196:199], v[14:17]
	v_mfma_f32_16x16x32_bf16 v[10:13], v[172:175], v[196:199], v[10:13]
	v_mfma_f32_16x16x32_bf16 v[6:9], v[164:167], v[206:209], v[6:9]
	v_mfma_f32_16x16x32_bf16 v[2:5], v[172:175], v[206:209], v[2:5]
	v_mfma_f32_16x16x32_bf16 v[46:49], v[168:171], v[184:187], v[46:49]
	v_mfma_f32_16x16x32_bf16 v[42:45], v[176:179], v[184:187], v[42:45]
	v_mfma_f32_16x16x32_bf16 v[30:33], v[168:171], v[192:195], v[30:33]
	v_mfma_f32_16x16x32_bf16 v[26:29], v[176:179], v[192:195], v[26:29]
	v_mfma_f32_16x16x32_bf16 v[14:17], v[168:171], v[200:203], v[14:17]
	v_mfma_f32_16x16x32_bf16 v[10:13], v[176:179], v[200:203], v[10:13]
	v_mfma_f32_16x16x32_bf16 v[6:9], v[168:171], v[210:213], v[6:9]
	v_mfma_f32_16x16x32_bf16 v[2:5], v[176:179], v[210:213], v[2:5]
	s_setprio 0
	s_barrier
	s_add_i32 s69, s69, 2
	s_add_u32 s36, s36, 0x100
	s_addc_u32 s37, s37, 0
	s_add_u32 s67, s67, 0x100
	s_addc_u32 s68, s68, 0
	s_cmp_gt_u32 s69, 5
.LBB0_477:
	ds_read_b128 v[148:151], v144
	ds_read_b128 v[152:155], v144 offset:1024
	ds_read_b128 v[156:159], v144 offset:2048
	ds_read_b128 v[160:163], v144 offset:3072
	ds_read_b128 v[164:167], v145
	ds_read_b128 v[168:171], v145 offset:1024
	ds_read_b128 v[172:175], v145 offset:2048
	ds_read_b128 v[176:179], v145 offset:3072
	s_add_u32 s38, s36, 0xfffe0080
	s_addc_u32 s39, s37, -1
	s_cmp_eq_u32 s69, 4
	s_cselect_b32 s43, s63, s39
	s_cselect_b32 s42, s64, s38
	s_cselect_b32 s39, s65, s68
	s_cselect_b32 s38, s66, s67
	v_lshl_add_u64 v[214:215], s[36:37], 0, v[138:139]
	s_add_i32 m0, s19, 0xc000
	ds_read_b128 v[180:183], v146
	ds_read_b128 v[184:187], v146 offset:1024
	ds_read_b128 v[188:191], v146 offset:2048
	ds_read_b128 v[192:195], v146 offset:3072
	ds_read_b128 v[196:199], v146 offset:4096
	ds_read_b128 v[200:203], v146 offset:5120
	ds_read_b128 v[206:209], v146 offset:6144
	ds_read_b128 v[210:213], v146 offset:7168
	global_load_lds_dwordx4 v[214:215], off
	s_add_i32 m0, s19, 0xe000
	v_lshl_add_u64 v[214:215], s[36:37], 0, v[140:141]
	global_load_lds_dwordx4 v[214:215], off
	s_setprio 1
	s_waitcnt vmcnt(8) lgkmcnt(0)
	s_barrier
	v_mfma_f32_16x16x32_bf16 v[126:129], v[148:151], v[180:183], v[126:129]
	v_mfma_f32_16x16x32_bf16 v[122:125], v[156:159], v[180:183], v[122:125]
	v_mfma_f32_16x16x32_bf16 v[118:121], v[148:151], v[188:191], v[118:121]
	v_mfma_f32_16x16x32_bf16 v[114:117], v[156:159], v[188:191], v[114:117]
	v_mfma_f32_16x16x32_bf16 v[102:105], v[148:151], v[196:199], v[102:105]
	v_mfma_f32_16x16x32_bf16 v[98:101], v[156:159], v[196:199], v[98:101]
	v_mfma_f32_16x16x32_bf16 v[86:89], v[148:151], v[206:209], v[86:89]
	v_mfma_f32_16x16x32_bf16 v[82:85], v[156:159], v[206:209], v[82:85]
	v_mfma_f32_16x16x32_bf16 v[126:129], v[152:155], v[184:187], v[126:129]
	v_mfma_f32_16x16x32_bf16 v[122:125], v[160:163], v[184:187], v[122:125]
	v_mfma_f32_16x16x32_bf16 v[118:121], v[152:155], v[192:195], v[118:121]
	v_mfma_f32_16x16x32_bf16 v[114:117], v[160:163], v[192:195], v[114:117]
	v_mfma_f32_16x16x32_bf16 v[102:105], v[152:155], v[200:203], v[102:105]
	v_mfma_f32_16x16x32_bf16 v[98:101], v[160:163], v[200:203], v[98:101]
	v_mfma_f32_16x16x32_bf16 v[86:89], v[152:155], v[210:213], v[86:89]
	v_mfma_f32_16x16x32_bf16 v[82:85], v[160:163], v[210:213], v[82:85]
	v_mfma_f32_16x16x32_bf16 v[110:113], v[164:167], v[180:183], v[110:113]
	v_mfma_f32_16x16x32_bf16 v[106:109], v[172:175], v[180:183], v[106:109]
	v_mfma_f32_16x16x32_bf16 v[94:97], v[164:167], v[188:191], v[94:97]
	v_mfma_f32_16x16x32_bf16 v[90:93], v[172:175], v[188:191], v[90:93]
	v_mfma_f32_16x16x32_bf16 v[78:81], v[164:167], v[196:199], v[78:81]
	v_mfma_f32_16x16x32_bf16 v[74:77], v[172:175], v[196:199], v[74:77]
	v_mfma_f32_16x16x32_bf16 v[70:73], v[164:167], v[206:209], v[70:73]
	v_mfma_f32_16x16x32_bf16 v[66:69], v[172:175], v[206:209], v[66:69]
	v_mfma_f32_16x16x32_bf16 v[110:113], v[168:171], v[184:187], v[110:113]
	v_mfma_f32_16x16x32_bf16 v[106:109], v[176:179], v[184:187], v[106:109]
	v_mfma_f32_16x16x32_bf16 v[94:97], v[168:171], v[192:195], v[94:97]
	v_mfma_f32_16x16x32_bf16 v[90:93], v[176:179], v[192:195], v[90:93]
	v_mfma_f32_16x16x32_bf16 v[78:81], v[168:171], v[200:203], v[78:81]
	v_mfma_f32_16x16x32_bf16 v[74:77], v[176:179], v[200:203], v[74:77]
	v_mfma_f32_16x16x32_bf16 v[70:73], v[168:171], v[210:213], v[70:73]
	v_mfma_f32_16x16x32_bf16 v[66:69], v[176:179], v[210:213], v[66:69]
	s_setprio 0
	s_barrier
	s_add_i32 s70, s35, s18
	v_lshl_add_u64 v[214:215], s[38:39], 0, v[134:135]
	s_mov_b32 m0, s70
	ds_read_b128 v[180:183], v146 offset:16384
	ds_read_b128 v[184:187], v146 offset:17408
	ds_read_b128 v[188:191], v146 offset:18432
	ds_read_b128 v[192:195], v146 offset:19456
	ds_read_b128 v[196:199], v146 offset:20480
	ds_read_b128 v[200:203], v146 offset:21504
	ds_read_b128 v[206:209], v146 offset:22528
	ds_read_b128 v[210:213], v146 offset:23552
	global_load_lds_dwordx4 v[214:215], off
	s_add_i32 m0, s70, 0x2000
	s_add_u32 s70, s38, 0x200000
	v_lshl_add_u64 v[216:217], s[38:39], 0, v[130:131]
	s_addc_u32 s71, s39, 0
	s_add_i32 s72, s44, s18
	global_load_lds_dwordx4 v[216:217], off
	v_lshl_add_u64 v[218:219], s[70:71], 0, v[134:135]
	s_mov_b32 m0, s72
	v_lshl_add_u64 v[220:221], s[42:43], 0, v[132:133]
	global_load_lds_dwordx4 v[218:219], off
	s_add_i32 m0, s72, 0x2000
	v_lshl_add_u64 v[218:219], s[70:71], 0, v[130:131]
	global_load_lds_dwordx4 v[218:219], off
	s_mov_b32 m0, s19
	v_lshl_add_u64 v[218:219], s[42:43], 0, v[136:137]
	global_load_lds_dwordx4 v[218:219], off
	s_mov_b32 m0, s24
	s_nop 0
	global_load_lds_dwordx4 v[220:221], off
	s_setprio 1
	s_waitcnt vmcnt(8) lgkmcnt(0)
	s_barrier
	v_mfma_f32_16x16x32_bf16 v[62:65], v[148:151], v[180:183], v[62:65]
	v_mfma_f32_16x16x32_bf16 v[58:61], v[156:159], v[180:183], v[58:61]
	v_mfma_f32_16x16x32_bf16 v[54:57], v[148:151], v[188:191], v[54:57]
	v_mfma_f32_16x16x32_bf16 v[50:53], v[156:159], v[188:191], v[50:53]
	v_mfma_f32_16x16x32_bf16 v[38:41], v[148:151], v[196:199], v[38:41]
	v_mfma_f32_16x16x32_bf16 v[34:37], v[156:159], v[196:199], v[34:37]
	v_mfma_f32_16x16x32_bf16 v[22:25], v[148:151], v[206:209], v[22:25]
	v_mfma_f32_16x16x32_bf16 v[18:21], v[156:159], v[206:209], v[18:21]
	v_mfma_f32_16x16x32_bf16 v[62:65], v[152:155], v[184:187], v[62:65]
	v_mfma_f32_16x16x32_bf16 v[58:61], v[160:163], v[184:187], v[58:61]
	v_mfma_f32_16x16x32_bf16 v[54:57], v[152:155], v[192:195], v[54:57]
	v_mfma_f32_16x16x32_bf16 v[50:53], v[160:163], v[192:195], v[50:53]
	v_mfma_f32_16x16x32_bf16 v[38:41], v[152:155], v[200:203], v[38:41]
	v_mfma_f32_16x16x32_bf16 v[34:37], v[160:163], v[200:203], v[34:37]
	v_mfma_f32_16x16x32_bf16 v[22:25], v[152:155], v[210:213], v[22:25]
	v_mfma_f32_16x16x32_bf16 v[18:21], v[160:163], v[210:213], v[18:21]
	v_mfma_f32_16x16x32_bf16 v[46:49], v[164:167], v[180:183], v[46:49]
	v_mfma_f32_16x16x32_bf16 v[42:45], v[172:175], v[180:183], v[42:45]
	v_mfma_f32_16x16x32_bf16 v[30:33], v[164:167], v[188:191], v[30:33]
	v_mfma_f32_16x16x32_bf16 v[26:29], v[172:175], v[188:191], v[26:29]
	v_mfma_f32_16x16x32_bf16 v[14:17], v[164:167], v[196:199], v[14:17]
	v_mfma_f32_16x16x32_bf16 v[10:13], v[172:175], v[196:199], v[10:13]
	v_mfma_f32_16x16x32_bf16 v[6:9], v[164:167], v[206:209], v[6:9]
	v_mfma_f32_16x16x32_bf16 v[2:5], v[172:175], v[206:209], v[2:5]
	v_mfma_f32_16x16x32_bf16 v[46:49], v[168:171], v[184:187], v[46:49]
	v_mfma_f32_16x16x32_bf16 v[42:45], v[176:179], v[184:187], v[42:45]
	v_mfma_f32_16x16x32_bf16 v[30:33], v[168:171], v[192:195], v[30:33]
	v_mfma_f32_16x16x32_bf16 v[26:29], v[176:179], v[192:195], v[26:29]
	v_mfma_f32_16x16x32_bf16 v[14:17], v[168:171], v[200:203], v[14:17]
	v_mfma_f32_16x16x32_bf16 v[10:13], v[176:179], v[200:203], v[10:13]
	v_mfma_f32_16x16x32_bf16 v[6:9], v[168:171], v[210:213], v[6:9]
	v_mfma_f32_16x16x32_bf16 v[2:5], v[176:179], v[210:213], v[2:5]
	s_setprio 0
	s_barrier
	s_add_i32 s70, 0, 0x18000
	v_add_u32_e32 v147, s70, v143
	s_add_i32 s71, 0, 0x1c000
	ds_read_b128 v[148:151], v147
	ds_read_b128 v[152:155], v147 offset:1024
	ds_read_b128 v[156:159], v147 offset:2048
	ds_read_b128 v[160:163], v147 offset:3072
	v_add_u32_e32 v147, s71, v143
	ds_read_b128 v[164:167], v147
	ds_read_b128 v[168:171], v147 offset:1024
	ds_read_b128 v[172:175], v147 offset:2048
	ds_read_b128 v[176:179], v147 offset:3072
	s_add_u32 s42, s42, 0x20000
	s_addc_u32 s43, s43, 0
	s_mov_b32 m0, s25
	v_lshl_add_u64 v[222:223], s[42:43], 0, v[136:137]
	ds_read_b128 v[180:183], v146 offset:32768
	ds_read_b128 v[184:187], v146 offset:33792
	ds_read_b128 v[188:191], v146 offset:34816
	ds_read_b128 v[192:195], v146 offset:35840
	ds_read_b128 v[196:199], v146 offset:36864
	ds_read_b128 v[200:203], v146 offset:37888
	ds_read_b128 v[206:209], v146 offset:38912
	ds_read_b128 v[210:213], v146 offset:39936
	global_load_lds_dwordx4 v[222:223], off
	s_mov_b32 m0, s28
	v_lshl_add_u64 v[222:223], s[42:43], 0, v[132:133]
	global_load_lds_dwordx4 v[222:223], off
	s_setprio 1
	s_waitcnt vmcnt(8) lgkmcnt(0)
	s_barrier
	v_mfma_f32_16x16x32_bf16 v[126:129], v[148:151], v[180:183], v[126:129]
	v_mfma_f32_16x16x32_bf16 v[122:125], v[156:159], v[180:183], v[122:125]
	v_mfma_f32_16x16x32_bf16 v[118:121], v[148:151], v[188:191], v[118:121]
	v_mfma_f32_16x16x32_bf16 v[114:117], v[156:159], v[188:191], v[114:117]
	v_mfma_f32_16x16x32_bf16 v[102:105], v[148:151], v[196:199], v[102:105]
	v_mfma_f32_16x16x32_bf16 v[98:101], v[156:159], v[196:199], v[98:101]
	v_mfma_f32_16x16x32_bf16 v[86:89], v[148:151], v[206:209], v[86:89]
	v_mfma_f32_16x16x32_bf16 v[82:85], v[156:159], v[206:209], v[82:85]
	v_mfma_f32_16x16x32_bf16 v[126:129], v[152:155], v[184:187], v[126:129]
	v_mfma_f32_16x16x32_bf16 v[122:125], v[160:163], v[184:187], v[122:125]
	v_mfma_f32_16x16x32_bf16 v[118:121], v[152:155], v[192:195], v[118:121]
	v_mfma_f32_16x16x32_bf16 v[114:117], v[160:163], v[192:195], v[114:117]
	v_mfma_f32_16x16x32_bf16 v[102:105], v[152:155], v[200:203], v[102:105]
	v_mfma_f32_16x16x32_bf16 v[98:101], v[160:163], v[200:203], v[98:101]
	v_mfma_f32_16x16x32_bf16 v[86:89], v[152:155], v[210:213], v[86:89]
	v_mfma_f32_16x16x32_bf16 v[82:85], v[160:163], v[210:213], v[82:85]
	v_mfma_f32_16x16x32_bf16 v[110:113], v[164:167], v[180:183], v[110:113]
	v_mfma_f32_16x16x32_bf16 v[106:109], v[172:175], v[180:183], v[106:109]
	v_mfma_f32_16x16x32_bf16 v[94:97], v[164:167], v[188:191], v[94:97]
	v_mfma_f32_16x16x32_bf16 v[90:93], v[172:175], v[188:191], v[90:93]
	v_mfma_f32_16x16x32_bf16 v[78:81], v[164:167], v[196:199], v[78:81]
	v_mfma_f32_16x16x32_bf16 v[74:77], v[172:175], v[196:199], v[74:77]
	v_mfma_f32_16x16x32_bf16 v[70:73], v[164:167], v[206:209], v[70:73]
	v_mfma_f32_16x16x32_bf16 v[66:69], v[172:175], v[206:209], v[66:69]
	v_mfma_f32_16x16x32_bf16 v[110:113], v[168:171], v[184:187], v[110:113]
	v_mfma_f32_16x16x32_bf16 v[106:109], v[176:179], v[184:187], v[106:109]
	v_mfma_f32_16x16x32_bf16 v[94:97], v[168:171], v[192:195], v[94:97]
	v_mfma_f32_16x16x32_bf16 v[90:93], v[176:179], v[192:195], v[90:93]
	v_mfma_f32_16x16x32_bf16 v[78:81], v[168:171], v[200:203], v[78:81]
	v_mfma_f32_16x16x32_bf16 v[74:77], v[176:179], v[200:203], v[74:77]
	v_mfma_f32_16x16x32_bf16 v[70:73], v[168:171], v[210:213], v[70:73]
	v_mfma_f32_16x16x32_bf16 v[66:69], v[176:179], v[210:213], v[66:69]
	s_setprio 0
	s_barrier
	s_add_i32 s42, s70, s18
	v_lshl_add_u64 v[214:215], v[214:215], 0, s[8:9]
	s_mov_b32 m0, s42
	ds_read_b128 v[180:183], v146 offset:49152
	ds_read_b128 v[184:187], v146 offset:50176
	ds_read_b128 v[188:191], v146 offset:51200
	ds_read_b128 v[192:195], v146 offset:52224
	ds_read_b128 v[196:199], v146 offset:53248
	ds_read_b128 v[200:203], v146 offset:54272
	ds_read_b128 v[206:209], v146 offset:55296
	ds_read_b128 v[210:213], v146 offset:56320
	global_load_lds_dwordx4 v[214:215], off
	s_add_i32 m0, s42, 0x2000
	s_add_u32 s38, s38, 0x200080
	v_lshl_add_u64 v[214:215], v[216:217], 0, s[8:9]
	s_addc_u32 s39, s39, 0
	s_add_i32 s42, s71, s18
	global_load_lds_dwordx4 v[214:215], off
	s_mov_b32 m0, s42
	v_lshl_add_u64 v[214:215], s[38:39], 0, v[134:135]
	global_load_lds_dwordx4 v[214:215], off
	s_add_i32 m0, s42, 0x2000
	v_lshl_add_u64 v[214:215], s[38:39], 0, v[130:131]
	global_load_lds_dwordx4 v[214:215], off
	s_mov_b32 m0, s33
	v_lshl_add_u64 v[214:215], v[218:219], 0, s[8:9]
	global_load_lds_dwordx4 v[214:215], off
	s_mov_b32 m0, s34
	v_lshl_add_u64 v[214:215], v[220:221], 0, s[8:9]
	global_load_lds_dwordx4 v[214:215], off
	s_setprio 1
	s_waitcnt vmcnt(8) lgkmcnt(0)
	s_barrier
	v_mfma_f32_16x16x32_bf16 v[62:65], v[148:151], v[180:183], v[62:65]
	v_mfma_f32_16x16x32_bf16 v[58:61], v[156:159], v[180:183], v[58:61]
	v_mfma_f32_16x16x32_bf16 v[54:57], v[148:151], v[188:191], v[54:57]
	v_mfma_f32_16x16x32_bf16 v[50:53], v[156:159], v[188:191], v[50:53]
	v_mfma_f32_16x16x32_bf16 v[38:41], v[148:151], v[196:199], v[38:41]
	v_mfma_f32_16x16x32_bf16 v[34:37], v[156:159], v[196:199], v[34:37]
	v_mfma_f32_16x16x32_bf16 v[22:25], v[148:151], v[206:209], v[22:25]
	v_mfma_f32_16x16x32_bf16 v[18:21], v[156:159], v[206:209], v[18:21]
	v_mfma_f32_16x16x32_bf16 v[62:65], v[152:155], v[184:187], v[62:65]
	v_mfma_f32_16x16x32_bf16 v[58:61], v[160:163], v[184:187], v[58:61]
	v_mfma_f32_16x16x32_bf16 v[54:57], v[152:155], v[192:195], v[54:57]
	v_mfma_f32_16x16x32_bf16 v[50:53], v[160:163], v[192:195], v[50:53]
	v_mfma_f32_16x16x32_bf16 v[38:41], v[152:155], v[200:203], v[38:41]
	v_mfma_f32_16x16x32_bf16 v[34:37], v[160:163], v[200:203], v[34:37]
	v_mfma_f32_16x16x32_bf16 v[22:25], v[152:155], v[210:213], v[22:25]
	v_mfma_f32_16x16x32_bf16 v[18:21], v[160:163], v[210:213], v[18:21]
	v_mfma_f32_16x16x32_bf16 v[46:49], v[164:167], v[180:183], v[46:49]
	v_mfma_f32_16x16x32_bf16 v[42:45], v[172:175], v[180:183], v[42:45]
	v_mfma_f32_16x16x32_bf16 v[30:33], v[164:167], v[188:191], v[30:33]
	v_mfma_f32_16x16x32_bf16 v[26:29], v[172:175], v[188:191], v[26:29]
	v_mfma_f32_16x16x32_bf16 v[14:17], v[164:167], v[196:199], v[14:17]
	v_mfma_f32_16x16x32_bf16 v[10:13], v[172:175], v[196:199], v[10:13]
	v_mfma_f32_16x16x32_bf16 v[6:9], v[164:167], v[206:209], v[6:9]
	v_mfma_f32_16x16x32_bf16 v[2:5], v[172:175], v[206:209], v[2:5]
	v_mfma_f32_16x16x32_bf16 v[46:49], v[168:171], v[184:187], v[46:49]
	v_mfma_f32_16x16x32_bf16 v[42:45], v[176:179], v[184:187], v[42:45]
	v_mfma_f32_16x16x32_bf16 v[30:33], v[168:171], v[192:195], v[30:33]
	v_mfma_f32_16x16x32_bf16 v[26:29], v[176:179], v[192:195], v[26:29]
	v_mfma_f32_16x16x32_bf16 v[14:17], v[168:171], v[200:203], v[14:17]
	v_mfma_f32_16x16x32_bf16 v[10:13], v[176:179], v[200:203], v[10:13]
	v_mfma_f32_16x16x32_bf16 v[6:9], v[168:171], v[210:213], v[6:9]
	v_mfma_f32_16x16x32_bf16 v[2:5], v[176:179], v[210:213], v[2:5]
	s_setprio 0
	s_barrier
	s_add_i32 s69, s69, 2
	s_add_u32 s36, s36, 0x100
	s_addc_u32 s37, s37, 0
	s_add_u32 s67, s67, 0x100
	s_addc_u32 s68, s68, 0
	s_cmp_gt_u32 s69, 5
	s_cbranch_scc0 .LBB0_477
	s_and_b64 vcc, exec, s[10:11]
	s_cbranch_vccz .LBB0_480
	s_barrier

.LBB0_565:
	v_readlane_b32 s62, v249, 27
	v_readlane_b32 s63, v249, 28
	s_add_u32 s72, s62, s68
	s_addc_u32 s73, s63, s69
	s_and_b64 s[62:63], s[70:71], exec
	s_cselect_b32 s31, s73, s77
	s_cselect_b32 s33, s72, s76
	s_add_u32 s74, s35, s66
	s_addc_u32 s75, s85, s67
	s_and_b64 s[62:63], s[70:71], exec
	s_cselect_b32 s34, s75, s79
	s_cselect_b32 s39, s74, s78
	s_add_i32 s45, s7, -2
	s_add_u32 s76, s76, 0x40080
	s_addc_u32 s77, s77, 0
	s_add_u32 s47, s78, 0x100
	s_addc_u32 s62, s79, 0
	s_mov_b32 s63, 0
	s_waitcnt vmcnt(0)
	ds_read_b128 v[114:117], v190
	ds_read_b128 v[118:121], v190 offset:1024
	ds_read_b128 v[122:125], v190 offset:2048
	ds_read_b128 v[126:129], v190 offset:3072
	ds_read_b128 v[146:149], v191
	ds_read_b128 v[150:153], v191 offset:1024
	ds_read_b128 v[154:157], v191 offset:2048
	ds_read_b128 v[158:161], v191 offset:3072
	s_add_i32 s82, s63, 2
	s_add_u32 s78, s76, 0xfffc0080
	s_addc_u32 s79, s77, -1
	s_cmp_eq_u32 s45, s63
	s_cselect_b32 s81, s31, s79
	s_cselect_b32 s80, s33, s78
	s_cselect_b32 s79, s34, s62
	s_cselect_b32 s78, s39, s47
	v_lshl_add_u64 v[186:187], s[76:77], 0, v[180:181]
	s_add_i32 m0, s87, 0xc000
	ds_read_b128 v[162:165], v192
	ds_read_b128 v[166:169], v192 offset:1024
	ds_read_b128 v[194:197], v192 offset:2048
	ds_read_b128 v[198:201], v192 offset:3072
	ds_read_b128 v[206:209], v192 offset:4096
	ds_read_b128 v[210:213], v192 offset:5120
	ds_read_b128 v[214:217], v192 offset:6144
	ds_read_b128 v[218:221], v192 offset:7168
	global_load_lds_dwordx4 v[186:187], off
	s_add_i32 m0, s87, 0xe000
	v_lshl_add_u64 v[186:187], s[76:77], 0, v[182:183]
	global_load_lds_dwordx4 v[186:187], off
	s_waitcnt vmcnt(8)
	s_waitcnt lgkmcnt(0)
	s_setprio 1
	s_barrier
	v_mfma_f32_16x16x32_bf16 v[142:145], v[114:117], v[162:165], 0
	v_mfma_f32_16x16x32_bf16 v[138:141], v[122:125], v[162:165], 0
	v_mfma_f32_16x16x32_bf16 v[110:113], v[114:117], v[194:197], 0
	v_mfma_f32_16x16x32_bf16 v[106:109], v[122:125], v[194:197], 0
	v_mfma_f32_16x16x32_bf16 v[98:101], v[114:117], v[206:209], 0
	v_mfma_f32_16x16x32_bf16 v[90:93], v[122:125], v[206:209], 0
	v_mfma_f32_16x16x32_bf16 v[82:85], v[114:117], v[214:217], 0
	v_mfma_f32_16x16x32_bf16 v[74:77], v[122:125], v[214:217], 0
	v_mfma_f32_16x16x32_bf16 v[142:145], v[118:121], v[166:169], v[142:145]
	v_mfma_f32_16x16x32_bf16 v[138:141], v[126:129], v[166:169], v[138:141]
	v_mfma_f32_16x16x32_bf16 v[110:113], v[118:121], v[198:201], v[110:113]
	v_mfma_f32_16x16x32_bf16 v[106:109], v[126:129], v[198:201], v[106:109]
	v_mfma_f32_16x16x32_bf16 v[98:101], v[118:121], v[210:213], v[98:101]
	v_mfma_f32_16x16x32_bf16 v[90:93], v[126:129], v[210:213], v[90:93]
	v_mfma_f32_16x16x32_bf16 v[82:85], v[118:121], v[218:221], v[82:85]
	v_mfma_f32_16x16x32_bf16 v[74:77], v[126:129], v[218:221], v[74:77]
	v_mfma_f32_16x16x32_bf16 v[134:137], v[146:149], v[162:165], 0
	v_mfma_f32_16x16x32_bf16 v[130:133], v[154:157], v[162:165], 0
	v_mfma_f32_16x16x32_bf16 v[102:105], v[146:149], v[194:197], 0
	v_mfma_f32_16x16x32_bf16 v[94:97], v[154:157], v[194:197], 0
	v_mfma_f32_16x16x32_bf16 v[86:89], v[146:149], v[206:209], 0
	v_mfma_f32_16x16x32_bf16 v[78:81], v[154:157], v[206:209], 0
	v_mfma_f32_16x16x32_bf16 v[70:73], v[146:149], v[214:217], 0
	v_mfma_f32_16x16x32_bf16 v[66:69], v[154:157], v[214:217], 0
	v_mfma_f32_16x16x32_bf16 v[134:137], v[150:153], v[166:169], v[134:137]
	v_mfma_f32_16x16x32_bf16 v[130:133], v[158:161], v[166:169], v[130:133]
	v_mfma_f32_16x16x32_bf16 v[102:105], v[150:153], v[198:201], v[102:105]
	v_mfma_f32_16x16x32_bf16 v[94:97], v[158:161], v[198:201], v[94:97]
	v_mfma_f32_16x16x32_bf16 v[86:89], v[150:153], v[210:213], v[86:89]
	v_mfma_f32_16x16x32_bf16 v[78:81], v[158:161], v[210:213], v[78:81]
	v_mfma_f32_16x16x32_bf16 v[70:73], v[150:153], v[218:221], v[70:73]
	v_mfma_f32_16x16x32_bf16 v[66:69], v[158:161], v[218:221], v[66:69]
	s_setprio 0
	s_barrier
	s_add_i32 s63, s24, s86
	v_lshl_add_u64 v[186:187], s[78:79], 0, v[172:173]
	s_mov_b32 m0, s63
	ds_read_b128 v[162:165], v192 offset:16384
	ds_read_b128 v[166:169], v192 offset:17408
	ds_read_b128 v[194:197], v192 offset:18432
	ds_read_b128 v[198:201], v192 offset:19456
	ds_read_b128 v[206:209], v192 offset:20480
	ds_read_b128 v[210:213], v192 offset:21504
	ds_read_b128 v[214:217], v192 offset:22528
	ds_read_b128 v[218:221], v192 offset:23552
	global_load_lds_dwordx4 v[186:187], off
	s_add_i32 m0, s63, 0x2000
	s_add_u32 vcc_lo, s78, 0x40000
	v_lshl_add_u64 v[202:203], s[78:79], 0, v[176:177]
	s_addc_u32 vcc_hi, s79, 0
	s_add_i32 s63, s25, s86
	global_load_lds_dwordx4 v[202:203], off
	v_lshl_add_u64 v[222:223], vcc, 0, v[172:173]
	s_mov_b32 m0, s63
	v_lshl_add_u64 v[224:225], s[80:81], 0, v[174:175]
	global_load_lds_dwordx4 v[222:223], off
	s_add_i32 m0, s63, 0x2000
	v_lshl_add_u64 v[222:223], vcc, 0, v[176:177]
	global_load_lds_dwordx4 v[222:223], off
	s_mov_b32 m0, s87
	v_lshl_add_u64 v[222:223], s[80:81], 0, v[170:171]
	global_load_lds_dwordx4 v[222:223], off
	s_mov_b32 m0, s88
	s_nop 0
	global_load_lds_dwordx4 v[224:225], off
	s_setprio 1
	s_waitcnt vmcnt(8) lgkmcnt(0)
	s_barrier
	v_mfma_f32_16x16x32_bf16 v[62:65], v[114:117], v[162:165], 0
	v_mfma_f32_16x16x32_bf16 v[58:61], v[122:125], v[162:165], 0
	v_mfma_f32_16x16x32_bf16 v[50:53], v[114:117], v[194:197], 0
	v_mfma_f32_16x16x32_bf16 v[42:45], v[122:125], v[194:197], 0
	v_mfma_f32_16x16x32_bf16 v[34:37], v[114:117], v[206:209], 0
	v_mfma_f32_16x16x32_bf16 v[26:29], v[122:125], v[206:209], 0
	v_mfma_f32_16x16x32_bf16 v[18:21], v[114:117], v[214:217], 0
	v_mfma_f32_16x16x32_bf16 v[10:13], v[122:125], v[214:217], 0
	v_mfma_f32_16x16x32_bf16 v[62:65], v[118:121], v[166:169], v[62:65]
	v_mfma_f32_16x16x32_bf16 v[58:61], v[126:129], v[166:169], v[58:61]
	v_mfma_f32_16x16x32_bf16 v[50:53], v[118:121], v[198:201], v[50:53]
	v_mfma_f32_16x16x32_bf16 v[42:45], v[126:129], v[198:201], v[42:45]
	v_mfma_f32_16x16x32_bf16 v[34:37], v[118:121], v[210:213], v[34:37]
	v_mfma_f32_16x16x32_bf16 v[26:29], v[126:129], v[210:213], v[26:29]
	v_mfma_f32_16x16x32_bf16 v[18:21], v[118:121], v[218:221], v[18:21]
	v_mfma_f32_16x16x32_bf16 v[10:13], v[126:129], v[218:221], v[10:13]
	v_mfma_f32_16x16x32_bf16 v[54:57], v[146:149], v[162:165], 0
	v_mfma_f32_16x16x32_bf16 v[46:49], v[154:157], v[162:165], 0
	v_mfma_f32_16x16x32_bf16 v[38:41], v[146:149], v[194:197], 0
	v_mfma_f32_16x16x32_bf16 v[30:33], v[154:157], v[194:197], 0
	v_mfma_f32_16x16x32_bf16 v[22:25], v[146:149], v[206:209], 0
	v_mfma_f32_16x16x32_bf16 v[14:17], v[154:157], v[206:209], 0
	v_mfma_f32_16x16x32_bf16 v[6:9], v[146:149], v[214:217], 0
	v_mfma_f32_16x16x32_bf16 v[2:5], v[154:157], v[214:217], 0
	v_mfma_f32_16x16x32_bf16 v[54:57], v[150:153], v[166:169], v[54:57]
	v_mfma_f32_16x16x32_bf16 v[46:49], v[158:161], v[166:169], v[46:49]
	v_mfma_f32_16x16x32_bf16 v[38:41], v[150:153], v[198:201], v[38:41]
	v_mfma_f32_16x16x32_bf16 v[30:33], v[158:161], v[198:201], v[30:33]
	v_mfma_f32_16x16x32_bf16 v[22:25], v[150:153], v[210:213], v[22:25]
	v_mfma_f32_16x16x32_bf16 v[14:17], v[158:161], v[210:213], v[14:17]
	v_mfma_f32_16x16x32_bf16 v[6:9], v[150:153], v[218:221], v[6:9]
	v_mfma_f32_16x16x32_bf16 v[2:5], v[158:161], v[218:221], v[2:5]
	s_setprio 0
	s_barrier
	s_add_i32 s63, 0, 0x18000
	s_add_i32 s83, 0, 0x1c000
	v_add_u32_e32 v126, s63, v189
	v_add_u32_e32 v158, s83, v189
	ds_read_b128 v[114:117], v126
	ds_read_b128 v[118:121], v126 offset:1024
	ds_read_b128 v[122:125], v126 offset:2048
	ds_read_b128 v[126:129], v126 offset:3072
	ds_read_b128 v[146:149], v158
	ds_read_b128 v[150:153], v158 offset:1024
	ds_read_b128 v[154:157], v158 offset:2048
	ds_read_b128 v[158:161], v158 offset:3072
	s_add_u32 s80, s80, 0x40000
	s_addc_u32 s81, s81, 0
	s_mov_b32 m0, s89
	v_lshl_add_u64 v[226:227], s[80:81], 0, v[170:171]
	ds_read_b128 v[162:165], v192 offset:32768
	ds_read_b128 v[166:169], v192 offset:33792
	ds_read_b128 v[194:197], v192 offset:34816
	ds_read_b128 v[198:201], v192 offset:35840
	ds_read_b128 v[206:209], v192 offset:36864
	ds_read_b128 v[210:213], v192 offset:37888
	ds_read_b128 v[214:217], v192 offset:38912
	ds_read_b128 v[218:221], v192 offset:39936
	global_load_lds_dwordx4 v[226:227], off
	s_mov_b32 m0, s90
	v_lshl_add_u64 v[226:227], s[80:81], 0, v[174:175]
	global_load_lds_dwordx4 v[226:227], off
	s_setprio 1
	s_waitcnt vmcnt(8) lgkmcnt(0)
	s_barrier
	v_mfma_f32_16x16x32_bf16 v[142:145], v[114:117], v[162:165], v[142:145]
	v_mfma_f32_16x16x32_bf16 v[138:141], v[122:125], v[162:165], v[138:141]
	v_mfma_f32_16x16x32_bf16 v[110:113], v[114:117], v[194:197], v[110:113]
	v_mfma_f32_16x16x32_bf16 v[106:109], v[122:125], v[194:197], v[106:109]
	v_mfma_f32_16x16x32_bf16 v[98:101], v[114:117], v[206:209], v[98:101]
	v_mfma_f32_16x16x32_bf16 v[90:93], v[122:125], v[206:209], v[90:93]
	v_mfma_f32_16x16x32_bf16 v[82:85], v[114:117], v[214:217], v[82:85]
	v_mfma_f32_16x16x32_bf16 v[74:77], v[122:125], v[214:217], v[74:77]
	v_mfma_f32_16x16x32_bf16 v[142:145], v[118:121], v[166:169], v[142:145]
	v_mfma_f32_16x16x32_bf16 v[138:141], v[126:129], v[166:169], v[138:141]
	v_mfma_f32_16x16x32_bf16 v[110:113], v[118:121], v[198:201], v[110:113]
	v_mfma_f32_16x16x32_bf16 v[106:109], v[126:129], v[198:201], v[106:109]
	v_mfma_f32_16x16x32_bf16 v[98:101], v[118:121], v[210:213], v[98:101]
	v_mfma_f32_16x16x32_bf16 v[90:93], v[126:129], v[210:213], v[90:93]
	v_mfma_f32_16x16x32_bf16 v[82:85], v[118:121], v[218:221], v[82:85]
	v_mfma_f32_16x16x32_bf16 v[74:77], v[126:129], v[218:221], v[74:77]
	v_mfma_f32_16x16x32_bf16 v[134:137], v[146:149], v[162:165], v[134:137]
	v_mfma_f32_16x16x32_bf16 v[130:133], v[154:157], v[162:165], v[130:133]
	v_mfma_f32_16x16x32_bf16 v[102:105], v[146:149], v[194:197], v[102:105]
	v_mfma_f32_16x16x32_bf16 v[94:97], v[154:157], v[194:197], v[94:97]
	v_mfma_f32_16x16x32_bf16 v[86:89], v[146:149], v[206:209], v[86:89]
	v_mfma_f32_16x16x32_bf16 v[78:81], v[154:157], v[206:209], v[78:81]
	v_mfma_f32_16x16x32_bf16 v[70:73], v[146:149], v[214:217], v[70:73]
	v_mfma_f32_16x16x32_bf16 v[66:69], v[154:157], v[214:217], v[66:69]
	v_mfma_f32_16x16x32_bf16 v[134:137], v[150:153], v[166:169], v[134:137]
	v_mfma_f32_16x16x32_bf16 v[130:133], v[158:161], v[166:169], v[130:133]
	v_mfma_f32_16x16x32_bf16 v[102:105], v[150:153], v[198:201], v[102:105]
	v_mfma_f32_16x16x32_bf16 v[94:97], v[158:161], v[198:201], v[94:97]
	v_mfma_f32_16x16x32_bf16 v[86:89], v[150:153], v[210:213], v[86:89]
	v_mfma_f32_16x16x32_bf16 v[78:81], v[158:161], v[210:213], v[78:81]
	v_mfma_f32_16x16x32_bf16 v[70:73], v[150:153], v[218:221], v[70:73]
	v_mfma_f32_16x16x32_bf16 v[66:69], v[158:161], v[218:221], v[66:69]
	s_setprio 0
	s_barrier
	s_add_i32 s63, s63, s86
	v_lshl_add_u64 v[186:187], v[186:187], 0, s[22:23]
	s_mov_b32 m0, s63
	ds_read_b128 v[162:165], v192 offset:49152
	ds_read_b128 v[166:169], v192 offset:50176
	ds_read_b128 v[194:197], v192 offset:51200
	ds_read_b128 v[198:201], v192 offset:52224
	ds_read_b128 v[206:209], v192 offset:53248
	ds_read_b128 v[210:213], v192 offset:54272
	ds_read_b128 v[214:217], v192 offset:55296
	ds_read_b128 v[218:221], v192 offset:56320
	global_load_lds_dwordx4 v[186:187], off
	s_add_i32 m0, s63, 0x2000
	s_add_u32 s78, s78, 0x40080
	v_lshl_add_u64 v[186:187], v[202:203], 0, s[22:23]
	s_addc_u32 s79, s79, 0
	s_add_i32 s63, s83, s86
	global_load_lds_dwordx4 v[186:187], off
	s_mov_b32 m0, s63
	v_lshl_add_u64 v[186:187], s[78:79], 0, v[172:173]
	global_load_lds_dwordx4 v[186:187], off
	s_add_i32 m0, s63, 0x2000
	v_lshl_add_u64 v[186:187], s[78:79], 0, v[176:177]
	global_load_lds_dwordx4 v[186:187], off
	s_mov_b32 m0, s95
	v_lshl_add_u64 v[186:187], v[222:223], 0, s[22:23]
	global_load_lds_dwordx4 v[186:187], off
	s_mov_b32 m0, s96
	v_lshl_add_u64 v[186:187], v[224:225], 0, s[22:23]
	global_load_lds_dwordx4 v[186:187], off
	s_setprio 1
	s_waitcnt vmcnt(8) lgkmcnt(0)
	s_barrier
	v_mfma_f32_16x16x32_bf16 v[62:65], v[114:117], v[162:165], v[62:65]
	v_mfma_f32_16x16x32_bf16 v[58:61], v[122:125], v[162:165], v[58:61]
	v_mfma_f32_16x16x32_bf16 v[50:53], v[114:117], v[194:197], v[50:53]
	v_mfma_f32_16x16x32_bf16 v[42:45], v[122:125], v[194:197], v[42:45]
	v_mfma_f32_16x16x32_bf16 v[34:37], v[114:117], v[206:209], v[34:37]
	v_mfma_f32_16x16x32_bf16 v[26:29], v[122:125], v[206:209], v[26:29]
	v_mfma_f32_16x16x32_bf16 v[18:21], v[114:117], v[214:217], v[18:21]
	v_mfma_f32_16x16x32_bf16 v[10:13], v[122:125], v[214:217], v[10:13]
	v_mfma_f32_16x16x32_bf16 v[62:65], v[118:121], v[166:169], v[62:65]
	v_mfma_f32_16x16x32_bf16 v[58:61], v[126:129], v[166:169], v[58:61]
	v_mfma_f32_16x16x32_bf16 v[50:53], v[118:121], v[198:201], v[50:53]
	v_mfma_f32_16x16x32_bf16 v[42:45], v[126:129], v[198:201], v[42:45]
	v_mfma_f32_16x16x32_bf16 v[34:37], v[118:121], v[210:213], v[34:37]
	v_mfma_f32_16x16x32_bf16 v[26:29], v[126:129], v[210:213], v[26:29]
	v_mfma_f32_16x16x32_bf16 v[18:21], v[118:121], v[218:221], v[18:21]
	v_mfma_f32_16x16x32_bf16 v[10:13], v[126:129], v[218:221], v[10:13]
	v_mfma_f32_16x16x32_bf16 v[54:57], v[146:149], v[162:165], v[54:57]
	v_mfma_f32_16x16x32_bf16 v[46:49], v[154:157], v[162:165], v[46:49]
	v_mfma_f32_16x16x32_bf16 v[38:41], v[146:149], v[194:197], v[38:41]
	v_mfma_f32_16x16x32_bf16 v[30:33], v[154:157], v[194:197], v[30:33]
	v_mfma_f32_16x16x32_bf16 v[22:25], v[146:149], v[206:209], v[22:25]
	v_mfma_f32_16x16x32_bf16 v[14:17], v[154:157], v[206:209], v[14:17]
	v_mfma_f32_16x16x32_bf16 v[6:9], v[146:149], v[214:217], v[6:9]
	v_mfma_f32_16x16x32_bf16 v[2:5], v[154:157], v[214:217], v[2:5]
	v_mfma_f32_16x16x32_bf16 v[54:57], v[150:153], v[166:169], v[54:57]
	v_mfma_f32_16x16x32_bf16 v[46:49], v[158:161], v[166:169], v[46:49]
	v_mfma_f32_16x16x32_bf16 v[38:41], v[150:153], v[198:201], v[38:41]
	v_mfma_f32_16x16x32_bf16 v[30:33], v[158:161], v[198:201], v[30:33]
	v_mfma_f32_16x16x32_bf16 v[22:25], v[150:153], v[210:213], v[22:25]
	v_mfma_f32_16x16x32_bf16 v[14:17], v[158:161], v[210:213], v[14:17]
	v_mfma_f32_16x16x32_bf16 v[6:9], v[150:153], v[218:221], v[6:9]
	v_mfma_f32_16x16x32_bf16 v[2:5], v[158:161], v[218:221], v[2:5]
	s_setprio 0
	s_barrier
	s_add_u32 s76, s76, 0x100
	s_addc_u32 s77, s77, 0
	s_add_u32 s47, s47, 0x100
	s_addc_u32 s62, s62, 0
	s_cmp_ge_i32 s82, s7
	s_mov_b32 s63, s82
.LBB0_566:
	s_waitcnt vmcnt(0)
	ds_read_b128 v[114:117], v190
	ds_read_b128 v[118:121], v190 offset:1024
	ds_read_b128 v[122:125], v190 offset:2048
	ds_read_b128 v[126:129], v190 offset:3072
	ds_read_b128 v[146:149], v191
	ds_read_b128 v[150:153], v191 offset:1024
	ds_read_b128 v[154:157], v191 offset:2048
	ds_read_b128 v[158:161], v191 offset:3072
	s_add_i32 s82, s63, 2
	s_add_u32 s78, s76, 0xfffc0080
	s_addc_u32 s79, s77, -1
	s_cmp_eq_u32 s45, s63
	s_cselect_b32 s81, s31, s79
	s_cselect_b32 s80, s33, s78
	s_cselect_b32 s79, s34, s62
	s_cselect_b32 s78, s39, s47
	v_lshl_add_u64 v[186:187], s[76:77], 0, v[180:181]
	s_add_i32 m0, s87, 0xc000
	ds_read_b128 v[162:165], v192
	ds_read_b128 v[166:169], v192 offset:1024
	ds_read_b128 v[194:197], v192 offset:2048
	ds_read_b128 v[198:201], v192 offset:3072
	ds_read_b128 v[206:209], v192 offset:4096
	ds_read_b128 v[210:213], v192 offset:5120
	ds_read_b128 v[214:217], v192 offset:6144
	ds_read_b128 v[218:221], v192 offset:7168
	global_load_lds_dwordx4 v[186:187], off
	s_add_i32 m0, s87, 0xe000
	v_lshl_add_u64 v[186:187], s[76:77], 0, v[182:183]
	global_load_lds_dwordx4 v[186:187], off
	s_waitcnt vmcnt(8)
	s_waitcnt lgkmcnt(0)
	s_setprio 1
	s_barrier
	v_mfma_f32_16x16x32_bf16 v[142:145], v[114:117], v[162:165], v[142:145]
	v_mfma_f32_16x16x32_bf16 v[138:141], v[122:125], v[162:165], v[138:141]
	v_mfma_f32_16x16x32_bf16 v[110:113], v[114:117], v[194:197], v[110:113]
	v_mfma_f32_16x16x32_bf16 v[106:109], v[122:125], v[194:197], v[106:109]
	v_mfma_f32_16x16x32_bf16 v[98:101], v[114:117], v[206:209], v[98:101]
	v_mfma_f32_16x16x32_bf16 v[90:93], v[122:125], v[206:209], v[90:93]
	v_mfma_f32_16x16x32_bf16 v[82:85], v[114:117], v[214:217], v[82:85]
	v_mfma_f32_16x16x32_bf16 v[74:77], v[122:125], v[214:217], v[74:77]
	v_mfma_f32_16x16x32_bf16 v[142:145], v[118:121], v[166:169], v[142:145]
	v_mfma_f32_16x16x32_bf16 v[138:141], v[126:129], v[166:169], v[138:141]
	v_mfma_f32_16x16x32_bf16 v[110:113], v[118:121], v[198:201], v[110:113]
	v_mfma_f32_16x16x32_bf16 v[106:109], v[126:129], v[198:201], v[106:109]
	v_mfma_f32_16x16x32_bf16 v[98:101], v[118:121], v[210:213], v[98:101]
	v_mfma_f32_16x16x32_bf16 v[90:93], v[126:129], v[210:213], v[90:93]
	v_mfma_f32_16x16x32_bf16 v[82:85], v[118:121], v[218:221], v[82:85]
	v_mfma_f32_16x16x32_bf16 v[74:77], v[126:129], v[218:221], v[74:77]
	v_mfma_f32_16x16x32_bf16 v[134:137], v[146:149], v[162:165], v[134:137]
	v_mfma_f32_16x16x32_bf16 v[130:133], v[154:157], v[162:165], v[130:133]
	v_mfma_f32_16x16x32_bf16 v[102:105], v[146:149], v[194:197], v[102:105]
	v_mfma_f32_16x16x32_bf16 v[94:97], v[154:157], v[194:197], v[94:97]
	v_mfma_f32_16x16x32_bf16 v[86:89], v[146:149], v[206:209], v[86:89]
	v_mfma_f32_16x16x32_bf16 v[78:81], v[154:157], v[206:209], v[78:81]
	v_mfma_f32_16x16x32_bf16 v[70:73], v[146:149], v[214:217], v[70:73]
	v_mfma_f32_16x16x32_bf16 v[66:69], v[154:157], v[214:217], v[66:69]
	v_mfma_f32_16x16x32_bf16 v[134:137], v[150:153], v[166:169], v[134:137]
	v_mfma_f32_16x16x32_bf16 v[130:133], v[158:161], v[166:169], v[130:133]
	v_mfma_f32_16x16x32_bf16 v[102:105], v[150:153], v[198:201], v[102:105]
	v_mfma_f32_16x16x32_bf16 v[94:97], v[158:161], v[198:201], v[94:97]
	v_mfma_f32_16x16x32_bf16 v[86:89], v[150:153], v[210:213], v[86:89]
	v_mfma_f32_16x16x32_bf16 v[78:81], v[158:161], v[210:213], v[78:81]
	v_mfma_f32_16x16x32_bf16 v[70:73], v[150:153], v[218:221], v[70:73]
	v_mfma_f32_16x16x32_bf16 v[66:69], v[158:161], v[218:221], v[66:69]
	s_setprio 0
	s_barrier
	s_add_i32 s63, s24, s86
	v_lshl_add_u64 v[186:187], s[78:79], 0, v[172:173]
	s_mov_b32 m0, s63
	ds_read_b128 v[162:165], v192 offset:16384
	ds_read_b128 v[166:169], v192 offset:17408
	ds_read_b128 v[194:197], v192 offset:18432
	ds_read_b128 v[198:201], v192 offset:19456
	ds_read_b128 v[206:209], v192 offset:20480
	ds_read_b128 v[210:213], v192 offset:21504
	ds_read_b128 v[214:217], v192 offset:22528
	ds_read_b128 v[218:221], v192 offset:23552
	global_load_lds_dwordx4 v[186:187], off
	s_add_i32 m0, s63, 0x2000
	s_add_u32 vcc_lo, s78, 0x40000
	v_lshl_add_u64 v[202:203], s[78:79], 0, v[176:177]
	s_addc_u32 vcc_hi, s79, 0
	s_add_i32 s63, s25, s86
	global_load_lds_dwordx4 v[202:203], off
	v_lshl_add_u64 v[222:223], vcc, 0, v[172:173]
	s_mov_b32 m0, s63
	v_lshl_add_u64 v[224:225], s[80:81], 0, v[174:175]
	global_load_lds_dwordx4 v[222:223], off
	s_add_i32 m0, s63, 0x2000
	v_lshl_add_u64 v[222:223], vcc, 0, v[176:177]
	global_load_lds_dwordx4 v[222:223], off
	s_mov_b32 m0, s87
	v_lshl_add_u64 v[222:223], s[80:81], 0, v[170:171]
	global_load_lds_dwordx4 v[222:223], off
	s_mov_b32 m0, s88
	s_nop 0
	global_load_lds_dwordx4 v[224:225], off
	s_setprio 1
	s_waitcnt vmcnt(8) lgkmcnt(0)
	s_barrier
	v_mfma_f32_16x16x32_bf16 v[62:65], v[114:117], v[162:165], v[62:65]
	v_mfma_f32_16x16x32_bf16 v[58:61], v[122:125], v[162:165], v[58:61]
	v_mfma_f32_16x16x32_bf16 v[50:53], v[114:117], v[194:197], v[50:53]
	v_mfma_f32_16x16x32_bf16 v[42:45], v[122:125], v[194:197], v[42:45]
	v_mfma_f32_16x16x32_bf16 v[34:37], v[114:117], v[206:209], v[34:37]
	v_mfma_f32_16x16x32_bf16 v[26:29], v[122:125], v[206:209], v[26:29]
	v_mfma_f32_16x16x32_bf16 v[18:21], v[114:117], v[214:217], v[18:21]
	v_mfma_f32_16x16x32_bf16 v[10:13], v[122:125], v[214:217], v[10:13]
	v_mfma_f32_16x16x32_bf16 v[62:65], v[118:121], v[166:169], v[62:65]
	v_mfma_f32_16x16x32_bf16 v[58:61], v[126:129], v[166:169], v[58:61]
	v_mfma_f32_16x16x32_bf16 v[50:53], v[118:121], v[198:201], v[50:53]
	v_mfma_f32_16x16x32_bf16 v[42:45], v[126:129], v[198:201], v[42:45]
	v_mfma_f32_16x16x32_bf16 v[34:37], v[118:121], v[210:213], v[34:37]
	v_mfma_f32_16x16x32_bf16 v[26:29], v[126:129], v[210:213], v[26:29]
	v_mfma_f32_16x16x32_bf16 v[18:21], v[118:121], v[218:221], v[18:21]
	v_mfma_f32_16x16x32_bf16 v[10:13], v[126:129], v[218:221], v[10:13]
	v_mfma_f32_16x16x32_bf16 v[54:57], v[146:149], v[162:165], v[54:57]
	v_mfma_f32_16x16x32_bf16 v[46:49], v[154:157], v[162:165], v[46:49]
	v_mfma_f32_16x16x32_bf16 v[38:41], v[146:149], v[194:197], v[38:41]
	v_mfma_f32_16x16x32_bf16 v[30:33], v[154:157], v[194:197], v[30:33]
	v_mfma_f32_16x16x32_bf16 v[22:25], v[146:149], v[206:209], v[22:25]
	v_mfma_f32_16x16x32_bf16 v[14:17], v[154:157], v[206:209], v[14:17]
	v_mfma_f32_16x16x32_bf16 v[6:9], v[146:149], v[214:217], v[6:9]
	v_mfma_f32_16x16x32_bf16 v[2:5], v[154:157], v[214:217], v[2:5]
	v_mfma_f32_16x16x32_bf16 v[54:57], v[150:153], v[166:169], v[54:57]
	v_mfma_f32_16x16x32_bf16 v[46:49], v[158:161], v[166:169], v[46:49]
	v_mfma_f32_16x16x32_bf16 v[38:41], v[150:153], v[198:201], v[38:41]
	v_mfma_f32_16x16x32_bf16 v[30:33], v[158:161], v[198:201], v[30:33]
	v_mfma_f32_16x16x32_bf16 v[22:25], v[150:153], v[210:213], v[22:25]
	v_mfma_f32_16x16x32_bf16 v[14:17], v[158:161], v[210:213], v[14:17]
	v_mfma_f32_16x16x32_bf16 v[6:9], v[150:153], v[218:221], v[6:9]
	v_mfma_f32_16x16x32_bf16 v[2:5], v[158:161], v[218:221], v[2:5]
	s_setprio 0
	s_barrier
	s_add_i32 s63, 0, 0x18000
	s_add_i32 s83, 0, 0x1c000
	v_add_u32_e32 v126, s63, v189
	v_add_u32_e32 v158, s83, v189
	ds_read_b128 v[114:117], v126
	ds_read_b128 v[118:121], v126 offset:1024
	ds_read_b128 v[122:125], v126 offset:2048
	ds_read_b128 v[126:129], v126 offset:3072
	ds_read_b128 v[146:149], v158
	ds_read_b128 v[150:153], v158 offset:1024
	ds_read_b128 v[154:157], v158 offset:2048
	ds_read_b128 v[158:161], v158 offset:3072
	s_add_u32 s80, s80, 0x40000
	s_addc_u32 s81, s81, 0
	s_mov_b32 m0, s89
	v_lshl_add_u64 v[226:227], s[80:81], 0, v[170:171]
	ds_read_b128 v[162:165], v192 offset:32768
	ds_read_b128 v[166:169], v192 offset:33792
	ds_read_b128 v[194:197], v192 offset:34816
	ds_read_b128 v[198:201], v192 offset:35840
	ds_read_b128 v[206:209], v192 offset:36864
	ds_read_b128 v[210:213], v192 offset:37888
	ds_read_b128 v[214:217], v192 offset:38912
	ds_read_b128 v[218:221], v192 offset:39936
	global_load_lds_dwordx4 v[226:227], off
	s_mov_b32 m0, s90
	v_lshl_add_u64 v[226:227], s[80:81], 0, v[174:175]
	global_load_lds_dwordx4 v[226:227], off
	s_setprio 1
	s_waitcnt vmcnt(8) lgkmcnt(0)
	s_barrier
	v_mfma_f32_16x16x32_bf16 v[142:145], v[114:117], v[162:165], v[142:145]
	v_mfma_f32_16x16x32_bf16 v[138:141], v[122:125], v[162:165], v[138:141]
	v_mfma_f32_16x16x32_bf16 v[110:113], v[114:117], v[194:197], v[110:113]
	v_mfma_f32_16x16x32_bf16 v[106:109], v[122:125], v[194:197], v[106:109]
	v_mfma_f32_16x16x32_bf16 v[98:101], v[114:117], v[206:209], v[98:101]
	v_mfma_f32_16x16x32_bf16 v[90:93], v[122:125], v[206:209], v[90:93]
	v_mfma_f32_16x16x32_bf16 v[82:85], v[114:117], v[214:217], v[82:85]
	v_mfma_f32_16x16x32_bf16 v[74:77], v[122:125], v[214:217], v[74:77]
	v_mfma_f32_16x16x32_bf16 v[142:145], v[118:121], v[166:169], v[142:145]
	v_mfma_f32_16x16x32_bf16 v[138:141], v[126:129], v[166:169], v[138:141]
	v_mfma_f32_16x16x32_bf16 v[110:113], v[118:121], v[198:201], v[110:113]
	v_mfma_f32_16x16x32_bf16 v[106:109], v[126:129], v[198:201], v[106:109]
	v_mfma_f32_16x16x32_bf16 v[98:101], v[118:121], v[210:213], v[98:101]
	v_mfma_f32_16x16x32_bf16 v[90:93], v[126:129], v[210:213], v[90:93]
	v_mfma_f32_16x16x32_bf16 v[82:85], v[118:121], v[218:221], v[82:85]
	v_mfma_f32_16x16x32_bf16 v[74:77], v[126:129], v[218:221], v[74:77]
	v_mfma_f32_16x16x32_bf16 v[134:137], v[146:149], v[162:165], v[134:137]
	v_mfma_f32_16x16x32_bf16 v[130:133], v[154:157], v[162:165], v[130:133]
	v_mfma_f32_16x16x32_bf16 v[102:105], v[146:149], v[194:197], v[102:105]
	v_mfma_f32_16x16x32_bf16 v[94:97], v[154:157], v[194:197], v[94:97]
	v_mfma_f32_16x16x32_bf16 v[86:89], v[146:149], v[206:209], v[86:89]
	v_mfma_f32_16x16x32_bf16 v[78:81], v[154:157], v[206:209], v[78:81]
	v_mfma_f32_16x16x32_bf16 v[70:73], v[146:149], v[214:217], v[70:73]
	v_mfma_f32_16x16x32_bf16 v[66:69], v[154:157], v[214:217], v[66:69]
	v_mfma_f32_16x16x32_bf16 v[134:137], v[150:153], v[166:169], v[134:137]
	v_mfma_f32_16x16x32_bf16 v[130:133], v[158:161], v[166:169], v[130:133]
	v_mfma_f32_16x16x32_bf16 v[102:105], v[150:153], v[198:201], v[102:105]
	v_mfma_f32_16x16x32_bf16 v[94:97], v[158:161], v[198:201], v[94:97]
	v_mfma_f32_16x16x32_bf16 v[86:89], v[150:153], v[210:213], v[86:89]
	v_mfma_f32_16x16x32_bf16 v[78:81], v[158:161], v[210:213], v[78:81]
	v_mfma_f32_16x16x32_bf16 v[70:73], v[150:153], v[218:221], v[70:73]
	v_mfma_f32_16x16x32_bf16 v[66:69], v[158:161], v[218:221], v[66:69]
	s_setprio 0
	s_barrier
	s_add_i32 s63, s63, s86
	v_lshl_add_u64 v[186:187], v[186:187], 0, s[22:23]
	s_mov_b32 m0, s63
	ds_read_b128 v[162:165], v192 offset:49152
	ds_read_b128 v[166:169], v192 offset:50176
	ds_read_b128 v[194:197], v192 offset:51200
	ds_read_b128 v[198:201], v192 offset:52224
	ds_read_b128 v[206:209], v192 offset:53248
	ds_read_b128 v[210:213], v192 offset:54272
	ds_read_b128 v[214:217], v192 offset:55296
	ds_read_b128 v[218:221], v192 offset:56320
	global_load_lds_dwordx4 v[186:187], off
	s_add_i32 m0, s63, 0x2000
	s_add_u32 s78, s78, 0x40080
	v_lshl_add_u64 v[186:187], v[202:203], 0, s[22:23]
	s_addc_u32 s79, s79, 0
	s_add_i32 s63, s83, s86
	global_load_lds_dwordx4 v[186:187], off
	s_mov_b32 m0, s63
	v_lshl_add_u64 v[186:187], s[78:79], 0, v[172:173]
	global_load_lds_dwordx4 v[186:187], off
	s_add_i32 m0, s63, 0x2000
	v_lshl_add_u64 v[186:187], s[78:79], 0, v[176:177]
	global_load_lds_dwordx4 v[186:187], off
	s_mov_b32 m0, s95
	v_lshl_add_u64 v[186:187], v[222:223], 0, s[22:23]
	global_load_lds_dwordx4 v[186:187], off
	s_mov_b32 m0, s96
	v_lshl_add_u64 v[186:187], v[224:225], 0, s[22:23]
	global_load_lds_dwordx4 v[186:187], off
	s_setprio 1
	s_waitcnt vmcnt(8) lgkmcnt(0)
	s_barrier
	v_mfma_f32_16x16x32_bf16 v[62:65], v[114:117], v[162:165], v[62:65]
	v_mfma_f32_16x16x32_bf16 v[58:61], v[122:125], v[162:165], v[58:61]
	v_mfma_f32_16x16x32_bf16 v[50:53], v[114:117], v[194:197], v[50:53]
	v_mfma_f32_16x16x32_bf16 v[42:45], v[122:125], v[194:197], v[42:45]
	v_mfma_f32_16x16x32_bf16 v[34:37], v[114:117], v[206:209], v[34:37]
	v_mfma_f32_16x16x32_bf16 v[26:29], v[122:125], v[206:209], v[26:29]
	v_mfma_f32_16x16x32_bf16 v[18:21], v[114:117], v[214:217], v[18:21]
	v_mfma_f32_16x16x32_bf16 v[10:13], v[122:125], v[214:217], v[10:13]
	v_mfma_f32_16x16x32_bf16 v[62:65], v[118:121], v[166:169], v[62:65]
	v_mfma_f32_16x16x32_bf16 v[58:61], v[126:129], v[166:169], v[58:61]
	v_mfma_f32_16x16x32_bf16 v[50:53], v[118:121], v[198:201], v[50:53]
	v_mfma_f32_16x16x32_bf16 v[42:45], v[126:129], v[198:201], v[42:45]
	v_mfma_f32_16x16x32_bf16 v[34:37], v[118:121], v[210:213], v[34:37]
	v_mfma_f32_16x16x32_bf16 v[26:29], v[126:129], v[210:213], v[26:29]
	v_mfma_f32_16x16x32_bf16 v[18:21], v[118:121], v[218:221], v[18:21]
	v_mfma_f32_16x16x32_bf16 v[10:13], v[126:129], v[218:221], v[10:13]
	v_mfma_f32_16x16x32_bf16 v[54:57], v[146:149], v[162:165], v[54:57]
	v_mfma_f32_16x16x32_bf16 v[46:49], v[154:157], v[162:165], v[46:49]
	v_mfma_f32_16x16x32_bf16 v[38:41], v[146:149], v[194:197], v[38:41]
	v_mfma_f32_16x16x32_bf16 v[30:33], v[154:157], v[194:197], v[30:33]
	v_mfma_f32_16x16x32_bf16 v[22:25], v[146:149], v[206:209], v[22:25]
	v_mfma_f32_16x16x32_bf16 v[14:17], v[154:157], v[206:209], v[14:17]
	v_mfma_f32_16x16x32_bf16 v[6:9], v[146:149], v[214:217], v[6:9]
	v_mfma_f32_16x16x32_bf16 v[2:5], v[154:157], v[214:217], v[2:5]
	v_mfma_f32_16x16x32_bf16 v[54:57], v[150:153], v[166:169], v[54:57]
	v_mfma_f32_16x16x32_bf16 v[46:49], v[158:161], v[166:169], v[46:49]
	v_mfma_f32_16x16x32_bf16 v[38:41], v[150:153], v[198:201], v[38:41]
	v_mfma_f32_16x16x32_bf16 v[30:33], v[158:161], v[198:201], v[30:33]
	v_mfma_f32_16x16x32_bf16 v[22:25], v[150:153], v[210:213], v[22:25]
	v_mfma_f32_16x16x32_bf16 v[14:17], v[158:161], v[210:213], v[14:17]
	v_mfma_f32_16x16x32_bf16 v[6:9], v[150:153], v[218:221], v[6:9]
	v_mfma_f32_16x16x32_bf16 v[2:5], v[158:161], v[218:221], v[2:5]
	s_setprio 0
	s_barrier
	s_add_u32 s76, s76, 0x100
	s_addc_u32 s77, s77, 0
	s_add_u32 s47, s47, 0x100
	s_addc_u32 s62, s62, 0
	s_cmp_ge_i32 s82, s7
	s_mov_b32 s63, s82
	s_cbranch_scc0 .LBB0_566
	s_and_b64 vcc, exec, s[26:27]
	s_cbranch_vccz .LBB0_569
	s_barrier

.LBB0_744:
	s_add_u32 s36, s96, s22
	s_addc_u32 s37, s97, s23
	s_and_b64 s[14:15], s[4:5], exec
	s_cselect_b32 s14, s37, s43
	s_cselect_b32 s15, s36, s42
	s_add_u32 s38, s2, s26
	s_addc_u32 s39, s3, s27
	s_and_b64 s[46:47], s[4:5], exec
	s_cselect_b32 s21, s39, s45
	s_cselect_b32 s65, s38, s44
	s_add_u32 s42, s42, 0x40080
	s_addc_u32 s43, s43, 0
	s_add_u32 s66, s44, 0x100
	s_addc_u32 s67, s45, 0
	s_mov_b32 s68, -2
	ds_read_b128 v[154:157], v150
	ds_read_b128 v[158:161], v150 offset:1024
	ds_read_b128 v[162:165], v150 offset:2048
	ds_read_b128 v[166:169], v150 offset:3072
	ds_read_b128 v[170:173], v151
	ds_read_b128 v[174:177], v151 offset:1024
	ds_read_b128 v[178:181], v151 offset:2048
	ds_read_b128 v[182:185], v151 offset:3072
	s_add_u32 s44, s42, 0xfffc0080
	s_addc_u32 s45, s43, -1
	s_cmp_eq_u32 s68, 12
	s_cselect_b32 s47, s14, s45
	s_cselect_b32 s46, s15, s44
	s_cselect_b32 s45, s21, s67
	s_cselect_b32 s44, s65, s66
	v_lshl_add_u64 v[146:147], s[42:43], 0, v[138:139]
	s_add_i32 m0, s19, 0xc000
	ds_read_b128 v[186:189], v152
	ds_read_b128 v[190:193], v152 offset:1024
	ds_read_b128 v[194:197], v152 offset:2048
	ds_read_b128 v[198:201], v152 offset:3072
	ds_read_b128 v[206:209], v152 offset:4096
	ds_read_b128 v[210:213], v152 offset:5120
	ds_read_b128 v[214:217], v152 offset:6144
	ds_read_b128 v[218:221], v152 offset:7168
	global_load_lds_dwordx4 v[146:147], off
	s_add_i32 m0, s19, 0xe000
	v_lshl_add_u64 v[146:147], s[42:43], 0, v[140:141]
	global_load_lds_dwordx4 v[146:147], off
	s_setprio 1
	s_waitcnt vmcnt(8) lgkmcnt(0)
	s_barrier
	v_mfma_f32_16x16x32_bf16 v[126:129], v[154:157], v[186:189], 0
	v_mfma_f32_16x16x32_bf16 v[122:125], v[162:165], v[186:189], 0
	v_mfma_f32_16x16x32_bf16 v[110:113], v[154:157], v[194:197], 0
	v_mfma_f32_16x16x32_bf16 v[106:109], v[162:165], v[194:197], 0
	v_mfma_f32_16x16x32_bf16 v[94:97], v[154:157], v[206:209], 0
	v_mfma_f32_16x16x32_bf16 v[90:93], v[162:165], v[206:209], 0
	v_mfma_f32_16x16x32_bf16 v[78:81], v[154:157], v[214:217], 0
	v_mfma_f32_16x16x32_bf16 v[74:77], v[162:165], v[214:217], 0
	v_mfma_f32_16x16x32_bf16 v[126:129], v[158:161], v[190:193], v[126:129]
	v_mfma_f32_16x16x32_bf16 v[122:125], v[166:169], v[190:193], v[122:125]
	v_mfma_f32_16x16x32_bf16 v[110:113], v[158:161], v[198:201], v[110:113]
	v_mfma_f32_16x16x32_bf16 v[106:109], v[166:169], v[198:201], v[106:109]
	v_mfma_f32_16x16x32_bf16 v[94:97], v[158:161], v[210:213], v[94:97]
	v_mfma_f32_16x16x32_bf16 v[90:93], v[166:169], v[210:213], v[90:93]
	v_mfma_f32_16x16x32_bf16 v[78:81], v[158:161], v[218:221], v[78:81]
	v_mfma_f32_16x16x32_bf16 v[74:77], v[166:169], v[218:221], v[74:77]
	v_mfma_f32_16x16x32_bf16 v[118:121], v[170:173], v[186:189], 0
	v_mfma_f32_16x16x32_bf16 v[114:117], v[178:181], v[186:189], 0
	v_mfma_f32_16x16x32_bf16 v[102:105], v[170:173], v[194:197], 0
	v_mfma_f32_16x16x32_bf16 v[98:101], v[178:181], v[194:197], 0
	v_mfma_f32_16x16x32_bf16 v[86:89], v[170:173], v[206:209], 0
	v_mfma_f32_16x16x32_bf16 v[82:85], v[178:181], v[206:209], 0
	v_mfma_f32_16x16x32_bf16 v[70:73], v[170:173], v[214:217], 0
	v_mfma_f32_16x16x32_bf16 v[66:69], v[178:181], v[214:217], 0
	v_mfma_f32_16x16x32_bf16 v[118:121], v[174:177], v[190:193], v[118:121]
	v_mfma_f32_16x16x32_bf16 v[114:117], v[182:185], v[190:193], v[114:117]
	v_mfma_f32_16x16x32_bf16 v[102:105], v[174:177], v[198:201], v[102:105]
	v_mfma_f32_16x16x32_bf16 v[98:101], v[182:185], v[198:201], v[98:101]
	v_mfma_f32_16x16x32_bf16 v[86:89], v[174:177], v[210:213], v[86:89]
	v_mfma_f32_16x16x32_bf16 v[82:85], v[182:185], v[210:213], v[82:85]
	v_mfma_f32_16x16x32_bf16 v[70:73], v[174:177], v[218:221], v[70:73]
	v_mfma_f32_16x16x32_bf16 v[66:69], v[182:185], v[218:221], v[66:69]
	s_setprio 0
	s_barrier
	s_add_i32 s69, s49, s16
	v_lshl_add_u64 v[146:147], s[44:45], 0, v[134:135]
	s_mov_b32 m0, s69
	ds_read_b128 v[186:189], v152 offset:16384
	ds_read_b128 v[190:193], v152 offset:17408
	ds_read_b128 v[194:197], v152 offset:18432
	ds_read_b128 v[198:201], v152 offset:19456
	ds_read_b128 v[206:209], v152 offset:20480
	ds_read_b128 v[210:213], v152 offset:21504
	ds_read_b128 v[214:217], v152 offset:22528
	ds_read_b128 v[218:221], v152 offset:23552
	global_load_lds_dwordx4 v[146:147], off
	s_add_i32 m0, s69, 0x2000
	s_add_u32 s70, s44, 0x40000
	v_lshl_add_u64 v[202:203], s[44:45], 0, v[130:131]
	s_addc_u32 s71, s45, 0
	s_add_i32 s69, s62, s16
	global_load_lds_dwordx4 v[202:203], off
	v_lshl_add_u64 v[222:223], s[70:71], 0, v[134:135]
	s_mov_b32 m0, s69
	v_lshl_add_u64 v[224:225], s[46:47], 0, v[132:133]
	global_load_lds_dwordx4 v[222:223], off
	s_add_i32 m0, s69, 0x2000
	v_lshl_add_u64 v[222:223], s[70:71], 0, v[130:131]
	global_load_lds_dwordx4 v[222:223], off
	s_mov_b32 m0, s19
	v_lshl_add_u64 v[222:223], s[46:47], 0, v[136:137]
	global_load_lds_dwordx4 v[222:223], off
	s_mov_b32 m0, s24
	s_nop 0
	global_load_lds_dwordx4 v[224:225], off
	s_setprio 1
	s_waitcnt vmcnt(8) lgkmcnt(0)
	s_barrier
	v_mfma_f32_16x16x32_bf16 v[62:65], v[154:157], v[186:189], 0
	v_mfma_f32_16x16x32_bf16 v[58:61], v[162:165], v[186:189], 0
	v_mfma_f32_16x16x32_bf16 v[46:49], v[154:157], v[194:197], 0
	v_mfma_f32_16x16x32_bf16 v[42:45], v[162:165], v[194:197], 0
	v_mfma_f32_16x16x32_bf16 v[30:33], v[154:157], v[206:209], 0
	v_mfma_f32_16x16x32_bf16 v[26:29], v[162:165], v[206:209], 0
	v_mfma_f32_16x16x32_bf16 v[14:17], v[154:157], v[214:217], 0
	v_mfma_f32_16x16x32_bf16 v[10:13], v[162:165], v[214:217], 0
	v_mfma_f32_16x16x32_bf16 v[62:65], v[158:161], v[190:193], v[62:65]
	v_mfma_f32_16x16x32_bf16 v[58:61], v[166:169], v[190:193], v[58:61]
	v_mfma_f32_16x16x32_bf16 v[46:49], v[158:161], v[198:201], v[46:49]
	v_mfma_f32_16x16x32_bf16 v[42:45], v[166:169], v[198:201], v[42:45]
	v_mfma_f32_16x16x32_bf16 v[30:33], v[158:161], v[210:213], v[30:33]
	v_mfma_f32_16x16x32_bf16 v[26:29], v[166:169], v[210:213], v[26:29]
	v_mfma_f32_16x16x32_bf16 v[14:17], v[158:161], v[218:221], v[14:17]
	v_mfma_f32_16x16x32_bf16 v[10:13], v[166:169], v[218:221], v[10:13]
	v_mfma_f32_16x16x32_bf16 v[54:57], v[170:173], v[186:189], 0
	v_mfma_f32_16x16x32_bf16 v[50:53], v[178:181], v[186:189], 0
	v_mfma_f32_16x16x32_bf16 v[38:41], v[170:173], v[194:197], 0
	v_mfma_f32_16x16x32_bf16 v[34:37], v[178:181], v[194:197], 0
	v_mfma_f32_16x16x32_bf16 v[22:25], v[170:173], v[206:209], 0
	v_mfma_f32_16x16x32_bf16 v[18:21], v[178:181], v[206:209], 0
	v_mfma_f32_16x16x32_bf16 v[6:9], v[170:173], v[214:217], 0
	v_mfma_f32_16x16x32_bf16 v[2:5], v[178:181], v[214:217], 0
	v_mfma_f32_16x16x32_bf16 v[54:57], v[174:177], v[190:193], v[54:57]
	v_mfma_f32_16x16x32_bf16 v[50:53], v[182:185], v[190:193], v[50:53]
	v_mfma_f32_16x16x32_bf16 v[38:41], v[174:177], v[198:201], v[38:41]
	v_mfma_f32_16x16x32_bf16 v[34:37], v[182:185], v[198:201], v[34:37]
	v_mfma_f32_16x16x32_bf16 v[22:25], v[174:177], v[210:213], v[22:25]
	v_mfma_f32_16x16x32_bf16 v[18:21], v[182:185], v[210:213], v[18:21]
	v_mfma_f32_16x16x32_bf16 v[6:9], v[174:177], v[218:221], v[6:9]
	v_mfma_f32_16x16x32_bf16 v[2:5], v[182:185], v[218:221], v[2:5]
	s_setprio 0
	s_barrier
	s_add_i32 s69, 0, 0x18000
	v_add_u32_e32 v153, s69, v149
	s_add_i32 s70, 0, 0x1c000
	ds_read_b128 v[154:157], v153
	ds_read_b128 v[158:161], v153 offset:1024
	ds_read_b128 v[162:165], v153 offset:2048
	ds_read_b128 v[166:169], v153 offset:3072
	v_add_u32_e32 v153, s70, v149
	ds_read_b128 v[170:173], v153
	ds_read_b128 v[174:177], v153 offset:1024
	ds_read_b128 v[178:181], v153 offset:2048
	ds_read_b128 v[182:185], v153 offset:3072
	s_add_u32 s46, s46, 0x40000
	s_addc_u32 s47, s47, 0
	s_mov_b32 m0, s25
	v_lshl_add_u64 v[226:227], s[46:47], 0, v[136:137]
	ds_read_b128 v[186:189], v152 offset:32768
	ds_read_b128 v[190:193], v152 offset:33792
	ds_read_b128 v[194:197], v152 offset:34816
	ds_read_b128 v[198:201], v152 offset:35840
	ds_read_b128 v[206:209], v152 offset:36864
	ds_read_b128 v[210:213], v152 offset:37888
	ds_read_b128 v[214:217], v152 offset:38912
	ds_read_b128 v[218:221], v152 offset:39936
	global_load_lds_dwordx4 v[226:227], off
	s_mov_b32 m0, s28
	v_lshl_add_u64 v[226:227], s[46:47], 0, v[132:133]
	global_load_lds_dwordx4 v[226:227], off
	s_setprio 1
	s_waitcnt vmcnt(8) lgkmcnt(0)
	s_barrier
	v_mfma_f32_16x16x32_bf16 v[126:129], v[154:157], v[186:189], v[126:129]
	v_mfma_f32_16x16x32_bf16 v[122:125], v[162:165], v[186:189], v[122:125]
	v_mfma_f32_16x16x32_bf16 v[110:113], v[154:157], v[194:197], v[110:113]
	v_mfma_f32_16x16x32_bf16 v[106:109], v[162:165], v[194:197], v[106:109]
	v_mfma_f32_16x16x32_bf16 v[94:97], v[154:157], v[206:209], v[94:97]
	v_mfma_f32_16x16x32_bf16 v[90:93], v[162:165], v[206:209], v[90:93]
	v_mfma_f32_16x16x32_bf16 v[78:81], v[154:157], v[214:217], v[78:81]
	v_mfma_f32_16x16x32_bf16 v[74:77], v[162:165], v[214:217], v[74:77]
	v_mfma_f32_16x16x32_bf16 v[126:129], v[158:161], v[190:193], v[126:129]
	v_mfma_f32_16x16x32_bf16 v[122:125], v[166:169], v[190:193], v[122:125]
	v_mfma_f32_16x16x32_bf16 v[110:113], v[158:161], v[198:201], v[110:113]
	v_mfma_f32_16x16x32_bf16 v[106:109], v[166:169], v[198:201], v[106:109]
	v_mfma_f32_16x16x32_bf16 v[94:97], v[158:161], v[210:213], v[94:97]
	v_mfma_f32_16x16x32_bf16 v[90:93], v[166:169], v[210:213], v[90:93]
	v_mfma_f32_16x16x32_bf16 v[78:81], v[158:161], v[218:221], v[78:81]
	v_mfma_f32_16x16x32_bf16 v[74:77], v[166:169], v[218:221], v[74:77]
	v_mfma_f32_16x16x32_bf16 v[118:121], v[170:173], v[186:189], v[118:121]
	v_mfma_f32_16x16x32_bf16 v[114:117], v[178:181], v[186:189], v[114:117]
	v_mfma_f32_16x16x32_bf16 v[102:105], v[170:173], v[194:197], v[102:105]
	v_mfma_f32_16x16x32_bf16 v[98:101], v[178:181], v[194:197], v[98:101]
	v_mfma_f32_16x16x32_bf16 v[86:89], v[170:173], v[206:209], v[86:89]
	v_mfma_f32_16x16x32_bf16 v[82:85], v[178:181], v[206:209], v[82:85]
	v_mfma_f32_16x16x32_bf16 v[70:73], v[170:173], v[214:217], v[70:73]
	v_mfma_f32_16x16x32_bf16 v[66:69], v[178:181], v[214:217], v[66:69]
	v_mfma_f32_16x16x32_bf16 v[118:121], v[174:177], v[190:193], v[118:121]
	v_mfma_f32_16x16x32_bf16 v[114:117], v[182:185], v[190:193], v[114:117]
	v_mfma_f32_16x16x32_bf16 v[102:105], v[174:177], v[198:201], v[102:105]
	v_mfma_f32_16x16x32_bf16 v[98:101], v[182:185], v[198:201], v[98:101]
	v_mfma_f32_16x16x32_bf16 v[86:89], v[174:177], v[210:213], v[86:89]
	v_mfma_f32_16x16x32_bf16 v[82:85], v[182:185], v[210:213], v[82:85]
	v_mfma_f32_16x16x32_bf16 v[70:73], v[174:177], v[218:221], v[70:73]
	v_mfma_f32_16x16x32_bf16 v[66:69], v[182:185], v[218:221], v[66:69]
	s_setprio 0
	s_barrier
	s_add_i32 s46, s69, s16
	v_lshl_add_u64 v[146:147], v[146:147], 0, s[10:11]
	s_mov_b32 m0, s46
	ds_read_b128 v[186:189], v152 offset:49152
	ds_read_b128 v[190:193], v152 offset:50176
	ds_read_b128 v[194:197], v152 offset:51200
	ds_read_b128 v[198:201], v152 offset:52224
	ds_read_b128 v[206:209], v152 offset:53248
	ds_read_b128 v[210:213], v152 offset:54272
	ds_read_b128 v[214:217], v152 offset:55296
	ds_read_b128 v[218:221], v152 offset:56320
	global_load_lds_dwordx4 v[146:147], off
	s_add_i32 m0, s46, 0x2000
	s_add_u32 s44, s44, 0x40080
	v_lshl_add_u64 v[146:147], v[202:203], 0, s[10:11]
	s_addc_u32 s45, s45, 0
	s_add_i32 s46, s70, s16
	global_load_lds_dwordx4 v[146:147], off
	s_mov_b32 m0, s46
	v_lshl_add_u64 v[146:147], s[44:45], 0, v[134:135]
	global_load_lds_dwordx4 v[146:147], off
	s_add_i32 m0, s46, 0x2000
	v_lshl_add_u64 v[146:147], s[44:45], 0, v[130:131]
	global_load_lds_dwordx4 v[146:147], off
	s_mov_b32 m0, s33
	v_lshl_add_u64 v[146:147], v[222:223], 0, s[10:11]
	global_load_lds_dwordx4 v[146:147], off
	s_mov_b32 m0, s35
	v_lshl_add_u64 v[146:147], v[224:225], 0, s[10:11]
	global_load_lds_dwordx4 v[146:147], off
	s_setprio 1
	s_waitcnt vmcnt(8) lgkmcnt(0)
	s_barrier
	v_mfma_f32_16x16x32_bf16 v[62:65], v[154:157], v[186:189], v[62:65]
	v_mfma_f32_16x16x32_bf16 v[58:61], v[162:165], v[186:189], v[58:61]
	v_mfma_f32_16x16x32_bf16 v[46:49], v[154:157], v[194:197], v[46:49]
	v_mfma_f32_16x16x32_bf16 v[42:45], v[162:165], v[194:197], v[42:45]
	v_mfma_f32_16x16x32_bf16 v[30:33], v[154:157], v[206:209], v[30:33]
	v_mfma_f32_16x16x32_bf16 v[26:29], v[162:165], v[206:209], v[26:29]
	v_mfma_f32_16x16x32_bf16 v[14:17], v[154:157], v[214:217], v[14:17]
	v_mfma_f32_16x16x32_bf16 v[10:13], v[162:165], v[214:217], v[10:13]
	v_mfma_f32_16x16x32_bf16 v[62:65], v[158:161], v[190:193], v[62:65]
	v_mfma_f32_16x16x32_bf16 v[58:61], v[166:169], v[190:193], v[58:61]
	v_mfma_f32_16x16x32_bf16 v[46:49], v[158:161], v[198:201], v[46:49]
	v_mfma_f32_16x16x32_bf16 v[42:45], v[166:169], v[198:201], v[42:45]
	v_mfma_f32_16x16x32_bf16 v[30:33], v[158:161], v[210:213], v[30:33]
	v_mfma_f32_16x16x32_bf16 v[26:29], v[166:169], v[210:213], v[26:29]
	v_mfma_f32_16x16x32_bf16 v[14:17], v[158:161], v[218:221], v[14:17]
	v_mfma_f32_16x16x32_bf16 v[10:13], v[166:169], v[218:221], v[10:13]
	v_mfma_f32_16x16x32_bf16 v[54:57], v[170:173], v[186:189], v[54:57]
	v_mfma_f32_16x16x32_bf16 v[50:53], v[178:181], v[186:189], v[50:53]
	v_mfma_f32_16x16x32_bf16 v[38:41], v[170:173], v[194:197], v[38:41]
	v_mfma_f32_16x16x32_bf16 v[34:37], v[178:181], v[194:197], v[34:37]
	v_mfma_f32_16x16x32_bf16 v[22:25], v[170:173], v[206:209], v[22:25]
	v_mfma_f32_16x16x32_bf16 v[18:21], v[178:181], v[206:209], v[18:21]
	v_mfma_f32_16x16x32_bf16 v[6:9], v[170:173], v[214:217], v[6:9]
	v_mfma_f32_16x16x32_bf16 v[2:5], v[178:181], v[214:217], v[2:5]
	v_mfma_f32_16x16x32_bf16 v[54:57], v[174:177], v[190:193], v[54:57]
	v_mfma_f32_16x16x32_bf16 v[50:53], v[182:185], v[190:193], v[50:53]
	v_mfma_f32_16x16x32_bf16 v[38:41], v[174:177], v[198:201], v[38:41]
	v_mfma_f32_16x16x32_bf16 v[34:37], v[182:185], v[198:201], v[34:37]
	v_mfma_f32_16x16x32_bf16 v[22:25], v[174:177], v[210:213], v[22:25]
	v_mfma_f32_16x16x32_bf16 v[18:21], v[182:185], v[210:213], v[18:21]
	v_mfma_f32_16x16x32_bf16 v[6:9], v[174:177], v[218:221], v[6:9]
	v_mfma_f32_16x16x32_bf16 v[2:5], v[182:185], v[218:221], v[2:5]
	s_setprio 0
	s_barrier
	s_add_i32 s68, s68, 2
	s_add_u32 s42, s42, 0x100
	s_addc_u32 s43, s43, 0
	s_add_u32 s66, s66, 0x100
	s_addc_u32 s67, s67, 0
	s_cmp_gt_u32 s68, 13
.LBB0_745:
	ds_read_b128 v[154:157], v150
	ds_read_b128 v[158:161], v150 offset:1024
	ds_read_b128 v[162:165], v150 offset:2048
	ds_read_b128 v[166:169], v150 offset:3072
	ds_read_b128 v[170:173], v151
	ds_read_b128 v[174:177], v151 offset:1024
	ds_read_b128 v[178:181], v151 offset:2048
	ds_read_b128 v[182:185], v151 offset:3072
	s_add_u32 s44, s42, 0xfffc0080
	s_addc_u32 s45, s43, -1
	s_cmp_eq_u32 s68, 12
	s_cselect_b32 s47, s14, s45
	s_cselect_b32 s46, s15, s44
	s_cselect_b32 s45, s21, s67
	s_cselect_b32 s44, s65, s66
	v_lshl_add_u64 v[146:147], s[42:43], 0, v[138:139]
	s_add_i32 m0, s19, 0xc000
	ds_read_b128 v[186:189], v152
	ds_read_b128 v[190:193], v152 offset:1024
	ds_read_b128 v[194:197], v152 offset:2048
	ds_read_b128 v[198:201], v152 offset:3072
	ds_read_b128 v[206:209], v152 offset:4096
	ds_read_b128 v[210:213], v152 offset:5120
	ds_read_b128 v[214:217], v152 offset:6144
	ds_read_b128 v[218:221], v152 offset:7168
	global_load_lds_dwordx4 v[146:147], off
	s_add_i32 m0, s19, 0xe000
	v_lshl_add_u64 v[146:147], s[42:43], 0, v[140:141]
	global_load_lds_dwordx4 v[146:147], off
	s_setprio 1
	s_waitcnt vmcnt(8) lgkmcnt(0)
	s_barrier
	v_mfma_f32_16x16x32_bf16 v[126:129], v[154:157], v[186:189], v[126:129]
	v_mfma_f32_16x16x32_bf16 v[122:125], v[162:165], v[186:189], v[122:125]
	v_mfma_f32_16x16x32_bf16 v[110:113], v[154:157], v[194:197], v[110:113]
	v_mfma_f32_16x16x32_bf16 v[106:109], v[162:165], v[194:197], v[106:109]
	v_mfma_f32_16x16x32_bf16 v[94:97], v[154:157], v[206:209], v[94:97]
	v_mfma_f32_16x16x32_bf16 v[90:93], v[162:165], v[206:209], v[90:93]
	v_mfma_f32_16x16x32_bf16 v[78:81], v[154:157], v[214:217], v[78:81]
	v_mfma_f32_16x16x32_bf16 v[74:77], v[162:165], v[214:217], v[74:77]
	v_mfma_f32_16x16x32_bf16 v[126:129], v[158:161], v[190:193], v[126:129]
	v_mfma_f32_16x16x32_bf16 v[122:125], v[166:169], v[190:193], v[122:125]
	v_mfma_f32_16x16x32_bf16 v[110:113], v[158:161], v[198:201], v[110:113]
	v_mfma_f32_16x16x32_bf16 v[106:109], v[166:169], v[198:201], v[106:109]
	v_mfma_f32_16x16x32_bf16 v[94:97], v[158:161], v[210:213], v[94:97]
	v_mfma_f32_16x16x32_bf16 v[90:93], v[166:169], v[210:213], v[90:93]
	v_mfma_f32_16x16x32_bf16 v[78:81], v[158:161], v[218:221], v[78:81]
	v_mfma_f32_16x16x32_bf16 v[74:77], v[166:169], v[218:221], v[74:77]
	v_mfma_f32_16x16x32_bf16 v[118:121], v[170:173], v[186:189], v[118:121]
	v_mfma_f32_16x16x32_bf16 v[114:117], v[178:181], v[186:189], v[114:117]
	v_mfma_f32_16x16x32_bf16 v[102:105], v[170:173], v[194:197], v[102:105]
	v_mfma_f32_16x16x32_bf16 v[98:101], v[178:181], v[194:197], v[98:101]
	v_mfma_f32_16x16x32_bf16 v[86:89], v[170:173], v[206:209], v[86:89]
	v_mfma_f32_16x16x32_bf16 v[82:85], v[178:181], v[206:209], v[82:85]
	v_mfma_f32_16x16x32_bf16 v[70:73], v[170:173], v[214:217], v[70:73]
	v_mfma_f32_16x16x32_bf16 v[66:69], v[178:181], v[214:217], v[66:69]
	v_mfma_f32_16x16x32_bf16 v[118:121], v[174:177], v[190:193], v[118:121]
	v_mfma_f32_16x16x32_bf16 v[114:117], v[182:185], v[190:193], v[114:117]
	v_mfma_f32_16x16x32_bf16 v[102:105], v[174:177], v[198:201], v[102:105]
	v_mfma_f32_16x16x32_bf16 v[98:101], v[182:185], v[198:201], v[98:101]
	v_mfma_f32_16x16x32_bf16 v[86:89], v[174:177], v[210:213], v[86:89]
	v_mfma_f32_16x16x32_bf16 v[82:85], v[182:185], v[210:213], v[82:85]
	v_mfma_f32_16x16x32_bf16 v[70:73], v[174:177], v[218:221], v[70:73]
	v_mfma_f32_16x16x32_bf16 v[66:69], v[182:185], v[218:221], v[66:69]
	s_setprio 0
	s_barrier
	s_add_i32 s69, s49, s16
	v_lshl_add_u64 v[146:147], s[44:45], 0, v[134:135]
	s_mov_b32 m0, s69
	ds_read_b128 v[186:189], v152 offset:16384
	ds_read_b128 v[190:193], v152 offset:17408
	ds_read_b128 v[194:197], v152 offset:18432
	ds_read_b128 v[198:201], v152 offset:19456
	ds_read_b128 v[206:209], v152 offset:20480
	ds_read_b128 v[210:213], v152 offset:21504
	ds_read_b128 v[214:217], v152 offset:22528
	ds_read_b128 v[218:221], v152 offset:23552
	global_load_lds_dwordx4 v[146:147], off
	s_add_i32 m0, s69, 0x2000
	s_add_u32 s70, s44, 0x40000
	v_lshl_add_u64 v[202:203], s[44:45], 0, v[130:131]
	s_addc_u32 s71, s45, 0
	s_add_i32 s69, s62, s16
	global_load_lds_dwordx4 v[202:203], off
	v_lshl_add_u64 v[222:223], s[70:71], 0, v[134:135]
	s_mov_b32 m0, s69
	v_lshl_add_u64 v[224:225], s[46:47], 0, v[132:133]
	global_load_lds_dwordx4 v[222:223], off
	s_add_i32 m0, s69, 0x2000
	v_lshl_add_u64 v[222:223], s[70:71], 0, v[130:131]
	global_load_lds_dwordx4 v[222:223], off
	s_mov_b32 m0, s19
	v_lshl_add_u64 v[222:223], s[46:47], 0, v[136:137]
	global_load_lds_dwordx4 v[222:223], off
	s_mov_b32 m0, s24
	s_nop 0
	global_load_lds_dwordx4 v[224:225], off
	s_setprio 1
	s_waitcnt vmcnt(8) lgkmcnt(0)
	s_barrier
	v_mfma_f32_16x16x32_bf16 v[62:65], v[154:157], v[186:189], v[62:65]
	v_mfma_f32_16x16x32_bf16 v[58:61], v[162:165], v[186:189], v[58:61]
	v_mfma_f32_16x16x32_bf16 v[46:49], v[154:157], v[194:197], v[46:49]
	v_mfma_f32_16x16x32_bf16 v[42:45], v[162:165], v[194:197], v[42:45]
	v_mfma_f32_16x16x32_bf16 v[30:33], v[154:157], v[206:209], v[30:33]
	v_mfma_f32_16x16x32_bf16 v[26:29], v[162:165], v[206:209], v[26:29]
	v_mfma_f32_16x16x32_bf16 v[14:17], v[154:157], v[214:217], v[14:17]
	v_mfma_f32_16x16x32_bf16 v[10:13], v[162:165], v[214:217], v[10:13]
	v_mfma_f32_16x16x32_bf16 v[62:65], v[158:161], v[190:193], v[62:65]
	v_mfma_f32_16x16x32_bf16 v[58:61], v[166:169], v[190:193], v[58:61]
	v_mfma_f32_16x16x32_bf16 v[46:49], v[158:161], v[198:201], v[46:49]
	v_mfma_f32_16x16x32_bf16 v[42:45], v[166:169], v[198:201], v[42:45]
	v_mfma_f32_16x16x32_bf16 v[30:33], v[158:161], v[210:213], v[30:33]
	v_mfma_f32_16x16x32_bf16 v[26:29], v[166:169], v[210:213], v[26:29]
	v_mfma_f32_16x16x32_bf16 v[14:17], v[158:161], v[218:221], v[14:17]
	v_mfma_f32_16x16x32_bf16 v[10:13], v[166:169], v[218:221], v[10:13]
	v_mfma_f32_16x16x32_bf16 v[54:57], v[170:173], v[186:189], v[54:57]
	v_mfma_f32_16x16x32_bf16 v[50:53], v[178:181], v[186:189], v[50:53]
	v_mfma_f32_16x16x32_bf16 v[38:41], v[170:173], v[194:197], v[38:41]
	v_mfma_f32_16x16x32_bf16 v[34:37], v[178:181], v[194:197], v[34:37]
	v_mfma_f32_16x16x32_bf16 v[22:25], v[170:173], v[206:209], v[22:25]
	v_mfma_f32_16x16x32_bf16 v[18:21], v[178:181], v[206:209], v[18:21]
	v_mfma_f32_16x16x32_bf16 v[6:9], v[170:173], v[214:217], v[6:9]
	v_mfma_f32_16x16x32_bf16 v[2:5], v[178:181], v[214:217], v[2:5]
	v_mfma_f32_16x16x32_bf16 v[54:57], v[174:177], v[190:193], v[54:57]
	v_mfma_f32_16x16x32_bf16 v[50:53], v[182:185], v[190:193], v[50:53]
	v_mfma_f32_16x16x32_bf16 v[38:41], v[174:177], v[198:201], v[38:41]
	v_mfma_f32_16x16x32_bf16 v[34:37], v[182:185], v[198:201], v[34:37]
	v_mfma_f32_16x16x32_bf16 v[22:25], v[174:177], v[210:213], v[22:25]
	v_mfma_f32_16x16x32_bf16 v[18:21], v[182:185], v[210:213], v[18:21]
	v_mfma_f32_16x16x32_bf16 v[6:9], v[174:177], v[218:221], v[6:9]
	v_mfma_f32_16x16x32_bf16 v[2:5], v[182:185], v[218:221], v[2:5]
	s_setprio 0
	s_barrier
	s_add_i32 s69, 0, 0x18000
	v_add_u32_e32 v153, s69, v149
	s_add_i32 s70, 0, 0x1c000
	ds_read_b128 v[154:157], v153
	ds_read_b128 v[158:161], v153 offset:1024
	ds_read_b128 v[162:165], v153 offset:2048
	ds_read_b128 v[166:169], v153 offset:3072
	v_add_u32_e32 v153, s70, v149
	ds_read_b128 v[170:173], v153
	ds_read_b128 v[174:177], v153 offset:1024
	ds_read_b128 v[178:181], v153 offset:2048
	ds_read_b128 v[182:185], v153 offset:3072
	s_add_u32 s46, s46, 0x40000
	s_addc_u32 s47, s47, 0
	s_mov_b32 m0, s25
	v_lshl_add_u64 v[226:227], s[46:47], 0, v[136:137]
	ds_read_b128 v[186:189], v152 offset:32768
	ds_read_b128 v[190:193], v152 offset:33792
	ds_read_b128 v[194:197], v152 offset:34816
	ds_read_b128 v[198:201], v152 offset:35840
	ds_read_b128 v[206:209], v152 offset:36864
	ds_read_b128 v[210:213], v152 offset:37888
	ds_read_b128 v[214:217], v152 offset:38912
	ds_read_b128 v[218:221], v152 offset:39936
	global_load_lds_dwordx4 v[226:227], off
	s_mov_b32 m0, s28
	v_lshl_add_u64 v[226:227], s[46:47], 0, v[132:133]
	global_load_lds_dwordx4 v[226:227], off
	s_setprio 1
	s_waitcnt vmcnt(8) lgkmcnt(0)
	s_barrier
	v_mfma_f32_16x16x32_bf16 v[126:129], v[154:157], v[186:189], v[126:129]
	v_mfma_f32_16x16x32_bf16 v[122:125], v[162:165], v[186:189], v[122:125]
	v_mfma_f32_16x16x32_bf16 v[110:113], v[154:157], v[194:197], v[110:113]
	v_mfma_f32_16x16x32_bf16 v[106:109], v[162:165], v[194:197], v[106:109]
	v_mfma_f32_16x16x32_bf16 v[94:97], v[154:157], v[206:209], v[94:97]
	v_mfma_f32_16x16x32_bf16 v[90:93], v[162:165], v[206:209], v[90:93]
	v_mfma_f32_16x16x32_bf16 v[78:81], v[154:157], v[214:217], v[78:81]
	v_mfma_f32_16x16x32_bf16 v[74:77], v[162:165], v[214:217], v[74:77]
	v_mfma_f32_16x16x32_bf16 v[126:129], v[158:161], v[190:193], v[126:129]
	v_mfma_f32_16x16x32_bf16 v[122:125], v[166:169], v[190:193], v[122:125]
	v_mfma_f32_16x16x32_bf16 v[110:113], v[158:161], v[198:201], v[110:113]
	v_mfma_f32_16x16x32_bf16 v[106:109], v[166:169], v[198:201], v[106:109]
	v_mfma_f32_16x16x32_bf16 v[94:97], v[158:161], v[210:213], v[94:97]
	v_mfma_f32_16x16x32_bf16 v[90:93], v[166:169], v[210:213], v[90:93]
	v_mfma_f32_16x16x32_bf16 v[78:81], v[158:161], v[218:221], v[78:81]
	v_mfma_f32_16x16x32_bf16 v[74:77], v[166:169], v[218:221], v[74:77]
	v_mfma_f32_16x16x32_bf16 v[118:121], v[170:173], v[186:189], v[118:121]
	v_mfma_f32_16x16x32_bf16 v[114:117], v[178:181], v[186:189], v[114:117]
	v_mfma_f32_16x16x32_bf16 v[102:105], v[170:173], v[194:197], v[102:105]
	v_mfma_f32_16x16x32_bf16 v[98:101], v[178:181], v[194:197], v[98:101]
	v_mfma_f32_16x16x32_bf16 v[86:89], v[170:173], v[206:209], v[86:89]
	v_mfma_f32_16x16x32_bf16 v[82:85], v[178:181], v[206:209], v[82:85]
	v_mfma_f32_16x16x32_bf16 v[70:73], v[170:173], v[214:217], v[70:73]
	v_mfma_f32_16x16x32_bf16 v[66:69], v[178:181], v[214:217], v[66:69]
	v_mfma_f32_16x16x32_bf16 v[118:121], v[174:177], v[190:193], v[118:121]
	v_mfma_f32_16x16x32_bf16 v[114:117], v[182:185], v[190:193], v[114:117]
	v_mfma_f32_16x16x32_bf16 v[102:105], v[174:177], v[198:201], v[102:105]
	v_mfma_f32_16x16x32_bf16 v[98:101], v[182:185], v[198:201], v[98:101]
	v_mfma_f32_16x16x32_bf16 v[86:89], v[174:177], v[210:213], v[86:89]
	v_mfma_f32_16x16x32_bf16 v[82:85], v[182:185], v[210:213], v[82:85]
	v_mfma_f32_16x16x32_bf16 v[70:73], v[174:177], v[218:221], v[70:73]
	v_mfma_f32_16x16x32_bf16 v[66:69], v[182:185], v[218:221], v[66:69]
	s_setprio 0
	s_barrier
	s_add_i32 s46, s69, s16
	v_lshl_add_u64 v[146:147], v[146:147], 0, s[10:11]
	s_mov_b32 m0, s46
	ds_read_b128 v[186:189], v152 offset:49152
	ds_read_b128 v[190:193], v152 offset:50176
	ds_read_b128 v[194:197], v152 offset:51200
	ds_read_b128 v[198:201], v152 offset:52224
	ds_read_b128 v[206:209], v152 offset:53248
	ds_read_b128 v[210:213], v152 offset:54272
	ds_read_b128 v[214:217], v152 offset:55296
	ds_read_b128 v[218:221], v152 offset:56320
	global_load_lds_dwordx4 v[146:147], off
	s_add_i32 m0, s46, 0x2000
	s_add_u32 s44, s44, 0x40080
	v_lshl_add_u64 v[146:147], v[202:203], 0, s[10:11]
	s_addc_u32 s45, s45, 0
	s_add_i32 s46, s70, s16
	global_load_lds_dwordx4 v[146:147], off
	s_mov_b32 m0, s46
	v_lshl_add_u64 v[146:147], s[44:45], 0, v[134:135]
	global_load_lds_dwordx4 v[146:147], off
	s_add_i32 m0, s46, 0x2000
	v_lshl_add_u64 v[146:147], s[44:45], 0, v[130:131]
	global_load_lds_dwordx4 v[146:147], off
	s_mov_b32 m0, s33
	v_lshl_add_u64 v[146:147], v[222:223], 0, s[10:11]
	global_load_lds_dwordx4 v[146:147], off
	s_mov_b32 m0, s35
	v_lshl_add_u64 v[146:147], v[224:225], 0, s[10:11]
	global_load_lds_dwordx4 v[146:147], off
	s_setprio 1
	s_waitcnt vmcnt(8) lgkmcnt(0)
	s_barrier
	v_mfma_f32_16x16x32_bf16 v[62:65], v[154:157], v[186:189], v[62:65]
	v_mfma_f32_16x16x32_bf16 v[58:61], v[162:165], v[186:189], v[58:61]
	v_mfma_f32_16x16x32_bf16 v[46:49], v[154:157], v[194:197], v[46:49]
	v_mfma_f32_16x16x32_bf16 v[42:45], v[162:165], v[194:197], v[42:45]
	v_mfma_f32_16x16x32_bf16 v[30:33], v[154:157], v[206:209], v[30:33]
	v_mfma_f32_16x16x32_bf16 v[26:29], v[162:165], v[206:209], v[26:29]
	v_mfma_f32_16x16x32_bf16 v[14:17], v[154:157], v[214:217], v[14:17]
	v_mfma_f32_16x16x32_bf16 v[10:13], v[162:165], v[214:217], v[10:13]
	v_mfma_f32_16x16x32_bf16 v[62:65], v[158:161], v[190:193], v[62:65]
	v_mfma_f32_16x16x32_bf16 v[58:61], v[166:169], v[190:193], v[58:61]
	v_mfma_f32_16x16x32_bf16 v[46:49], v[158:161], v[198:201], v[46:49]
	v_mfma_f32_16x16x32_bf16 v[42:45], v[166:169], v[198:201], v[42:45]
	v_mfma_f32_16x16x32_bf16 v[30:33], v[158:161], v[210:213], v[30:33]
	v_mfma_f32_16x16x32_bf16 v[26:29], v[166:169], v[210:213], v[26:29]
	v_mfma_f32_16x16x32_bf16 v[14:17], v[158:161], v[218:221], v[14:17]
	v_mfma_f32_16x16x32_bf16 v[10:13], v[166:169], v[218:221], v[10:13]
	v_mfma_f32_16x16x32_bf16 v[54:57], v[170:173], v[186:189], v[54:57]
	v_mfma_f32_16x16x32_bf16 v[50:53], v[178:181], v[186:189], v[50:53]
	v_mfma_f32_16x16x32_bf16 v[38:41], v[170:173], v[194:197], v[38:41]
	v_mfma_f32_16x16x32_bf16 v[34:37], v[178:181], v[194:197], v[34:37]
	v_mfma_f32_16x16x32_bf16 v[22:25], v[170:173], v[206:209], v[22:25]
	v_mfma_f32_16x16x32_bf16 v[18:21], v[178:181], v[206:209], v[18:21]
	v_mfma_f32_16x16x32_bf16 v[6:9], v[170:173], v[214:217], v[6:9]
	v_mfma_f32_16x16x32_bf16 v[2:5], v[178:181], v[214:217], v[2:5]
	v_mfma_f32_16x16x32_bf16 v[54:57], v[174:177], v[190:193], v[54:57]
	v_mfma_f32_16x16x32_bf16 v[50:53], v[182:185], v[190:193], v[50:53]
	v_mfma_f32_16x16x32_bf16 v[38:41], v[174:177], v[198:201], v[38:41]
	v_mfma_f32_16x16x32_bf16 v[34:37], v[182:185], v[198:201], v[34:37]
	v_mfma_f32_16x16x32_bf16 v[22:25], v[174:177], v[210:213], v[22:25]
	v_mfma_f32_16x16x32_bf16 v[18:21], v[182:185], v[210:213], v[18:21]
	v_mfma_f32_16x16x32_bf16 v[6:9], v[174:177], v[218:221], v[6:9]
	v_mfma_f32_16x16x32_bf16 v[2:5], v[182:185], v[218:221], v[2:5]
	s_setprio 0
	s_barrier
	s_add_i32 s68, s68, 2
	s_add_u32 s42, s42, 0x100
	s_addc_u32 s43, s43, 0
	s_add_u32 s66, s66, 0x100
	s_addc_u32 s67, s67, 0
	s_cmp_gt_u32 s68, 13
	s_cbranch_scc0 .LBB0_745
	s_and_b64 vcc, exec, s[12:13]
	s_cbranch_vccz .LBB0_748
	s_barrier

.LBB0_833:
	s_add_u32 s72, s0, s68
	s_addc_u32 s73, s1, s69
	s_and_b64 s[62:63], s[70:71], exec
	s_cselect_b32 s15, s73, s77
	s_cselect_b32 s33, s72, s76
	s_add_u32 s74, s35, s66
	s_addc_u32 s75, s85, s67
	s_and_b64 s[62:63], s[70:71], exec
	s_cselect_b32 s34, s75, s79
	s_cselect_b32 s39, s74, s78
	s_add_i32 s45, s7, -2
	s_add_u32 s76, s76, 0x100080
	s_addc_u32 s77, s77, 0
	s_add_u32 s47, s78, 0x100
	s_addc_u32 s62, s79, 0
	s_mov_b32 s63, 0
	s_waitcnt vmcnt(0)
	ds_read_b128 v[114:117], v190
	ds_read_b128 v[118:121], v190 offset:1024
	ds_read_b128 v[122:125], v190 offset:2048
	ds_read_b128 v[126:129], v190 offset:3072
	ds_read_b128 v[146:149], v191
	ds_read_b128 v[150:153], v191 offset:1024
	ds_read_b128 v[154:157], v191 offset:2048
	ds_read_b128 v[158:161], v191 offset:3072
	s_add_i32 s82, s63, 2
	s_add_u32 s78, s76, 0xfff00080
	s_addc_u32 s79, s77, -1
	s_cmp_eq_u32 s45, s63
	s_cselect_b32 s81, s15, s79
	s_cselect_b32 s80, s33, s78
	s_cselect_b32 s79, s34, s62
	s_cselect_b32 s78, s39, s47
	v_lshl_add_u64 v[186:187], s[76:77], 0, v[180:181]
	s_add_i32 m0, s87, 0xc000
	ds_read_b128 v[162:165], v192
	ds_read_b128 v[166:169], v192 offset:1024
	ds_read_b128 v[194:197], v192 offset:2048
	ds_read_b128 v[198:201], v192 offset:3072
	ds_read_b128 v[206:209], v192 offset:4096
	ds_read_b128 v[210:213], v192 offset:5120
	ds_read_b128 v[214:217], v192 offset:6144
	ds_read_b128 v[218:221], v192 offset:7168
	global_load_lds_dwordx4 v[186:187], off
	s_add_i32 m0, s87, 0xe000
	v_lshl_add_u64 v[186:187], s[76:77], 0, v[182:183]
	global_load_lds_dwordx4 v[186:187], off
	s_setprio 1
	s_waitcnt vmcnt(8) lgkmcnt(0)
	s_barrier
	v_mfma_f32_16x16x32_bf16 v[142:145], v[114:117], v[162:165], 0
	v_mfma_f32_16x16x32_bf16 v[138:141], v[122:125], v[162:165], 0
	v_mfma_f32_16x16x32_bf16 v[110:113], v[114:117], v[194:197], 0
	v_mfma_f32_16x16x32_bf16 v[106:109], v[122:125], v[194:197], 0
	v_mfma_f32_16x16x32_bf16 v[98:101], v[114:117], v[206:209], 0
	v_mfma_f32_16x16x32_bf16 v[90:93], v[122:125], v[206:209], 0
	v_mfma_f32_16x16x32_bf16 v[82:85], v[114:117], v[214:217], 0
	v_mfma_f32_16x16x32_bf16 v[74:77], v[122:125], v[214:217], 0
	v_mfma_f32_16x16x32_bf16 v[142:145], v[118:121], v[166:169], v[142:145]
	v_mfma_f32_16x16x32_bf16 v[138:141], v[126:129], v[166:169], v[138:141]
	v_mfma_f32_16x16x32_bf16 v[110:113], v[118:121], v[198:201], v[110:113]
	v_mfma_f32_16x16x32_bf16 v[106:109], v[126:129], v[198:201], v[106:109]
	v_mfma_f32_16x16x32_bf16 v[98:101], v[118:121], v[210:213], v[98:101]
	v_mfma_f32_16x16x32_bf16 v[90:93], v[126:129], v[210:213], v[90:93]
	v_mfma_f32_16x16x32_bf16 v[82:85], v[118:121], v[218:221], v[82:85]
	v_mfma_f32_16x16x32_bf16 v[74:77], v[126:129], v[218:221], v[74:77]
	v_mfma_f32_16x16x32_bf16 v[134:137], v[146:149], v[162:165], 0
	v_mfma_f32_16x16x32_bf16 v[130:133], v[154:157], v[162:165], 0
	v_mfma_f32_16x16x32_bf16 v[102:105], v[146:149], v[194:197], 0
	v_mfma_f32_16x16x32_bf16 v[94:97], v[154:157], v[194:197], 0
	v_mfma_f32_16x16x32_bf16 v[86:89], v[146:149], v[206:209], 0
	v_mfma_f32_16x16x32_bf16 v[78:81], v[154:157], v[206:209], 0
	v_mfma_f32_16x16x32_bf16 v[70:73], v[146:149], v[214:217], 0
	v_mfma_f32_16x16x32_bf16 v[66:69], v[154:157], v[214:217], 0
	v_mfma_f32_16x16x32_bf16 v[134:137], v[150:153], v[166:169], v[134:137]
	v_mfma_f32_16x16x32_bf16 v[130:133], v[158:161], v[166:169], v[130:133]
	v_mfma_f32_16x16x32_bf16 v[102:105], v[150:153], v[198:201], v[102:105]
	v_mfma_f32_16x16x32_bf16 v[94:97], v[158:161], v[198:201], v[94:97]
	v_mfma_f32_16x16x32_bf16 v[86:89], v[150:153], v[210:213], v[86:89]
	v_mfma_f32_16x16x32_bf16 v[78:81], v[158:161], v[210:213], v[78:81]
	v_mfma_f32_16x16x32_bf16 v[70:73], v[150:153], v[218:221], v[70:73]
	v_mfma_f32_16x16x32_bf16 v[66:69], v[158:161], v[218:221], v[66:69]
	s_setprio 0
	s_barrier
	s_add_i32 s63, s24, s86
	v_lshl_add_u64 v[186:187], s[78:79], 0, v[172:173]
	s_mov_b32 m0, s63
	ds_read_b128 v[162:165], v192 offset:16384
	ds_read_b128 v[166:169], v192 offset:17408
	ds_read_b128 v[194:197], v192 offset:18432
	ds_read_b128 v[198:201], v192 offset:19456
	ds_read_b128 v[206:209], v192 offset:20480
	ds_read_b128 v[210:213], v192 offset:21504
	ds_read_b128 v[214:217], v192 offset:22528
	ds_read_b128 v[218:221], v192 offset:23552
	global_load_lds_dwordx4 v[186:187], off
	s_add_i32 m0, s63, 0x2000
	s_add_u32 vcc_lo, s78, 0x100000
	v_lshl_add_u64 v[202:203], s[78:79], 0, v[176:177]
	s_addc_u32 vcc_hi, s79, 0
	s_add_i32 s63, s25, s86
	global_load_lds_dwordx4 v[202:203], off
	v_lshl_add_u64 v[222:223], vcc, 0, v[172:173]
	s_mov_b32 m0, s63
	v_lshl_add_u64 v[224:225], s[80:81], 0, v[174:175]
	global_load_lds_dwordx4 v[222:223], off
	s_add_i32 m0, s63, 0x2000
	v_lshl_add_u64 v[222:223], vcc, 0, v[176:177]
	global_load_lds_dwordx4 v[222:223], off
	s_mov_b32 m0, s87
	v_lshl_add_u64 v[222:223], s[80:81], 0, v[170:171]
	global_load_lds_dwordx4 v[222:223], off
	s_mov_b32 m0, s88
	s_nop 0
	global_load_lds_dwordx4 v[224:225], off
	s_setprio 1
	s_waitcnt vmcnt(8) lgkmcnt(0)
	s_barrier
	v_mfma_f32_16x16x32_bf16 v[62:65], v[114:117], v[162:165], 0
	v_mfma_f32_16x16x32_bf16 v[58:61], v[122:125], v[162:165], 0
	v_mfma_f32_16x16x32_bf16 v[50:53], v[114:117], v[194:197], 0
	v_mfma_f32_16x16x32_bf16 v[42:45], v[122:125], v[194:197], 0
	v_mfma_f32_16x16x32_bf16 v[34:37], v[114:117], v[206:209], 0
	v_mfma_f32_16x16x32_bf16 v[26:29], v[122:125], v[206:209], 0
	v_mfma_f32_16x16x32_bf16 v[18:21], v[114:117], v[214:217], 0
	v_mfma_f32_16x16x32_bf16 v[10:13], v[122:125], v[214:217], 0
	v_mfma_f32_16x16x32_bf16 v[62:65], v[118:121], v[166:169], v[62:65]
	v_mfma_f32_16x16x32_bf16 v[58:61], v[126:129], v[166:169], v[58:61]
	v_mfma_f32_16x16x32_bf16 v[50:53], v[118:121], v[198:201], v[50:53]
	v_mfma_f32_16x16x32_bf16 v[42:45], v[126:129], v[198:201], v[42:45]
	v_mfma_f32_16x16x32_bf16 v[34:37], v[118:121], v[210:213], v[34:37]
	v_mfma_f32_16x16x32_bf16 v[26:29], v[126:129], v[210:213], v[26:29]
	v_mfma_f32_16x16x32_bf16 v[18:21], v[118:121], v[218:221], v[18:21]
	v_mfma_f32_16x16x32_bf16 v[10:13], v[126:129], v[218:221], v[10:13]
	v_mfma_f32_16x16x32_bf16 v[54:57], v[146:149], v[162:165], 0
	v_mfma_f32_16x16x32_bf16 v[46:49], v[154:157], v[162:165], 0
	v_mfma_f32_16x16x32_bf16 v[38:41], v[146:149], v[194:197], 0
	v_mfma_f32_16x16x32_bf16 v[30:33], v[154:157], v[194:197], 0
	v_mfma_f32_16x16x32_bf16 v[22:25], v[146:149], v[206:209], 0
	v_mfma_f32_16x16x32_bf16 v[14:17], v[154:157], v[206:209], 0
	v_mfma_f32_16x16x32_bf16 v[6:9], v[146:149], v[214:217], 0
	v_mfma_f32_16x16x32_bf16 v[2:5], v[154:157], v[214:217], 0
	v_mfma_f32_16x16x32_bf16 v[54:57], v[150:153], v[166:169], v[54:57]
	v_mfma_f32_16x16x32_bf16 v[46:49], v[158:161], v[166:169], v[46:49]
	v_mfma_f32_16x16x32_bf16 v[38:41], v[150:153], v[198:201], v[38:41]
	v_mfma_f32_16x16x32_bf16 v[30:33], v[158:161], v[198:201], v[30:33]
	v_mfma_f32_16x16x32_bf16 v[22:25], v[150:153], v[210:213], v[22:25]
	v_mfma_f32_16x16x32_bf16 v[14:17], v[158:161], v[210:213], v[14:17]
	v_mfma_f32_16x16x32_bf16 v[6:9], v[150:153], v[218:221], v[6:9]
	v_mfma_f32_16x16x32_bf16 v[2:5], v[158:161], v[218:221], v[2:5]
	s_setprio 0
	s_barrier
	s_add_i32 s63, 0, 0x18000
	s_add_i32 s83, 0, 0x1c000
	v_add_u32_e32 v126, s63, v189
	v_add_u32_e32 v158, s83, v189
	ds_read_b128 v[114:117], v126
	ds_read_b128 v[118:121], v126 offset:1024
	ds_read_b128 v[122:125], v126 offset:2048
	ds_read_b128 v[126:129], v126 offset:3072
	ds_read_b128 v[146:149], v158
	ds_read_b128 v[150:153], v158 offset:1024
	ds_read_b128 v[154:157], v158 offset:2048
	ds_read_b128 v[158:161], v158 offset:3072
	s_add_u32 s80, s80, 0x100000
	s_addc_u32 s81, s81, 0
	s_mov_b32 m0, s89
	v_lshl_add_u64 v[226:227], s[80:81], 0, v[170:171]
	ds_read_b128 v[162:165], v192 offset:32768
	ds_read_b128 v[166:169], v192 offset:33792
	ds_read_b128 v[194:197], v192 offset:34816
	ds_read_b128 v[198:201], v192 offset:35840
	ds_read_b128 v[206:209], v192 offset:36864
	ds_read_b128 v[210:213], v192 offset:37888
	ds_read_b128 v[214:217], v192 offset:38912
	ds_read_b128 v[218:221], v192 offset:39936
	global_load_lds_dwordx4 v[226:227], off
	s_mov_b32 m0, s90
	v_lshl_add_u64 v[226:227], s[80:81], 0, v[174:175]
	global_load_lds_dwordx4 v[226:227], off
	s_setprio 1
	s_waitcnt vmcnt(8) lgkmcnt(0)
	s_barrier
	v_mfma_f32_16x16x32_bf16 v[142:145], v[114:117], v[162:165], v[142:145]
	v_mfma_f32_16x16x32_bf16 v[138:141], v[122:125], v[162:165], v[138:141]
	v_mfma_f32_16x16x32_bf16 v[110:113], v[114:117], v[194:197], v[110:113]
	v_mfma_f32_16x16x32_bf16 v[106:109], v[122:125], v[194:197], v[106:109]
	v_mfma_f32_16x16x32_bf16 v[98:101], v[114:117], v[206:209], v[98:101]
	v_mfma_f32_16x16x32_bf16 v[90:93], v[122:125], v[206:209], v[90:93]
	v_mfma_f32_16x16x32_bf16 v[82:85], v[114:117], v[214:217], v[82:85]
	v_mfma_f32_16x16x32_bf16 v[74:77], v[122:125], v[214:217], v[74:77]
	v_mfma_f32_16x16x32_bf16 v[142:145], v[118:121], v[166:169], v[142:145]
	v_mfma_f32_16x16x32_bf16 v[138:141], v[126:129], v[166:169], v[138:141]
	v_mfma_f32_16x16x32_bf16 v[110:113], v[118:121], v[198:201], v[110:113]
	v_mfma_f32_16x16x32_bf16 v[106:109], v[126:129], v[198:201], v[106:109]
	v_mfma_f32_16x16x32_bf16 v[98:101], v[118:121], v[210:213], v[98:101]
	v_mfma_f32_16x16x32_bf16 v[90:93], v[126:129], v[210:213], v[90:93]
	v_mfma_f32_16x16x32_bf16 v[82:85], v[118:121], v[218:221], v[82:85]
	v_mfma_f32_16x16x32_bf16 v[74:77], v[126:129], v[218:221], v[74:77]
	v_mfma_f32_16x16x32_bf16 v[134:137], v[146:149], v[162:165], v[134:137]
	v_mfma_f32_16x16x32_bf16 v[130:133], v[154:157], v[162:165], v[130:133]
	v_mfma_f32_16x16x32_bf16 v[102:105], v[146:149], v[194:197], v[102:105]
	v_mfma_f32_16x16x32_bf16 v[94:97], v[154:157], v[194:197], v[94:97]
	v_mfma_f32_16x16x32_bf16 v[86:89], v[146:149], v[206:209], v[86:89]
	v_mfma_f32_16x16x32_bf16 v[78:81], v[154:157], v[206:209], v[78:81]
	v_mfma_f32_16x16x32_bf16 v[70:73], v[146:149], v[214:217], v[70:73]
	v_mfma_f32_16x16x32_bf16 v[66:69], v[154:157], v[214:217], v[66:69]
	v_mfma_f32_16x16x32_bf16 v[134:137], v[150:153], v[166:169], v[134:137]
	v_mfma_f32_16x16x32_bf16 v[130:133], v[158:161], v[166:169], v[130:133]
	v_mfma_f32_16x16x32_bf16 v[102:105], v[150:153], v[198:201], v[102:105]
	v_mfma_f32_16x16x32_bf16 v[94:97], v[158:161], v[198:201], v[94:97]
	v_mfma_f32_16x16x32_bf16 v[86:89], v[150:153], v[210:213], v[86:89]
	v_mfma_f32_16x16x32_bf16 v[78:81], v[158:161], v[210:213], v[78:81]
	v_mfma_f32_16x16x32_bf16 v[70:73], v[150:153], v[218:221], v[70:73]
	v_mfma_f32_16x16x32_bf16 v[66:69], v[158:161], v[218:221], v[66:69]
	s_setprio 0
	s_barrier
	s_add_i32 s63, s63, s86
	v_lshl_add_u64 v[186:187], v[186:187], 0, s[22:23]
	s_mov_b32 m0, s63
	ds_read_b128 v[162:165], v192 offset:49152
	ds_read_b128 v[166:169], v192 offset:50176
	ds_read_b128 v[194:197], v192 offset:51200
	ds_read_b128 v[198:201], v192 offset:52224
	ds_read_b128 v[206:209], v192 offset:53248
	ds_read_b128 v[210:213], v192 offset:54272
	ds_read_b128 v[214:217], v192 offset:55296
	ds_read_b128 v[218:221], v192 offset:56320
	global_load_lds_dwordx4 v[186:187], off
	s_add_i32 m0, s63, 0x2000
	s_add_u32 s78, s78, 0x100080
	v_lshl_add_u64 v[186:187], v[202:203], 0, s[22:23]
	s_addc_u32 s79, s79, 0
	s_add_i32 s63, s83, s86
	global_load_lds_dwordx4 v[186:187], off
	s_mov_b32 m0, s63
	v_lshl_add_u64 v[186:187], s[78:79], 0, v[172:173]
	global_load_lds_dwordx4 v[186:187], off
	s_add_i32 m0, s63, 0x2000
	v_lshl_add_u64 v[186:187], s[78:79], 0, v[176:177]
	global_load_lds_dwordx4 v[186:187], off
	s_mov_b32 m0, s95
	v_lshl_add_u64 v[186:187], v[222:223], 0, s[22:23]
	global_load_lds_dwordx4 v[186:187], off
	s_mov_b32 m0, s96
	v_lshl_add_u64 v[186:187], v[224:225], 0, s[22:23]
	global_load_lds_dwordx4 v[186:187], off
	s_setprio 1
	s_waitcnt vmcnt(8) lgkmcnt(0)
	s_barrier
	v_mfma_f32_16x16x32_bf16 v[62:65], v[114:117], v[162:165], v[62:65]
	v_mfma_f32_16x16x32_bf16 v[58:61], v[122:125], v[162:165], v[58:61]
	v_mfma_f32_16x16x32_bf16 v[50:53], v[114:117], v[194:197], v[50:53]
	v_mfma_f32_16x16x32_bf16 v[42:45], v[122:125], v[194:197], v[42:45]
	v_mfma_f32_16x16x32_bf16 v[34:37], v[114:117], v[206:209], v[34:37]
	v_mfma_f32_16x16x32_bf16 v[26:29], v[122:125], v[206:209], v[26:29]
	v_mfma_f32_16x16x32_bf16 v[18:21], v[114:117], v[214:217], v[18:21]
	v_mfma_f32_16x16x32_bf16 v[10:13], v[122:125], v[214:217], v[10:13]
	v_mfma_f32_16x16x32_bf16 v[62:65], v[118:121], v[166:169], v[62:65]
	v_mfma_f32_16x16x32_bf16 v[58:61], v[126:129], v[166:169], v[58:61]
	v_mfma_f32_16x16x32_bf16 v[50:53], v[118:121], v[198:201], v[50:53]
	v_mfma_f32_16x16x32_bf16 v[42:45], v[126:129], v[198:201], v[42:45]
	v_mfma_f32_16x16x32_bf16 v[34:37], v[118:121], v[210:213], v[34:37]
	v_mfma_f32_16x16x32_bf16 v[26:29], v[126:129], v[210:213], v[26:29]
	v_mfma_f32_16x16x32_bf16 v[18:21], v[118:121], v[218:221], v[18:21]
	v_mfma_f32_16x16x32_bf16 v[10:13], v[126:129], v[218:221], v[10:13]
	v_mfma_f32_16x16x32_bf16 v[54:57], v[146:149], v[162:165], v[54:57]
	v_mfma_f32_16x16x32_bf16 v[46:49], v[154:157], v[162:165], v[46:49]
	v_mfma_f32_16x16x32_bf16 v[38:41], v[146:149], v[194:197], v[38:41]
	v_mfma_f32_16x16x32_bf16 v[30:33], v[154:157], v[194:197], v[30:33]
	v_mfma_f32_16x16x32_bf16 v[22:25], v[146:149], v[206:209], v[22:25]
	v_mfma_f32_16x16x32_bf16 v[14:17], v[154:157], v[206:209], v[14:17]
	v_mfma_f32_16x16x32_bf16 v[6:9], v[146:149], v[214:217], v[6:9]
	v_mfma_f32_16x16x32_bf16 v[2:5], v[154:157], v[214:217], v[2:5]
	v_mfma_f32_16x16x32_bf16 v[54:57], v[150:153], v[166:169], v[54:57]
	v_mfma_f32_16x16x32_bf16 v[46:49], v[158:161], v[166:169], v[46:49]
	v_mfma_f32_16x16x32_bf16 v[38:41], v[150:153], v[198:201], v[38:41]
	v_mfma_f32_16x16x32_bf16 v[30:33], v[158:161], v[198:201], v[30:33]
	v_mfma_f32_16x16x32_bf16 v[22:25], v[150:153], v[210:213], v[22:25]
	v_mfma_f32_16x16x32_bf16 v[14:17], v[158:161], v[210:213], v[14:17]
	v_mfma_f32_16x16x32_bf16 v[6:9], v[150:153], v[218:221], v[6:9]
	v_mfma_f32_16x16x32_bf16 v[2:5], v[158:161], v[218:221], v[2:5]
	s_setprio 0
	s_barrier
	s_add_u32 s76, s76, 0x100
	s_addc_u32 s77, s77, 0
	s_add_u32 s47, s47, 0x100
	s_addc_u32 s62, s62, 0
	s_cmp_ge_i32 s82, s7
	s_mov_b32 s63, s82
.LBB0_834:
	ds_read_b128 v[114:117], v190
	ds_read_b128 v[118:121], v190 offset:1024
	ds_read_b128 v[122:125], v190 offset:2048
	ds_read_b128 v[126:129], v190 offset:3072
	ds_read_b128 v[146:149], v191
	ds_read_b128 v[150:153], v191 offset:1024
	ds_read_b128 v[154:157], v191 offset:2048
	ds_read_b128 v[158:161], v191 offset:3072
	s_add_i32 s82, s63, 2
	s_add_u32 s78, s76, 0xfff00080
	s_addc_u32 s79, s77, -1
	s_cmp_eq_u32 s45, s63
	s_cselect_b32 s81, s15, s79
	s_cselect_b32 s80, s33, s78
	s_cselect_b32 s79, s34, s62
	s_cselect_b32 s78, s39, s47
	v_lshl_add_u64 v[186:187], s[76:77], 0, v[180:181]
	s_add_i32 m0, s87, 0xc000
	ds_read_b128 v[162:165], v192
	ds_read_b128 v[166:169], v192 offset:1024
	ds_read_b128 v[194:197], v192 offset:2048
	ds_read_b128 v[198:201], v192 offset:3072
	ds_read_b128 v[206:209], v192 offset:4096
	ds_read_b128 v[210:213], v192 offset:5120
	ds_read_b128 v[214:217], v192 offset:6144
	ds_read_b128 v[218:221], v192 offset:7168
	global_load_lds_dwordx4 v[186:187], off
	s_add_i32 m0, s87, 0xe000
	v_lshl_add_u64 v[186:187], s[76:77], 0, v[182:183]
	global_load_lds_dwordx4 v[186:187], off
	s_setprio 1
	s_waitcnt vmcnt(8) lgkmcnt(0)
	s_barrier
	v_mfma_f32_16x16x32_bf16 v[142:145], v[114:117], v[162:165], v[142:145]
	v_mfma_f32_16x16x32_bf16 v[138:141], v[122:125], v[162:165], v[138:141]
	v_mfma_f32_16x16x32_bf16 v[110:113], v[114:117], v[194:197], v[110:113]
	v_mfma_f32_16x16x32_bf16 v[106:109], v[122:125], v[194:197], v[106:109]
	v_mfma_f32_16x16x32_bf16 v[98:101], v[114:117], v[206:209], v[98:101]
	v_mfma_f32_16x16x32_bf16 v[90:93], v[122:125], v[206:209], v[90:93]
	v_mfma_f32_16x16x32_bf16 v[82:85], v[114:117], v[214:217], v[82:85]
	v_mfma_f32_16x16x32_bf16 v[74:77], v[122:125], v[214:217], v[74:77]
	v_mfma_f32_16x16x32_bf16 v[142:145], v[118:121], v[166:169], v[142:145]
	v_mfma_f32_16x16x32_bf16 v[138:141], v[126:129], v[166:169], v[138:141]
	v_mfma_f32_16x16x32_bf16 v[110:113], v[118:121], v[198:201], v[110:113]
	v_mfma_f32_16x16x32_bf16 v[106:109], v[126:129], v[198:201], v[106:109]
	v_mfma_f32_16x16x32_bf16 v[98:101], v[118:121], v[210:213], v[98:101]
	v_mfma_f32_16x16x32_bf16 v[90:93], v[126:129], v[210:213], v[90:93]
	v_mfma_f32_16x16x32_bf16 v[82:85], v[118:121], v[218:221], v[82:85]
	v_mfma_f32_16x16x32_bf16 v[74:77], v[126:129], v[218:221], v[74:77]
	v_mfma_f32_16x16x32_bf16 v[134:137], v[146:149], v[162:165], v[134:137]
	v_mfma_f32_16x16x32_bf16 v[130:133], v[154:157], v[162:165], v[130:133]
	v_mfma_f32_16x16x32_bf16 v[102:105], v[146:149], v[194:197], v[102:105]
	v_mfma_f32_16x16x32_bf16 v[94:97], v[154:157], v[194:197], v[94:97]
	v_mfma_f32_16x16x32_bf16 v[86:89], v[146:149], v[206:209], v[86:89]
	v_mfma_f32_16x16x32_bf16 v[78:81], v[154:157], v[206:209], v[78:81]
	v_mfma_f32_16x16x32_bf16 v[70:73], v[146:149], v[214:217], v[70:73]
	v_mfma_f32_16x16x32_bf16 v[66:69], v[154:157], v[214:217], v[66:69]
	v_mfma_f32_16x16x32_bf16 v[134:137], v[150:153], v[166:169], v[134:137]
	v_mfma_f32_16x16x32_bf16 v[130:133], v[158:161], v[166:169], v[130:133]
	v_mfma_f32_16x16x32_bf16 v[102:105], v[150:153], v[198:201], v[102:105]
	v_mfma_f32_16x16x32_bf16 v[94:97], v[158:161], v[198:201], v[94:97]
	v_mfma_f32_16x16x32_bf16 v[86:89], v[150:153], v[210:213], v[86:89]
	v_mfma_f32_16x16x32_bf16 v[78:81], v[158:161], v[210:213], v[78:81]
	v_mfma_f32_16x16x32_bf16 v[70:73], v[150:153], v[218:221], v[70:73]
	v_mfma_f32_16x16x32_bf16 v[66:69], v[158:161], v[218:221], v[66:69]
	s_setprio 0
	s_barrier
	s_add_i32 s63, s24, s86
	v_lshl_add_u64 v[186:187], s[78:79], 0, v[172:173]
	s_mov_b32 m0, s63
	ds_read_b128 v[162:165], v192 offset:16384
	ds_read_b128 v[166:169], v192 offset:17408
	ds_read_b128 v[194:197], v192 offset:18432
	ds_read_b128 v[198:201], v192 offset:19456
	ds_read_b128 v[206:209], v192 offset:20480
	ds_read_b128 v[210:213], v192 offset:21504
	ds_read_b128 v[214:217], v192 offset:22528
	ds_read_b128 v[218:221], v192 offset:23552
	global_load_lds_dwordx4 v[186:187], off
	s_add_i32 m0, s63, 0x2000
	s_add_u32 vcc_lo, s78, 0x100000
	v_lshl_add_u64 v[202:203], s[78:79], 0, v[176:177]
	s_addc_u32 vcc_hi, s79, 0
	s_add_i32 s63, s25, s86
	global_load_lds_dwordx4 v[202:203], off
	v_lshl_add_u64 v[222:223], vcc, 0, v[172:173]
	s_mov_b32 m0, s63
	v_lshl_add_u64 v[224:225], s[80:81], 0, v[174:175]
	global_load_lds_dwordx4 v[222:223], off
	s_add_i32 m0, s63, 0x2000
	v_lshl_add_u64 v[222:223], vcc, 0, v[176:177]
	global_load_lds_dwordx4 v[222:223], off
	s_mov_b32 m0, s87
	v_lshl_add_u64 v[222:223], s[80:81], 0, v[170:171]
	global_load_lds_dwordx4 v[222:223], off
	s_mov_b32 m0, s88
	s_nop 0
	global_load_lds_dwordx4 v[224:225], off
	s_setprio 1
	s_waitcnt vmcnt(8) lgkmcnt(0)
	s_barrier
	v_mfma_f32_16x16x32_bf16 v[62:65], v[114:117], v[162:165], v[62:65]
	v_mfma_f32_16x16x32_bf16 v[58:61], v[122:125], v[162:165], v[58:61]
	v_mfma_f32_16x16x32_bf16 v[50:53], v[114:117], v[194:197], v[50:53]
	v_mfma_f32_16x16x32_bf16 v[42:45], v[122:125], v[194:197], v[42:45]
	v_mfma_f32_16x16x32_bf16 v[34:37], v[114:117], v[206:209], v[34:37]
	v_mfma_f32_16x16x32_bf16 v[26:29], v[122:125], v[206:209], v[26:29]
	v_mfma_f32_16x16x32_bf16 v[18:21], v[114:117], v[214:217], v[18:21]
	v_mfma_f32_16x16x32_bf16 v[10:13], v[122:125], v[214:217], v[10:13]
	v_mfma_f32_16x16x32_bf16 v[62:65], v[118:121], v[166:169], v[62:65]
	v_mfma_f32_16x16x32_bf16 v[58:61], v[126:129], v[166:169], v[58:61]
	v_mfma_f32_16x16x32_bf16 v[50:53], v[118:121], v[198:201], v[50:53]
	v_mfma_f32_16x16x32_bf16 v[42:45], v[126:129], v[198:201], v[42:45]
	v_mfma_f32_16x16x32_bf16 v[34:37], v[118:121], v[210:213], v[34:37]
	v_mfma_f32_16x16x32_bf16 v[26:29], v[126:129], v[210:213], v[26:29]
	v_mfma_f32_16x16x32_bf16 v[18:21], v[118:121], v[218:221], v[18:21]
	v_mfma_f32_16x16x32_bf16 v[10:13], v[126:129], v[218:221], v[10:13]
	v_mfma_f32_16x16x32_bf16 v[54:57], v[146:149], v[162:165], v[54:57]
	v_mfma_f32_16x16x32_bf16 v[46:49], v[154:157], v[162:165], v[46:49]
	v_mfma_f32_16x16x32_bf16 v[38:41], v[146:149], v[194:197], v[38:41]
	v_mfma_f32_16x16x32_bf16 v[30:33], v[154:157], v[194:197], v[30:33]
	v_mfma_f32_16x16x32_bf16 v[22:25], v[146:149], v[206:209], v[22:25]
	v_mfma_f32_16x16x32_bf16 v[14:17], v[154:157], v[206:209], v[14:17]
	v_mfma_f32_16x16x32_bf16 v[6:9], v[146:149], v[214:217], v[6:9]
	v_mfma_f32_16x16x32_bf16 v[2:5], v[154:157], v[214:217], v[2:5]
	v_mfma_f32_16x16x32_bf16 v[54:57], v[150:153], v[166:169], v[54:57]
	v_mfma_f32_16x16x32_bf16 v[46:49], v[158:161], v[166:169], v[46:49]
	v_mfma_f32_16x16x32_bf16 v[38:41], v[150:153], v[198:201], v[38:41]
	v_mfma_f32_16x16x32_bf16 v[30:33], v[158:161], v[198:201], v[30:33]
	v_mfma_f32_16x16x32_bf16 v[22:25], v[150:153], v[210:213], v[22:25]
	v_mfma_f32_16x16x32_bf16 v[14:17], v[158:161], v[210:213], v[14:17]
	v_mfma_f32_16x16x32_bf16 v[6:9], v[150:153], v[218:221], v[6:9]
	v_mfma_f32_16x16x32_bf16 v[2:5], v[158:161], v[218:221], v[2:5]
	s_setprio 0
	s_barrier
	s_add_i32 s63, 0, 0x18000
	s_add_i32 s83, 0, 0x1c000
	v_add_u32_e32 v126, s63, v189
	v_add_u32_e32 v158, s83, v189
	ds_read_b128 v[114:117], v126
	ds_read_b128 v[118:121], v126 offset:1024
	ds_read_b128 v[122:125], v126 offset:2048
	ds_read_b128 v[126:129], v126 offset:3072
	ds_read_b128 v[146:149], v158
	ds_read_b128 v[150:153], v158 offset:1024
	ds_read_b128 v[154:157], v158 offset:2048
	ds_read_b128 v[158:161], v158 offset:3072
	s_add_u32 s80, s80, 0x100000
	s_addc_u32 s81, s81, 0
	s_mov_b32 m0, s89
	v_lshl_add_u64 v[226:227], s[80:81], 0, v[170:171]
	ds_read_b128 v[162:165], v192 offset:32768
	ds_read_b128 v[166:169], v192 offset:33792
	ds_read_b128 v[194:197], v192 offset:34816
	ds_read_b128 v[198:201], v192 offset:35840
	ds_read_b128 v[206:209], v192 offset:36864
	ds_read_b128 v[210:213], v192 offset:37888
	ds_read_b128 v[214:217], v192 offset:38912
	ds_read_b128 v[218:221], v192 offset:39936
	global_load_lds_dwordx4 v[226:227], off
	s_mov_b32 m0, s90
	v_lshl_add_u64 v[226:227], s[80:81], 0, v[174:175]
	global_load_lds_dwordx4 v[226:227], off
	s_setprio 1
	s_waitcnt vmcnt(8) lgkmcnt(0)
	s_barrier
	v_mfma_f32_16x16x32_bf16 v[142:145], v[114:117], v[162:165], v[142:145]
	v_mfma_f32_16x16x32_bf16 v[138:141], v[122:125], v[162:165], v[138:141]
	v_mfma_f32_16x16x32_bf16 v[110:113], v[114:117], v[194:197], v[110:113]
	v_mfma_f32_16x16x32_bf16 v[106:109], v[122:125], v[194:197], v[106:109]
	v_mfma_f32_16x16x32_bf16 v[98:101], v[114:117], v[206:209], v[98:101]
	v_mfma_f32_16x16x32_bf16 v[90:93], v[122:125], v[206:209], v[90:93]
	v_mfma_f32_16x16x32_bf16 v[82:85], v[114:117], v[214:217], v[82:85]
	v_mfma_f32_16x16x32_bf16 v[74:77], v[122:125], v[214:217], v[74:77]
	v_mfma_f32_16x16x32_bf16 v[142:145], v[118:121], v[166:169], v[142:145]
	v_mfma_f32_16x16x32_bf16 v[138:141], v[126:129], v[166:169], v[138:141]
	v_mfma_f32_16x16x32_bf16 v[110:113], v[118:121], v[198:201], v[110:113]
	v_mfma_f32_16x16x32_bf16 v[106:109], v[126:129], v[198:201], v[106:109]
	v_mfma_f32_16x16x32_bf16 v[98:101], v[118:121], v[210:213], v[98:101]
	v_mfma_f32_16x16x32_bf16 v[90:93], v[126:129], v[210:213], v[90:93]
	v_mfma_f32_16x16x32_bf16 v[82:85], v[118:121], v[218:221], v[82:85]
	v_mfma_f32_16x16x32_bf16 v[74:77], v[126:129], v[218:221], v[74:77]
	v_mfma_f32_16x16x32_bf16 v[134:137], v[146:149], v[162:165], v[134:137]
	v_mfma_f32_16x16x32_bf16 v[130:133], v[154:157], v[162:165], v[130:133]
	v_mfma_f32_16x16x32_bf16 v[102:105], v[146:149], v[194:197], v[102:105]
	v_mfma_f32_16x16x32_bf16 v[94:97], v[154:157], v[194:197], v[94:97]
	v_mfma_f32_16x16x32_bf16 v[86:89], v[146:149], v[206:209], v[86:89]
	v_mfma_f32_16x16x32_bf16 v[78:81], v[154:157], v[206:209], v[78:81]
	v_mfma_f32_16x16x32_bf16 v[70:73], v[146:149], v[214:217], v[70:73]
	v_mfma_f32_16x16x32_bf16 v[66:69], v[154:157], v[214:217], v[66:69]
	v_mfma_f32_16x16x32_bf16 v[134:137], v[150:153], v[166:169], v[134:137]
	v_mfma_f32_16x16x32_bf16 v[130:133], v[158:161], v[166:169], v[130:133]
	v_mfma_f32_16x16x32_bf16 v[102:105], v[150:153], v[198:201], v[102:105]
	v_mfma_f32_16x16x32_bf16 v[94:97], v[158:161], v[198:201], v[94:97]
	v_mfma_f32_16x16x32_bf16 v[86:89], v[150:153], v[210:213], v[86:89]
	v_mfma_f32_16x16x32_bf16 v[78:81], v[158:161], v[210:213], v[78:81]
	v_mfma_f32_16x16x32_bf16 v[70:73], v[150:153], v[218:221], v[70:73]
	v_mfma_f32_16x16x32_bf16 v[66:69], v[158:161], v[218:221], v[66:69]
	s_setprio 0
	s_barrier
	s_add_i32 s63, s63, s86
	v_lshl_add_u64 v[186:187], v[186:187], 0, s[22:23]
	s_mov_b32 m0, s63
	ds_read_b128 v[162:165], v192 offset:49152
	ds_read_b128 v[166:169], v192 offset:50176
	ds_read_b128 v[194:197], v192 offset:51200
	ds_read_b128 v[198:201], v192 offset:52224
	ds_read_b128 v[206:209], v192 offset:53248
	ds_read_b128 v[210:213], v192 offset:54272
	ds_read_b128 v[214:217], v192 offset:55296
	ds_read_b128 v[218:221], v192 offset:56320
	global_load_lds_dwordx4 v[186:187], off
	s_add_i32 m0, s63, 0x2000
	s_add_u32 s78, s78, 0x100080
	v_lshl_add_u64 v[186:187], v[202:203], 0, s[22:23]
	s_addc_u32 s79, s79, 0
	s_add_i32 s63, s83, s86
	global_load_lds_dwordx4 v[186:187], off
	s_mov_b32 m0, s63
	v_lshl_add_u64 v[186:187], s[78:79], 0, v[172:173]
	global_load_lds_dwordx4 v[186:187], off
	s_add_i32 m0, s63, 0x2000
	v_lshl_add_u64 v[186:187], s[78:79], 0, v[176:177]
	global_load_lds_dwordx4 v[186:187], off
	s_mov_b32 m0, s95
	v_lshl_add_u64 v[186:187], v[222:223], 0, s[22:23]
	global_load_lds_dwordx4 v[186:187], off
	s_mov_b32 m0, s96
	v_lshl_add_u64 v[186:187], v[224:225], 0, s[22:23]
	global_load_lds_dwordx4 v[186:187], off
	s_setprio 1
	s_waitcnt vmcnt(8) lgkmcnt(0)
	s_barrier
	v_mfma_f32_16x16x32_bf16 v[62:65], v[114:117], v[162:165], v[62:65]
	v_mfma_f32_16x16x32_bf16 v[58:61], v[122:125], v[162:165], v[58:61]
	v_mfma_f32_16x16x32_bf16 v[50:53], v[114:117], v[194:197], v[50:53]
	v_mfma_f32_16x16x32_bf16 v[42:45], v[122:125], v[194:197], v[42:45]
	v_mfma_f32_16x16x32_bf16 v[34:37], v[114:117], v[206:209], v[34:37]
	v_mfma_f32_16x16x32_bf16 v[26:29], v[122:125], v[206:209], v[26:29]
	v_mfma_f32_16x16x32_bf16 v[18:21], v[114:117], v[214:217], v[18:21]
	v_mfma_f32_16x16x32_bf16 v[10:13], v[122:125], v[214:217], v[10:13]
	v_mfma_f32_16x16x32_bf16 v[62:65], v[118:121], v[166:169], v[62:65]
	v_mfma_f32_16x16x32_bf16 v[58:61], v[126:129], v[166:169], v[58:61]
	v_mfma_f32_16x16x32_bf16 v[50:53], v[118:121], v[198:201], v[50:53]
	v_mfma_f32_16x16x32_bf16 v[42:45], v[126:129], v[198:201], v[42:45]
	v_mfma_f32_16x16x32_bf16 v[34:37], v[118:121], v[210:213], v[34:37]
	v_mfma_f32_16x16x32_bf16 v[26:29], v[126:129], v[210:213], v[26:29]
	v_mfma_f32_16x16x32_bf16 v[18:21], v[118:121], v[218:221], v[18:21]
	v_mfma_f32_16x16x32_bf16 v[10:13], v[126:129], v[218:221], v[10:13]
	v_mfma_f32_16x16x32_bf16 v[54:57], v[146:149], v[162:165], v[54:57]
	v_mfma_f32_16x16x32_bf16 v[46:49], v[154:157], v[162:165], v[46:49]
	v_mfma_f32_16x16x32_bf16 v[38:41], v[146:149], v[194:197], v[38:41]
	v_mfma_f32_16x16x32_bf16 v[30:33], v[154:157], v[194:197], v[30:33]
	v_mfma_f32_16x16x32_bf16 v[22:25], v[146:149], v[206:209], v[22:25]
	v_mfma_f32_16x16x32_bf16 v[14:17], v[154:157], v[206:209], v[14:17]
	v_mfma_f32_16x16x32_bf16 v[6:9], v[146:149], v[214:217], v[6:9]
	v_mfma_f32_16x16x32_bf16 v[2:5], v[154:157], v[214:217], v[2:5]
	v_mfma_f32_16x16x32_bf16 v[54:57], v[150:153], v[166:169], v[54:57]
	v_mfma_f32_16x16x32_bf16 v[46:49], v[158:161], v[166:169], v[46:49]
	v_mfma_f32_16x16x32_bf16 v[38:41], v[150:153], v[198:201], v[38:41]
	v_mfma_f32_16x16x32_bf16 v[30:33], v[158:161], v[198:201], v[30:33]
	v_mfma_f32_16x16x32_bf16 v[22:25], v[150:153], v[210:213], v[22:25]
	v_mfma_f32_16x16x32_bf16 v[14:17], v[158:161], v[210:213], v[14:17]
	v_mfma_f32_16x16x32_bf16 v[6:9], v[150:153], v[218:221], v[6:9]
	v_mfma_f32_16x16x32_bf16 v[2:5], v[158:161], v[218:221], v[2:5]
	s_setprio 0
	s_barrier
	s_add_u32 s76, s76, 0x100
	s_addc_u32 s77, s77, 0
	s_add_u32 s47, s47, 0x100
	s_addc_u32 s62, s62, 0
	s_cmp_ge_i32 s82, s7
	s_mov_b32 s63, s82
	s_cbranch_scc0 .LBB0_834
	s_and_b64 vcc, exec, s[26:27]
	s_cbranch_vccz .LBB0_837
	s_barrier

.LBB0_1012:
	s_add_u32 s48, s96, s44
	s_addc_u32 s49, s97, s45
	s_and_b64 s[14:15], s[4:5], exec
	s_cselect_b32 s6, s49, s65
	s_cselect_b32 s14, s48, s64
	s_add_u32 s50, s3, s46
	s_addc_u32 s51, s35, s47
	s_and_b64 s[18:19], s[4:5], exec
	s_cselect_b32 s15, s51, s67
	s_cselect_b32 s17, s50, s66
	s_add_u32 s64, s64, 0x40080
	s_addc_u32 s65, s65, 0
	s_add_u32 s18, s66, 0x100
	s_addc_u32 s19, s67, 0
	s_mov_b32 s24, -2
	s_waitcnt vmcnt(0)
	ds_read_b128 v[130:133], v172
	ds_read_b128 v[134:137], v172 offset:1024
	ds_read_b128 v[138:141], v172 offset:2048
	ds_read_b128 v[142:145], v172 offset:3072
	ds_read_b128 v[164:167], v173
	ds_read_b128 v[176:179], v173 offset:1024
	ds_read_b128 v[180:183], v173 offset:2048
	ds_read_b128 v[184:187], v173 offset:3072
	s_add_u32 s25, s64, 0xfffc0080
	s_addc_u32 s28, s65, -1
	s_cmp_eq_u32 s24, 12
	s_cselect_b32 s69, s6, s28
	s_cselect_b32 s68, s14, s25
	s_cselect_b32 s67, s15, s19
	s_cselect_b32 s66, s17, s18
	v_lshl_add_u64 v[168:169], s[64:65], 0, v[156:157]
	s_add_i32 m0, s73, 0xc000
	ds_read_b128 v[188:191], v174
	ds_read_b128 v[192:195], v174 offset:1024
	ds_read_b128 v[196:199], v174 offset:2048
	ds_read_b128 v[200:203], v174 offset:3072
	ds_read_b128 v[206:209], v174 offset:4096
	ds_read_b128 v[210:213], v174 offset:5120
	ds_read_b128 v[214:217], v174 offset:6144
	ds_read_b128 v[218:221], v174 offset:7168
	global_load_lds_dwordx4 v[168:169], off
	s_add_i32 m0, s73, 0xe000
	v_lshl_add_u64 v[168:169], s[64:65], 0, v[158:159]
	global_load_lds_dwordx4 v[168:169], off
	s_setprio 1
	s_waitcnt vmcnt(8) lgkmcnt(0)
	s_barrier
	v_mfma_f32_16x16x32_bf16 v[126:129], v[130:133], v[188:191], 0
	v_mfma_f32_16x16x32_bf16 v[122:125], v[138:141], v[188:191], 0
	v_mfma_f32_16x16x32_bf16 v[110:113], v[130:133], v[196:199], 0
	v_mfma_f32_16x16x32_bf16 v[106:109], v[138:141], v[196:199], 0
	v_mfma_f32_16x16x32_bf16 v[94:97], v[130:133], v[206:209], 0
	v_mfma_f32_16x16x32_bf16 v[90:93], v[138:141], v[206:209], 0
	v_mfma_f32_16x16x32_bf16 v[78:81], v[130:133], v[214:217], 0
	v_mfma_f32_16x16x32_bf16 v[74:77], v[138:141], v[214:217], 0
	v_mfma_f32_16x16x32_bf16 v[126:129], v[134:137], v[192:195], v[126:129]
	v_mfma_f32_16x16x32_bf16 v[122:125], v[142:145], v[192:195], v[122:125]
	v_mfma_f32_16x16x32_bf16 v[110:113], v[134:137], v[200:203], v[110:113]
	v_mfma_f32_16x16x32_bf16 v[106:109], v[142:145], v[200:203], v[106:109]
	v_mfma_f32_16x16x32_bf16 v[94:97], v[134:137], v[210:213], v[94:97]
	v_mfma_f32_16x16x32_bf16 v[90:93], v[142:145], v[210:213], v[90:93]
	v_mfma_f32_16x16x32_bf16 v[78:81], v[134:137], v[218:221], v[78:81]
	v_mfma_f32_16x16x32_bf16 v[74:77], v[142:145], v[218:221], v[74:77]
	v_mfma_f32_16x16x32_bf16 v[118:121], v[164:167], v[188:191], 0
	v_mfma_f32_16x16x32_bf16 v[114:117], v[180:183], v[188:191], 0
	v_mfma_f32_16x16x32_bf16 v[102:105], v[164:167], v[196:199], 0
	v_mfma_f32_16x16x32_bf16 v[98:101], v[180:183], v[196:199], 0
	v_mfma_f32_16x16x32_bf16 v[86:89], v[164:167], v[206:209], 0
	v_mfma_f32_16x16x32_bf16 v[82:85], v[180:183], v[206:209], 0
	v_mfma_f32_16x16x32_bf16 v[70:73], v[164:167], v[214:217], 0
	v_mfma_f32_16x16x32_bf16 v[66:69], v[180:183], v[214:217], 0
	v_mfma_f32_16x16x32_bf16 v[118:121], v[176:179], v[192:195], v[118:121]
	v_mfma_f32_16x16x32_bf16 v[114:117], v[184:187], v[192:195], v[114:117]
	v_mfma_f32_16x16x32_bf16 v[102:105], v[176:179], v[200:203], v[102:105]
	v_mfma_f32_16x16x32_bf16 v[98:101], v[184:187], v[200:203], v[98:101]
	v_mfma_f32_16x16x32_bf16 v[86:89], v[176:179], v[210:213], v[86:89]
	v_mfma_f32_16x16x32_bf16 v[82:85], v[184:187], v[210:213], v[82:85]
	v_mfma_f32_16x16x32_bf16 v[70:73], v[176:179], v[218:221], v[70:73]
	v_mfma_f32_16x16x32_bf16 v[66:69], v[184:187], v[218:221], v[66:69]
	s_setprio 0
	s_barrier
	s_add_i32 s25, s82, s70
	v_lshl_add_u64 v[168:169], s[66:67], 0, v[150:151]
	s_mov_b32 m0, s25
	ds_read_b128 v[188:191], v174 offset:16384
	ds_read_b128 v[192:195], v174 offset:17408
	ds_read_b128 v[196:199], v174 offset:18432
	ds_read_b128 v[200:203], v174 offset:19456
	ds_read_b128 v[206:209], v174 offset:20480
	ds_read_b128 v[210:213], v174 offset:21504
	ds_read_b128 v[214:217], v174 offset:22528
	ds_read_b128 v[218:221], v174 offset:23552
	global_load_lds_dwordx4 v[168:169], off
	s_add_i32 m0, s25, 0x2000
	s_add_u32 s28, s66, 0x40000
	v_lshl_add_u64 v[222:223], s[66:67], 0, v[146:147]
	s_addc_u32 s29, s67, 0
	s_add_i32 s25, s83, s70
	global_load_lds_dwordx4 v[222:223], off
	v_lshl_add_u64 v[224:225], s[28:29], 0, v[150:151]
	s_mov_b32 m0, s25
	v_lshl_add_u64 v[226:227], s[68:69], 0, v[148:149]
	global_load_lds_dwordx4 v[224:225], off
	s_add_i32 m0, s25, 0x2000
	v_lshl_add_u64 v[224:225], s[28:29], 0, v[146:147]
	global_load_lds_dwordx4 v[224:225], off
	s_mov_b32 m0, s73
	v_lshl_add_u64 v[224:225], s[68:69], 0, v[152:153]
	global_load_lds_dwordx4 v[224:225], off
	s_mov_b32 m0, s74
	s_nop 0
	global_load_lds_dwordx4 v[226:227], off
	s_setprio 1
	s_waitcnt vmcnt(8) lgkmcnt(0)
	s_barrier
	v_mfma_f32_16x16x32_bf16 v[62:65], v[130:133], v[188:191], 0
	v_mfma_f32_16x16x32_bf16 v[58:61], v[138:141], v[188:191], 0
	v_mfma_f32_16x16x32_bf16 v[46:49], v[130:133], v[196:199], 0
	v_mfma_f32_16x16x32_bf16 v[42:45], v[138:141], v[196:199], 0
	v_mfma_f32_16x16x32_bf16 v[30:33], v[130:133], v[206:209], 0
	v_mfma_f32_16x16x32_bf16 v[26:29], v[138:141], v[206:209], 0
	v_mfma_f32_16x16x32_bf16 v[14:17], v[130:133], v[214:217], 0
	v_mfma_f32_16x16x32_bf16 v[10:13], v[138:141], v[214:217], 0
	v_mfma_f32_16x16x32_bf16 v[62:65], v[134:137], v[192:195], v[62:65]
	v_mfma_f32_16x16x32_bf16 v[58:61], v[142:145], v[192:195], v[58:61]
	v_mfma_f32_16x16x32_bf16 v[46:49], v[134:137], v[200:203], v[46:49]
	v_mfma_f32_16x16x32_bf16 v[42:45], v[142:145], v[200:203], v[42:45]
	v_mfma_f32_16x16x32_bf16 v[30:33], v[134:137], v[210:213], v[30:33]
	v_mfma_f32_16x16x32_bf16 v[26:29], v[142:145], v[210:213], v[26:29]
	v_mfma_f32_16x16x32_bf16 v[14:17], v[134:137], v[218:221], v[14:17]
	v_mfma_f32_16x16x32_bf16 v[10:13], v[142:145], v[218:221], v[10:13]
	v_mfma_f32_16x16x32_bf16 v[54:57], v[164:167], v[188:191], 0
	v_mfma_f32_16x16x32_bf16 v[50:53], v[180:183], v[188:191], 0
	v_mfma_f32_16x16x32_bf16 v[38:41], v[164:167], v[196:199], 0
	v_mfma_f32_16x16x32_bf16 v[34:37], v[180:183], v[196:199], 0
	v_mfma_f32_16x16x32_bf16 v[22:25], v[164:167], v[206:209], 0
	v_mfma_f32_16x16x32_bf16 v[18:21], v[180:183], v[206:209], 0
	v_mfma_f32_16x16x32_bf16 v[6:9], v[164:167], v[214:217], 0
	v_mfma_f32_16x16x32_bf16 v[2:5], v[180:183], v[214:217], 0
	v_mfma_f32_16x16x32_bf16 v[54:57], v[176:179], v[192:195], v[54:57]
	v_mfma_f32_16x16x32_bf16 v[50:53], v[184:187], v[192:195], v[50:53]
	v_mfma_f32_16x16x32_bf16 v[38:41], v[176:179], v[200:203], v[38:41]
	v_mfma_f32_16x16x32_bf16 v[34:37], v[184:187], v[200:203], v[34:37]
	v_mfma_f32_16x16x32_bf16 v[22:25], v[176:179], v[210:213], v[22:25]
	v_mfma_f32_16x16x32_bf16 v[18:21], v[184:187], v[210:213], v[18:21]
	v_mfma_f32_16x16x32_bf16 v[6:9], v[176:179], v[218:221], v[6:9]
	v_mfma_f32_16x16x32_bf16 v[2:5], v[184:187], v[218:221], v[2:5]
	s_setprio 0
	s_barrier
	s_add_i32 s25, 0, 0x18000
	s_add_i32 s30, 0, 0x1c000
	v_add_u32_e32 v142, s25, v171
	v_add_u32_e32 v175, s30, v171
	ds_read_b128 v[130:133], v142
	ds_read_b128 v[134:137], v142 offset:1024
	ds_read_b128 v[138:141], v142 offset:2048
	ds_read_b128 v[142:145], v142 offset:3072
	ds_read_b128 v[164:167], v175
	ds_read_b128 v[176:179], v175 offset:1024
	ds_read_b128 v[180:183], v175 offset:2048
	ds_read_b128 v[184:187], v175 offset:3072
	s_add_u32 s28, s68, 0x40000
	s_addc_u32 s29, s69, 0
	s_mov_b32 m0, s75
	v_lshl_add_u64 v[228:229], s[28:29], 0, v[152:153]
	ds_read_b128 v[188:191], v174 offset:32768
	ds_read_b128 v[192:195], v174 offset:33792
	ds_read_b128 v[196:199], v174 offset:34816
	ds_read_b128 v[200:203], v174 offset:35840
	ds_read_b128 v[206:209], v174 offset:36864
	ds_read_b128 v[210:213], v174 offset:37888
	ds_read_b128 v[214:217], v174 offset:38912
	ds_read_b128 v[218:221], v174 offset:39936
	global_load_lds_dwordx4 v[228:229], off
	s_mov_b32 m0, s76
	v_lshl_add_u64 v[228:229], s[28:29], 0, v[148:149]
	global_load_lds_dwordx4 v[228:229], off
	s_setprio 1
	s_waitcnt vmcnt(8) lgkmcnt(0)
	s_barrier
	v_mfma_f32_16x16x32_bf16 v[126:129], v[130:133], v[188:191], v[126:129]
	v_mfma_f32_16x16x32_bf16 v[122:125], v[138:141], v[188:191], v[122:125]
	v_mfma_f32_16x16x32_bf16 v[110:113], v[130:133], v[196:199], v[110:113]
	v_mfma_f32_16x16x32_bf16 v[106:109], v[138:141], v[196:199], v[106:109]
	v_mfma_f32_16x16x32_bf16 v[94:97], v[130:133], v[206:209], v[94:97]
	v_mfma_f32_16x16x32_bf16 v[90:93], v[138:141], v[206:209], v[90:93]
	v_mfma_f32_16x16x32_bf16 v[78:81], v[130:133], v[214:217], v[78:81]
	v_mfma_f32_16x16x32_bf16 v[74:77], v[138:141], v[214:217], v[74:77]
	v_mfma_f32_16x16x32_bf16 v[126:129], v[134:137], v[192:195], v[126:129]
	v_mfma_f32_16x16x32_bf16 v[122:125], v[142:145], v[192:195], v[122:125]
	v_mfma_f32_16x16x32_bf16 v[110:113], v[134:137], v[200:203], v[110:113]
	v_mfma_f32_16x16x32_bf16 v[106:109], v[142:145], v[200:203], v[106:109]
	v_mfma_f32_16x16x32_bf16 v[94:97], v[134:137], v[210:213], v[94:97]
	v_mfma_f32_16x16x32_bf16 v[90:93], v[142:145], v[210:213], v[90:93]
	v_mfma_f32_16x16x32_bf16 v[78:81], v[134:137], v[218:221], v[78:81]
	v_mfma_f32_16x16x32_bf16 v[74:77], v[142:145], v[218:221], v[74:77]
	v_mfma_f32_16x16x32_bf16 v[118:121], v[164:167], v[188:191], v[118:121]
	v_mfma_f32_16x16x32_bf16 v[114:117], v[180:183], v[188:191], v[114:117]
	v_mfma_f32_16x16x32_bf16 v[102:105], v[164:167], v[196:199], v[102:105]
	v_mfma_f32_16x16x32_bf16 v[98:101], v[180:183], v[196:199], v[98:101]
	v_mfma_f32_16x16x32_bf16 v[86:89], v[164:167], v[206:209], v[86:89]
	v_mfma_f32_16x16x32_bf16 v[82:85], v[180:183], v[206:209], v[82:85]
	v_mfma_f32_16x16x32_bf16 v[70:73], v[164:167], v[214:217], v[70:73]
	v_mfma_f32_16x16x32_bf16 v[66:69], v[180:183], v[214:217], v[66:69]
	v_mfma_f32_16x16x32_bf16 v[118:121], v[176:179], v[192:195], v[118:121]
	v_mfma_f32_16x16x32_bf16 v[114:117], v[184:187], v[192:195], v[114:117]
	v_mfma_f32_16x16x32_bf16 v[102:105], v[176:179], v[200:203], v[102:105]
	v_mfma_f32_16x16x32_bf16 v[98:101], v[184:187], v[200:203], v[98:101]
	v_mfma_f32_16x16x32_bf16 v[86:89], v[176:179], v[210:213], v[86:89]
	v_mfma_f32_16x16x32_bf16 v[82:85], v[184:187], v[210:213], v[82:85]
	v_mfma_f32_16x16x32_bf16 v[70:73], v[176:179], v[218:221], v[70:73]
	v_mfma_f32_16x16x32_bf16 v[66:69], v[184:187], v[218:221], v[66:69]
	s_setprio 0
	s_barrier
	s_add_i32 s25, s25, s70
	v_lshl_add_u64 v[168:169], v[168:169], 0, s[36:37]
	s_mov_b32 m0, s25
	ds_read_b128 v[188:191], v174 offset:49152
	ds_read_b128 v[192:195], v174 offset:50176
	ds_read_b128 v[196:199], v174 offset:51200
	ds_read_b128 v[200:203], v174 offset:52224
	ds_read_b128 v[206:209], v174 offset:53248
	ds_read_b128 v[210:213], v174 offset:54272
	ds_read_b128 v[214:217], v174 offset:55296
	ds_read_b128 v[218:221], v174 offset:56320
	global_load_lds_dwordx4 v[168:169], off
	s_add_i32 m0, s25, 0x2000
	s_add_u32 s28, s66, 0x40080
	v_lshl_add_u64 v[168:169], v[222:223], 0, s[36:37]
	s_addc_u32 s29, s67, 0
	s_add_i32 s25, s30, s70
	global_load_lds_dwordx4 v[168:169], off
	s_mov_b32 m0, s25
	v_lshl_add_u64 v[168:169], s[28:29], 0, v[150:151]
	global_load_lds_dwordx4 v[168:169], off
	s_add_i32 m0, s25, 0x2000
	v_lshl_add_u64 v[168:169], s[28:29], 0, v[146:147]
	global_load_lds_dwordx4 v[168:169], off
	s_mov_b32 m0, s79
	v_lshl_add_u64 v[168:169], v[224:225], 0, s[36:37]
	global_load_lds_dwordx4 v[168:169], off
	s_mov_b32 m0, s80
	v_lshl_add_u64 v[168:169], v[226:227], 0, s[36:37]
	global_load_lds_dwordx4 v[168:169], off
	s_setprio 1
	s_waitcnt vmcnt(8) lgkmcnt(0)
	s_barrier
	v_mfma_f32_16x16x32_bf16 v[62:65], v[130:133], v[188:191], v[62:65]
	v_mfma_f32_16x16x32_bf16 v[58:61], v[138:141], v[188:191], v[58:61]
	v_mfma_f32_16x16x32_bf16 v[46:49], v[130:133], v[196:199], v[46:49]
	v_mfma_f32_16x16x32_bf16 v[42:45], v[138:141], v[196:199], v[42:45]
	v_mfma_f32_16x16x32_bf16 v[30:33], v[130:133], v[206:209], v[30:33]
	v_mfma_f32_16x16x32_bf16 v[26:29], v[138:141], v[206:209], v[26:29]
	v_mfma_f32_16x16x32_bf16 v[14:17], v[130:133], v[214:217], v[14:17]
	v_mfma_f32_16x16x32_bf16 v[10:13], v[138:141], v[214:217], v[10:13]
	v_mfma_f32_16x16x32_bf16 v[62:65], v[134:137], v[192:195], v[62:65]
	v_mfma_f32_16x16x32_bf16 v[58:61], v[142:145], v[192:195], v[58:61]
	v_mfma_f32_16x16x32_bf16 v[46:49], v[134:137], v[200:203], v[46:49]
	v_mfma_f32_16x16x32_bf16 v[42:45], v[142:145], v[200:203], v[42:45]
	v_mfma_f32_16x16x32_bf16 v[30:33], v[134:137], v[210:213], v[30:33]
	v_mfma_f32_16x16x32_bf16 v[26:29], v[142:145], v[210:213], v[26:29]
	v_mfma_f32_16x16x32_bf16 v[14:17], v[134:137], v[218:221], v[14:17]
	v_mfma_f32_16x16x32_bf16 v[10:13], v[142:145], v[218:221], v[10:13]
	v_mfma_f32_16x16x32_bf16 v[54:57], v[164:167], v[188:191], v[54:57]
	v_mfma_f32_16x16x32_bf16 v[50:53], v[180:183], v[188:191], v[50:53]
	v_mfma_f32_16x16x32_bf16 v[38:41], v[164:167], v[196:199], v[38:41]
	v_mfma_f32_16x16x32_bf16 v[34:37], v[180:183], v[196:199], v[34:37]
	v_mfma_f32_16x16x32_bf16 v[22:25], v[164:167], v[206:209], v[22:25]
	v_mfma_f32_16x16x32_bf16 v[18:21], v[180:183], v[206:209], v[18:21]
	v_mfma_f32_16x16x32_bf16 v[6:9], v[164:167], v[214:217], v[6:9]
	v_mfma_f32_16x16x32_bf16 v[2:5], v[180:183], v[214:217], v[2:5]
	v_mfma_f32_16x16x32_bf16 v[54:57], v[176:179], v[192:195], v[54:57]
	v_mfma_f32_16x16x32_bf16 v[50:53], v[184:187], v[192:195], v[50:53]
	v_mfma_f32_16x16x32_bf16 v[38:41], v[176:179], v[200:203], v[38:41]
	v_mfma_f32_16x16x32_bf16 v[34:37], v[184:187], v[200:203], v[34:37]
	v_mfma_f32_16x16x32_bf16 v[22:25], v[176:179], v[210:213], v[22:25]
	v_mfma_f32_16x16x32_bf16 v[18:21], v[184:187], v[210:213], v[18:21]
	v_mfma_f32_16x16x32_bf16 v[6:9], v[176:179], v[218:221], v[6:9]
	v_mfma_f32_16x16x32_bf16 v[2:5], v[184:187], v[218:221], v[2:5]
	s_setprio 0
	s_barrier
	s_add_i32 s24, s24, 2
	s_add_u32 s64, s64, 0x100
	s_addc_u32 s65, s65, 0
	s_add_u32 s18, s18, 0x100
	s_addc_u32 s19, s19, 0
	s_cmp_gt_u32 s24, 13
.LBB0_1013:
	ds_read_b128 v[130:133], v172
	ds_read_b128 v[134:137], v172 offset:1024
	ds_read_b128 v[138:141], v172 offset:2048
	ds_read_b128 v[142:145], v172 offset:3072
	ds_read_b128 v[164:167], v173
	ds_read_b128 v[176:179], v173 offset:1024
	ds_read_b128 v[180:183], v173 offset:2048
	ds_read_b128 v[184:187], v173 offset:3072
	s_add_u32 s25, s64, 0xfffc0080
	s_addc_u32 s28, s65, -1
	s_cmp_eq_u32 s24, 12
	s_cselect_b32 s69, s6, s28
	s_cselect_b32 s68, s14, s25
	s_cselect_b32 s67, s15, s19
	s_cselect_b32 s66, s17, s18
	v_lshl_add_u64 v[168:169], s[64:65], 0, v[156:157]
	s_add_i32 m0, s73, 0xc000
	ds_read_b128 v[188:191], v174
	ds_read_b128 v[192:195], v174 offset:1024
	ds_read_b128 v[196:199], v174 offset:2048
	ds_read_b128 v[200:203], v174 offset:3072
	ds_read_b128 v[206:209], v174 offset:4096
	ds_read_b128 v[210:213], v174 offset:5120
	ds_read_b128 v[214:217], v174 offset:6144
	ds_read_b128 v[218:221], v174 offset:7168
	global_load_lds_dwordx4 v[168:169], off
	s_add_i32 m0, s73, 0xe000
	v_lshl_add_u64 v[168:169], s[64:65], 0, v[158:159]
	global_load_lds_dwordx4 v[168:169], off
	s_setprio 1
	s_waitcnt vmcnt(8) lgkmcnt(0)
	s_barrier
	v_mfma_f32_16x16x32_bf16 v[126:129], v[130:133], v[188:191], v[126:129]
	v_mfma_f32_16x16x32_bf16 v[122:125], v[138:141], v[188:191], v[122:125]
	v_mfma_f32_16x16x32_bf16 v[110:113], v[130:133], v[196:199], v[110:113]
	v_mfma_f32_16x16x32_bf16 v[106:109], v[138:141], v[196:199], v[106:109]
	v_mfma_f32_16x16x32_bf16 v[94:97], v[130:133], v[206:209], v[94:97]
	v_mfma_f32_16x16x32_bf16 v[90:93], v[138:141], v[206:209], v[90:93]
	v_mfma_f32_16x16x32_bf16 v[78:81], v[130:133], v[214:217], v[78:81]
	v_mfma_f32_16x16x32_bf16 v[74:77], v[138:141], v[214:217], v[74:77]
	v_mfma_f32_16x16x32_bf16 v[126:129], v[134:137], v[192:195], v[126:129]
	v_mfma_f32_16x16x32_bf16 v[122:125], v[142:145], v[192:195], v[122:125]
	v_mfma_f32_16x16x32_bf16 v[110:113], v[134:137], v[200:203], v[110:113]
	v_mfma_f32_16x16x32_bf16 v[106:109], v[142:145], v[200:203], v[106:109]
	v_mfma_f32_16x16x32_bf16 v[94:97], v[134:137], v[210:213], v[94:97]
	v_mfma_f32_16x16x32_bf16 v[90:93], v[142:145], v[210:213], v[90:93]
	v_mfma_f32_16x16x32_bf16 v[78:81], v[134:137], v[218:221], v[78:81]
	v_mfma_f32_16x16x32_bf16 v[74:77], v[142:145], v[218:221], v[74:77]
	v_mfma_f32_16x16x32_bf16 v[118:121], v[164:167], v[188:191], v[118:121]
	v_mfma_f32_16x16x32_bf16 v[114:117], v[180:183], v[188:191], v[114:117]
	v_mfma_f32_16x16x32_bf16 v[102:105], v[164:167], v[196:199], v[102:105]
	v_mfma_f32_16x16x32_bf16 v[98:101], v[180:183], v[196:199], v[98:101]
	v_mfma_f32_16x16x32_bf16 v[86:89], v[164:167], v[206:209], v[86:89]
	v_mfma_f32_16x16x32_bf16 v[82:85], v[180:183], v[206:209], v[82:85]
	v_mfma_f32_16x16x32_bf16 v[70:73], v[164:167], v[214:217], v[70:73]
	v_mfma_f32_16x16x32_bf16 v[66:69], v[180:183], v[214:217], v[66:69]
	v_mfma_f32_16x16x32_bf16 v[118:121], v[176:179], v[192:195], v[118:121]
	v_mfma_f32_16x16x32_bf16 v[114:117], v[184:187], v[192:195], v[114:117]
	v_mfma_f32_16x16x32_bf16 v[102:105], v[176:179], v[200:203], v[102:105]
	v_mfma_f32_16x16x32_bf16 v[98:101], v[184:187], v[200:203], v[98:101]
	v_mfma_f32_16x16x32_bf16 v[86:89], v[176:179], v[210:213], v[86:89]
	v_mfma_f32_16x16x32_bf16 v[82:85], v[184:187], v[210:213], v[82:85]
	v_mfma_f32_16x16x32_bf16 v[70:73], v[176:179], v[218:221], v[70:73]
	v_mfma_f32_16x16x32_bf16 v[66:69], v[184:187], v[218:221], v[66:69]
	s_setprio 0
	s_barrier
	s_add_i32 s25, s82, s70
	v_lshl_add_u64 v[168:169], s[66:67], 0, v[150:151]
	s_mov_b32 m0, s25
	ds_read_b128 v[188:191], v174 offset:16384
	ds_read_b128 v[192:195], v174 offset:17408
	ds_read_b128 v[196:199], v174 offset:18432
	ds_read_b128 v[200:203], v174 offset:19456
	ds_read_b128 v[206:209], v174 offset:20480
	ds_read_b128 v[210:213], v174 offset:21504
	ds_read_b128 v[214:217], v174 offset:22528
	ds_read_b128 v[218:221], v174 offset:23552
	global_load_lds_dwordx4 v[168:169], off
	s_add_i32 m0, s25, 0x2000
	s_add_u32 s28, s66, 0x40000
	v_lshl_add_u64 v[222:223], s[66:67], 0, v[146:147]
	s_addc_u32 s29, s67, 0
	s_add_i32 s25, s83, s70
	global_load_lds_dwordx4 v[222:223], off
	v_lshl_add_u64 v[224:225], s[28:29], 0, v[150:151]
	s_mov_b32 m0, s25
	v_lshl_add_u64 v[226:227], s[68:69], 0, v[148:149]
	global_load_lds_dwordx4 v[224:225], off
	s_add_i32 m0, s25, 0x2000
	v_lshl_add_u64 v[224:225], s[28:29], 0, v[146:147]
	global_load_lds_dwordx4 v[224:225], off
	s_mov_b32 m0, s73
	v_lshl_add_u64 v[224:225], s[68:69], 0, v[152:153]
	global_load_lds_dwordx4 v[224:225], off
	s_mov_b32 m0, s74
	s_nop 0
	global_load_lds_dwordx4 v[226:227], off
	s_setprio 1
	s_waitcnt vmcnt(8) lgkmcnt(0)
	s_barrier
	v_mfma_f32_16x16x32_bf16 v[62:65], v[130:133], v[188:191], v[62:65]
	v_mfma_f32_16x16x32_bf16 v[58:61], v[138:141], v[188:191], v[58:61]
	v_mfma_f32_16x16x32_bf16 v[46:49], v[130:133], v[196:199], v[46:49]
	v_mfma_f32_16x16x32_bf16 v[42:45], v[138:141], v[196:199], v[42:45]
	v_mfma_f32_16x16x32_bf16 v[30:33], v[130:133], v[206:209], v[30:33]
	v_mfma_f32_16x16x32_bf16 v[26:29], v[138:141], v[206:209], v[26:29]
	v_mfma_f32_16x16x32_bf16 v[14:17], v[130:133], v[214:217], v[14:17]
	v_mfma_f32_16x16x32_bf16 v[10:13], v[138:141], v[214:217], v[10:13]
	v_mfma_f32_16x16x32_bf16 v[62:65], v[134:137], v[192:195], v[62:65]
	v_mfma_f32_16x16x32_bf16 v[58:61], v[142:145], v[192:195], v[58:61]
	v_mfma_f32_16x16x32_bf16 v[46:49], v[134:137], v[200:203], v[46:49]
	v_mfma_f32_16x16x32_bf16 v[42:45], v[142:145], v[200:203], v[42:45]
	v_mfma_f32_16x16x32_bf16 v[30:33], v[134:137], v[210:213], v[30:33]
	v_mfma_f32_16x16x32_bf16 v[26:29], v[142:145], v[210:213], v[26:29]
	v_mfma_f32_16x16x32_bf16 v[14:17], v[134:137], v[218:221], v[14:17]
	v_mfma_f32_16x16x32_bf16 v[10:13], v[142:145], v[218:221], v[10:13]
	v_mfma_f32_16x16x32_bf16 v[54:57], v[164:167], v[188:191], v[54:57]
	v_mfma_f32_16x16x32_bf16 v[50:53], v[180:183], v[188:191], v[50:53]
	v_mfma_f32_16x16x32_bf16 v[38:41], v[164:167], v[196:199], v[38:41]
	v_mfma_f32_16x16x32_bf16 v[34:37], v[180:183], v[196:199], v[34:37]
	v_mfma_f32_16x16x32_bf16 v[22:25], v[164:167], v[206:209], v[22:25]
	v_mfma_f32_16x16x32_bf16 v[18:21], v[180:183], v[206:209], v[18:21]
	v_mfma_f32_16x16x32_bf16 v[6:9], v[164:167], v[214:217], v[6:9]
	v_mfma_f32_16x16x32_bf16 v[2:5], v[180:183], v[214:217], v[2:5]
	v_mfma_f32_16x16x32_bf16 v[54:57], v[176:179], v[192:195], v[54:57]
	v_mfma_f32_16x16x32_bf16 v[50:53], v[184:187], v[192:195], v[50:53]
	v_mfma_f32_16x16x32_bf16 v[38:41], v[176:179], v[200:203], v[38:41]
	v_mfma_f32_16x16x32_bf16 v[34:37], v[184:187], v[200:203], v[34:37]
	v_mfma_f32_16x16x32_bf16 v[22:25], v[176:179], v[210:213], v[22:25]
	v_mfma_f32_16x16x32_bf16 v[18:21], v[184:187], v[210:213], v[18:21]
	v_mfma_f32_16x16x32_bf16 v[6:9], v[176:179], v[218:221], v[6:9]
	v_mfma_f32_16x16x32_bf16 v[2:5], v[184:187], v[218:221], v[2:5]
	s_setprio 0
	s_barrier
	s_add_i32 s25, 0, 0x18000
	s_add_i32 s30, 0, 0x1c000
	v_add_u32_e32 v142, s25, v171
	v_add_u32_e32 v175, s30, v171
	ds_read_b128 v[130:133], v142
	ds_read_b128 v[134:137], v142 offset:1024
	ds_read_b128 v[138:141], v142 offset:2048
	ds_read_b128 v[142:145], v142 offset:3072
	ds_read_b128 v[164:167], v175
	ds_read_b128 v[176:179], v175 offset:1024
	ds_read_b128 v[180:183], v175 offset:2048
	ds_read_b128 v[184:187], v175 offset:3072
	s_add_u32 s28, s68, 0x40000
	s_addc_u32 s29, s69, 0
	s_mov_b32 m0, s75
	v_lshl_add_u64 v[228:229], s[28:29], 0, v[152:153]
	ds_read_b128 v[188:191], v174 offset:32768
	ds_read_b128 v[192:195], v174 offset:33792
	ds_read_b128 v[196:199], v174 offset:34816
	ds_read_b128 v[200:203], v174 offset:35840
	ds_read_b128 v[206:209], v174 offset:36864
	ds_read_b128 v[210:213], v174 offset:37888
	ds_read_b128 v[214:217], v174 offset:38912
	ds_read_b128 v[218:221], v174 offset:39936
	global_load_lds_dwordx4 v[228:229], off
	s_mov_b32 m0, s76
	v_lshl_add_u64 v[228:229], s[28:29], 0, v[148:149]
	global_load_lds_dwordx4 v[228:229], off
	s_setprio 1
	s_waitcnt vmcnt(8) lgkmcnt(0)
	s_barrier
	v_mfma_f32_16x16x32_bf16 v[126:129], v[130:133], v[188:191], v[126:129]
	v_mfma_f32_16x16x32_bf16 v[122:125], v[138:141], v[188:191], v[122:125]
	v_mfma_f32_16x16x32_bf16 v[110:113], v[130:133], v[196:199], v[110:113]
	v_mfma_f32_16x16x32_bf16 v[106:109], v[138:141], v[196:199], v[106:109]
	v_mfma_f32_16x16x32_bf16 v[94:97], v[130:133], v[206:209], v[94:97]
	v_mfma_f32_16x16x32_bf16 v[90:93], v[138:141], v[206:209], v[90:93]
	v_mfma_f32_16x16x32_bf16 v[78:81], v[130:133], v[214:217], v[78:81]
	v_mfma_f32_16x16x32_bf16 v[74:77], v[138:141], v[214:217], v[74:77]
	v_mfma_f32_16x16x32_bf16 v[126:129], v[134:137], v[192:195], v[126:129]
	v_mfma_f32_16x16x32_bf16 v[122:125], v[142:145], v[192:195], v[122:125]
	v_mfma_f32_16x16x32_bf16 v[110:113], v[134:137], v[200:203], v[110:113]
	v_mfma_f32_16x16x32_bf16 v[106:109], v[142:145], v[200:203], v[106:109]
	v_mfma_f32_16x16x32_bf16 v[94:97], v[134:137], v[210:213], v[94:97]
	v_mfma_f32_16x16x32_bf16 v[90:93], v[142:145], v[210:213], v[90:93]
	v_mfma_f32_16x16x32_bf16 v[78:81], v[134:137], v[218:221], v[78:81]
	v_mfma_f32_16x16x32_bf16 v[74:77], v[142:145], v[218:221], v[74:77]
	v_mfma_f32_16x16x32_bf16 v[118:121], v[164:167], v[188:191], v[118:121]
	v_mfma_f32_16x16x32_bf16 v[114:117], v[180:183], v[188:191], v[114:117]
	v_mfma_f32_16x16x32_bf16 v[102:105], v[164:167], v[196:199], v[102:105]
	v_mfma_f32_16x16x32_bf16 v[98:101], v[180:183], v[196:199], v[98:101]
	v_mfma_f32_16x16x32_bf16 v[86:89], v[164:167], v[206:209], v[86:89]
	v_mfma_f32_16x16x32_bf16 v[82:85], v[180:183], v[206:209], v[82:85]
	v_mfma_f32_16x16x32_bf16 v[70:73], v[164:167], v[214:217], v[70:73]
	v_mfma_f32_16x16x32_bf16 v[66:69], v[180:183], v[214:217], v[66:69]
	v_mfma_f32_16x16x32_bf16 v[118:121], v[176:179], v[192:195], v[118:121]
	v_mfma_f32_16x16x32_bf16 v[114:117], v[184:187], v[192:195], v[114:117]
	v_mfma_f32_16x16x32_bf16 v[102:105], v[176:179], v[200:203], v[102:105]
	v_mfma_f32_16x16x32_bf16 v[98:101], v[184:187], v[200:203], v[98:101]
	v_mfma_f32_16x16x32_bf16 v[86:89], v[176:179], v[210:213], v[86:89]
	v_mfma_f32_16x16x32_bf16 v[82:85], v[184:187], v[210:213], v[82:85]
	v_mfma_f32_16x16x32_bf16 v[70:73], v[176:179], v[218:221], v[70:73]
	v_mfma_f32_16x16x32_bf16 v[66:69], v[184:187], v[218:221], v[66:69]
	s_setprio 0
	s_barrier
	s_add_i32 s25, s25, s70
	v_lshl_add_u64 v[168:169], v[168:169], 0, s[36:37]
	s_mov_b32 m0, s25
	ds_read_b128 v[188:191], v174 offset:49152
	ds_read_b128 v[192:195], v174 offset:50176
	ds_read_b128 v[196:199], v174 offset:51200
	ds_read_b128 v[200:203], v174 offset:52224
	ds_read_b128 v[206:209], v174 offset:53248
	ds_read_b128 v[210:213], v174 offset:54272
	ds_read_b128 v[214:217], v174 offset:55296
	ds_read_b128 v[218:221], v174 offset:56320
	global_load_lds_dwordx4 v[168:169], off
	s_add_i32 m0, s25, 0x2000
	s_add_u32 s28, s66, 0x40080
	v_lshl_add_u64 v[168:169], v[222:223], 0, s[36:37]
	s_addc_u32 s29, s67, 0
	s_add_i32 s25, s30, s70
	global_load_lds_dwordx4 v[168:169], off
	s_mov_b32 m0, s25
	v_lshl_add_u64 v[168:169], s[28:29], 0, v[150:151]
	global_load_lds_dwordx4 v[168:169], off
	s_add_i32 m0, s25, 0x2000
	v_lshl_add_u64 v[168:169], s[28:29], 0, v[146:147]
	global_load_lds_dwordx4 v[168:169], off
	s_mov_b32 m0, s79
	v_lshl_add_u64 v[168:169], v[224:225], 0, s[36:37]
	global_load_lds_dwordx4 v[168:169], off
	s_mov_b32 m0, s80
	v_lshl_add_u64 v[168:169], v[226:227], 0, s[36:37]
	global_load_lds_dwordx4 v[168:169], off
	s_setprio 1
	s_waitcnt vmcnt(8) lgkmcnt(0)
	s_barrier
	v_mfma_f32_16x16x32_bf16 v[62:65], v[130:133], v[188:191], v[62:65]
	v_mfma_f32_16x16x32_bf16 v[58:61], v[138:141], v[188:191], v[58:61]
	v_mfma_f32_16x16x32_bf16 v[46:49], v[130:133], v[196:199], v[46:49]
	v_mfma_f32_16x16x32_bf16 v[42:45], v[138:141], v[196:199], v[42:45]
	v_mfma_f32_16x16x32_bf16 v[30:33], v[130:133], v[206:209], v[30:33]
	v_mfma_f32_16x16x32_bf16 v[26:29], v[138:141], v[206:209], v[26:29]
	v_mfma_f32_16x16x32_bf16 v[14:17], v[130:133], v[214:217], v[14:17]
	v_mfma_f32_16x16x32_bf16 v[10:13], v[138:141], v[214:217], v[10:13]
	v_mfma_f32_16x16x32_bf16 v[62:65], v[134:137], v[192:195], v[62:65]
	v_mfma_f32_16x16x32_bf16 v[58:61], v[142:145], v[192:195], v[58:61]
	v_mfma_f32_16x16x32_bf16 v[46:49], v[134:137], v[200:203], v[46:49]
	v_mfma_f32_16x16x32_bf16 v[42:45], v[142:145], v[200:203], v[42:45]
	v_mfma_f32_16x16x32_bf16 v[30:33], v[134:137], v[210:213], v[30:33]
	v_mfma_f32_16x16x32_bf16 v[26:29], v[142:145], v[210:213], v[26:29]
	v_mfma_f32_16x16x32_bf16 v[14:17], v[134:137], v[218:221], v[14:17]
	v_mfma_f32_16x16x32_bf16 v[10:13], v[142:145], v[218:221], v[10:13]
	v_mfma_f32_16x16x32_bf16 v[54:57], v[164:167], v[188:191], v[54:57]
	v_mfma_f32_16x16x32_bf16 v[50:53], v[180:183], v[188:191], v[50:53]
	v_mfma_f32_16x16x32_bf16 v[38:41], v[164:167], v[196:199], v[38:41]
	v_mfma_f32_16x16x32_bf16 v[34:37], v[180:183], v[196:199], v[34:37]
	v_mfma_f32_16x16x32_bf16 v[22:25], v[164:167], v[206:209], v[22:25]
	v_mfma_f32_16x16x32_bf16 v[18:21], v[180:183], v[206:209], v[18:21]
	v_mfma_f32_16x16x32_bf16 v[6:9], v[164:167], v[214:217], v[6:9]
	v_mfma_f32_16x16x32_bf16 v[2:5], v[180:183], v[214:217], v[2:5]
	v_mfma_f32_16x16x32_bf16 v[54:57], v[176:179], v[192:195], v[54:57]
	v_mfma_f32_16x16x32_bf16 v[50:53], v[184:187], v[192:195], v[50:53]
	v_mfma_f32_16x16x32_bf16 v[38:41], v[176:179], v[200:203], v[38:41]
	v_mfma_f32_16x16x32_bf16 v[34:37], v[184:187], v[200:203], v[34:37]
	v_mfma_f32_16x16x32_bf16 v[22:25], v[176:179], v[210:213], v[22:25]
	v_mfma_f32_16x16x32_bf16 v[18:21], v[184:187], v[210:213], v[18:21]
	v_mfma_f32_16x16x32_bf16 v[6:9], v[176:179], v[218:221], v[6:9]
	v_mfma_f32_16x16x32_bf16 v[2:5], v[184:187], v[218:221], v[2:5]
	s_setprio 0
	s_barrier
	s_add_i32 s24, s24, 2
	s_add_u32 s64, s64, 0x100
	s_addc_u32 s65, s65, 0
	s_add_u32 s18, s18, 0x100
	s_addc_u32 s19, s19, 0
	s_cmp_gt_u32 s24, 13
	s_cbranch_scc0 .LBB0_1013
	s_and_b64 vcc, exec, s[38:39]
	s_cbranch_vccz .LBB0_1016
	s_barrier

.LBB0_1427:
	s_add_u32 s90, s35, s86
	s_addc_u32 s91, s64, s87
	s_and_b64 s[14:15], s[88:89], exec
	s_cselect_b32 s14, s91, s11
	s_cselect_b32 s15, s90, s10
	s_add_u32 s92, s65, s74
	s_addc_u32 s93, s68, s75
	s_and_b64 s[66:67], s[88:89], exec
	s_cselect_b32 s51, s93, s95
	s_cselect_b32 s84, s92, s94
	s_add_i32 s85, s18, -2
	s_add_u32 s10, s10, 0x40080
	s_addc_u32 s11, s11, 0
	s_add_u32 vcc_lo, s94, 0x100
	s_addc_u32 vcc_hi, s95, 0
	s_mov_b32 s94, 0
	s_waitcnt vmcnt(0)
	s_add_i32 s66, s94, 2
	s_add_u32 s67, s10, 0xfffc0080
	s_addc_u32 s72, s11, -1
	s_cmp_eq_u32 s85, s94
	s_cselect_b32 s97, s14, s72
	s_cselect_b32 s96, s15, s67
	s_cselect_b32 s95, s51, vcc_hi
	s_cselect_b32 s94, s84, vcc_lo
	s_add_i32 s67, 0, 0x10000
	s_add_i32 s62, 0, 0x14000
	v_add_u32_e32 v126, s67, v199
	v_add_u32_e32 v158, s62, v199
	ds_read_b128 v[114:117], v126
	ds_read_b128 v[118:121], v126 offset:1024
	ds_read_b128 v[122:125], v126 offset:2048
	ds_read_b128 v[126:129], v126 offset:3072
	ds_read_b128 v[146:149], v158
	ds_read_b128 v[150:153], v158 offset:1024
	ds_read_b128 v[154:157], v158 offset:2048
	ds_read_b128 v[158:161], v158 offset:3072
	v_lshl_add_u64 v[202:203], s[10:11], 0, v[196:197]
	s_add_i32 m0, s28, 0xc000
	ds_read_b128 v[162:165], v214
	ds_read_b128 v[166:169], v214 offset:1024
	ds_read_b128 v[216:219], v214 offset:2048
	ds_read_b128 v[220:223], v214 offset:3072
	ds_read_b128 v[224:227], v214 offset:4096
	ds_read_b128 v[228:231], v214 offset:5120
	ds_read_b128 v[232:235], v214 offset:6144
	ds_read_b128 v[236:239], v214 offset:7168
	global_load_lds_dwordx4 v[202:203], off
	s_add_i32 m0, s28, 0xe000
	v_lshl_add_u64 v[202:203], s[10:11], 0, v[176:177]
	global_load_lds_dwordx4 v[202:203], off
	s_setprio 1
	s_waitcnt vmcnt(8) lgkmcnt(0)
	s_barrier
	v_mfma_f32_16x16x32_bf16 v[142:145], v[114:117], v[162:165], 0
	v_mfma_f32_16x16x32_bf16 v[138:141], v[122:125], v[162:165], 0
	v_mfma_f32_16x16x32_bf16 v[110:113], v[114:117], v[216:219], 0
	v_mfma_f32_16x16x32_bf16 v[106:109], v[122:125], v[216:219], 0
	v_mfma_f32_16x16x32_bf16 v[98:101], v[114:117], v[224:227], 0
	v_mfma_f32_16x16x32_bf16 v[90:93], v[122:125], v[224:227], 0
	v_mfma_f32_16x16x32_bf16 v[82:85], v[114:117], v[232:235], 0
	v_mfma_f32_16x16x32_bf16 v[74:77], v[122:125], v[232:235], 0
	v_mfma_f32_16x16x32_bf16 v[142:145], v[118:121], v[166:169], v[142:145]
	v_mfma_f32_16x16x32_bf16 v[138:141], v[126:129], v[166:169], v[138:141]
	v_mfma_f32_16x16x32_bf16 v[110:113], v[118:121], v[220:223], v[110:113]
	v_mfma_f32_16x16x32_bf16 v[106:109], v[126:129], v[220:223], v[106:109]
	v_mfma_f32_16x16x32_bf16 v[98:101], v[118:121], v[228:231], v[98:101]
	v_mfma_f32_16x16x32_bf16 v[90:93], v[126:129], v[228:231], v[90:93]
	v_mfma_f32_16x16x32_bf16 v[82:85], v[118:121], v[236:239], v[82:85]
	v_mfma_f32_16x16x32_bf16 v[74:77], v[126:129], v[236:239], v[74:77]
	v_mfma_f32_16x16x32_bf16 v[134:137], v[146:149], v[162:165], 0
	v_mfma_f32_16x16x32_bf16 v[130:133], v[154:157], v[162:165], 0
	v_mfma_f32_16x16x32_bf16 v[102:105], v[146:149], v[216:219], 0
	v_mfma_f32_16x16x32_bf16 v[94:97], v[154:157], v[216:219], 0
	v_mfma_f32_16x16x32_bf16 v[86:89], v[146:149], v[224:227], 0
	v_mfma_f32_16x16x32_bf16 v[78:81], v[154:157], v[224:227], 0
	v_mfma_f32_16x16x32_bf16 v[70:73], v[146:149], v[232:235], 0
	v_mfma_f32_16x16x32_bf16 v[66:69], v[154:157], v[232:235], 0
	v_mfma_f32_16x16x32_bf16 v[134:137], v[150:153], v[166:169], v[134:137]
	v_mfma_f32_16x16x32_bf16 v[130:133], v[158:161], v[166:169], v[130:133]
	v_mfma_f32_16x16x32_bf16 v[102:105], v[150:153], v[220:223], v[102:105]
	v_mfma_f32_16x16x32_bf16 v[94:97], v[158:161], v[220:223], v[94:97]
	v_mfma_f32_16x16x32_bf16 v[86:89], v[150:153], v[228:231], v[86:89]
	v_mfma_f32_16x16x32_bf16 v[78:81], v[158:161], v[228:231], v[78:81]
	v_mfma_f32_16x16x32_bf16 v[70:73], v[150:153], v[236:239], v[70:73]
	v_mfma_f32_16x16x32_bf16 v[66:69], v[158:161], v[236:239], v[66:69]
	s_setprio 0
	s_barrier
	s_add_i32 s63, s67, s17
	v_lshl_add_u64 v[202:203], s[94:95], 0, v[174:175]
	s_mov_b32 m0, s63
	ds_read_b128 v[162:165], v214 offset:16384
	ds_read_b128 v[166:169], v214 offset:17408
	ds_read_b128 v[216:219], v214 offset:18432
	ds_read_b128 v[220:223], v214 offset:19456
	ds_read_b128 v[224:227], v214 offset:20480
	ds_read_b128 v[228:231], v214 offset:21504
	ds_read_b128 v[232:235], v214 offset:22528
	ds_read_b128 v[236:239], v214 offset:23552
	global_load_lds_dwordx4 v[202:203], off
	s_add_i32 m0, s63, 0x2000
	s_add_u32 s72, s94, 0x40000
	v_lshl_add_u64 v[240:241], s[94:95], 0, v[178:179]
	s_addc_u32 s73, s95, 0
	s_add_i32 s62, s62, s17
	global_load_lds_dwordx4 v[240:241], off
	v_lshl_add_u64 v[242:243], s[72:73], 0, v[174:175]
	s_mov_b32 m0, s62
	v_lshl_add_u64 v[244:245], s[96:97], 0, v[176:177]
	global_load_lds_dwordx4 v[242:243], off
	s_add_i32 m0, s62, 0x2000
	v_lshl_add_u64 v[242:243], s[72:73], 0, v[178:179]
	global_load_lds_dwordx4 v[242:243], off
	s_mov_b32 m0, s28
	v_lshl_add_u64 v[242:243], s[96:97], 0, v[172:173]
	global_load_lds_dwordx4 v[242:243], off
	s_mov_b32 m0, s29
	s_nop 0
	global_load_lds_dwordx4 v[244:245], off
	s_setprio 1
	s_waitcnt vmcnt(8) lgkmcnt(0)
	s_barrier
	v_mfma_f32_16x16x32_bf16 v[62:65], v[114:117], v[162:165], 0
	v_mfma_f32_16x16x32_bf16 v[58:61], v[122:125], v[162:165], 0
	v_mfma_f32_16x16x32_bf16 v[50:53], v[114:117], v[216:219], 0
	v_mfma_f32_16x16x32_bf16 v[42:45], v[122:125], v[216:219], 0
	v_mfma_f32_16x16x32_bf16 v[34:37], v[114:117], v[224:227], 0
	v_mfma_f32_16x16x32_bf16 v[26:29], v[122:125], v[224:227], 0
	v_mfma_f32_16x16x32_bf16 v[18:21], v[114:117], v[232:235], 0
	v_mfma_f32_16x16x32_bf16 v[10:13], v[122:125], v[232:235], 0
	v_mfma_f32_16x16x32_bf16 v[62:65], v[118:121], v[166:169], v[62:65]
	v_mfma_f32_16x16x32_bf16 v[58:61], v[126:129], v[166:169], v[58:61]
	v_mfma_f32_16x16x32_bf16 v[50:53], v[118:121], v[220:223], v[50:53]
	v_mfma_f32_16x16x32_bf16 v[42:45], v[126:129], v[220:223], v[42:45]
	v_mfma_f32_16x16x32_bf16 v[34:37], v[118:121], v[228:231], v[34:37]
	v_mfma_f32_16x16x32_bf16 v[26:29], v[126:129], v[228:231], v[26:29]
	v_mfma_f32_16x16x32_bf16 v[18:21], v[118:121], v[236:239], v[18:21]
	v_mfma_f32_16x16x32_bf16 v[10:13], v[126:129], v[236:239], v[10:13]
	v_mfma_f32_16x16x32_bf16 v[54:57], v[146:149], v[162:165], 0
	v_mfma_f32_16x16x32_bf16 v[46:49], v[154:157], v[162:165], 0
	v_mfma_f32_16x16x32_bf16 v[38:41], v[146:149], v[216:219], 0
	v_mfma_f32_16x16x32_bf16 v[30:33], v[154:157], v[216:219], 0
	v_mfma_f32_16x16x32_bf16 v[22:25], v[146:149], v[224:227], 0
	v_mfma_f32_16x16x32_bf16 v[14:17], v[154:157], v[224:227], 0
	v_mfma_f32_16x16x32_bf16 v[6:9], v[146:149], v[232:235], 0
	v_mfma_f32_16x16x32_bf16 v[2:5], v[154:157], v[232:235], 0
	v_mfma_f32_16x16x32_bf16 v[54:57], v[150:153], v[166:169], v[54:57]
	v_mfma_f32_16x16x32_bf16 v[46:49], v[158:161], v[166:169], v[46:49]
	v_mfma_f32_16x16x32_bf16 v[38:41], v[150:153], v[220:223], v[38:41]
	v_mfma_f32_16x16x32_bf16 v[30:33], v[158:161], v[220:223], v[30:33]
	v_mfma_f32_16x16x32_bf16 v[22:25], v[150:153], v[228:231], v[22:25]
	v_mfma_f32_16x16x32_bf16 v[14:17], v[158:161], v[228:231], v[14:17]
	v_mfma_f32_16x16x32_bf16 v[6:9], v[150:153], v[236:239], v[6:9]
	v_mfma_f32_16x16x32_bf16 v[2:5], v[158:161], v[236:239], v[2:5]
	s_setprio 0
	s_barrier
	s_add_i32 s62, 0, 0x18000
	s_add_i32 s63, 0, 0x1c000
	v_add_u32_e32 v126, s62, v199
	v_add_u32_e32 v158, s63, v199
	ds_read_b128 v[114:117], v126
	ds_read_b128 v[118:121], v126 offset:1024
	ds_read_b128 v[122:125], v126 offset:2048
	ds_read_b128 v[126:129], v126 offset:3072
	ds_read_b128 v[146:149], v158
	ds_read_b128 v[150:153], v158 offset:1024
	ds_read_b128 v[154:157], v158 offset:2048
	ds_read_b128 v[158:161], v158 offset:3072
	s_add_u32 s72, s96, 0x40000
	s_addc_u32 s73, s97, 0
	s_mov_b32 m0, s30
	v_lshl_add_u64 v[246:247], s[72:73], 0, v[172:173]
	ds_read_b128 v[162:165], v214 offset:32768
	ds_read_b128 v[166:169], v214 offset:33792
	ds_read_b128 v[216:219], v214 offset:34816
	ds_read_b128 v[220:223], v214 offset:35840
	ds_read_b128 v[224:227], v214 offset:36864
	ds_read_b128 v[228:231], v214 offset:37888
	ds_read_b128 v[232:235], v214 offset:38912
	ds_read_b128 v[236:239], v214 offset:39936
	global_load_lds_dwordx4 v[246:247], off
	s_mov_b32 m0, s31
	v_lshl_add_u64 v[246:247], s[72:73], 0, v[176:177]
	global_load_lds_dwordx4 v[246:247], off
	s_setprio 1
	s_waitcnt vmcnt(8) lgkmcnt(0)
	s_barrier
	v_mfma_f32_16x16x32_bf16 v[142:145], v[114:117], v[162:165], v[142:145]
	v_mfma_f32_16x16x32_bf16 v[138:141], v[122:125], v[162:165], v[138:141]
	v_mfma_f32_16x16x32_bf16 v[110:113], v[114:117], v[216:219], v[110:113]
	v_mfma_f32_16x16x32_bf16 v[106:109], v[122:125], v[216:219], v[106:109]
	v_mfma_f32_16x16x32_bf16 v[98:101], v[114:117], v[224:227], v[98:101]
	v_mfma_f32_16x16x32_bf16 v[90:93], v[122:125], v[224:227], v[90:93]
	v_mfma_f32_16x16x32_bf16 v[82:85], v[114:117], v[232:235], v[82:85]
	v_mfma_f32_16x16x32_bf16 v[74:77], v[122:125], v[232:235], v[74:77]
	v_mfma_f32_16x16x32_bf16 v[142:145], v[118:121], v[166:169], v[142:145]
	v_mfma_f32_16x16x32_bf16 v[138:141], v[126:129], v[166:169], v[138:141]
	v_mfma_f32_16x16x32_bf16 v[110:113], v[118:121], v[220:223], v[110:113]
	v_mfma_f32_16x16x32_bf16 v[106:109], v[126:129], v[220:223], v[106:109]
	v_mfma_f32_16x16x32_bf16 v[98:101], v[118:121], v[228:231], v[98:101]
	v_mfma_f32_16x16x32_bf16 v[90:93], v[126:129], v[228:231], v[90:93]
	v_mfma_f32_16x16x32_bf16 v[82:85], v[118:121], v[236:239], v[82:85]
	v_mfma_f32_16x16x32_bf16 v[74:77], v[126:129], v[236:239], v[74:77]
	v_mfma_f32_16x16x32_bf16 v[134:137], v[146:149], v[162:165], v[134:137]
	v_mfma_f32_16x16x32_bf16 v[130:133], v[154:157], v[162:165], v[130:133]
	v_mfma_f32_16x16x32_bf16 v[102:105], v[146:149], v[216:219], v[102:105]
	v_mfma_f32_16x16x32_bf16 v[94:97], v[154:157], v[216:219], v[94:97]
	v_mfma_f32_16x16x32_bf16 v[86:89], v[146:149], v[224:227], v[86:89]
	v_mfma_f32_16x16x32_bf16 v[78:81], v[154:157], v[224:227], v[78:81]
	v_mfma_f32_16x16x32_bf16 v[70:73], v[146:149], v[232:235], v[70:73]
	v_mfma_f32_16x16x32_bf16 v[66:69], v[154:157], v[232:235], v[66:69]
	v_mfma_f32_16x16x32_bf16 v[134:137], v[150:153], v[166:169], v[134:137]
	v_mfma_f32_16x16x32_bf16 v[130:133], v[158:161], v[166:169], v[130:133]
	v_mfma_f32_16x16x32_bf16 v[102:105], v[150:153], v[220:223], v[102:105]
	v_mfma_f32_16x16x32_bf16 v[94:97], v[158:161], v[220:223], v[94:97]
	v_mfma_f32_16x16x32_bf16 v[86:89], v[150:153], v[228:231], v[86:89]
	v_mfma_f32_16x16x32_bf16 v[78:81], v[158:161], v[228:231], v[78:81]
	v_mfma_f32_16x16x32_bf16 v[70:73], v[150:153], v[236:239], v[70:73]
	v_mfma_f32_16x16x32_bf16 v[66:69], v[158:161], v[236:239], v[66:69]
	s_setprio 0
	s_barrier
	s_add_i32 s62, s62, s17
	v_lshl_add_u64 v[202:203], v[202:203], 0, s[76:77]
	s_mov_b32 m0, s62
	ds_read_b128 v[162:165], v214 offset:49152
	ds_read_b128 v[166:169], v214 offset:50176
	ds_read_b128 v[216:219], v214 offset:51200
	ds_read_b128 v[220:223], v214 offset:52224
	ds_read_b128 v[224:227], v214 offset:53248
	ds_read_b128 v[228:231], v214 offset:54272
	ds_read_b128 v[232:235], v214 offset:55296
	ds_read_b128 v[236:239], v214 offset:56320
	global_load_lds_dwordx4 v[202:203], off
	s_add_i32 m0, s62, 0x2000
	s_add_u32 s72, s94, 0x40080
	v_lshl_add_u64 v[202:203], v[240:241], 0, s[76:77]
	s_addc_u32 s73, s95, 0
	s_add_i32 s62, s63, s17
	global_load_lds_dwordx4 v[202:203], off
	s_mov_b32 m0, s62
	v_lshl_add_u64 v[202:203], s[72:73], 0, v[174:175]
	global_load_lds_dwordx4 v[202:203], off
	s_add_i32 m0, s62, 0x2000
	v_lshl_add_u64 v[202:203], s[72:73], 0, v[178:179]
	global_load_lds_dwordx4 v[202:203], off
	s_mov_b32 m0, s44
	v_lshl_add_u64 v[202:203], v[242:243], 0, s[76:77]
	global_load_lds_dwordx4 v[202:203], off
	s_mov_b32 m0, s36
	v_lshl_add_u64 v[202:203], v[244:245], 0, s[76:77]
	global_load_lds_dwordx4 v[202:203], off
	s_setprio 1
	s_waitcnt vmcnt(8) lgkmcnt(0)
	s_barrier
	v_mfma_f32_16x16x32_bf16 v[62:65], v[114:117], v[162:165], v[62:65]
	v_mfma_f32_16x16x32_bf16 v[58:61], v[122:125], v[162:165], v[58:61]
	v_mfma_f32_16x16x32_bf16 v[50:53], v[114:117], v[216:219], v[50:53]
	v_mfma_f32_16x16x32_bf16 v[42:45], v[122:125], v[216:219], v[42:45]
	v_mfma_f32_16x16x32_bf16 v[34:37], v[114:117], v[224:227], v[34:37]
	v_mfma_f32_16x16x32_bf16 v[26:29], v[122:125], v[224:227], v[26:29]
	v_mfma_f32_16x16x32_bf16 v[18:21], v[114:117], v[232:235], v[18:21]
	v_mfma_f32_16x16x32_bf16 v[10:13], v[122:125], v[232:235], v[10:13]
	v_mfma_f32_16x16x32_bf16 v[62:65], v[118:121], v[166:169], v[62:65]
	v_mfma_f32_16x16x32_bf16 v[58:61], v[126:129], v[166:169], v[58:61]
	v_mfma_f32_16x16x32_bf16 v[50:53], v[118:121], v[220:223], v[50:53]
	v_mfma_f32_16x16x32_bf16 v[42:45], v[126:129], v[220:223], v[42:45]
	v_mfma_f32_16x16x32_bf16 v[34:37], v[118:121], v[228:231], v[34:37]
	v_mfma_f32_16x16x32_bf16 v[26:29], v[126:129], v[228:231], v[26:29]
	v_mfma_f32_16x16x32_bf16 v[18:21], v[118:121], v[236:239], v[18:21]
	v_mfma_f32_16x16x32_bf16 v[10:13], v[126:129], v[236:239], v[10:13]
	v_mfma_f32_16x16x32_bf16 v[54:57], v[146:149], v[162:165], v[54:57]
	v_mfma_f32_16x16x32_bf16 v[46:49], v[154:157], v[162:165], v[46:49]
	v_mfma_f32_16x16x32_bf16 v[38:41], v[146:149], v[216:219], v[38:41]
	v_mfma_f32_16x16x32_bf16 v[30:33], v[154:157], v[216:219], v[30:33]
	v_mfma_f32_16x16x32_bf16 v[22:25], v[146:149], v[224:227], v[22:25]
	v_mfma_f32_16x16x32_bf16 v[14:17], v[154:157], v[224:227], v[14:17]
	v_mfma_f32_16x16x32_bf16 v[6:9], v[146:149], v[232:235], v[6:9]
	v_mfma_f32_16x16x32_bf16 v[2:5], v[154:157], v[232:235], v[2:5]
	v_mfma_f32_16x16x32_bf16 v[54:57], v[150:153], v[166:169], v[54:57]
	v_mfma_f32_16x16x32_bf16 v[46:49], v[158:161], v[166:169], v[46:49]
	v_mfma_f32_16x16x32_bf16 v[38:41], v[150:153], v[220:223], v[38:41]
	v_mfma_f32_16x16x32_bf16 v[30:33], v[158:161], v[220:223], v[30:33]
	v_mfma_f32_16x16x32_bf16 v[22:25], v[150:153], v[228:231], v[22:25]
	v_mfma_f32_16x16x32_bf16 v[14:17], v[158:161], v[228:231], v[14:17]
	v_mfma_f32_16x16x32_bf16 v[6:9], v[150:153], v[236:239], v[6:9]
	v_mfma_f32_16x16x32_bf16 v[2:5], v[158:161], v[236:239], v[2:5]
	s_setprio 0
	s_barrier
	s_add_u32 s10, s10, 0x100
	s_addc_u32 s11, s11, 0
	s_add_u32 vcc_lo, vcc_lo, 0x100
	s_addc_u32 vcc_hi, vcc_hi, 0
	s_cmp_ge_i32 s66, s18
	s_mov_b32 s94, s66
.LBB0_1428:
	s_add_i32 s66, s94, 2
	s_add_u32 s67, s10, 0xfffc0080
	s_addc_u32 s72, s11, -1
	s_cmp_eq_u32 s85, s94
	s_cselect_b32 s97, s14, s72
	s_cselect_b32 s96, s15, s67
	s_cselect_b32 s95, s51, vcc_hi
	s_cselect_b32 s94, s84, vcc_lo
	s_add_i32 s67, 0, 0x10000
	s_add_i32 s62, 0, 0x14000
	v_add_u32_e32 v126, s67, v199
	v_add_u32_e32 v158, s62, v199
	ds_read_b128 v[114:117], v126
	ds_read_b128 v[118:121], v126 offset:1024
	ds_read_b128 v[122:125], v126 offset:2048
	ds_read_b128 v[126:129], v126 offset:3072
	ds_read_b128 v[146:149], v158
	ds_read_b128 v[150:153], v158 offset:1024
	ds_read_b128 v[154:157], v158 offset:2048
	ds_read_b128 v[158:161], v158 offset:3072
	v_lshl_add_u64 v[202:203], s[10:11], 0, v[196:197]
	s_add_i32 m0, s28, 0xc000
	ds_read_b128 v[162:165], v214
	ds_read_b128 v[166:169], v214 offset:1024
	ds_read_b128 v[216:219], v214 offset:2048
	ds_read_b128 v[220:223], v214 offset:3072
	ds_read_b128 v[224:227], v214 offset:4096
	ds_read_b128 v[228:231], v214 offset:5120
	ds_read_b128 v[232:235], v214 offset:6144
	ds_read_b128 v[236:239], v214 offset:7168
	global_load_lds_dwordx4 v[202:203], off
	s_add_i32 m0, s28, 0xe000
	v_lshl_add_u64 v[202:203], s[10:11], 0, v[176:177]
	global_load_lds_dwordx4 v[202:203], off
	s_setprio 1
	s_waitcnt vmcnt(8) lgkmcnt(0)
	s_barrier
	v_mfma_f32_16x16x32_bf16 v[142:145], v[114:117], v[162:165], v[142:145]
	v_mfma_f32_16x16x32_bf16 v[138:141], v[122:125], v[162:165], v[138:141]
	v_mfma_f32_16x16x32_bf16 v[110:113], v[114:117], v[216:219], v[110:113]
	v_mfma_f32_16x16x32_bf16 v[106:109], v[122:125], v[216:219], v[106:109]
	v_mfma_f32_16x16x32_bf16 v[98:101], v[114:117], v[224:227], v[98:101]
	v_mfma_f32_16x16x32_bf16 v[90:93], v[122:125], v[224:227], v[90:93]
	v_mfma_f32_16x16x32_bf16 v[82:85], v[114:117], v[232:235], v[82:85]
	v_mfma_f32_16x16x32_bf16 v[74:77], v[122:125], v[232:235], v[74:77]
	v_mfma_f32_16x16x32_bf16 v[142:145], v[118:121], v[166:169], v[142:145]
	v_mfma_f32_16x16x32_bf16 v[138:141], v[126:129], v[166:169], v[138:141]
	v_mfma_f32_16x16x32_bf16 v[110:113], v[118:121], v[220:223], v[110:113]
	v_mfma_f32_16x16x32_bf16 v[106:109], v[126:129], v[220:223], v[106:109]
	v_mfma_f32_16x16x32_bf16 v[98:101], v[118:121], v[228:231], v[98:101]
	v_mfma_f32_16x16x32_bf16 v[90:93], v[126:129], v[228:231], v[90:93]
	v_mfma_f32_16x16x32_bf16 v[82:85], v[118:121], v[236:239], v[82:85]
	v_mfma_f32_16x16x32_bf16 v[74:77], v[126:129], v[236:239], v[74:77]
	v_mfma_f32_16x16x32_bf16 v[134:137], v[146:149], v[162:165], v[134:137]
	v_mfma_f32_16x16x32_bf16 v[130:133], v[154:157], v[162:165], v[130:133]
	v_mfma_f32_16x16x32_bf16 v[102:105], v[146:149], v[216:219], v[102:105]
	v_mfma_f32_16x16x32_bf16 v[94:97], v[154:157], v[216:219], v[94:97]
	v_mfma_f32_16x16x32_bf16 v[86:89], v[146:149], v[224:227], v[86:89]
	v_mfma_f32_16x16x32_bf16 v[78:81], v[154:157], v[224:227], v[78:81]
	v_mfma_f32_16x16x32_bf16 v[70:73], v[146:149], v[232:235], v[70:73]
	v_mfma_f32_16x16x32_bf16 v[66:69], v[154:157], v[232:235], v[66:69]
	v_mfma_f32_16x16x32_bf16 v[134:137], v[150:153], v[166:169], v[134:137]
	v_mfma_f32_16x16x32_bf16 v[130:133], v[158:161], v[166:169], v[130:133]
	v_mfma_f32_16x16x32_bf16 v[102:105], v[150:153], v[220:223], v[102:105]
	v_mfma_f32_16x16x32_bf16 v[94:97], v[158:161], v[220:223], v[94:97]
	v_mfma_f32_16x16x32_bf16 v[86:89], v[150:153], v[228:231], v[86:89]
	v_mfma_f32_16x16x32_bf16 v[78:81], v[158:161], v[228:231], v[78:81]
	v_mfma_f32_16x16x32_bf16 v[70:73], v[150:153], v[236:239], v[70:73]
	v_mfma_f32_16x16x32_bf16 v[66:69], v[158:161], v[236:239], v[66:69]
	s_setprio 0
	s_barrier
	s_add_i32 s63, s67, s17
	v_lshl_add_u64 v[202:203], s[94:95], 0, v[174:175]
	s_mov_b32 m0, s63
	ds_read_b128 v[162:165], v214 offset:16384
	ds_read_b128 v[166:169], v214 offset:17408
	ds_read_b128 v[216:219], v214 offset:18432
	ds_read_b128 v[220:223], v214 offset:19456
	ds_read_b128 v[224:227], v214 offset:20480
	ds_read_b128 v[228:231], v214 offset:21504
	ds_read_b128 v[232:235], v214 offset:22528
	ds_read_b128 v[236:239], v214 offset:23552
	global_load_lds_dwordx4 v[202:203], off
	s_add_i32 m0, s63, 0x2000
	s_add_u32 s72, s94, 0x40000
	v_lshl_add_u64 v[240:241], s[94:95], 0, v[178:179]
	s_addc_u32 s73, s95, 0
	s_add_i32 s62, s62, s17
	global_load_lds_dwordx4 v[240:241], off
	v_lshl_add_u64 v[242:243], s[72:73], 0, v[174:175]
	s_mov_b32 m0, s62
	v_lshl_add_u64 v[244:245], s[96:97], 0, v[176:177]
	global_load_lds_dwordx4 v[242:243], off
	s_add_i32 m0, s62, 0x2000
	v_lshl_add_u64 v[242:243], s[72:73], 0, v[178:179]
	global_load_lds_dwordx4 v[242:243], off
	s_mov_b32 m0, s28
	v_lshl_add_u64 v[242:243], s[96:97], 0, v[172:173]
	global_load_lds_dwordx4 v[242:243], off
	s_mov_b32 m0, s29
	s_nop 0
	global_load_lds_dwordx4 v[244:245], off
	s_setprio 1
	s_waitcnt vmcnt(8) lgkmcnt(0)
	s_barrier
	v_mfma_f32_16x16x32_bf16 v[62:65], v[114:117], v[162:165], v[62:65]
	v_mfma_f32_16x16x32_bf16 v[58:61], v[122:125], v[162:165], v[58:61]
	v_mfma_f32_16x16x32_bf16 v[50:53], v[114:117], v[216:219], v[50:53]
	v_mfma_f32_16x16x32_bf16 v[42:45], v[122:125], v[216:219], v[42:45]
	v_mfma_f32_16x16x32_bf16 v[34:37], v[114:117], v[224:227], v[34:37]
	v_mfma_f32_16x16x32_bf16 v[26:29], v[122:125], v[224:227], v[26:29]
	v_mfma_f32_16x16x32_bf16 v[18:21], v[114:117], v[232:235], v[18:21]
	v_mfma_f32_16x16x32_bf16 v[10:13], v[122:125], v[232:235], v[10:13]
	v_mfma_f32_16x16x32_bf16 v[62:65], v[118:121], v[166:169], v[62:65]
	v_mfma_f32_16x16x32_bf16 v[58:61], v[126:129], v[166:169], v[58:61]
	v_mfma_f32_16x16x32_bf16 v[50:53], v[118:121], v[220:223], v[50:53]
	v_mfma_f32_16x16x32_bf16 v[42:45], v[126:129], v[220:223], v[42:45]
	v_mfma_f32_16x16x32_bf16 v[34:37], v[118:121], v[228:231], v[34:37]
	v_mfma_f32_16x16x32_bf16 v[26:29], v[126:129], v[228:231], v[26:29]
	v_mfma_f32_16x16x32_bf16 v[18:21], v[118:121], v[236:239], v[18:21]
	v_mfma_f32_16x16x32_bf16 v[10:13], v[126:129], v[236:239], v[10:13]
	v_mfma_f32_16x16x32_bf16 v[54:57], v[146:149], v[162:165], v[54:57]
	v_mfma_f32_16x16x32_bf16 v[46:49], v[154:157], v[162:165], v[46:49]
	v_mfma_f32_16x16x32_bf16 v[38:41], v[146:149], v[216:219], v[38:41]
	v_mfma_f32_16x16x32_bf16 v[30:33], v[154:157], v[216:219], v[30:33]
	v_mfma_f32_16x16x32_bf16 v[22:25], v[146:149], v[224:227], v[22:25]
	v_mfma_f32_16x16x32_bf16 v[14:17], v[154:157], v[224:227], v[14:17]
	v_mfma_f32_16x16x32_bf16 v[6:9], v[146:149], v[232:235], v[6:9]
	v_mfma_f32_16x16x32_bf16 v[2:5], v[154:157], v[232:235], v[2:5]
	v_mfma_f32_16x16x32_bf16 v[54:57], v[150:153], v[166:169], v[54:57]
	v_mfma_f32_16x16x32_bf16 v[46:49], v[158:161], v[166:169], v[46:49]
	v_mfma_f32_16x16x32_bf16 v[38:41], v[150:153], v[220:223], v[38:41]
	v_mfma_f32_16x16x32_bf16 v[30:33], v[158:161], v[220:223], v[30:33]
	v_mfma_f32_16x16x32_bf16 v[22:25], v[150:153], v[228:231], v[22:25]
	v_mfma_f32_16x16x32_bf16 v[14:17], v[158:161], v[228:231], v[14:17]
	v_mfma_f32_16x16x32_bf16 v[6:9], v[150:153], v[236:239], v[6:9]
	v_mfma_f32_16x16x32_bf16 v[2:5], v[158:161], v[236:239], v[2:5]
	s_setprio 0
	s_barrier
	s_add_i32 s62, 0, 0x18000
	s_add_i32 s63, 0, 0x1c000
	v_add_u32_e32 v126, s62, v199
	v_add_u32_e32 v158, s63, v199
	ds_read_b128 v[114:117], v126
	ds_read_b128 v[118:121], v126 offset:1024
	ds_read_b128 v[122:125], v126 offset:2048
	ds_read_b128 v[126:129], v126 offset:3072
	ds_read_b128 v[146:149], v158
	ds_read_b128 v[150:153], v158 offset:1024
	ds_read_b128 v[154:157], v158 offset:2048
	ds_read_b128 v[158:161], v158 offset:3072
	s_add_u32 s72, s96, 0x40000
	s_addc_u32 s73, s97, 0
	s_mov_b32 m0, s30
	v_lshl_add_u64 v[246:247], s[72:73], 0, v[172:173]
	ds_read_b128 v[162:165], v214 offset:32768
	ds_read_b128 v[166:169], v214 offset:33792
	ds_read_b128 v[216:219], v214 offset:34816
	ds_read_b128 v[220:223], v214 offset:35840
	ds_read_b128 v[224:227], v214 offset:36864
	ds_read_b128 v[228:231], v214 offset:37888
	ds_read_b128 v[232:235], v214 offset:38912
	ds_read_b128 v[236:239], v214 offset:39936
	global_load_lds_dwordx4 v[246:247], off
	s_mov_b32 m0, s31
	v_lshl_add_u64 v[246:247], s[72:73], 0, v[176:177]
	global_load_lds_dwordx4 v[246:247], off
	s_setprio 1
	s_waitcnt vmcnt(8) lgkmcnt(0)
	s_barrier
	v_mfma_f32_16x16x32_bf16 v[142:145], v[114:117], v[162:165], v[142:145]
	v_mfma_f32_16x16x32_bf16 v[138:141], v[122:125], v[162:165], v[138:141]
	v_mfma_f32_16x16x32_bf16 v[110:113], v[114:117], v[216:219], v[110:113]
	v_mfma_f32_16x16x32_bf16 v[106:109], v[122:125], v[216:219], v[106:109]
	v_mfma_f32_16x16x32_bf16 v[98:101], v[114:117], v[224:227], v[98:101]
	v_mfma_f32_16x16x32_bf16 v[90:93], v[122:125], v[224:227], v[90:93]
	v_mfma_f32_16x16x32_bf16 v[82:85], v[114:117], v[232:235], v[82:85]
	v_mfma_f32_16x16x32_bf16 v[74:77], v[122:125], v[232:235], v[74:77]
	v_mfma_f32_16x16x32_bf16 v[142:145], v[118:121], v[166:169], v[142:145]
	v_mfma_f32_16x16x32_bf16 v[138:141], v[126:129], v[166:169], v[138:141]
	v_mfma_f32_16x16x32_bf16 v[110:113], v[118:121], v[220:223], v[110:113]
	v_mfma_f32_16x16x32_bf16 v[106:109], v[126:129], v[220:223], v[106:109]
	v_mfma_f32_16x16x32_bf16 v[98:101], v[118:121], v[228:231], v[98:101]
	v_mfma_f32_16x16x32_bf16 v[90:93], v[126:129], v[228:231], v[90:93]
	v_mfma_f32_16x16x32_bf16 v[82:85], v[118:121], v[236:239], v[82:85]
	v_mfma_f32_16x16x32_bf16 v[74:77], v[126:129], v[236:239], v[74:77]
	v_mfma_f32_16x16x32_bf16 v[134:137], v[146:149], v[162:165], v[134:137]
	v_mfma_f32_16x16x32_bf16 v[130:133], v[154:157], v[162:165], v[130:133]
	v_mfma_f32_16x16x32_bf16 v[102:105], v[146:149], v[216:219], v[102:105]
	v_mfma_f32_16x16x32_bf16 v[94:97], v[154:157], v[216:219], v[94:97]
	v_mfma_f32_16x16x32_bf16 v[86:89], v[146:149], v[224:227], v[86:89]
	v_mfma_f32_16x16x32_bf16 v[78:81], v[154:157], v[224:227], v[78:81]
	v_mfma_f32_16x16x32_bf16 v[70:73], v[146:149], v[232:235], v[70:73]
	v_mfma_f32_16x16x32_bf16 v[66:69], v[154:157], v[232:235], v[66:69]
	v_mfma_f32_16x16x32_bf16 v[134:137], v[150:153], v[166:169], v[134:137]
	v_mfma_f32_16x16x32_bf16 v[130:133], v[158:161], v[166:169], v[130:133]
	v_mfma_f32_16x16x32_bf16 v[102:105], v[150:153], v[220:223], v[102:105]
	v_mfma_f32_16x16x32_bf16 v[94:97], v[158:161], v[220:223], v[94:97]
	v_mfma_f32_16x16x32_bf16 v[86:89], v[150:153], v[228:231], v[86:89]
	v_mfma_f32_16x16x32_bf16 v[78:81], v[158:161], v[228:231], v[78:81]
	v_mfma_f32_16x16x32_bf16 v[70:73], v[150:153], v[236:239], v[70:73]
	v_mfma_f32_16x16x32_bf16 v[66:69], v[158:161], v[236:239], v[66:69]
	s_setprio 0
	s_barrier
	s_add_i32 s62, s62, s17
	v_lshl_add_u64 v[202:203], v[202:203], 0, s[76:77]
	s_mov_b32 m0, s62
	ds_read_b128 v[162:165], v214 offset:49152
	ds_read_b128 v[166:169], v214 offset:50176
	ds_read_b128 v[216:219], v214 offset:51200
	ds_read_b128 v[220:223], v214 offset:52224
	ds_read_b128 v[224:227], v214 offset:53248
	ds_read_b128 v[228:231], v214 offset:54272
	ds_read_b128 v[232:235], v214 offset:55296
	ds_read_b128 v[236:239], v214 offset:56320
	global_load_lds_dwordx4 v[202:203], off
	s_add_i32 m0, s62, 0x2000
	s_add_u32 s72, s94, 0x40080
	v_lshl_add_u64 v[202:203], v[240:241], 0, s[76:77]
	s_addc_u32 s73, s95, 0
	s_add_i32 s62, s63, s17
	global_load_lds_dwordx4 v[202:203], off
	s_mov_b32 m0, s62
	v_lshl_add_u64 v[202:203], s[72:73], 0, v[174:175]
	global_load_lds_dwordx4 v[202:203], off
	s_add_i32 m0, s62, 0x2000
	v_lshl_add_u64 v[202:203], s[72:73], 0, v[178:179]
	global_load_lds_dwordx4 v[202:203], off
	s_mov_b32 m0, s44
	v_lshl_add_u64 v[202:203], v[242:243], 0, s[76:77]
	global_load_lds_dwordx4 v[202:203], off
	s_mov_b32 m0, s36
	v_lshl_add_u64 v[202:203], v[244:245], 0, s[76:77]
	global_load_lds_dwordx4 v[202:203], off
	s_setprio 1
	s_waitcnt vmcnt(8) lgkmcnt(0)
	s_barrier
	v_mfma_f32_16x16x32_bf16 v[62:65], v[114:117], v[162:165], v[62:65]
	v_mfma_f32_16x16x32_bf16 v[58:61], v[122:125], v[162:165], v[58:61]
	v_mfma_f32_16x16x32_bf16 v[50:53], v[114:117], v[216:219], v[50:53]
	v_mfma_f32_16x16x32_bf16 v[42:45], v[122:125], v[216:219], v[42:45]
	v_mfma_f32_16x16x32_bf16 v[34:37], v[114:117], v[224:227], v[34:37]
	v_mfma_f32_16x16x32_bf16 v[26:29], v[122:125], v[224:227], v[26:29]
	v_mfma_f32_16x16x32_bf16 v[18:21], v[114:117], v[232:235], v[18:21]
	v_mfma_f32_16x16x32_bf16 v[10:13], v[122:125], v[232:235], v[10:13]
	v_mfma_f32_16x16x32_bf16 v[62:65], v[118:121], v[166:169], v[62:65]
	v_mfma_f32_16x16x32_bf16 v[58:61], v[126:129], v[166:169], v[58:61]
	v_mfma_f32_16x16x32_bf16 v[50:53], v[118:121], v[220:223], v[50:53]
	v_mfma_f32_16x16x32_bf16 v[42:45], v[126:129], v[220:223], v[42:45]
	v_mfma_f32_16x16x32_bf16 v[34:37], v[118:121], v[228:231], v[34:37]
	v_mfma_f32_16x16x32_bf16 v[26:29], v[126:129], v[228:231], v[26:29]
	v_mfma_f32_16x16x32_bf16 v[18:21], v[118:121], v[236:239], v[18:21]
	v_mfma_f32_16x16x32_bf16 v[10:13], v[126:129], v[236:239], v[10:13]
	v_mfma_f32_16x16x32_bf16 v[54:57], v[146:149], v[162:165], v[54:57]
	v_mfma_f32_16x16x32_bf16 v[46:49], v[154:157], v[162:165], v[46:49]
	v_mfma_f32_16x16x32_bf16 v[38:41], v[146:149], v[216:219], v[38:41]
	v_mfma_f32_16x16x32_bf16 v[30:33], v[154:157], v[216:219], v[30:33]
	v_mfma_f32_16x16x32_bf16 v[22:25], v[146:149], v[224:227], v[22:25]
	v_mfma_f32_16x16x32_bf16 v[14:17], v[154:157], v[224:227], v[14:17]
	v_mfma_f32_16x16x32_bf16 v[6:9], v[146:149], v[232:235], v[6:9]
	v_mfma_f32_16x16x32_bf16 v[2:5], v[154:157], v[232:235], v[2:5]
	v_mfma_f32_16x16x32_bf16 v[54:57], v[150:153], v[166:169], v[54:57]
	v_mfma_f32_16x16x32_bf16 v[46:49], v[158:161], v[166:169], v[46:49]
	v_mfma_f32_16x16x32_bf16 v[38:41], v[150:153], v[220:223], v[38:41]
	v_mfma_f32_16x16x32_bf16 v[30:33], v[158:161], v[220:223], v[30:33]
	v_mfma_f32_16x16x32_bf16 v[22:25], v[150:153], v[228:231], v[22:25]
	v_mfma_f32_16x16x32_bf16 v[14:17], v[158:161], v[228:231], v[14:17]
	v_mfma_f32_16x16x32_bf16 v[6:9], v[150:153], v[236:239], v[6:9]
	v_mfma_f32_16x16x32_bf16 v[2:5], v[158:161], v[236:239], v[2:5]
	s_setprio 0
	s_barrier
	s_add_u32 s10, s10, 0x100
	s_addc_u32 s11, s11, 0
	s_add_u32 vcc_lo, vcc_lo, 0x100
	s_addc_u32 vcc_hi, vcc_hi, 0
	s_cmp_ge_i32 s66, s18
	s_mov_b32 s94, s66
	s_cbranch_scc0 .LBB0_1428
	s_and_b64 vcc, exec, s[82:83]
	s_cbranch_vccz .LBB0_1431
	s_barrier

.LBB0_1618:
	s_add_u32 s24, s96, s20
	s_addc_u32 s25, s97, s21
	s_and_b64 s[14:15], s[4:5], exec
	s_cselect_b32 s14, s25, s29
	s_cselect_b32 s15, s24, s28
	s_add_u32 s26, s2, s22
	s_addc_u32 s27, s3, s23
	s_and_b64 s[36:37], s[4:5], exec
	s_cselect_b32 s17, s27, s31
	s_cselect_b32 s49, s26, s30
	s_add_u32 s28, s28, 0x40080
	s_addc_u32 s29, s29, 0
	s_add_u32 s50, s30, 0x100
	s_addc_u32 s51, s31, 0
	s_mov_b32 s62, -2
	ds_read_b128 v[154:157], v150
	ds_read_b128 v[158:161], v150 offset:1024
	ds_read_b128 v[162:165], v150 offset:2048
	ds_read_b128 v[166:169], v150 offset:3072
	ds_read_b128 v[170:173], v151
	ds_read_b128 v[174:177], v151 offset:1024
	ds_read_b128 v[178:181], v151 offset:2048
	ds_read_b128 v[182:185], v151 offset:3072
	s_add_u32 s30, s28, 0xfffc0080
	s_addc_u32 s31, s29, -1
	s_cmp_eq_u32 s62, 12
	s_cselect_b32 s37, s14, s31
	s_cselect_b32 s36, s15, s30
	s_cselect_b32 s31, s17, s51
	s_cselect_b32 s30, s49, s50
	v_lshl_add_u64 v[146:147], s[28:29], 0, v[138:139]
	s_add_i32 m0, s19, 0xc000
	ds_read_b128 v[186:189], v152
	ds_read_b128 v[190:193], v152 offset:1024
	ds_read_b128 v[194:197], v152 offset:2048
	ds_read_b128 v[198:201], v152 offset:3072
	ds_read_b128 v[206:209], v152 offset:4096
	ds_read_b128 v[210:213], v152 offset:5120
	ds_read_b128 v[214:217], v152 offset:6144
	ds_read_b128 v[218:221], v152 offset:7168
	global_load_lds_dwordx4 v[146:147], off
	s_add_i32 m0, s19, 0xe000
	v_lshl_add_u64 v[146:147], s[28:29], 0, v[140:141]
	global_load_lds_dwordx4 v[146:147], off
	s_setprio 1
	s_waitcnt vmcnt(8) lgkmcnt(0)
	s_barrier
	v_mfma_f32_16x16x32_bf16 v[126:129], v[154:157], v[186:189], 0
	v_mfma_f32_16x16x32_bf16 v[122:125], v[162:165], v[186:189], 0
	v_mfma_f32_16x16x32_bf16 v[110:113], v[154:157], v[194:197], 0
	v_mfma_f32_16x16x32_bf16 v[106:109], v[162:165], v[194:197], 0
	v_mfma_f32_16x16x32_bf16 v[94:97], v[154:157], v[206:209], 0
	v_mfma_f32_16x16x32_bf16 v[90:93], v[162:165], v[206:209], 0
	v_mfma_f32_16x16x32_bf16 v[78:81], v[154:157], v[214:217], 0
	v_mfma_f32_16x16x32_bf16 v[74:77], v[162:165], v[214:217], 0
	v_mfma_f32_16x16x32_bf16 v[126:129], v[158:161], v[190:193], v[126:129]
	v_mfma_f32_16x16x32_bf16 v[122:125], v[166:169], v[190:193], v[122:125]
	v_mfma_f32_16x16x32_bf16 v[110:113], v[158:161], v[198:201], v[110:113]
	v_mfma_f32_16x16x32_bf16 v[106:109], v[166:169], v[198:201], v[106:109]
	v_mfma_f32_16x16x32_bf16 v[94:97], v[158:161], v[210:213], v[94:97]
	v_mfma_f32_16x16x32_bf16 v[90:93], v[166:169], v[210:213], v[90:93]
	v_mfma_f32_16x16x32_bf16 v[78:81], v[158:161], v[218:221], v[78:81]
	v_mfma_f32_16x16x32_bf16 v[74:77], v[166:169], v[218:221], v[74:77]
	v_mfma_f32_16x16x32_bf16 v[118:121], v[170:173], v[186:189], 0
	v_mfma_f32_16x16x32_bf16 v[114:117], v[178:181], v[186:189], 0
	v_mfma_f32_16x16x32_bf16 v[102:105], v[170:173], v[194:197], 0
	v_mfma_f32_16x16x32_bf16 v[98:101], v[178:181], v[194:197], 0
	v_mfma_f32_16x16x32_bf16 v[86:89], v[170:173], v[206:209], 0
	v_mfma_f32_16x16x32_bf16 v[82:85], v[178:181], v[206:209], 0
	v_mfma_f32_16x16x32_bf16 v[70:73], v[170:173], v[214:217], 0
	v_mfma_f32_16x16x32_bf16 v[66:69], v[178:181], v[214:217], 0
	v_mfma_f32_16x16x32_bf16 v[118:121], v[174:177], v[190:193], v[118:121]
	v_mfma_f32_16x16x32_bf16 v[114:117], v[182:185], v[190:193], v[114:117]
	v_mfma_f32_16x16x32_bf16 v[102:105], v[174:177], v[198:201], v[102:105]
	v_mfma_f32_16x16x32_bf16 v[98:101], v[182:185], v[198:201], v[98:101]
	v_mfma_f32_16x16x32_bf16 v[86:89], v[174:177], v[210:213], v[86:89]
	v_mfma_f32_16x16x32_bf16 v[82:85], v[182:185], v[210:213], v[82:85]
	v_mfma_f32_16x16x32_bf16 v[70:73], v[174:177], v[218:221], v[70:73]
	v_mfma_f32_16x16x32_bf16 v[66:69], v[182:185], v[218:221], v[66:69]
	s_setprio 0
	s_barrier
	s_add_i32 s63, s45, s12
	v_lshl_add_u64 v[146:147], s[30:31], 0, v[134:135]
	s_mov_b32 m0, s63
	ds_read_b128 v[186:189], v152 offset:16384
	ds_read_b128 v[190:193], v152 offset:17408
	ds_read_b128 v[194:197], v152 offset:18432
	ds_read_b128 v[198:201], v152 offset:19456
	ds_read_b128 v[206:209], v152 offset:20480
	ds_read_b128 v[210:213], v152 offset:21504
	ds_read_b128 v[214:217], v152 offset:22528
	ds_read_b128 v[218:221], v152 offset:23552
	global_load_lds_dwordx4 v[146:147], off
	s_add_i32 m0, s63, 0x2000
	s_add_u32 s64, s30, 0x40000
	v_lshl_add_u64 v[202:203], s[30:31], 0, v[130:131]
	s_addc_u32 s65, s31, 0
	s_add_i32 s63, s46, s12
	global_load_lds_dwordx4 v[202:203], off
	v_lshl_add_u64 v[222:223], s[64:65], 0, v[134:135]
	s_mov_b32 m0, s63
	v_lshl_add_u64 v[224:225], s[36:37], 0, v[132:133]
	global_load_lds_dwordx4 v[222:223], off
	s_add_i32 m0, s63, 0x2000
	v_lshl_add_u64 v[222:223], s[64:65], 0, v[130:131]
	global_load_lds_dwordx4 v[222:223], off
	s_mov_b32 m0, s19
	v_lshl_add_u64 v[222:223], s[36:37], 0, v[136:137]
	global_load_lds_dwordx4 v[222:223], off
	s_mov_b32 m0, s33
	s_nop 0
	global_load_lds_dwordx4 v[224:225], off
	s_setprio 1
	s_waitcnt vmcnt(8) lgkmcnt(0)
	s_barrier
	v_mfma_f32_16x16x32_bf16 v[62:65], v[154:157], v[186:189], 0
	v_mfma_f32_16x16x32_bf16 v[58:61], v[162:165], v[186:189], 0
	v_mfma_f32_16x16x32_bf16 v[46:49], v[154:157], v[194:197], 0
	v_mfma_f32_16x16x32_bf16 v[42:45], v[162:165], v[194:197], 0
	v_mfma_f32_16x16x32_bf16 v[30:33], v[154:157], v[206:209], 0
	v_mfma_f32_16x16x32_bf16 v[26:29], v[162:165], v[206:209], 0
	v_mfma_f32_16x16x32_bf16 v[14:17], v[154:157], v[214:217], 0
	v_mfma_f32_16x16x32_bf16 v[10:13], v[162:165], v[214:217], 0
	v_mfma_f32_16x16x32_bf16 v[62:65], v[158:161], v[190:193], v[62:65]
	v_mfma_f32_16x16x32_bf16 v[58:61], v[166:169], v[190:193], v[58:61]
	v_mfma_f32_16x16x32_bf16 v[46:49], v[158:161], v[198:201], v[46:49]
	v_mfma_f32_16x16x32_bf16 v[42:45], v[166:169], v[198:201], v[42:45]
	v_mfma_f32_16x16x32_bf16 v[30:33], v[158:161], v[210:213], v[30:33]
	v_mfma_f32_16x16x32_bf16 v[26:29], v[166:169], v[210:213], v[26:29]
	v_mfma_f32_16x16x32_bf16 v[14:17], v[158:161], v[218:221], v[14:17]
	v_mfma_f32_16x16x32_bf16 v[10:13], v[166:169], v[218:221], v[10:13]
	v_mfma_f32_16x16x32_bf16 v[54:57], v[170:173], v[186:189], 0
	v_mfma_f32_16x16x32_bf16 v[50:53], v[178:181], v[186:189], 0
	v_mfma_f32_16x16x32_bf16 v[38:41], v[170:173], v[194:197], 0
	v_mfma_f32_16x16x32_bf16 v[34:37], v[178:181], v[194:197], 0
	v_mfma_f32_16x16x32_bf16 v[22:25], v[170:173], v[206:209], 0
	v_mfma_f32_16x16x32_bf16 v[18:21], v[178:181], v[206:209], 0
	v_mfma_f32_16x16x32_bf16 v[6:9], v[170:173], v[214:217], 0
	v_mfma_f32_16x16x32_bf16 v[2:5], v[178:181], v[214:217], 0
	v_mfma_f32_16x16x32_bf16 v[54:57], v[174:177], v[190:193], v[54:57]
	v_mfma_f32_16x16x32_bf16 v[50:53], v[182:185], v[190:193], v[50:53]
	v_mfma_f32_16x16x32_bf16 v[38:41], v[174:177], v[198:201], v[38:41]
	v_mfma_f32_16x16x32_bf16 v[34:37], v[182:185], v[198:201], v[34:37]
	v_mfma_f32_16x16x32_bf16 v[22:25], v[174:177], v[210:213], v[22:25]
	v_mfma_f32_16x16x32_bf16 v[18:21], v[182:185], v[210:213], v[18:21]
	v_mfma_f32_16x16x32_bf16 v[6:9], v[174:177], v[218:221], v[6:9]
	v_mfma_f32_16x16x32_bf16 v[2:5], v[182:185], v[218:221], v[2:5]
	s_setprio 0
	s_barrier
	s_add_i32 s63, 0, 0x18000
	v_add_u32_e32 v153, s63, v149
	s_add_i32 s64, 0, 0x1c000
	ds_read_b128 v[154:157], v153
	ds_read_b128 v[158:161], v153 offset:1024
	ds_read_b128 v[162:165], v153 offset:2048
	ds_read_b128 v[166:169], v153 offset:3072
	v_add_u32_e32 v153, s64, v149
	ds_read_b128 v[170:173], v153
	ds_read_b128 v[174:177], v153 offset:1024
	ds_read_b128 v[178:181], v153 offset:2048
	ds_read_b128 v[182:185], v153 offset:3072
	s_add_u32 s36, s36, 0x40000
	s_addc_u32 s37, s37, 0
	s_mov_b32 m0, s35
	v_lshl_add_u64 v[226:227], s[36:37], 0, v[136:137]
	ds_read_b128 v[186:189], v152 offset:32768
	ds_read_b128 v[190:193], v152 offset:33792
	ds_read_b128 v[194:197], v152 offset:34816
	ds_read_b128 v[198:201], v152 offset:35840
	ds_read_b128 v[206:209], v152 offset:36864
	ds_read_b128 v[210:213], v152 offset:37888
	ds_read_b128 v[214:217], v152 offset:38912
	ds_read_b128 v[218:221], v152 offset:39936
	global_load_lds_dwordx4 v[226:227], off
	s_mov_b32 m0, s38
	v_lshl_add_u64 v[226:227], s[36:37], 0, v[132:133]
	global_load_lds_dwordx4 v[226:227], off
	s_setprio 1
	s_waitcnt vmcnt(8) lgkmcnt(0)
	s_barrier
	v_mfma_f32_16x16x32_bf16 v[126:129], v[154:157], v[186:189], v[126:129]
	v_mfma_f32_16x16x32_bf16 v[122:125], v[162:165], v[186:189], v[122:125]
	v_mfma_f32_16x16x32_bf16 v[110:113], v[154:157], v[194:197], v[110:113]
	v_mfma_f32_16x16x32_bf16 v[106:109], v[162:165], v[194:197], v[106:109]
	v_mfma_f32_16x16x32_bf16 v[94:97], v[154:157], v[206:209], v[94:97]
	v_mfma_f32_16x16x32_bf16 v[90:93], v[162:165], v[206:209], v[90:93]
	v_mfma_f32_16x16x32_bf16 v[78:81], v[154:157], v[214:217], v[78:81]
	v_mfma_f32_16x16x32_bf16 v[74:77], v[162:165], v[214:217], v[74:77]
	v_mfma_f32_16x16x32_bf16 v[126:129], v[158:161], v[190:193], v[126:129]
	v_mfma_f32_16x16x32_bf16 v[122:125], v[166:169], v[190:193], v[122:125]
	v_mfma_f32_16x16x32_bf16 v[110:113], v[158:161], v[198:201], v[110:113]
	v_mfma_f32_16x16x32_bf16 v[106:109], v[166:169], v[198:201], v[106:109]
	v_mfma_f32_16x16x32_bf16 v[94:97], v[158:161], v[210:213], v[94:97]
	v_mfma_f32_16x16x32_bf16 v[90:93], v[166:169], v[210:213], v[90:93]
	v_mfma_f32_16x16x32_bf16 v[78:81], v[158:161], v[218:221], v[78:81]
	v_mfma_f32_16x16x32_bf16 v[74:77], v[166:169], v[218:221], v[74:77]
	v_mfma_f32_16x16x32_bf16 v[118:121], v[170:173], v[186:189], v[118:121]
	v_mfma_f32_16x16x32_bf16 v[114:117], v[178:181], v[186:189], v[114:117]
	v_mfma_f32_16x16x32_bf16 v[102:105], v[170:173], v[194:197], v[102:105]
	v_mfma_f32_16x16x32_bf16 v[98:101], v[178:181], v[194:197], v[98:101]
	v_mfma_f32_16x16x32_bf16 v[86:89], v[170:173], v[206:209], v[86:89]
	v_mfma_f32_16x16x32_bf16 v[82:85], v[178:181], v[206:209], v[82:85]
	v_mfma_f32_16x16x32_bf16 v[70:73], v[170:173], v[214:217], v[70:73]
	v_mfma_f32_16x16x32_bf16 v[66:69], v[178:181], v[214:217], v[66:69]
	v_mfma_f32_16x16x32_bf16 v[118:121], v[174:177], v[190:193], v[118:121]
	v_mfma_f32_16x16x32_bf16 v[114:117], v[182:185], v[190:193], v[114:117]
	v_mfma_f32_16x16x32_bf16 v[102:105], v[174:177], v[198:201], v[102:105]
	v_mfma_f32_16x16x32_bf16 v[98:101], v[182:185], v[198:201], v[98:101]
	v_mfma_f32_16x16x32_bf16 v[86:89], v[174:177], v[210:213], v[86:89]
	v_mfma_f32_16x16x32_bf16 v[82:85], v[182:185], v[210:213], v[82:85]
	v_mfma_f32_16x16x32_bf16 v[70:73], v[174:177], v[218:221], v[70:73]
	v_mfma_f32_16x16x32_bf16 v[66:69], v[182:185], v[218:221], v[66:69]
	s_setprio 0
	s_barrier
	s_add_i32 s36, s63, s12
	v_lshl_add_u64 v[146:147], v[146:147], 0, s[8:9]
	s_mov_b32 m0, s36
	ds_read_b128 v[186:189], v152 offset:49152
	ds_read_b128 v[190:193], v152 offset:50176
	ds_read_b128 v[194:197], v152 offset:51200
	ds_read_b128 v[198:201], v152 offset:52224
	ds_read_b128 v[206:209], v152 offset:53248
	ds_read_b128 v[210:213], v152 offset:54272
	ds_read_b128 v[214:217], v152 offset:55296
	ds_read_b128 v[218:221], v152 offset:56320
	global_load_lds_dwordx4 v[146:147], off
	s_add_i32 m0, s36, 0x2000
	s_add_u32 s30, s30, 0x40080
	v_lshl_add_u64 v[146:147], v[202:203], 0, s[8:9]
	s_addc_u32 s31, s31, 0
	s_add_i32 s36, s64, s12
	global_load_lds_dwordx4 v[146:147], off
	s_mov_b32 m0, s36
	v_lshl_add_u64 v[146:147], s[30:31], 0, v[134:135]
	global_load_lds_dwordx4 v[146:147], off
	s_add_i32 m0, s36, 0x2000
	v_lshl_add_u64 v[146:147], s[30:31], 0, v[130:131]
	global_load_lds_dwordx4 v[146:147], off
	s_mov_b32 m0, s42
	v_lshl_add_u64 v[146:147], v[222:223], 0, s[8:9]
	global_load_lds_dwordx4 v[146:147], off
	s_mov_b32 m0, s43
	v_lshl_add_u64 v[146:147], v[224:225], 0, s[8:9]
	global_load_lds_dwordx4 v[146:147], off
	s_setprio 1
	s_waitcnt vmcnt(8) lgkmcnt(0)
	s_barrier
	v_mfma_f32_16x16x32_bf16 v[62:65], v[154:157], v[186:189], v[62:65]
	v_mfma_f32_16x16x32_bf16 v[58:61], v[162:165], v[186:189], v[58:61]
	v_mfma_f32_16x16x32_bf16 v[46:49], v[154:157], v[194:197], v[46:49]
	v_mfma_f32_16x16x32_bf16 v[42:45], v[162:165], v[194:197], v[42:45]
	v_mfma_f32_16x16x32_bf16 v[30:33], v[154:157], v[206:209], v[30:33]
	v_mfma_f32_16x16x32_bf16 v[26:29], v[162:165], v[206:209], v[26:29]
	v_mfma_f32_16x16x32_bf16 v[14:17], v[154:157], v[214:217], v[14:17]
	v_mfma_f32_16x16x32_bf16 v[10:13], v[162:165], v[214:217], v[10:13]
	v_mfma_f32_16x16x32_bf16 v[62:65], v[158:161], v[190:193], v[62:65]
	v_mfma_f32_16x16x32_bf16 v[58:61], v[166:169], v[190:193], v[58:61]
	v_mfma_f32_16x16x32_bf16 v[46:49], v[158:161], v[198:201], v[46:49]
	v_mfma_f32_16x16x32_bf16 v[42:45], v[166:169], v[198:201], v[42:45]
	v_mfma_f32_16x16x32_bf16 v[30:33], v[158:161], v[210:213], v[30:33]
	v_mfma_f32_16x16x32_bf16 v[26:29], v[166:169], v[210:213], v[26:29]
	v_mfma_f32_16x16x32_bf16 v[14:17], v[158:161], v[218:221], v[14:17]
	v_mfma_f32_16x16x32_bf16 v[10:13], v[166:169], v[218:221], v[10:13]
	v_mfma_f32_16x16x32_bf16 v[54:57], v[170:173], v[186:189], v[54:57]
	v_mfma_f32_16x16x32_bf16 v[50:53], v[178:181], v[186:189], v[50:53]
	v_mfma_f32_16x16x32_bf16 v[38:41], v[170:173], v[194:197], v[38:41]
	v_mfma_f32_16x16x32_bf16 v[34:37], v[178:181], v[194:197], v[34:37]
	v_mfma_f32_16x16x32_bf16 v[22:25], v[170:173], v[206:209], v[22:25]
	v_mfma_f32_16x16x32_bf16 v[18:21], v[178:181], v[206:209], v[18:21]
	v_mfma_f32_16x16x32_bf16 v[6:9], v[170:173], v[214:217], v[6:9]
	v_mfma_f32_16x16x32_bf16 v[2:5], v[178:181], v[214:217], v[2:5]
	v_mfma_f32_16x16x32_bf16 v[54:57], v[174:177], v[190:193], v[54:57]
	v_mfma_f32_16x16x32_bf16 v[50:53], v[182:185], v[190:193], v[50:53]
	v_mfma_f32_16x16x32_bf16 v[38:41], v[174:177], v[198:201], v[38:41]
	v_mfma_f32_16x16x32_bf16 v[34:37], v[182:185], v[198:201], v[34:37]
	v_mfma_f32_16x16x32_bf16 v[22:25], v[174:177], v[210:213], v[22:25]
	v_mfma_f32_16x16x32_bf16 v[18:21], v[182:185], v[210:213], v[18:21]
	v_mfma_f32_16x16x32_bf16 v[6:9], v[174:177], v[218:221], v[6:9]
	v_mfma_f32_16x16x32_bf16 v[2:5], v[182:185], v[218:221], v[2:5]
	s_setprio 0
	s_barrier
	s_add_i32 s62, s62, 2
	s_add_u32 s28, s28, 0x100
	s_addc_u32 s29, s29, 0
	s_add_u32 s50, s50, 0x100
	s_addc_u32 s51, s51, 0
	s_cmp_gt_u32 s62, 13
.LBB0_1619:
	ds_read_b128 v[154:157], v150
	ds_read_b128 v[158:161], v150 offset:1024
	ds_read_b128 v[162:165], v150 offset:2048
	ds_read_b128 v[166:169], v150 offset:3072
	ds_read_b128 v[170:173], v151
	ds_read_b128 v[174:177], v151 offset:1024
	ds_read_b128 v[178:181], v151 offset:2048
	ds_read_b128 v[182:185], v151 offset:3072
	s_add_u32 s30, s28, 0xfffc0080
	s_addc_u32 s31, s29, -1
	s_cmp_eq_u32 s62, 12
	s_cselect_b32 s37, s14, s31
	s_cselect_b32 s36, s15, s30
	s_cselect_b32 s31, s17, s51
	s_cselect_b32 s30, s49, s50
	v_lshl_add_u64 v[146:147], s[28:29], 0, v[138:139]
	s_add_i32 m0, s19, 0xc000
	ds_read_b128 v[186:189], v152
	ds_read_b128 v[190:193], v152 offset:1024
	ds_read_b128 v[194:197], v152 offset:2048
	ds_read_b128 v[198:201], v152 offset:3072
	ds_read_b128 v[206:209], v152 offset:4096
	ds_read_b128 v[210:213], v152 offset:5120
	ds_read_b128 v[214:217], v152 offset:6144
	ds_read_b128 v[218:221], v152 offset:7168
	global_load_lds_dwordx4 v[146:147], off
	s_add_i32 m0, s19, 0xe000
	v_lshl_add_u64 v[146:147], s[28:29], 0, v[140:141]
	global_load_lds_dwordx4 v[146:147], off
	s_setprio 1
	s_waitcnt vmcnt(8) lgkmcnt(0)
	s_barrier
	v_mfma_f32_16x16x32_bf16 v[126:129], v[154:157], v[186:189], v[126:129]
	v_mfma_f32_16x16x32_bf16 v[122:125], v[162:165], v[186:189], v[122:125]
	v_mfma_f32_16x16x32_bf16 v[110:113], v[154:157], v[194:197], v[110:113]
	v_mfma_f32_16x16x32_bf16 v[106:109], v[162:165], v[194:197], v[106:109]
	v_mfma_f32_16x16x32_bf16 v[94:97], v[154:157], v[206:209], v[94:97]
	v_mfma_f32_16x16x32_bf16 v[90:93], v[162:165], v[206:209], v[90:93]
	v_mfma_f32_16x16x32_bf16 v[78:81], v[154:157], v[214:217], v[78:81]
	v_mfma_f32_16x16x32_bf16 v[74:77], v[162:165], v[214:217], v[74:77]
	v_mfma_f32_16x16x32_bf16 v[126:129], v[158:161], v[190:193], v[126:129]
	v_mfma_f32_16x16x32_bf16 v[122:125], v[166:169], v[190:193], v[122:125]
	v_mfma_f32_16x16x32_bf16 v[110:113], v[158:161], v[198:201], v[110:113]
	v_mfma_f32_16x16x32_bf16 v[106:109], v[166:169], v[198:201], v[106:109]
	v_mfma_f32_16x16x32_bf16 v[94:97], v[158:161], v[210:213], v[94:97]
	v_mfma_f32_16x16x32_bf16 v[90:93], v[166:169], v[210:213], v[90:93]
	v_mfma_f32_16x16x32_bf16 v[78:81], v[158:161], v[218:221], v[78:81]
	v_mfma_f32_16x16x32_bf16 v[74:77], v[166:169], v[218:221], v[74:77]
	v_mfma_f32_16x16x32_bf16 v[118:121], v[170:173], v[186:189], v[118:121]
	v_mfma_f32_16x16x32_bf16 v[114:117], v[178:181], v[186:189], v[114:117]
	v_mfma_f32_16x16x32_bf16 v[102:105], v[170:173], v[194:197], v[102:105]
	v_mfma_f32_16x16x32_bf16 v[98:101], v[178:181], v[194:197], v[98:101]
	v_mfma_f32_16x16x32_bf16 v[86:89], v[170:173], v[206:209], v[86:89]
	v_mfma_f32_16x16x32_bf16 v[82:85], v[178:181], v[206:209], v[82:85]
	v_mfma_f32_16x16x32_bf16 v[70:73], v[170:173], v[214:217], v[70:73]
	v_mfma_f32_16x16x32_bf16 v[66:69], v[178:181], v[214:217], v[66:69]
	v_mfma_f32_16x16x32_bf16 v[118:121], v[174:177], v[190:193], v[118:121]
	v_mfma_f32_16x16x32_bf16 v[114:117], v[182:185], v[190:193], v[114:117]
	v_mfma_f32_16x16x32_bf16 v[102:105], v[174:177], v[198:201], v[102:105]
	v_mfma_f32_16x16x32_bf16 v[98:101], v[182:185], v[198:201], v[98:101]
	v_mfma_f32_16x16x32_bf16 v[86:89], v[174:177], v[210:213], v[86:89]
	v_mfma_f32_16x16x32_bf16 v[82:85], v[182:185], v[210:213], v[82:85]
	v_mfma_f32_16x16x32_bf16 v[70:73], v[174:177], v[218:221], v[70:73]
	v_mfma_f32_16x16x32_bf16 v[66:69], v[182:185], v[218:221], v[66:69]
	s_setprio 0
	s_barrier
	s_add_i32 s63, s45, s12
	v_lshl_add_u64 v[146:147], s[30:31], 0, v[134:135]
	s_mov_b32 m0, s63
	ds_read_b128 v[186:189], v152 offset:16384
	ds_read_b128 v[190:193], v152 offset:17408
	ds_read_b128 v[194:197], v152 offset:18432
	ds_read_b128 v[198:201], v152 offset:19456
	ds_read_b128 v[206:209], v152 offset:20480
	ds_read_b128 v[210:213], v152 offset:21504
	ds_read_b128 v[214:217], v152 offset:22528
	ds_read_b128 v[218:221], v152 offset:23552
	global_load_lds_dwordx4 v[146:147], off
	s_add_i32 m0, s63, 0x2000
	s_add_u32 s64, s30, 0x40000
	v_lshl_add_u64 v[202:203], s[30:31], 0, v[130:131]
	s_addc_u32 s65, s31, 0
	s_add_i32 s63, s46, s12
	global_load_lds_dwordx4 v[202:203], off
	v_lshl_add_u64 v[222:223], s[64:65], 0, v[134:135]
	s_mov_b32 m0, s63
	v_lshl_add_u64 v[224:225], s[36:37], 0, v[132:133]
	global_load_lds_dwordx4 v[222:223], off
	s_add_i32 m0, s63, 0x2000
	v_lshl_add_u64 v[222:223], s[64:65], 0, v[130:131]
	global_load_lds_dwordx4 v[222:223], off
	s_mov_b32 m0, s19
	v_lshl_add_u64 v[222:223], s[36:37], 0, v[136:137]
	global_load_lds_dwordx4 v[222:223], off
	s_mov_b32 m0, s33
	s_nop 0
	global_load_lds_dwordx4 v[224:225], off
	s_setprio 1
	s_waitcnt vmcnt(8) lgkmcnt(0)
	s_barrier
	v_mfma_f32_16x16x32_bf16 v[62:65], v[154:157], v[186:189], v[62:65]
	v_mfma_f32_16x16x32_bf16 v[58:61], v[162:165], v[186:189], v[58:61]
	v_mfma_f32_16x16x32_bf16 v[46:49], v[154:157], v[194:197], v[46:49]
	v_mfma_f32_16x16x32_bf16 v[42:45], v[162:165], v[194:197], v[42:45]
	v_mfma_f32_16x16x32_bf16 v[30:33], v[154:157], v[206:209], v[30:33]
	v_mfma_f32_16x16x32_bf16 v[26:29], v[162:165], v[206:209], v[26:29]
	v_mfma_f32_16x16x32_bf16 v[14:17], v[154:157], v[214:217], v[14:17]
	v_mfma_f32_16x16x32_bf16 v[10:13], v[162:165], v[214:217], v[10:13]
	v_mfma_f32_16x16x32_bf16 v[62:65], v[158:161], v[190:193], v[62:65]
	v_mfma_f32_16x16x32_bf16 v[58:61], v[166:169], v[190:193], v[58:61]
	v_mfma_f32_16x16x32_bf16 v[46:49], v[158:161], v[198:201], v[46:49]
	v_mfma_f32_16x16x32_bf16 v[42:45], v[166:169], v[198:201], v[42:45]
	v_mfma_f32_16x16x32_bf16 v[30:33], v[158:161], v[210:213], v[30:33]
	v_mfma_f32_16x16x32_bf16 v[26:29], v[166:169], v[210:213], v[26:29]
	v_mfma_f32_16x16x32_bf16 v[14:17], v[158:161], v[218:221], v[14:17]
	v_mfma_f32_16x16x32_bf16 v[10:13], v[166:169], v[218:221], v[10:13]
	v_mfma_f32_16x16x32_bf16 v[54:57], v[170:173], v[186:189], v[54:57]
	v_mfma_f32_16x16x32_bf16 v[50:53], v[178:181], v[186:189], v[50:53]
	v_mfma_f32_16x16x32_bf16 v[38:41], v[170:173], v[194:197], v[38:41]
	v_mfma_f32_16x16x32_bf16 v[34:37], v[178:181], v[194:197], v[34:37]
	v_mfma_f32_16x16x32_bf16 v[22:25], v[170:173], v[206:209], v[22:25]
	v_mfma_f32_16x16x32_bf16 v[18:21], v[178:181], v[206:209], v[18:21]
	v_mfma_f32_16x16x32_bf16 v[6:9], v[170:173], v[214:217], v[6:9]
	v_mfma_f32_16x16x32_bf16 v[2:5], v[178:181], v[214:217], v[2:5]
	v_mfma_f32_16x16x32_bf16 v[54:57], v[174:177], v[190:193], v[54:57]
	v_mfma_f32_16x16x32_bf16 v[50:53], v[182:185], v[190:193], v[50:53]
	v_mfma_f32_16x16x32_bf16 v[38:41], v[174:177], v[198:201], v[38:41]
	v_mfma_f32_16x16x32_bf16 v[34:37], v[182:185], v[198:201], v[34:37]
	v_mfma_f32_16x16x32_bf16 v[22:25], v[174:177], v[210:213], v[22:25]
	v_mfma_f32_16x16x32_bf16 v[18:21], v[182:185], v[210:213], v[18:21]
	v_mfma_f32_16x16x32_bf16 v[6:9], v[174:177], v[218:221], v[6:9]
	v_mfma_f32_16x16x32_bf16 v[2:5], v[182:185], v[218:221], v[2:5]
	s_setprio 0
	s_barrier
	s_add_i32 s63, 0, 0x18000
	v_add_u32_e32 v153, s63, v149
	s_add_i32 s64, 0, 0x1c000
	ds_read_b128 v[154:157], v153
	ds_read_b128 v[158:161], v153 offset:1024
	ds_read_b128 v[162:165], v153 offset:2048
	ds_read_b128 v[166:169], v153 offset:3072
	v_add_u32_e32 v153, s64, v149
	ds_read_b128 v[170:173], v153
	ds_read_b128 v[174:177], v153 offset:1024
	ds_read_b128 v[178:181], v153 offset:2048
	ds_read_b128 v[182:185], v153 offset:3072
	s_add_u32 s36, s36, 0x40000
	s_addc_u32 s37, s37, 0
	s_mov_b32 m0, s35
	v_lshl_add_u64 v[226:227], s[36:37], 0, v[136:137]
	ds_read_b128 v[186:189], v152 offset:32768
	ds_read_b128 v[190:193], v152 offset:33792
	ds_read_b128 v[194:197], v152 offset:34816
	ds_read_b128 v[198:201], v152 offset:35840
	ds_read_b128 v[206:209], v152 offset:36864
	ds_read_b128 v[210:213], v152 offset:37888
	ds_read_b128 v[214:217], v152 offset:38912
	ds_read_b128 v[218:221], v152 offset:39936
	global_load_lds_dwordx4 v[226:227], off
	s_mov_b32 m0, s38
	v_lshl_add_u64 v[226:227], s[36:37], 0, v[132:133]
	global_load_lds_dwordx4 v[226:227], off
	s_setprio 1
	s_waitcnt vmcnt(8) lgkmcnt(0)
	s_barrier
	v_mfma_f32_16x16x32_bf16 v[126:129], v[154:157], v[186:189], v[126:129]
	v_mfma_f32_16x16x32_bf16 v[122:125], v[162:165], v[186:189], v[122:125]
	v_mfma_f32_16x16x32_bf16 v[110:113], v[154:157], v[194:197], v[110:113]
	v_mfma_f32_16x16x32_bf16 v[106:109], v[162:165], v[194:197], v[106:109]
	v_mfma_f32_16x16x32_bf16 v[94:97], v[154:157], v[206:209], v[94:97]
	v_mfma_f32_16x16x32_bf16 v[90:93], v[162:165], v[206:209], v[90:93]
	v_mfma_f32_16x16x32_bf16 v[78:81], v[154:157], v[214:217], v[78:81]
	v_mfma_f32_16x16x32_bf16 v[74:77], v[162:165], v[214:217], v[74:77]
	v_mfma_f32_16x16x32_bf16 v[126:129], v[158:161], v[190:193], v[126:129]
	v_mfma_f32_16x16x32_bf16 v[122:125], v[166:169], v[190:193], v[122:125]
	v_mfma_f32_16x16x32_bf16 v[110:113], v[158:161], v[198:201], v[110:113]
	v_mfma_f32_16x16x32_bf16 v[106:109], v[166:169], v[198:201], v[106:109]
	v_mfma_f32_16x16x32_bf16 v[94:97], v[158:161], v[210:213], v[94:97]
	v_mfma_f32_16x16x32_bf16 v[90:93], v[166:169], v[210:213], v[90:93]
	v_mfma_f32_16x16x32_bf16 v[78:81], v[158:161], v[218:221], v[78:81]
	v_mfma_f32_16x16x32_bf16 v[74:77], v[166:169], v[218:221], v[74:77]
	v_mfma_f32_16x16x32_bf16 v[118:121], v[170:173], v[186:189], v[118:121]
	v_mfma_f32_16x16x32_bf16 v[114:117], v[178:181], v[186:189], v[114:117]
	v_mfma_f32_16x16x32_bf16 v[102:105], v[170:173], v[194:197], v[102:105]
	v_mfma_f32_16x16x32_bf16 v[98:101], v[178:181], v[194:197], v[98:101]
	v_mfma_f32_16x16x32_bf16 v[86:89], v[170:173], v[206:209], v[86:89]
	v_mfma_f32_16x16x32_bf16 v[82:85], v[178:181], v[206:209], v[82:85]
	v_mfma_f32_16x16x32_bf16 v[70:73], v[170:173], v[214:217], v[70:73]
	v_mfma_f32_16x16x32_bf16 v[66:69], v[178:181], v[214:217], v[66:69]
	v_mfma_f32_16x16x32_bf16 v[118:121], v[174:177], v[190:193], v[118:121]
	v_mfma_f32_16x16x32_bf16 v[114:117], v[182:185], v[190:193], v[114:117]
	v_mfma_f32_16x16x32_bf16 v[102:105], v[174:177], v[198:201], v[102:105]
	v_mfma_f32_16x16x32_bf16 v[98:101], v[182:185], v[198:201], v[98:101]
	v_mfma_f32_16x16x32_bf16 v[86:89], v[174:177], v[210:213], v[86:89]
	v_mfma_f32_16x16x32_bf16 v[82:85], v[182:185], v[210:213], v[82:85]
	v_mfma_f32_16x16x32_bf16 v[70:73], v[174:177], v[218:221], v[70:73]
	v_mfma_f32_16x16x32_bf16 v[66:69], v[182:185], v[218:221], v[66:69]
	s_setprio 0
	s_barrier
	s_add_i32 s36, s63, s12
	v_lshl_add_u64 v[146:147], v[146:147], 0, s[8:9]
	s_mov_b32 m0, s36
	ds_read_b128 v[186:189], v152 offset:49152
	ds_read_b128 v[190:193], v152 offset:50176
	ds_read_b128 v[194:197], v152 offset:51200
	ds_read_b128 v[198:201], v152 offset:52224
	ds_read_b128 v[206:209], v152 offset:53248
	ds_read_b128 v[210:213], v152 offset:54272
	ds_read_b128 v[214:217], v152 offset:55296
	ds_read_b128 v[218:221], v152 offset:56320
	global_load_lds_dwordx4 v[146:147], off
	s_add_i32 m0, s36, 0x2000
	s_add_u32 s30, s30, 0x40080
	v_lshl_add_u64 v[146:147], v[202:203], 0, s[8:9]
	s_addc_u32 s31, s31, 0
	s_add_i32 s36, s64, s12
	global_load_lds_dwordx4 v[146:147], off
	s_mov_b32 m0, s36
	v_lshl_add_u64 v[146:147], s[30:31], 0, v[134:135]
	global_load_lds_dwordx4 v[146:147], off
	s_add_i32 m0, s36, 0x2000
	v_lshl_add_u64 v[146:147], s[30:31], 0, v[130:131]
	global_load_lds_dwordx4 v[146:147], off
	s_mov_b32 m0, s42
	v_lshl_add_u64 v[146:147], v[222:223], 0, s[8:9]
	global_load_lds_dwordx4 v[146:147], off
	s_mov_b32 m0, s43
	v_lshl_add_u64 v[146:147], v[224:225], 0, s[8:9]
	global_load_lds_dwordx4 v[146:147], off
	s_setprio 1
	s_waitcnt vmcnt(8) lgkmcnt(0)
	s_barrier
	v_mfma_f32_16x16x32_bf16 v[62:65], v[154:157], v[186:189], v[62:65]
	v_mfma_f32_16x16x32_bf16 v[58:61], v[162:165], v[186:189], v[58:61]
	v_mfma_f32_16x16x32_bf16 v[46:49], v[154:157], v[194:197], v[46:49]
	v_mfma_f32_16x16x32_bf16 v[42:45], v[162:165], v[194:197], v[42:45]
	v_mfma_f32_16x16x32_bf16 v[30:33], v[154:157], v[206:209], v[30:33]
	v_mfma_f32_16x16x32_bf16 v[26:29], v[162:165], v[206:209], v[26:29]
	v_mfma_f32_16x16x32_bf16 v[14:17], v[154:157], v[214:217], v[14:17]
	v_mfma_f32_16x16x32_bf16 v[10:13], v[162:165], v[214:217], v[10:13]
	v_mfma_f32_16x16x32_bf16 v[62:65], v[158:161], v[190:193], v[62:65]
	v_mfma_f32_16x16x32_bf16 v[58:61], v[166:169], v[190:193], v[58:61]
	v_mfma_f32_16x16x32_bf16 v[46:49], v[158:161], v[198:201], v[46:49]
	v_mfma_f32_16x16x32_bf16 v[42:45], v[166:169], v[198:201], v[42:45]
	v_mfma_f32_16x16x32_bf16 v[30:33], v[158:161], v[210:213], v[30:33]
	v_mfma_f32_16x16x32_bf16 v[26:29], v[166:169], v[210:213], v[26:29]
	v_mfma_f32_16x16x32_bf16 v[14:17], v[158:161], v[218:221], v[14:17]
	v_mfma_f32_16x16x32_bf16 v[10:13], v[166:169], v[218:221], v[10:13]
	v_mfma_f32_16x16x32_bf16 v[54:57], v[170:173], v[186:189], v[54:57]
	v_mfma_f32_16x16x32_bf16 v[50:53], v[178:181], v[186:189], v[50:53]
	v_mfma_f32_16x16x32_bf16 v[38:41], v[170:173], v[194:197], v[38:41]
	v_mfma_f32_16x16x32_bf16 v[34:37], v[178:181], v[194:197], v[34:37]
	v_mfma_f32_16x16x32_bf16 v[22:25], v[170:173], v[206:209], v[22:25]
	v_mfma_f32_16x16x32_bf16 v[18:21], v[178:181], v[206:209], v[18:21]
	v_mfma_f32_16x16x32_bf16 v[6:9], v[170:173], v[214:217], v[6:9]
	v_mfma_f32_16x16x32_bf16 v[2:5], v[178:181], v[214:217], v[2:5]
	v_mfma_f32_16x16x32_bf16 v[54:57], v[174:177], v[190:193], v[54:57]
	v_mfma_f32_16x16x32_bf16 v[50:53], v[182:185], v[190:193], v[50:53]
	v_mfma_f32_16x16x32_bf16 v[38:41], v[174:177], v[198:201], v[38:41]
	v_mfma_f32_16x16x32_bf16 v[34:37], v[182:185], v[198:201], v[34:37]
	v_mfma_f32_16x16x32_bf16 v[22:25], v[174:177], v[210:213], v[22:25]
	v_mfma_f32_16x16x32_bf16 v[18:21], v[182:185], v[210:213], v[18:21]
	v_mfma_f32_16x16x32_bf16 v[6:9], v[174:177], v[218:221], v[6:9]
	v_mfma_f32_16x16x32_bf16 v[2:5], v[182:185], v[218:221], v[2:5]
	s_setprio 0
	s_barrier
	s_add_i32 s62, s62, 2
	s_add_u32 s28, s28, 0x100
	s_addc_u32 s29, s29, 0
	s_add_u32 s50, s50, 0x100
	s_addc_u32 s51, s51, 0
	s_cmp_gt_u32 s62, 13
	s_cbranch_scc0 .LBB0_1619
	s_and_b64 vcc, exec, s[10:11]
	s_cbranch_vccz .LBB0_1622
	s_barrier

.LBB0_1707:
	v_readlane_b32 s46, v249, 32
	v_readlane_b32 s47, v249, 33
	s_add_u32 s46, s46, s42
	s_addc_u32 s47, s47, s43
	s_and_b64 s[48:49], s[44:45], exec
	s_cselect_b32 s34, s47, s51
	s_cselect_b32 s66, s46, s50
	s_add_u32 s48, s35, s40
	s_addc_u32 s49, s70, s41
	s_and_b64 s[64:65], s[44:45], exec
	s_cselect_b32 s67, s49, s63
	s_cselect_b32 s68, s48, s62
	s_add_i32 s69, s7, -2
	s_add_u32 s50, s50, 0x100080
	s_addc_u32 s51, s51, 0
	s_add_u32 s91, s62, 0x100
	s_addc_u32 s92, s63, 0
	s_mov_b32 s62, 0
	s_waitcnt vmcnt(0)
	ds_read_b128 v[130:133], v168
	ds_read_b128 v[134:137], v168 offset:1024
	ds_read_b128 v[138:141], v168 offset:2048
	ds_read_b128 v[142:145], v168 offset:3072
	ds_read_b128 v[162:165], v169
	ds_read_b128 v[172:175], v169 offset:1024
	ds_read_b128 v[176:179], v169 offset:2048
	ds_read_b128 v[180:183], v169 offset:3072
	s_add_i32 s93, s62, 2
	s_add_u32 s63, s50, 0xfff00080
	s_addc_u32 s64, s51, -1
	s_cmp_eq_u32 s69, s62
	s_cselect_b32 s62, s68, s91
	s_cselect_b32 s65, s34, s64
	s_cselect_b32 s64, s66, s63
	s_cselect_b32 s63, s67, s92
	v_lshl_add_u64 v[218:219], s[50:51], 0, v[156:157]
	s_add_i32 m0, s12, 0xc000
	ds_read_b128 v[184:187], v170
	ds_read_b128 v[188:191], v170 offset:1024
	ds_read_b128 v[192:195], v170 offset:2048
	ds_read_b128 v[196:199], v170 offset:3072
	ds_read_b128 v[200:203], v170 offset:4096
	ds_read_b128 v[206:209], v170 offset:5120
	ds_read_b128 v[210:213], v170 offset:6144
	ds_read_b128 v[214:217], v170 offset:7168
	global_load_lds_dwordx4 v[218:219], off
	s_add_i32 m0, s12, 0xe000
	v_lshl_add_u64 v[218:219], s[50:51], 0, v[158:159]
	global_load_lds_dwordx4 v[218:219], off
	s_setprio 1
	s_waitcnt vmcnt(8) lgkmcnt(0)
	s_barrier
	v_mfma_f32_16x16x32_bf16 v[126:129], v[130:133], v[184:187], 0
	v_mfma_f32_16x16x32_bf16 v[122:125], v[138:141], v[184:187], 0
	v_mfma_f32_16x16x32_bf16 v[110:113], v[130:133], v[192:195], 0
	v_mfma_f32_16x16x32_bf16 v[106:109], v[138:141], v[192:195], 0
	v_mfma_f32_16x16x32_bf16 v[98:101], v[130:133], v[200:203], 0
	v_mfma_f32_16x16x32_bf16 v[90:93], v[138:141], v[200:203], 0
	v_mfma_f32_16x16x32_bf16 v[82:85], v[130:133], v[210:213], 0
	v_mfma_f32_16x16x32_bf16 v[74:77], v[138:141], v[210:213], 0
	v_mfma_f32_16x16x32_bf16 v[126:129], v[134:137], v[188:191], v[126:129]
	v_mfma_f32_16x16x32_bf16 v[122:125], v[142:145], v[188:191], v[122:125]
	v_mfma_f32_16x16x32_bf16 v[110:113], v[134:137], v[196:199], v[110:113]
	v_mfma_f32_16x16x32_bf16 v[106:109], v[142:145], v[196:199], v[106:109]
	v_mfma_f32_16x16x32_bf16 v[98:101], v[134:137], v[206:209], v[98:101]
	v_mfma_f32_16x16x32_bf16 v[90:93], v[142:145], v[206:209], v[90:93]
	v_mfma_f32_16x16x32_bf16 v[82:85], v[134:137], v[214:217], v[82:85]
	v_mfma_f32_16x16x32_bf16 v[74:77], v[142:145], v[214:217], v[74:77]
	v_mfma_f32_16x16x32_bf16 v[118:121], v[162:165], v[184:187], 0
	v_mfma_f32_16x16x32_bf16 v[114:117], v[176:179], v[184:187], 0
	v_mfma_f32_16x16x32_bf16 v[102:105], v[162:165], v[192:195], 0
	v_mfma_f32_16x16x32_bf16 v[94:97], v[176:179], v[192:195], 0
	v_mfma_f32_16x16x32_bf16 v[86:89], v[162:165], v[200:203], 0
	v_mfma_f32_16x16x32_bf16 v[78:81], v[176:179], v[200:203], 0
	v_mfma_f32_16x16x32_bf16 v[70:73], v[162:165], v[210:213], 0
	v_mfma_f32_16x16x32_bf16 v[66:69], v[176:179], v[210:213], 0
	v_mfma_f32_16x16x32_bf16 v[118:121], v[172:175], v[188:191], v[118:121]
	v_mfma_f32_16x16x32_bf16 v[114:117], v[180:183], v[188:191], v[114:117]
	v_mfma_f32_16x16x32_bf16 v[102:105], v[172:175], v[196:199], v[102:105]
	v_mfma_f32_16x16x32_bf16 v[94:97], v[180:183], v[196:199], v[94:97]
	v_mfma_f32_16x16x32_bf16 v[86:89], v[172:175], v[206:209], v[86:89]
	v_mfma_f32_16x16x32_bf16 v[78:81], v[180:183], v[206:209], v[78:81]
	v_mfma_f32_16x16x32_bf16 v[70:73], v[172:175], v[214:217], v[70:73]
	v_mfma_f32_16x16x32_bf16 v[66:69], v[180:183], v[214:217], v[66:69]
	s_setprio 0
	s_barrier
	s_add_i32 s94, s31, s2
	v_lshl_add_u64 v[218:219], s[62:63], 0, v[148:149]
	s_mov_b32 m0, s94
	ds_read_b128 v[184:187], v170 offset:16384
	ds_read_b128 v[188:191], v170 offset:17408
	ds_read_b128 v[192:195], v170 offset:18432
	ds_read_b128 v[196:199], v170 offset:19456
	ds_read_b128 v[200:203], v170 offset:20480
	ds_read_b128 v[206:209], v170 offset:21504
	ds_read_b128 v[210:213], v170 offset:22528
	ds_read_b128 v[214:217], v170 offset:23552
	global_load_lds_dwordx4 v[218:219], off
	s_add_i32 m0, s94, 0x2000
	s_add_u32 s94, s62, 0x100000
	v_lshl_add_u64 v[220:221], s[62:63], 0, v[152:153]
	s_addc_u32 s95, s63, 0
	s_add_i32 s96, s82, s2
	global_load_lds_dwordx4 v[220:221], off
	v_lshl_add_u64 v[222:223], s[94:95], 0, v[148:149]
	s_mov_b32 m0, s96
	v_lshl_add_u64 v[224:225], s[64:65], 0, v[150:151]
	global_load_lds_dwordx4 v[222:223], off
	s_add_i32 m0, s96, 0x2000
	v_lshl_add_u64 v[222:223], s[94:95], 0, v[152:153]
	global_load_lds_dwordx4 v[222:223], off
	s_mov_b32 m0, s12
	v_lshl_add_u64 v[222:223], s[64:65], 0, v[146:147]
	global_load_lds_dwordx4 v[222:223], off
	s_mov_b32 m0, s13
	s_nop 0
	global_load_lds_dwordx4 v[224:225], off
	s_setprio 1
	s_waitcnt vmcnt(8) lgkmcnt(0)
	s_barrier
	v_mfma_f32_16x16x32_bf16 v[62:65], v[130:133], v[184:187], 0
	v_mfma_f32_16x16x32_bf16 v[58:61], v[138:141], v[184:187], 0
	v_mfma_f32_16x16x32_bf16 v[50:53], v[130:133], v[192:195], 0
	v_mfma_f32_16x16x32_bf16 v[42:45], v[138:141], v[192:195], 0
	v_mfma_f32_16x16x32_bf16 v[34:37], v[130:133], v[200:203], 0
	v_mfma_f32_16x16x32_bf16 v[26:29], v[138:141], v[200:203], 0
	v_mfma_f32_16x16x32_bf16 v[18:21], v[130:133], v[210:213], 0
	v_mfma_f32_16x16x32_bf16 v[10:13], v[138:141], v[210:213], 0
	v_mfma_f32_16x16x32_bf16 v[62:65], v[134:137], v[188:191], v[62:65]
	v_mfma_f32_16x16x32_bf16 v[58:61], v[142:145], v[188:191], v[58:61]
	v_mfma_f32_16x16x32_bf16 v[50:53], v[134:137], v[196:199], v[50:53]
	v_mfma_f32_16x16x32_bf16 v[42:45], v[142:145], v[196:199], v[42:45]
	v_mfma_f32_16x16x32_bf16 v[34:37], v[134:137], v[206:209], v[34:37]
	v_mfma_f32_16x16x32_bf16 v[26:29], v[142:145], v[206:209], v[26:29]
	v_mfma_f32_16x16x32_bf16 v[18:21], v[134:137], v[214:217], v[18:21]
	v_mfma_f32_16x16x32_bf16 v[10:13], v[142:145], v[214:217], v[10:13]
	v_mfma_f32_16x16x32_bf16 v[54:57], v[162:165], v[184:187], 0
	v_mfma_f32_16x16x32_bf16 v[46:49], v[176:179], v[184:187], 0
	v_mfma_f32_16x16x32_bf16 v[38:41], v[162:165], v[192:195], 0
	v_mfma_f32_16x16x32_bf16 v[30:33], v[176:179], v[192:195], 0
	v_mfma_f32_16x16x32_bf16 v[22:25], v[162:165], v[200:203], 0
	v_mfma_f32_16x16x32_bf16 v[14:17], v[176:179], v[200:203], 0
	v_mfma_f32_16x16x32_bf16 v[6:9], v[162:165], v[210:213], 0
	v_mfma_f32_16x16x32_bf16 v[2:5], v[176:179], v[210:213], 0
	v_mfma_f32_16x16x32_bf16 v[54:57], v[172:175], v[188:191], v[54:57]
	v_mfma_f32_16x16x32_bf16 v[46:49], v[180:183], v[188:191], v[46:49]
	v_mfma_f32_16x16x32_bf16 v[38:41], v[172:175], v[196:199], v[38:41]
	v_mfma_f32_16x16x32_bf16 v[30:33], v[180:183], v[196:199], v[30:33]
	v_mfma_f32_16x16x32_bf16 v[22:25], v[172:175], v[206:209], v[22:25]
	v_mfma_f32_16x16x32_bf16 v[14:17], v[180:183], v[206:209], v[14:17]
	v_mfma_f32_16x16x32_bf16 v[6:9], v[172:175], v[214:217], v[6:9]
	v_mfma_f32_16x16x32_bf16 v[2:5], v[180:183], v[214:217], v[2:5]
	s_setprio 0
	s_barrier
	s_add_i32 s94, 0, 0x18000
	s_add_i32 s95, 0, 0x1c000
	v_add_u32_e32 v142, s94, v167
	v_add_u32_e32 v154, s95, v167
	ds_read_b128 v[130:133], v142
	ds_read_b128 v[134:137], v142 offset:1024
	ds_read_b128 v[138:141], v142 offset:2048
	ds_read_b128 v[142:145], v142 offset:3072
	ds_read_b128 v[162:165], v154
	ds_read_b128 v[172:175], v154 offset:1024
	ds_read_b128 v[176:179], v154 offset:2048
	ds_read_b128 v[180:183], v154 offset:3072
	s_add_u32 s64, s64, 0x100000
	s_addc_u32 s65, s65, 0
	s_mov_b32 m0, s18
	v_lshl_add_u64 v[226:227], s[64:65], 0, v[146:147]
	ds_read_b128 v[184:187], v170 offset:32768
	ds_read_b128 v[188:191], v170 offset:33792
	ds_read_b128 v[192:195], v170 offset:34816
	ds_read_b128 v[196:199], v170 offset:35840
	ds_read_b128 v[200:203], v170 offset:36864
	ds_read_b128 v[206:209], v170 offset:37888
	ds_read_b128 v[210:213], v170 offset:38912
	ds_read_b128 v[214:217], v170 offset:39936
	global_load_lds_dwordx4 v[226:227], off
	s_mov_b32 m0, s19
	v_lshl_add_u64 v[226:227], s[64:65], 0, v[150:151]
	global_load_lds_dwordx4 v[226:227], off
	s_setprio 1
	s_waitcnt vmcnt(8) lgkmcnt(0)
	s_barrier
	v_mfma_f32_16x16x32_bf16 v[126:129], v[130:133], v[184:187], v[126:129]
	v_mfma_f32_16x16x32_bf16 v[122:125], v[138:141], v[184:187], v[122:125]
	v_mfma_f32_16x16x32_bf16 v[110:113], v[130:133], v[192:195], v[110:113]
	v_mfma_f32_16x16x32_bf16 v[106:109], v[138:141], v[192:195], v[106:109]
	v_mfma_f32_16x16x32_bf16 v[98:101], v[130:133], v[200:203], v[98:101]
	v_mfma_f32_16x16x32_bf16 v[90:93], v[138:141], v[200:203], v[90:93]
	v_mfma_f32_16x16x32_bf16 v[82:85], v[130:133], v[210:213], v[82:85]
	v_mfma_f32_16x16x32_bf16 v[74:77], v[138:141], v[210:213], v[74:77]
	v_mfma_f32_16x16x32_bf16 v[126:129], v[134:137], v[188:191], v[126:129]
	v_mfma_f32_16x16x32_bf16 v[122:125], v[142:145], v[188:191], v[122:125]
	v_mfma_f32_16x16x32_bf16 v[110:113], v[134:137], v[196:199], v[110:113]
	v_mfma_f32_16x16x32_bf16 v[106:109], v[142:145], v[196:199], v[106:109]
	v_mfma_f32_16x16x32_bf16 v[98:101], v[134:137], v[206:209], v[98:101]
	v_mfma_f32_16x16x32_bf16 v[90:93], v[142:145], v[206:209], v[90:93]
	v_mfma_f32_16x16x32_bf16 v[82:85], v[134:137], v[214:217], v[82:85]
	v_mfma_f32_16x16x32_bf16 v[74:77], v[142:145], v[214:217], v[74:77]
	v_mfma_f32_16x16x32_bf16 v[118:121], v[162:165], v[184:187], v[118:121]
	v_mfma_f32_16x16x32_bf16 v[114:117], v[176:179], v[184:187], v[114:117]
	v_mfma_f32_16x16x32_bf16 v[102:105], v[162:165], v[192:195], v[102:105]
	v_mfma_f32_16x16x32_bf16 v[94:97], v[176:179], v[192:195], v[94:97]
	v_mfma_f32_16x16x32_bf16 v[86:89], v[162:165], v[200:203], v[86:89]
	v_mfma_f32_16x16x32_bf16 v[78:81], v[176:179], v[200:203], v[78:81]
	v_mfma_f32_16x16x32_bf16 v[70:73], v[162:165], v[210:213], v[70:73]
	v_mfma_f32_16x16x32_bf16 v[66:69], v[176:179], v[210:213], v[66:69]
	v_mfma_f32_16x16x32_bf16 v[118:121], v[172:175], v[188:191], v[118:121]
	v_mfma_f32_16x16x32_bf16 v[114:117], v[180:183], v[188:191], v[114:117]
	v_mfma_f32_16x16x32_bf16 v[102:105], v[172:175], v[196:199], v[102:105]
	v_mfma_f32_16x16x32_bf16 v[94:97], v[180:183], v[196:199], v[94:97]
	v_mfma_f32_16x16x32_bf16 v[86:89], v[172:175], v[206:209], v[86:89]
	v_mfma_f32_16x16x32_bf16 v[78:81], v[180:183], v[206:209], v[78:81]
	v_mfma_f32_16x16x32_bf16 v[70:73], v[172:175], v[214:217], v[70:73]
	v_mfma_f32_16x16x32_bf16 v[66:69], v[180:183], v[214:217], v[66:69]
	s_setprio 0
	s_barrier
	s_add_i32 s64, s94, s2
	v_lshl_add_u64 v[218:219], v[218:219], 0, s[16:17]
	s_mov_b32 m0, s64
	ds_read_b128 v[184:187], v170 offset:49152
	ds_read_b128 v[188:191], v170 offset:50176
	ds_read_b128 v[192:195], v170 offset:51200
	ds_read_b128 v[196:199], v170 offset:52224
	ds_read_b128 v[200:203], v170 offset:53248
	ds_read_b128 v[206:209], v170 offset:54272
	ds_read_b128 v[210:213], v170 offset:55296
	ds_read_b128 v[214:217], v170 offset:56320
	global_load_lds_dwordx4 v[218:219], off
	s_add_i32 m0, s64, 0x2000
	s_add_u32 s62, s62, 0x100080
	v_lshl_add_u64 v[218:219], v[220:221], 0, s[16:17]
	s_addc_u32 s63, s63, 0
	s_add_i32 s64, s95, s2
	global_load_lds_dwordx4 v[218:219], off
	s_mov_b32 m0, s64
	v_lshl_add_u64 v[218:219], s[62:63], 0, v[148:149]
	global_load_lds_dwordx4 v[218:219], off
	s_add_i32 m0, s64, 0x2000
	v_lshl_add_u64 v[218:219], s[62:63], 0, v[152:153]
	global_load_lds_dwordx4 v[218:219], off
	s_mov_b32 m0, s74
	v_lshl_add_u64 v[218:219], v[222:223], 0, s[16:17]
	global_load_lds_dwordx4 v[218:219], off
	s_mov_b32 m0, s75
	v_lshl_add_u64 v[218:219], v[224:225], 0, s[16:17]
	global_load_lds_dwordx4 v[218:219], off
	s_setprio 1
	s_waitcnt vmcnt(8) lgkmcnt(0)
	s_barrier
	v_mfma_f32_16x16x32_bf16 v[62:65], v[130:133], v[184:187], v[62:65]
	v_mfma_f32_16x16x32_bf16 v[58:61], v[138:141], v[184:187], v[58:61]
	v_mfma_f32_16x16x32_bf16 v[50:53], v[130:133], v[192:195], v[50:53]
	v_mfma_f32_16x16x32_bf16 v[42:45], v[138:141], v[192:195], v[42:45]
	v_mfma_f32_16x16x32_bf16 v[34:37], v[130:133], v[200:203], v[34:37]
	v_mfma_f32_16x16x32_bf16 v[26:29], v[138:141], v[200:203], v[26:29]
	v_mfma_f32_16x16x32_bf16 v[18:21], v[130:133], v[210:213], v[18:21]
	v_mfma_f32_16x16x32_bf16 v[10:13], v[138:141], v[210:213], v[10:13]
	v_mfma_f32_16x16x32_bf16 v[62:65], v[134:137], v[188:191], v[62:65]
	v_mfma_f32_16x16x32_bf16 v[58:61], v[142:145], v[188:191], v[58:61]
	v_mfma_f32_16x16x32_bf16 v[50:53], v[134:137], v[196:199], v[50:53]
	v_mfma_f32_16x16x32_bf16 v[42:45], v[142:145], v[196:199], v[42:45]
	v_mfma_f32_16x16x32_bf16 v[34:37], v[134:137], v[206:209], v[34:37]
	v_mfma_f32_16x16x32_bf16 v[26:29], v[142:145], v[206:209], v[26:29]
	v_mfma_f32_16x16x32_bf16 v[18:21], v[134:137], v[214:217], v[18:21]
	v_mfma_f32_16x16x32_bf16 v[10:13], v[142:145], v[214:217], v[10:13]
	v_mfma_f32_16x16x32_bf16 v[54:57], v[162:165], v[184:187], v[54:57]
	v_mfma_f32_16x16x32_bf16 v[46:49], v[176:179], v[184:187], v[46:49]
	v_mfma_f32_16x16x32_bf16 v[38:41], v[162:165], v[192:195], v[38:41]
	v_mfma_f32_16x16x32_bf16 v[30:33], v[176:179], v[192:195], v[30:33]
	v_mfma_f32_16x16x32_bf16 v[22:25], v[162:165], v[200:203], v[22:25]
	v_mfma_f32_16x16x32_bf16 v[14:17], v[176:179], v[200:203], v[14:17]
	v_mfma_f32_16x16x32_bf16 v[6:9], v[162:165], v[210:213], v[6:9]
	v_mfma_f32_16x16x32_bf16 v[2:5], v[176:179], v[210:213], v[2:5]
	v_mfma_f32_16x16x32_bf16 v[54:57], v[172:175], v[188:191], v[54:57]
	v_mfma_f32_16x16x32_bf16 v[46:49], v[180:183], v[188:191], v[46:49]
	v_mfma_f32_16x16x32_bf16 v[38:41], v[172:175], v[196:199], v[38:41]
	v_mfma_f32_16x16x32_bf16 v[30:33], v[180:183], v[196:199], v[30:33]
	v_mfma_f32_16x16x32_bf16 v[22:25], v[172:175], v[206:209], v[22:25]
	v_mfma_f32_16x16x32_bf16 v[14:17], v[180:183], v[206:209], v[14:17]
	v_mfma_f32_16x16x32_bf16 v[6:9], v[172:175], v[214:217], v[6:9]
	v_mfma_f32_16x16x32_bf16 v[2:5], v[180:183], v[214:217], v[2:5]
	s_setprio 0
	s_barrier
	s_add_u32 s50, s50, 0x100
	s_addc_u32 s51, s51, 0
	s_add_u32 s91, s91, 0x100
	s_addc_u32 s92, s92, 0
	s_cmp_ge_i32 s93, s7
	s_mov_b32 s62, s93
.LBB0_1708:
	ds_read_b128 v[130:133], v168
	ds_read_b128 v[134:137], v168 offset:1024
	ds_read_b128 v[138:141], v168 offset:2048
	ds_read_b128 v[142:145], v168 offset:3072
	ds_read_b128 v[162:165], v169
	ds_read_b128 v[172:175], v169 offset:1024
	ds_read_b128 v[176:179], v169 offset:2048
	ds_read_b128 v[180:183], v169 offset:3072
	s_add_i32 s93, s62, 2
	s_add_u32 s63, s50, 0xfff00080
	s_addc_u32 s64, s51, -1
	s_cmp_eq_u32 s69, s62
	s_cselect_b32 s62, s68, s91
	s_cselect_b32 s65, s34, s64
	s_cselect_b32 s64, s66, s63
	s_cselect_b32 s63, s67, s92
	v_lshl_add_u64 v[218:219], s[50:51], 0, v[156:157]
	s_add_i32 m0, s12, 0xc000
	ds_read_b128 v[184:187], v170
	ds_read_b128 v[188:191], v170 offset:1024
	ds_read_b128 v[192:195], v170 offset:2048
	ds_read_b128 v[196:199], v170 offset:3072
	ds_read_b128 v[200:203], v170 offset:4096
	ds_read_b128 v[206:209], v170 offset:5120
	ds_read_b128 v[210:213], v170 offset:6144
	ds_read_b128 v[214:217], v170 offset:7168
	global_load_lds_dwordx4 v[218:219], off
	s_add_i32 m0, s12, 0xe000
	v_lshl_add_u64 v[218:219], s[50:51], 0, v[158:159]
	global_load_lds_dwordx4 v[218:219], off
	s_setprio 1
	s_waitcnt vmcnt(8) lgkmcnt(0)
	s_barrier
	v_mfma_f32_16x16x32_bf16 v[126:129], v[130:133], v[184:187], v[126:129]
	v_mfma_f32_16x16x32_bf16 v[122:125], v[138:141], v[184:187], v[122:125]
	v_mfma_f32_16x16x32_bf16 v[110:113], v[130:133], v[192:195], v[110:113]
	v_mfma_f32_16x16x32_bf16 v[106:109], v[138:141], v[192:195], v[106:109]
	v_mfma_f32_16x16x32_bf16 v[98:101], v[130:133], v[200:203], v[98:101]
	v_mfma_f32_16x16x32_bf16 v[90:93], v[138:141], v[200:203], v[90:93]
	v_mfma_f32_16x16x32_bf16 v[82:85], v[130:133], v[210:213], v[82:85]
	v_mfma_f32_16x16x32_bf16 v[74:77], v[138:141], v[210:213], v[74:77]
	v_mfma_f32_16x16x32_bf16 v[126:129], v[134:137], v[188:191], v[126:129]
	v_mfma_f32_16x16x32_bf16 v[122:125], v[142:145], v[188:191], v[122:125]
	v_mfma_f32_16x16x32_bf16 v[110:113], v[134:137], v[196:199], v[110:113]
	v_mfma_f32_16x16x32_bf16 v[106:109], v[142:145], v[196:199], v[106:109]
	v_mfma_f32_16x16x32_bf16 v[98:101], v[134:137], v[206:209], v[98:101]
	v_mfma_f32_16x16x32_bf16 v[90:93], v[142:145], v[206:209], v[90:93]
	v_mfma_f32_16x16x32_bf16 v[82:85], v[134:137], v[214:217], v[82:85]
	v_mfma_f32_16x16x32_bf16 v[74:77], v[142:145], v[214:217], v[74:77]
	v_mfma_f32_16x16x32_bf16 v[118:121], v[162:165], v[184:187], v[118:121]
	v_mfma_f32_16x16x32_bf16 v[114:117], v[176:179], v[184:187], v[114:117]
	v_mfma_f32_16x16x32_bf16 v[102:105], v[162:165], v[192:195], v[102:105]
	v_mfma_f32_16x16x32_bf16 v[94:97], v[176:179], v[192:195], v[94:97]
	v_mfma_f32_16x16x32_bf16 v[86:89], v[162:165], v[200:203], v[86:89]
	v_mfma_f32_16x16x32_bf16 v[78:81], v[176:179], v[200:203], v[78:81]
	v_mfma_f32_16x16x32_bf16 v[70:73], v[162:165], v[210:213], v[70:73]
	v_mfma_f32_16x16x32_bf16 v[66:69], v[176:179], v[210:213], v[66:69]
	v_mfma_f32_16x16x32_bf16 v[118:121], v[172:175], v[188:191], v[118:121]
	v_mfma_f32_16x16x32_bf16 v[114:117], v[180:183], v[188:191], v[114:117]
	v_mfma_f32_16x16x32_bf16 v[102:105], v[172:175], v[196:199], v[102:105]
	v_mfma_f32_16x16x32_bf16 v[94:97], v[180:183], v[196:199], v[94:97]
	v_mfma_f32_16x16x32_bf16 v[86:89], v[172:175], v[206:209], v[86:89]
	v_mfma_f32_16x16x32_bf16 v[78:81], v[180:183], v[206:209], v[78:81]
	v_mfma_f32_16x16x32_bf16 v[70:73], v[172:175], v[214:217], v[70:73]
	v_mfma_f32_16x16x32_bf16 v[66:69], v[180:183], v[214:217], v[66:69]
	s_setprio 0
	s_barrier
	s_add_i32 s94, s31, s2
	v_lshl_add_u64 v[218:219], s[62:63], 0, v[148:149]
	s_mov_b32 m0, s94
	ds_read_b128 v[184:187], v170 offset:16384
	ds_read_b128 v[188:191], v170 offset:17408
	ds_read_b128 v[192:195], v170 offset:18432
	ds_read_b128 v[196:199], v170 offset:19456
	ds_read_b128 v[200:203], v170 offset:20480
	ds_read_b128 v[206:209], v170 offset:21504
	ds_read_b128 v[210:213], v170 offset:22528
	ds_read_b128 v[214:217], v170 offset:23552
	global_load_lds_dwordx4 v[218:219], off
	s_add_i32 m0, s94, 0x2000
	s_add_u32 s94, s62, 0x100000
	v_lshl_add_u64 v[220:221], s[62:63], 0, v[152:153]
	s_addc_u32 s95, s63, 0
	s_add_i32 s96, s82, s2
	global_load_lds_dwordx4 v[220:221], off
	v_lshl_add_u64 v[222:223], s[94:95], 0, v[148:149]
	s_mov_b32 m0, s96
	v_lshl_add_u64 v[224:225], s[64:65], 0, v[150:151]
	global_load_lds_dwordx4 v[222:223], off
	s_add_i32 m0, s96, 0x2000
	v_lshl_add_u64 v[222:223], s[94:95], 0, v[152:153]
	global_load_lds_dwordx4 v[222:223], off
	s_mov_b32 m0, s12
	v_lshl_add_u64 v[222:223], s[64:65], 0, v[146:147]
	global_load_lds_dwordx4 v[222:223], off
	s_mov_b32 m0, s13
	s_nop 0
	global_load_lds_dwordx4 v[224:225], off
	s_setprio 1
	s_waitcnt vmcnt(8) lgkmcnt(0)
	s_barrier
	v_mfma_f32_16x16x32_bf16 v[62:65], v[130:133], v[184:187], v[62:65]
	v_mfma_f32_16x16x32_bf16 v[58:61], v[138:141], v[184:187], v[58:61]
	v_mfma_f32_16x16x32_bf16 v[50:53], v[130:133], v[192:195], v[50:53]
	v_mfma_f32_16x16x32_bf16 v[42:45], v[138:141], v[192:195], v[42:45]
	v_mfma_f32_16x16x32_bf16 v[34:37], v[130:133], v[200:203], v[34:37]
	v_mfma_f32_16x16x32_bf16 v[26:29], v[138:141], v[200:203], v[26:29]
	v_mfma_f32_16x16x32_bf16 v[18:21], v[130:133], v[210:213], v[18:21]
	v_mfma_f32_16x16x32_bf16 v[10:13], v[138:141], v[210:213], v[10:13]
	v_mfma_f32_16x16x32_bf16 v[62:65], v[134:137], v[188:191], v[62:65]
	v_mfma_f32_16x16x32_bf16 v[58:61], v[142:145], v[188:191], v[58:61]
	v_mfma_f32_16x16x32_bf16 v[50:53], v[134:137], v[196:199], v[50:53]
	v_mfma_f32_16x16x32_bf16 v[42:45], v[142:145], v[196:199], v[42:45]
	v_mfma_f32_16x16x32_bf16 v[34:37], v[134:137], v[206:209], v[34:37]
	v_mfma_f32_16x16x32_bf16 v[26:29], v[142:145], v[206:209], v[26:29]
	v_mfma_f32_16x16x32_bf16 v[18:21], v[134:137], v[214:217], v[18:21]
	v_mfma_f32_16x16x32_bf16 v[10:13], v[142:145], v[214:217], v[10:13]
	v_mfma_f32_16x16x32_bf16 v[54:57], v[162:165], v[184:187], v[54:57]
	v_mfma_f32_16x16x32_bf16 v[46:49], v[176:179], v[184:187], v[46:49]
	v_mfma_f32_16x16x32_bf16 v[38:41], v[162:165], v[192:195], v[38:41]
	v_mfma_f32_16x16x32_bf16 v[30:33], v[176:179], v[192:195], v[30:33]
	v_mfma_f32_16x16x32_bf16 v[22:25], v[162:165], v[200:203], v[22:25]
	v_mfma_f32_16x16x32_bf16 v[14:17], v[176:179], v[200:203], v[14:17]
	v_mfma_f32_16x16x32_bf16 v[6:9], v[162:165], v[210:213], v[6:9]
	v_mfma_f32_16x16x32_bf16 v[2:5], v[176:179], v[210:213], v[2:5]
	v_mfma_f32_16x16x32_bf16 v[54:57], v[172:175], v[188:191], v[54:57]
	v_mfma_f32_16x16x32_bf16 v[46:49], v[180:183], v[188:191], v[46:49]
	v_mfma_f32_16x16x32_bf16 v[38:41], v[172:175], v[196:199], v[38:41]
	v_mfma_f32_16x16x32_bf16 v[30:33], v[180:183], v[196:199], v[30:33]
	v_mfma_f32_16x16x32_bf16 v[22:25], v[172:175], v[206:209], v[22:25]
	v_mfma_f32_16x16x32_bf16 v[14:17], v[180:183], v[206:209], v[14:17]
	v_mfma_f32_16x16x32_bf16 v[6:9], v[172:175], v[214:217], v[6:9]
	v_mfma_f32_16x16x32_bf16 v[2:5], v[180:183], v[214:217], v[2:5]
	s_setprio 0
	s_barrier
	s_add_i32 s94, 0, 0x18000
	s_add_i32 s95, 0, 0x1c000
	v_add_u32_e32 v142, s94, v167
	v_add_u32_e32 v154, s95, v167
	ds_read_b128 v[130:133], v142
	ds_read_b128 v[134:137], v142 offset:1024
	ds_read_b128 v[138:141], v142 offset:2048
	ds_read_b128 v[142:145], v142 offset:3072
	ds_read_b128 v[162:165], v154
	ds_read_b128 v[172:175], v154 offset:1024
	ds_read_b128 v[176:179], v154 offset:2048
	ds_read_b128 v[180:183], v154 offset:3072
	s_add_u32 s64, s64, 0x100000
	s_addc_u32 s65, s65, 0
	s_mov_b32 m0, s18
	v_lshl_add_u64 v[226:227], s[64:65], 0, v[146:147]
	ds_read_b128 v[184:187], v170 offset:32768
	ds_read_b128 v[188:191], v170 offset:33792
	ds_read_b128 v[192:195], v170 offset:34816
	ds_read_b128 v[196:199], v170 offset:35840
	ds_read_b128 v[200:203], v170 offset:36864
	ds_read_b128 v[206:209], v170 offset:37888
	ds_read_b128 v[210:213], v170 offset:38912
	ds_read_b128 v[214:217], v170 offset:39936
	global_load_lds_dwordx4 v[226:227], off
	s_mov_b32 m0, s19
	v_lshl_add_u64 v[226:227], s[64:65], 0, v[150:151]
	global_load_lds_dwordx4 v[226:227], off
	s_setprio 1
	s_waitcnt vmcnt(8) lgkmcnt(0)
	s_barrier
	v_mfma_f32_16x16x32_bf16 v[126:129], v[130:133], v[184:187], v[126:129]
	v_mfma_f32_16x16x32_bf16 v[122:125], v[138:141], v[184:187], v[122:125]
	v_mfma_f32_16x16x32_bf16 v[110:113], v[130:133], v[192:195], v[110:113]
	v_mfma_f32_16x16x32_bf16 v[106:109], v[138:141], v[192:195], v[106:109]
	v_mfma_f32_16x16x32_bf16 v[98:101], v[130:133], v[200:203], v[98:101]
	v_mfma_f32_16x16x32_bf16 v[90:93], v[138:141], v[200:203], v[90:93]
	v_mfma_f32_16x16x32_bf16 v[82:85], v[130:133], v[210:213], v[82:85]
	v_mfma_f32_16x16x32_bf16 v[74:77], v[138:141], v[210:213], v[74:77]
	v_mfma_f32_16x16x32_bf16 v[126:129], v[134:137], v[188:191], v[126:129]
	v_mfma_f32_16x16x32_bf16 v[122:125], v[142:145], v[188:191], v[122:125]
	v_mfma_f32_16x16x32_bf16 v[110:113], v[134:137], v[196:199], v[110:113]
	v_mfma_f32_16x16x32_bf16 v[106:109], v[142:145], v[196:199], v[106:109]
	v_mfma_f32_16x16x32_bf16 v[98:101], v[134:137], v[206:209], v[98:101]
	v_mfma_f32_16x16x32_bf16 v[90:93], v[142:145], v[206:209], v[90:93]
	v_mfma_f32_16x16x32_bf16 v[82:85], v[134:137], v[214:217], v[82:85]
	v_mfma_f32_16x16x32_bf16 v[74:77], v[142:145], v[214:217], v[74:77]
	v_mfma_f32_16x16x32_bf16 v[118:121], v[162:165], v[184:187], v[118:121]
	v_mfma_f32_16x16x32_bf16 v[114:117], v[176:179], v[184:187], v[114:117]
	v_mfma_f32_16x16x32_bf16 v[102:105], v[162:165], v[192:195], v[102:105]
	v_mfma_f32_16x16x32_bf16 v[94:97], v[176:179], v[192:195], v[94:97]
	v_mfma_f32_16x16x32_bf16 v[86:89], v[162:165], v[200:203], v[86:89]
	v_mfma_f32_16x16x32_bf16 v[78:81], v[176:179], v[200:203], v[78:81]
	v_mfma_f32_16x16x32_bf16 v[70:73], v[162:165], v[210:213], v[70:73]
	v_mfma_f32_16x16x32_bf16 v[66:69], v[176:179], v[210:213], v[66:69]
	v_mfma_f32_16x16x32_bf16 v[118:121], v[172:175], v[188:191], v[118:121]
	v_mfma_f32_16x16x32_bf16 v[114:117], v[180:183], v[188:191], v[114:117]
	v_mfma_f32_16x16x32_bf16 v[102:105], v[172:175], v[196:199], v[102:105]
	v_mfma_f32_16x16x32_bf16 v[94:97], v[180:183], v[196:199], v[94:97]
	v_mfma_f32_16x16x32_bf16 v[86:89], v[172:175], v[206:209], v[86:89]
	v_mfma_f32_16x16x32_bf16 v[78:81], v[180:183], v[206:209], v[78:81]
	v_mfma_f32_16x16x32_bf16 v[70:73], v[172:175], v[214:217], v[70:73]
	v_mfma_f32_16x16x32_bf16 v[66:69], v[180:183], v[214:217], v[66:69]
	s_setprio 0
	s_barrier
	s_add_i32 s64, s94, s2
	v_lshl_add_u64 v[218:219], v[218:219], 0, s[16:17]
	s_mov_b32 m0, s64
	ds_read_b128 v[184:187], v170 offset:49152
	ds_read_b128 v[188:191], v170 offset:50176
	ds_read_b128 v[192:195], v170 offset:51200
	ds_read_b128 v[196:199], v170 offset:52224
	ds_read_b128 v[200:203], v170 offset:53248
	ds_read_b128 v[206:209], v170 offset:54272
	ds_read_b128 v[210:213], v170 offset:55296
	ds_read_b128 v[214:217], v170 offset:56320
	global_load_lds_dwordx4 v[218:219], off
	s_add_i32 m0, s64, 0x2000
	s_add_u32 s62, s62, 0x100080
	v_lshl_add_u64 v[218:219], v[220:221], 0, s[16:17]
	s_addc_u32 s63, s63, 0
	s_add_i32 s64, s95, s2
	global_load_lds_dwordx4 v[218:219], off
	s_mov_b32 m0, s64
	v_lshl_add_u64 v[218:219], s[62:63], 0, v[148:149]
	global_load_lds_dwordx4 v[218:219], off
	s_add_i32 m0, s64, 0x2000
	v_lshl_add_u64 v[218:219], s[62:63], 0, v[152:153]
	global_load_lds_dwordx4 v[218:219], off
	s_mov_b32 m0, s74
	v_lshl_add_u64 v[218:219], v[222:223], 0, s[16:17]
	global_load_lds_dwordx4 v[218:219], off
	s_mov_b32 m0, s75
	v_lshl_add_u64 v[218:219], v[224:225], 0, s[16:17]
	global_load_lds_dwordx4 v[218:219], off
	s_setprio 1
	s_waitcnt vmcnt(8) lgkmcnt(0)
	s_barrier
	v_mfma_f32_16x16x32_bf16 v[62:65], v[130:133], v[184:187], v[62:65]
	v_mfma_f32_16x16x32_bf16 v[58:61], v[138:141], v[184:187], v[58:61]
	v_mfma_f32_16x16x32_bf16 v[50:53], v[130:133], v[192:195], v[50:53]
	v_mfma_f32_16x16x32_bf16 v[42:45], v[138:141], v[192:195], v[42:45]
	v_mfma_f32_16x16x32_bf16 v[34:37], v[130:133], v[200:203], v[34:37]
	v_mfma_f32_16x16x32_bf16 v[26:29], v[138:141], v[200:203], v[26:29]
	v_mfma_f32_16x16x32_bf16 v[18:21], v[130:133], v[210:213], v[18:21]
	v_mfma_f32_16x16x32_bf16 v[10:13], v[138:141], v[210:213], v[10:13]
	v_mfma_f32_16x16x32_bf16 v[62:65], v[134:137], v[188:191], v[62:65]
	v_mfma_f32_16x16x32_bf16 v[58:61], v[142:145], v[188:191], v[58:61]
	v_mfma_f32_16x16x32_bf16 v[50:53], v[134:137], v[196:199], v[50:53]
	v_mfma_f32_16x16x32_bf16 v[42:45], v[142:145], v[196:199], v[42:45]
	v_mfma_f32_16x16x32_bf16 v[34:37], v[134:137], v[206:209], v[34:37]
	v_mfma_f32_16x16x32_bf16 v[26:29], v[142:145], v[206:209], v[26:29]
	v_mfma_f32_16x16x32_bf16 v[18:21], v[134:137], v[214:217], v[18:21]
	v_mfma_f32_16x16x32_bf16 v[10:13], v[142:145], v[214:217], v[10:13]
	v_mfma_f32_16x16x32_bf16 v[54:57], v[162:165], v[184:187], v[54:57]
	v_mfma_f32_16x16x32_bf16 v[46:49], v[176:179], v[184:187], v[46:49]
	v_mfma_f32_16x16x32_bf16 v[38:41], v[162:165], v[192:195], v[38:41]
	v_mfma_f32_16x16x32_bf16 v[30:33], v[176:179], v[192:195], v[30:33]
	v_mfma_f32_16x16x32_bf16 v[22:25], v[162:165], v[200:203], v[22:25]
	v_mfma_f32_16x16x32_bf16 v[14:17], v[176:179], v[200:203], v[14:17]
	v_mfma_f32_16x16x32_bf16 v[6:9], v[162:165], v[210:213], v[6:9]
	v_mfma_f32_16x16x32_bf16 v[2:5], v[176:179], v[210:213], v[2:5]
	v_mfma_f32_16x16x32_bf16 v[54:57], v[172:175], v[188:191], v[54:57]
	v_mfma_f32_16x16x32_bf16 v[46:49], v[180:183], v[188:191], v[46:49]
	v_mfma_f32_16x16x32_bf16 v[38:41], v[172:175], v[196:199], v[38:41]
	v_mfma_f32_16x16x32_bf16 v[30:33], v[180:183], v[196:199], v[30:33]
	v_mfma_f32_16x16x32_bf16 v[22:25], v[172:175], v[206:209], v[22:25]
	v_mfma_f32_16x16x32_bf16 v[14:17], v[180:183], v[206:209], v[14:17]
	v_mfma_f32_16x16x32_bf16 v[6:9], v[172:175], v[214:217], v[6:9]
	v_mfma_f32_16x16x32_bf16 v[2:5], v[180:183], v[214:217], v[2:5]
	s_setprio 0
	s_barrier
	s_add_u32 s50, s50, 0x100
	s_addc_u32 s51, s51, 0
	s_add_u32 s91, s91, 0x100
	s_addc_u32 s92, s92, 0
	s_cmp_ge_i32 s93, s7
	s_mov_b32 s62, s93
	s_cbranch_scc0 .LBB0_1708
	s_and_b64 vcc, exec, s[20:21]
	s_cbranch_vccz .LBB0_1711
	s_barrier
